# PEER expert gathers: row addresses formed with scalar adds (SGPR base + per-lane VGPR offset) instead of a 64-bit VALU add per row
# speedup vs baseline: 1.0651x; 1.0020x over previous
.LBB0_2100:
	v_cmp_gt_u32_e64 s[12:13], 64, v127
	s_nop 1
	v_cndmask_b32_e64 v70, v118, v117, s[12:13]
	v_readfirstlane_b32 s92, v127
	v_readfirstlane_b32 s93, v38
	v_readfirstlane_b32 s94, v39
	s_nop 1
	v_subrev_u32_e32 v255, s93, v38
	s_nop 1
	s_and_b32 s92, s92, 32
	s_cbranch_scc1 .Lh3_u10_hi
	v_readlane_b32 s84, v70, 0
	v_readlane_b32 s86, v70, 1
	v_readlane_b32 s88, v70, 2
	v_readlane_b32 s90, v70, 3
	s_lshl_b32 s84, s84, 9
	s_lshl_b32 s86, s86, 9
	s_lshl_b32 s88, s88, 9
	s_lshl_b32 s90, s90, 9
	s_add_u32 s84, s93, s84
	s_addc_u32 s85, s94, 0
	s_add_u32 s86, s93, s86
	s_addc_u32 s87, s94, 0
	s_add_u32 s88, s93, s88
	s_addc_u32 s89, s94, 0
	s_add_u32 s90, s93, s90
	s_addc_u32 s91, s94, 0
	global_load_dwordx2 v[72:73], v255, s[84:85]
	global_load_dwordx2 v[74:75], v255, s[86:87]
	global_load_dwordx2 v[76:77], v255, s[88:89]
	global_load_dwordx2 v[78:79], v255, s[90:91]
	v_readlane_b32 s84, v70, 4
	v_readlane_b32 s86, v70, 5
	v_readlane_b32 s88, v70, 6
	v_readlane_b32 s90, v70, 7
	s_lshl_b32 s84, s84, 9
	s_lshl_b32 s86, s86, 9
	s_lshl_b32 s88, s88, 9
	s_lshl_b32 s90, s90, 9
	s_add_u32 s84, s93, s84
	s_addc_u32 s85, s94, 0
	s_add_u32 s86, s93, s86
	s_addc_u32 s87, s94, 0
	s_add_u32 s88, s93, s88
	s_addc_u32 s89, s94, 0
	s_add_u32 s90, s93, s90
	s_addc_u32 s91, s94, 0
	global_load_dwordx2 v[80:81], v255, s[84:85]
	global_load_dwordx2 v[82:83], v255, s[86:87]
	global_load_dwordx2 v[84:85], v255, s[88:89]
	global_load_dwordx2 v[86:87], v255, s[90:91]
	v_readlane_b32 s84, v70, 8
	v_readlane_b32 s86, v70, 9
	v_readlane_b32 s88, v70, 10
	v_readlane_b32 s90, v70, 11
	s_lshl_b32 s84, s84, 9
	s_lshl_b32 s86, s86, 9
	s_lshl_b32 s88, s88, 9
	s_lshl_b32 s90, s90, 9
	s_add_u32 s84, s93, s84
	s_addc_u32 s85, s94, 0
	s_add_u32 s86, s93, s86
	s_addc_u32 s87, s94, 0
	s_add_u32 s88, s93, s88
	s_addc_u32 s89, s94, 0
	s_add_u32 s90, s93, s90
	s_addc_u32 s91, s94, 0
	global_load_dwordx2 v[88:89], v255, s[84:85]
	global_load_dwordx2 v[90:91], v255, s[86:87]
	global_load_dwordx2 v[92:93], v255, s[88:89]
	global_load_dwordx2 v[94:95], v255, s[90:91]
	v_readlane_b32 s84, v70, 12
	v_readlane_b32 s86, v70, 13
	v_readlane_b32 s88, v70, 14
	v_readlane_b32 s90, v70, 15
	s_lshl_b32 s84, s84, 9
	s_lshl_b32 s86, s86, 9
	s_lshl_b32 s88, s88, 9
	s_lshl_b32 s90, s90, 9
	s_add_u32 s84, s93, s84
	s_addc_u32 s85, s94, 0
	s_add_u32 s86, s93, s86
	s_addc_u32 s87, s94, 0
	s_add_u32 s88, s93, s88
	s_addc_u32 s89, s94, 0
	s_add_u32 s90, s93, s90
	s_addc_u32 s91, s94, 0
	global_load_dwordx2 v[96:97], v255, s[84:85]
	global_load_dwordx2 v[98:99], v255, s[86:87]
	global_load_dwordx2 v[100:101], v255, s[88:89]
	global_load_dwordx2 v[102:103], v255, s[90:91]
	v_readlane_b32 s84, v70, 16
	v_readlane_b32 s86, v70, 17
	v_readlane_b32 s88, v70, 18
	v_readlane_b32 s90, v70, 19
	s_lshl_b32 s84, s84, 9
	s_lshl_b32 s86, s86, 9
	s_lshl_b32 s88, s88, 9
	s_lshl_b32 s90, s90, 9
	s_add_u32 s84, s93, s84
	s_addc_u32 s85, s94, 0
	s_add_u32 s86, s93, s86
	s_addc_u32 s87, s94, 0
	s_add_u32 s88, s93, s88
	s_addc_u32 s89, s94, 0
	s_add_u32 s90, s93, s90
	s_addc_u32 s91, s94, 0
	global_load_dwordx2 v[20:21], v255, s[84:85]
	global_load_dwordx2 v[22:23], v255, s[86:87]
	global_load_dwordx2 v[24:25], v255, s[88:89]
	global_load_dwordx2 v[26:27], v255, s[90:91]
	v_readlane_b32 s84, v70, 20
	v_readlane_b32 s86, v70, 21
	v_readlane_b32 s88, v70, 22
	v_readlane_b32 s90, v70, 23
	s_lshl_b32 s84, s84, 9
	s_lshl_b32 s86, s86, 9
	s_lshl_b32 s88, s88, 9
	s_lshl_b32 s90, s90, 9
	s_add_u32 s84, s93, s84
	s_addc_u32 s85, s94, 0
	s_add_u32 s86, s93, s86
	s_addc_u32 s87, s94, 0
	s_add_u32 s88, s93, s88
	s_addc_u32 s89, s94, 0
	s_add_u32 s90, s93, s90
	s_addc_u32 s91, s94, 0
	global_load_dwordx2 v[28:29], v255, s[84:85]
	global_load_dwordx2 v[30:31], v255, s[86:87]
	global_load_dwordx2 v[32:33], v255, s[88:89]
	global_load_dwordx2 v[34:35], v255, s[90:91]
	v_readlane_b32 s84, v70, 24
	v_readlane_b32 s86, v70, 25
	v_readlane_b32 s88, v70, 26
	v_readlane_b32 s90, v70, 27
	s_lshl_b32 s84, s84, 9
	s_lshl_b32 s86, s86, 9
	s_lshl_b32 s88, s88, 9
	s_lshl_b32 s90, s90, 9
	s_add_u32 s84, s93, s84
	s_addc_u32 s85, s94, 0
	s_add_u32 s86, s93, s86
	s_addc_u32 s87, s94, 0
	s_add_u32 s88, s93, s88
	s_addc_u32 s89, s94, 0
	s_add_u32 s90, s93, s90
	s_addc_u32 s91, s94, 0
	global_load_dwordx2 v[56:57], v255, s[84:85]
	global_load_dwordx2 v[58:59], v255, s[86:87]
	global_load_dwordx2 v[60:61], v255, s[88:89]
	global_load_dwordx2 v[62:63], v255, s[90:91]
	v_readlane_b32 s84, v70, 28
	v_readlane_b32 s86, v70, 29
	v_readlane_b32 s88, v70, 30
	v_readlane_b32 s90, v70, 31
	s_lshl_b32 s84, s84, 9
	s_lshl_b32 s86, s86, 9
	s_lshl_b32 s88, s88, 9
	s_lshl_b32 s90, s90, 9
	s_add_u32 s84, s93, s84
	s_addc_u32 s85, s94, 0
	s_add_u32 s86, s93, s86
	s_addc_u32 s87, s94, 0
	s_add_u32 s88, s93, s88
	s_addc_u32 s89, s94, 0
	s_add_u32 s90, s93, s90
	s_addc_u32 s91, s94, 0
	global_load_dwordx2 v[64:65], v255, s[84:85]
	global_load_dwordx2 v[66:67], v255, s[86:87]
	global_load_dwordx2 v[68:69], v255, s[88:89]
	global_load_dwordx2 v[70:71], v255, s[90:91]
	s_waitcnt vmcnt(31)
	v_cvt_scalef32_pk_f32_fp4 v[132:133], v72, 1.0 op_sel:[1,0,0]
	s_nop 0
	v_cvt_scalef32_pk_f32_fp4 v[130:131], v72, 1.0
	v_pk_mul_f32 v[132:133], v[132:133], v[6:7]
	s_nop 0
	v_pk_fma_f32 v[130:131], v[130:131], v[4:5], v[132:133]
	v_cvt_scalef32_pk_f32_fp4 v[132:133], v72, 1.0 op_sel:[0,1,0]
	v_pk_fma_f32 v[130:131], v[132:133], v[8:9], v[130:131]
	v_cvt_scalef32_pk_f32_fp4 v[132:133], v72, 1.0 op_sel:[1,1,0]
	v_pk_fma_f32 v[130:131], v[132:133], v[10:11], v[130:131]
	v_cvt_scalef32_pk_f32_fp4 v[132:133], v73, 1.0
	v_pk_fma_f32 v[130:131], v[132:133], v[12:13], v[130:131]
	v_cvt_scalef32_pk_f32_fp4 v[132:133], v73, 1.0 op_sel:[1,0,0]
	v_pk_fma_f32 v[130:131], v[132:133], v[14:15], v[130:131]
	v_cvt_scalef32_pk_f32_fp4 v[132:133], v73, 1.0 op_sel:[0,1,0]
	v_pk_fma_f32 v[130:131], v[132:133], v[16:17], v[130:131]
	v_cvt_scalef32_pk_f32_fp4 v[72:73], v73, 1.0 op_sel:[1,1,0]
	v_pk_fma_f32 v[72:73], v[72:73], v[18:19], v[130:131]
	s_waitcnt vmcnt(30)
	v_cvt_scalef32_pk_f32_fp4 v[130:131], v74, 1.0 op_sel:[1,0,0]
	v_add_f32_e32 v132, v72, v73
	v_cvt_scalef32_pk_f32_fp4 v[72:73], v74, 1.0
	v_pk_mul_f32 v[130:131], v[130:131], v[6:7]
	s_nop 0
	v_pk_fma_f32 v[72:73], v[72:73], v[4:5], v[130:131]
	v_cvt_scalef32_pk_f32_fp4 v[130:131], v74, 1.0 op_sel:[0,1,0]
	v_pk_fma_f32 v[72:73], v[130:131], v[8:9], v[72:73]
	v_cvt_scalef32_pk_f32_fp4 v[130:131], v74, 1.0 op_sel:[1,1,0]
	v_pk_fma_f32 v[72:73], v[130:131], v[10:11], v[72:73]
	v_cvt_scalef32_pk_f32_fp4 v[130:131], v75, 1.0
	v_pk_fma_f32 v[72:73], v[130:131], v[12:13], v[72:73]
	v_cvt_scalef32_pk_f32_fp4 v[130:131], v75, 1.0 op_sel:[1,0,0]
	v_pk_fma_f32 v[72:73], v[130:131], v[14:15], v[72:73]
	v_cvt_scalef32_pk_f32_fp4 v[130:131], v75, 1.0 op_sel:[0,1,0]
	v_pk_fma_f32 v[72:73], v[130:131], v[16:17], v[72:73]
	v_cvt_scalef32_pk_f32_fp4 v[74:75], v75, 1.0 op_sel:[1,1,0]
	v_pk_fma_f32 v[72:73], v[74:75], v[18:19], v[72:73]
	s_waitcnt vmcnt(29)
	v_cvt_scalef32_pk_f32_fp4 v[74:75], v76, 1.0 op_sel:[1,0,0]
	v_add_f32_e32 v130, v72, v73
	v_cvt_scalef32_pk_f32_fp4 v[72:73], v76, 1.0
	v_pk_mul_f32 v[74:75], v[74:75], v[6:7]
	s_nop 0
	v_pk_fma_f32 v[72:73], v[72:73], v[4:5], v[74:75]
	v_cvt_scalef32_pk_f32_fp4 v[74:75], v76, 1.0 op_sel:[0,1,0]
	v_pk_fma_f32 v[72:73], v[74:75], v[8:9], v[72:73]
	v_cvt_scalef32_pk_f32_fp4 v[74:75], v76, 1.0 op_sel:[1,1,0]
	v_pk_fma_f32 v[72:73], v[74:75], v[10:11], v[72:73]
	v_cvt_scalef32_pk_f32_fp4 v[74:75], v77, 1.0
	v_pk_fma_f32 v[72:73], v[74:75], v[12:13], v[72:73]
	v_cvt_scalef32_pk_f32_fp4 v[74:75], v77, 1.0 op_sel:[1,0,0]
	v_pk_fma_f32 v[72:73], v[74:75], v[14:15], v[72:73]
	v_cvt_scalef32_pk_f32_fp4 v[74:75], v77, 1.0 op_sel:[0,1,0]
	v_pk_fma_f32 v[72:73], v[74:75], v[16:17], v[72:73]
	v_cvt_scalef32_pk_f32_fp4 v[74:75], v77, 1.0 op_sel:[1,1,0]
	v_pk_fma_f32 v[72:73], v[74:75], v[18:19], v[72:73]
	s_waitcnt vmcnt(28)
	v_cvt_scalef32_pk_f32_fp4 v[74:75], v78, 1.0 op_sel:[1,0,0]
	v_add_f32_e32 v76, v72, v73
	v_cvt_scalef32_pk_f32_fp4 v[72:73], v78, 1.0
	v_pk_mul_f32 v[74:75], v[74:75], v[6:7]
	s_nop 0
	v_pk_fma_f32 v[72:73], v[72:73], v[4:5], v[74:75]
	v_cvt_scalef32_pk_f32_fp4 v[74:75], v78, 1.0 op_sel:[0,1,0]
	v_pk_fma_f32 v[72:73], v[74:75], v[8:9], v[72:73]
	v_cvt_scalef32_pk_f32_fp4 v[74:75], v78, 1.0 op_sel:[1,1,0]
	v_pk_fma_f32 v[72:73], v[74:75], v[10:11], v[72:73]
	v_cvt_scalef32_pk_f32_fp4 v[74:75], v79, 1.0
	v_pk_fma_f32 v[72:73], v[74:75], v[12:13], v[72:73]
	v_cvt_scalef32_pk_f32_fp4 v[74:75], v79, 1.0 op_sel:[1,0,0]
	v_pk_fma_f32 v[72:73], v[74:75], v[14:15], v[72:73]
	v_cvt_scalef32_pk_f32_fp4 v[74:75], v79, 1.0 op_sel:[0,1,0]
	v_pk_fma_f32 v[72:73], v[74:75], v[16:17], v[72:73]
	v_cvt_scalef32_pk_f32_fp4 v[74:75], v79, 1.0 op_sel:[1,1,0]
	v_pk_fma_f32 v[72:73], v[74:75], v[18:19], v[72:73]
	s_waitcnt vmcnt(27)
	v_cvt_scalef32_pk_f32_fp4 v[74:75], v80, 1.0 op_sel:[1,0,0]
	v_add_f32_e32 v77, v72, v73
	v_cvt_scalef32_pk_f32_fp4 v[72:73], v80, 1.0
	v_pk_mul_f32 v[74:75], v[74:75], v[6:7]
	s_nop 0
	v_pk_fma_f32 v[72:73], v[72:73], v[4:5], v[74:75]
	v_cvt_scalef32_pk_f32_fp4 v[74:75], v80, 1.0 op_sel:[0,1,0]
	v_pk_fma_f32 v[72:73], v[74:75], v[8:9], v[72:73]
	v_cvt_scalef32_pk_f32_fp4 v[74:75], v80, 1.0 op_sel:[1,1,0]
	v_pk_fma_f32 v[72:73], v[74:75], v[10:11], v[72:73]
	v_cvt_scalef32_pk_f32_fp4 v[74:75], v81, 1.0
	v_pk_fma_f32 v[72:73], v[74:75], v[12:13], v[72:73]
	v_cvt_scalef32_pk_f32_fp4 v[74:75], v81, 1.0 op_sel:[1,0,0]
	v_pk_fma_f32 v[72:73], v[74:75], v[14:15], v[72:73]
	v_cvt_scalef32_pk_f32_fp4 v[74:75], v81, 1.0 op_sel:[0,1,0]
	v_pk_fma_f32 v[72:73], v[74:75], v[16:17], v[72:73]
	v_cvt_scalef32_pk_f32_fp4 v[74:75], v81, 1.0 op_sel:[1,1,0]
	v_pk_fma_f32 v[72:73], v[74:75], v[18:19], v[72:73]
	s_waitcnt vmcnt(26)
	v_cvt_scalef32_pk_f32_fp4 v[74:75], v82, 1.0 op_sel:[1,0,0]
	v_add_f32_e32 v78, v72, v73
	v_cvt_scalef32_pk_f32_fp4 v[72:73], v82, 1.0
	v_pk_mul_f32 v[74:75], v[74:75], v[6:7]
	s_nop 0
	v_pk_fma_f32 v[72:73], v[72:73], v[4:5], v[74:75]
	v_cvt_scalef32_pk_f32_fp4 v[74:75], v82, 1.0 op_sel:[0,1,0]
	v_pk_fma_f32 v[72:73], v[74:75], v[8:9], v[72:73]
	v_cvt_scalef32_pk_f32_fp4 v[74:75], v82, 1.0 op_sel:[1,1,0]
	v_pk_fma_f32 v[72:73], v[74:75], v[10:11], v[72:73]
	v_cvt_scalef32_pk_f32_fp4 v[74:75], v83, 1.0
	v_pk_fma_f32 v[72:73], v[74:75], v[12:13], v[72:73]
	v_cvt_scalef32_pk_f32_fp4 v[74:75], v83, 1.0 op_sel:[1,0,0]
	v_pk_fma_f32 v[72:73], v[74:75], v[14:15], v[72:73]
	v_cvt_scalef32_pk_f32_fp4 v[74:75], v83, 1.0 op_sel:[0,1,0]
	v_pk_fma_f32 v[72:73], v[74:75], v[16:17], v[72:73]
	v_cvt_scalef32_pk_f32_fp4 v[74:75], v83, 1.0 op_sel:[1,1,0]
	v_pk_fma_f32 v[72:73], v[74:75], v[18:19], v[72:73]
	s_waitcnt vmcnt(25)
	v_cvt_scalef32_pk_f32_fp4 v[74:75], v84, 1.0 op_sel:[1,0,0]
	v_add_f32_e32 v79, v72, v73
	v_cvt_scalef32_pk_f32_fp4 v[72:73], v84, 1.0
	v_pk_mul_f32 v[74:75], v[74:75], v[6:7]
	s_nop 0
	v_pk_fma_f32 v[72:73], v[72:73], v[4:5], v[74:75]
	v_cvt_scalef32_pk_f32_fp4 v[74:75], v84, 1.0 op_sel:[0,1,0]
	v_pk_fma_f32 v[72:73], v[74:75], v[8:9], v[72:73]
	v_cvt_scalef32_pk_f32_fp4 v[74:75], v84, 1.0 op_sel:[1,1,0]
	v_pk_fma_f32 v[72:73], v[74:75], v[10:11], v[72:73]
	v_cvt_scalef32_pk_f32_fp4 v[74:75], v85, 1.0
	v_pk_fma_f32 v[72:73], v[74:75], v[12:13], v[72:73]
	v_cvt_scalef32_pk_f32_fp4 v[74:75], v85, 1.0 op_sel:[1,0,0]
	v_pk_fma_f32 v[72:73], v[74:75], v[14:15], v[72:73]
	v_cvt_scalef32_pk_f32_fp4 v[74:75], v85, 1.0 op_sel:[0,1,0]
	v_pk_fma_f32 v[72:73], v[74:75], v[16:17], v[72:73]
	v_cvt_scalef32_pk_f32_fp4 v[74:75], v85, 1.0 op_sel:[1,1,0]
	v_pk_fma_f32 v[72:73], v[74:75], v[18:19], v[72:73]
	s_waitcnt vmcnt(24)
	v_cvt_scalef32_pk_f32_fp4 v[74:75], v86, 1.0 op_sel:[1,0,0]
	v_add_f32_e32 v80, v72, v73
	v_cvt_scalef32_pk_f32_fp4 v[72:73], v86, 1.0
	v_pk_mul_f32 v[74:75], v[74:75], v[6:7]
	s_nop 0
	v_pk_fma_f32 v[72:73], v[72:73], v[4:5], v[74:75]
	v_cvt_scalef32_pk_f32_fp4 v[74:75], v86, 1.0 op_sel:[0,1,0]
	v_pk_fma_f32 v[72:73], v[74:75], v[8:9], v[72:73]
	v_cvt_scalef32_pk_f32_fp4 v[74:75], v86, 1.0 op_sel:[1,1,0]
	v_pk_fma_f32 v[72:73], v[74:75], v[10:11], v[72:73]
	v_cvt_scalef32_pk_f32_fp4 v[74:75], v87, 1.0
	v_pk_fma_f32 v[72:73], v[74:75], v[12:13], v[72:73]
	v_cvt_scalef32_pk_f32_fp4 v[74:75], v87, 1.0 op_sel:[1,0,0]
	v_pk_fma_f32 v[72:73], v[74:75], v[14:15], v[72:73]
	v_cvt_scalef32_pk_f32_fp4 v[74:75], v87, 1.0 op_sel:[0,1,0]
	v_pk_fma_f32 v[72:73], v[74:75], v[16:17], v[72:73]
	v_cvt_scalef32_pk_f32_fp4 v[74:75], v87, 1.0 op_sel:[1,1,0]
	v_pk_fma_f32 v[72:73], v[74:75], v[18:19], v[72:73]
	s_waitcnt vmcnt(23)
	v_cvt_scalef32_pk_f32_fp4 v[74:75], v88, 1.0 op_sel:[1,0,0]
	v_add_f32_e32 v81, v72, v73
	v_cvt_scalef32_pk_f32_fp4 v[72:73], v88, 1.0
	v_pk_mul_f32 v[74:75], v[74:75], v[6:7]
	s_nop 0
	v_pk_fma_f32 v[72:73], v[72:73], v[4:5], v[74:75]
	v_cvt_scalef32_pk_f32_fp4 v[74:75], v88, 1.0 op_sel:[0,1,0]
	v_pk_fma_f32 v[72:73], v[74:75], v[8:9], v[72:73]
	v_cvt_scalef32_pk_f32_fp4 v[74:75], v88, 1.0 op_sel:[1,1,0]
	v_pk_fma_f32 v[72:73], v[74:75], v[10:11], v[72:73]
	v_cvt_scalef32_pk_f32_fp4 v[74:75], v89, 1.0
	v_pk_fma_f32 v[72:73], v[74:75], v[12:13], v[72:73]
	v_cvt_scalef32_pk_f32_fp4 v[74:75], v89, 1.0 op_sel:[1,0,0]
	v_pk_fma_f32 v[72:73], v[74:75], v[14:15], v[72:73]
	v_cvt_scalef32_pk_f32_fp4 v[74:75], v89, 1.0 op_sel:[0,1,0]
	v_pk_fma_f32 v[72:73], v[74:75], v[16:17], v[72:73]
	v_cvt_scalef32_pk_f32_fp4 v[74:75], v89, 1.0 op_sel:[1,1,0]
	v_pk_fma_f32 v[72:73], v[74:75], v[18:19], v[72:73]
	s_waitcnt vmcnt(22)
	v_cvt_scalef32_pk_f32_fp4 v[74:75], v90, 1.0 op_sel:[1,0,0]
	v_add_f32_e32 v82, v72, v73
	v_cvt_scalef32_pk_f32_fp4 v[72:73], v90, 1.0
	v_pk_mul_f32 v[74:75], v[74:75], v[6:7]
	s_nop 0
	v_pk_fma_f32 v[72:73], v[72:73], v[4:5], v[74:75]
	v_cvt_scalef32_pk_f32_fp4 v[74:75], v90, 1.0 op_sel:[0,1,0]
	v_pk_fma_f32 v[72:73], v[74:75], v[8:9], v[72:73]
	v_cvt_scalef32_pk_f32_fp4 v[74:75], v90, 1.0 op_sel:[1,1,0]
	v_pk_fma_f32 v[72:73], v[74:75], v[10:11], v[72:73]
	v_cvt_scalef32_pk_f32_fp4 v[74:75], v91, 1.0
	v_pk_fma_f32 v[72:73], v[74:75], v[12:13], v[72:73]
	v_cvt_scalef32_pk_f32_fp4 v[74:75], v91, 1.0 op_sel:[1,0,0]
	v_pk_fma_f32 v[72:73], v[74:75], v[14:15], v[72:73]
	v_cvt_scalef32_pk_f32_fp4 v[74:75], v91, 1.0 op_sel:[0,1,0]
	v_pk_fma_f32 v[72:73], v[74:75], v[16:17], v[72:73]
	v_cvt_scalef32_pk_f32_fp4 v[74:75], v91, 1.0 op_sel:[1,1,0]
	v_pk_fma_f32 v[72:73], v[74:75], v[18:19], v[72:73]
	s_waitcnt vmcnt(21)
	v_cvt_scalef32_pk_f32_fp4 v[74:75], v92, 1.0 op_sel:[1,0,0]
	v_add_f32_e32 v83, v72, v73
	v_cvt_scalef32_pk_f32_fp4 v[72:73], v92, 1.0
	v_pk_mul_f32 v[74:75], v[74:75], v[6:7]
	s_nop 0
	v_pk_fma_f32 v[72:73], v[72:73], v[4:5], v[74:75]
	v_cvt_scalef32_pk_f32_fp4 v[74:75], v92, 1.0 op_sel:[0,1,0]
	v_pk_fma_f32 v[72:73], v[74:75], v[8:9], v[72:73]
	v_cvt_scalef32_pk_f32_fp4 v[74:75], v92, 1.0 op_sel:[1,1,0]
	v_pk_fma_f32 v[72:73], v[74:75], v[10:11], v[72:73]
	v_cvt_scalef32_pk_f32_fp4 v[74:75], v93, 1.0
	v_pk_fma_f32 v[72:73], v[74:75], v[12:13], v[72:73]
	v_cvt_scalef32_pk_f32_fp4 v[74:75], v93, 1.0 op_sel:[1,0,0]
	v_pk_fma_f32 v[72:73], v[74:75], v[14:15], v[72:73]
	v_cvt_scalef32_pk_f32_fp4 v[74:75], v93, 1.0 op_sel:[0,1,0]
	v_pk_fma_f32 v[72:73], v[74:75], v[16:17], v[72:73]
	v_cvt_scalef32_pk_f32_fp4 v[74:75], v93, 1.0 op_sel:[1,1,0]
	v_pk_fma_f32 v[72:73], v[74:75], v[18:19], v[72:73]
	s_waitcnt vmcnt(20)
	v_cvt_scalef32_pk_f32_fp4 v[74:75], v94, 1.0 op_sel:[1,0,0]
	v_add_f32_e32 v84, v72, v73
	v_cvt_scalef32_pk_f32_fp4 v[72:73], v94, 1.0
	v_pk_mul_f32 v[74:75], v[74:75], v[6:7]
	s_nop 0
	v_pk_fma_f32 v[72:73], v[72:73], v[4:5], v[74:75]
	v_cvt_scalef32_pk_f32_fp4 v[74:75], v94, 1.0 op_sel:[0,1,0]
	v_pk_fma_f32 v[72:73], v[74:75], v[8:9], v[72:73]
	v_cvt_scalef32_pk_f32_fp4 v[74:75], v94, 1.0 op_sel:[1,1,0]
	v_pk_fma_f32 v[72:73], v[74:75], v[10:11], v[72:73]
	v_cvt_scalef32_pk_f32_fp4 v[74:75], v95, 1.0
	v_pk_fma_f32 v[72:73], v[74:75], v[12:13], v[72:73]
	v_cvt_scalef32_pk_f32_fp4 v[74:75], v95, 1.0 op_sel:[1,0,0]
	v_pk_fma_f32 v[72:73], v[74:75], v[14:15], v[72:73]
	v_cvt_scalef32_pk_f32_fp4 v[74:75], v95, 1.0 op_sel:[0,1,0]
	v_pk_fma_f32 v[72:73], v[74:75], v[16:17], v[72:73]
	v_cvt_scalef32_pk_f32_fp4 v[74:75], v95, 1.0 op_sel:[1,1,0]
	v_pk_fma_f32 v[72:73], v[74:75], v[18:19], v[72:73]
	s_waitcnt vmcnt(19)
	v_cvt_scalef32_pk_f32_fp4 v[74:75], v96, 1.0 op_sel:[1,0,0]
	v_add_f32_e32 v85, v72, v73
	v_cvt_scalef32_pk_f32_fp4 v[72:73], v96, 1.0
	v_pk_mul_f32 v[74:75], v[74:75], v[6:7]
	s_nop 0
	v_pk_fma_f32 v[72:73], v[72:73], v[4:5], v[74:75]
	v_cvt_scalef32_pk_f32_fp4 v[74:75], v96, 1.0 op_sel:[0,1,0]
	v_pk_fma_f32 v[72:73], v[74:75], v[8:9], v[72:73]
	v_cvt_scalef32_pk_f32_fp4 v[74:75], v96, 1.0 op_sel:[1,1,0]
	v_pk_fma_f32 v[72:73], v[74:75], v[10:11], v[72:73]
	v_cvt_scalef32_pk_f32_fp4 v[74:75], v97, 1.0
	v_pk_fma_f32 v[72:73], v[74:75], v[12:13], v[72:73]
	v_cvt_scalef32_pk_f32_fp4 v[74:75], v97, 1.0 op_sel:[1,0,0]
	v_pk_fma_f32 v[72:73], v[74:75], v[14:15], v[72:73]
	v_cvt_scalef32_pk_f32_fp4 v[74:75], v97, 1.0 op_sel:[0,1,0]
	v_pk_fma_f32 v[72:73], v[74:75], v[16:17], v[72:73]
	v_cvt_scalef32_pk_f32_fp4 v[74:75], v97, 1.0 op_sel:[1,1,0]
	v_pk_fma_f32 v[72:73], v[74:75], v[18:19], v[72:73]
	s_waitcnt vmcnt(18)
	v_cvt_scalef32_pk_f32_fp4 v[74:75], v98, 1.0 op_sel:[1,0,0]
	v_add_f32_e32 v86, v72, v73
	v_cvt_scalef32_pk_f32_fp4 v[72:73], v98, 1.0
	v_pk_mul_f32 v[74:75], v[74:75], v[6:7]
	s_nop 0
	v_pk_fma_f32 v[72:73], v[72:73], v[4:5], v[74:75]
	v_cvt_scalef32_pk_f32_fp4 v[74:75], v98, 1.0 op_sel:[0,1,0]
	v_pk_fma_f32 v[72:73], v[74:75], v[8:9], v[72:73]
	v_cvt_scalef32_pk_f32_fp4 v[74:75], v98, 1.0 op_sel:[1,1,0]
	v_pk_fma_f32 v[72:73], v[74:75], v[10:11], v[72:73]
	v_cvt_scalef32_pk_f32_fp4 v[74:75], v99, 1.0
	v_pk_fma_f32 v[72:73], v[74:75], v[12:13], v[72:73]
	v_cvt_scalef32_pk_f32_fp4 v[74:75], v99, 1.0 op_sel:[1,0,0]
	v_pk_fma_f32 v[72:73], v[74:75], v[14:15], v[72:73]
	v_cvt_scalef32_pk_f32_fp4 v[74:75], v99, 1.0 op_sel:[0,1,0]
	v_pk_fma_f32 v[72:73], v[74:75], v[16:17], v[72:73]
	v_cvt_scalef32_pk_f32_fp4 v[74:75], v99, 1.0 op_sel:[1,1,0]
	v_pk_fma_f32 v[72:73], v[74:75], v[18:19], v[72:73]
	s_waitcnt vmcnt(17)
	v_cvt_scalef32_pk_f32_fp4 v[74:75], v100, 1.0 op_sel:[1,0,0]
	v_add_f32_e32 v87, v72, v73
	v_cvt_scalef32_pk_f32_fp4 v[72:73], v100, 1.0
	v_pk_mul_f32 v[74:75], v[74:75], v[6:7]
	s_nop 0
	v_pk_fma_f32 v[72:73], v[72:73], v[4:5], v[74:75]
	v_cvt_scalef32_pk_f32_fp4 v[74:75], v100, 1.0 op_sel:[0,1,0]
	v_pk_fma_f32 v[72:73], v[74:75], v[8:9], v[72:73]
	v_cvt_scalef32_pk_f32_fp4 v[74:75], v100, 1.0 op_sel:[1,1,0]
	v_pk_fma_f32 v[72:73], v[74:75], v[10:11], v[72:73]
	v_cvt_scalef32_pk_f32_fp4 v[74:75], v101, 1.0
	v_pk_fma_f32 v[72:73], v[74:75], v[12:13], v[72:73]
	v_cvt_scalef32_pk_f32_fp4 v[74:75], v101, 1.0 op_sel:[1,0,0]
	v_pk_fma_f32 v[72:73], v[74:75], v[14:15], v[72:73]
	v_cvt_scalef32_pk_f32_fp4 v[74:75], v101, 1.0 op_sel:[0,1,0]
	v_pk_fma_f32 v[72:73], v[74:75], v[16:17], v[72:73]
	v_cvt_scalef32_pk_f32_fp4 v[74:75], v101, 1.0 op_sel:[1,1,0]
	v_pk_fma_f32 v[72:73], v[74:75], v[18:19], v[72:73]
	s_waitcnt vmcnt(16)
	v_cvt_scalef32_pk_f32_fp4 v[74:75], v102, 1.0 op_sel:[1,0,0]
	v_add_f32_e32 v88, v72, v73
	v_cvt_scalef32_pk_f32_fp4 v[72:73], v102, 1.0
	v_pk_mul_f32 v[74:75], v[74:75], v[6:7]
	s_nop 0
	v_pk_fma_f32 v[72:73], v[72:73], v[4:5], v[74:75]
	v_cvt_scalef32_pk_f32_fp4 v[74:75], v102, 1.0 op_sel:[0,1,0]
	v_pk_fma_f32 v[72:73], v[74:75], v[8:9], v[72:73]
	v_cvt_scalef32_pk_f32_fp4 v[74:75], v102, 1.0 op_sel:[1,1,0]
	v_pk_fma_f32 v[72:73], v[74:75], v[10:11], v[72:73]
	v_cvt_scalef32_pk_f32_fp4 v[74:75], v103, 1.0
	v_pk_fma_f32 v[72:73], v[74:75], v[12:13], v[72:73]
	v_cvt_scalef32_pk_f32_fp4 v[74:75], v103, 1.0 op_sel:[1,0,0]
	v_pk_fma_f32 v[72:73], v[74:75], v[14:15], v[72:73]
	v_cvt_scalef32_pk_f32_fp4 v[74:75], v103, 1.0 op_sel:[0,1,0]
	v_pk_fma_f32 v[72:73], v[74:75], v[16:17], v[72:73]
	v_cvt_scalef32_pk_f32_fp4 v[74:75], v103, 1.0 op_sel:[1,1,0]
	v_pk_fma_f32 v[72:73], v[74:75], v[18:19], v[72:73]
	v_cndmask_b32_e64 v74, v132, v82, s[0:1]
	v_add_f32_e32 v72, v72, v73
	v_cndmask_b32_e64 v73, v82, v132, s[0:1]
	v_cndmask_b32_e64 v75, v130, v83, s[0:1]
	s_nop 0
	v_add_f32_dpp v73, v74, v73 quad_perm:[1,0,3,2] row_mask:0xf bank_mask:0xf bound_ctrl:1
	v_cndmask_b32_e64 v74, v83, v130, s[0:1]
	v_add_u32_e32 v127, 32, v127
	s_nop 0
	v_add_f32_dpp v74, v75, v74 quad_perm:[1,0,3,2] row_mask:0xf bank_mask:0xf bound_ctrl:1
	v_cndmask_b32_e64 v75, v84, v76, s[0:1]
	v_cndmask_b32_e64 v76, v76, v84, s[0:1]
	s_nop 1
	v_add_f32_dpp v75, v76, v75 quad_perm:[1,0,3,2] row_mask:0xf bank_mask:0xf bound_ctrl:1
	v_cndmask_b32_e64 v76, v85, v77, s[0:1]
	v_cndmask_b32_e64 v77, v77, v85, s[0:1]
	s_nop 1
	v_add_f32_dpp v76, v77, v76 quad_perm:[1,0,3,2] row_mask:0xf bank_mask:0xf bound_ctrl:1
	v_cndmask_b32_e64 v77, v86, v78, s[0:1]
	v_cndmask_b32_e64 v78, v78, v86, s[0:1]
	s_nop 1
	v_add_f32_dpp v77, v78, v77 quad_perm:[1,0,3,2] row_mask:0xf bank_mask:0xf bound_ctrl:1
	v_cndmask_b32_e64 v78, v87, v79, s[0:1]
	v_cndmask_b32_e64 v79, v79, v87, s[0:1]
	s_nop 0
	s_nop 0
	v_add_f32_dpp v78, v79, v78 quad_perm:[1,0,3,2] row_mask:0xf bank_mask:0xf bound_ctrl:1
	v_cndmask_b32_e64 v79, v88, v80, s[0:1]
	v_cndmask_b32_e64 v80, v80, v88, s[0:1]
	s_nop 1
	v_add_f32_dpp v79, v80, v79 quad_perm:[1,0,3,2] row_mask:0xf bank_mask:0xf bound_ctrl:1
	v_cndmask_b32_e64 v80, v72, v81, s[0:1]
	v_cndmask_b32_e64 v72, v81, v72, s[0:1]
	s_nop 1
	v_add_f32_dpp v72, v72, v80 quad_perm:[1,0,3,2] row_mask:0xf bank_mask:0xf bound_ctrl:1
	v_cndmask_b32_e64 v80, v77, v73, s[4:5]
	v_cndmask_b32_e64 v73, v73, v77, s[4:5]
	v_cndmask_b32_e64 v77, v78, v74, s[4:5]
	v_cndmask_b32_e64 v74, v74, v78, s[4:5]
	v_add_f32_dpp v73, v73, v80 quad_perm:[2,3,0,1] row_mask:0xf bank_mask:0xf bound_ctrl:1
	s_nop 0
	v_add_f32_dpp v74, v74, v77 quad_perm:[2,3,0,1] row_mask:0xf bank_mask:0xf bound_ctrl:1
	v_cndmask_b32_e64 v77, v79, v75, s[4:5]
	v_cndmask_b32_e64 v75, v75, v79, s[4:5]
	s_nop 0
	s_nop 0
	v_add_f32_dpp v75, v75, v77 quad_perm:[2,3,0,1] row_mask:0xf bank_mask:0xf bound_ctrl:1
	v_cndmask_b32_e64 v77, v72, v76, s[4:5]
	v_cndmask_b32_e64 v72, v76, v72, s[4:5]
	v_cndmask_b32_e64 v76, v75, v73, s[6:7]
	v_cndmask_b32_e64 v73, v73, v75, s[6:7]
	v_add_f32_dpp v72, v72, v77 quad_perm:[2,3,0,1] row_mask:0xf bank_mask:0xf bound_ctrl:1
	v_cndmask_b32_e64 v75, v72, v74, s[6:7]
	v_cndmask_b32_e64 v72, v74, v72, s[6:7]
	v_mov_b32_dpp v73, v73 row_half_mirror row_mask:0xf bank_mask:0xf bound_ctrl:1
	s_nop 0
	v_mov_b32_dpp v72, v72 row_half_mirror row_mask:0xf bank_mask:0xf bound_ctrl:1
	v_add_f32_dpp v73, v73, v76 quad_perm:[3,2,1,0] row_mask:0xf bank_mask:0xf bound_ctrl:1
	s_nop 0
	v_add_f32_dpp v72, v72, v75 quad_perm:[3,2,1,0] row_mask:0xf bank_mask:0xf bound_ctrl:1
	v_cndmask_b32_e64 v74, v72, v73, s[8:9]
	v_cndmask_b32_e64 v72, v73, v72, s[8:9]
	s_nop 1
	v_mov_b32_dpp v72, v72 row_mirror row_mask:0xf bank_mask:0xf bound_ctrl:1
	v_and_b32_e32 v76, 2, v124
	s_nop 0
	v_add_f32_dpp v72, v72, v74 row_half_mirror row_mask:0xf bank_mask:0xf bound_ctrl:1
	ds_bpermute_b32 v73, v125, v72
	v_cmp_eq_u32_e64 s[14:15], v106, v76
	s_waitcnt lgkmcnt(0)
	v_add_f32_e32 v72, v72, v73
	ds_bpermute_b32 v73, v126, v72
	s_waitcnt vmcnt(15)
	v_cvt_scalef32_pk_f32_fp4 v[74:75], v20, 1.0 op_sel:[1,0,0]
	v_pk_mul_f32 v[74:75], v[74:75], v[6:7]
	s_waitcnt lgkmcnt(0)
	v_add_f32_e32 v72, v72, v73
	v_cndmask_b32_e64 v73, v72, v128, s[12:13]
	v_cndmask_b32_e64 v77, v128, v73, s[14:15]
	s_and_b64 s[14:15], s[14:15], s[12:13]
	v_cndmask_b32_e64 v78, v129, v72, s[14:15]
	v_cvt_scalef32_pk_f32_fp4 v[72:73], v20, 1.0
	v_pk_fma_f32 v[72:73], v[72:73], v[4:5], v[74:75]
	v_cvt_scalef32_pk_f32_fp4 v[74:75], v20, 1.0 op_sel:[0,1,0]
	v_pk_fma_f32 v[72:73], v[74:75], v[8:9], v[72:73]
	v_cvt_scalef32_pk_f32_fp4 v[74:75], v20, 1.0 op_sel:[1,1,0]
	v_pk_fma_f32 v[72:73], v[74:75], v[10:11], v[72:73]
	v_cvt_scalef32_pk_f32_fp4 v[74:75], v21, 1.0
	v_pk_fma_f32 v[72:73], v[74:75], v[12:13], v[72:73]
	v_cvt_scalef32_pk_f32_fp4 v[74:75], v21, 1.0 op_sel:[1,0,0]
	v_pk_fma_f32 v[72:73], v[74:75], v[14:15], v[72:73]
	v_cvt_scalef32_pk_f32_fp4 v[74:75], v21, 1.0 op_sel:[0,1,0]
	v_pk_fma_f32 v[72:73], v[74:75], v[16:17], v[72:73]
	v_cvt_scalef32_pk_f32_fp4 v[20:21], v21, 1.0 op_sel:[1,1,0]
	v_pk_fma_f32 v[20:21], v[20:21], v[18:19], v[72:73]
	s_waitcnt vmcnt(14)
	v_cvt_scalef32_pk_f32_fp4 v[72:73], v22, 1.0 op_sel:[1,0,0]
	v_add_f32_e32 v74, v20, v21
	v_cvt_scalef32_pk_f32_fp4 v[20:21], v22, 1.0
	v_pk_mul_f32 v[72:73], v[72:73], v[6:7]
	s_nop 0
	v_pk_fma_f32 v[20:21], v[20:21], v[4:5], v[72:73]
	v_cvt_scalef32_pk_f32_fp4 v[72:73], v22, 1.0 op_sel:[0,1,0]
	v_pk_fma_f32 v[20:21], v[72:73], v[8:9], v[20:21]
	v_cvt_scalef32_pk_f32_fp4 v[72:73], v22, 1.0 op_sel:[1,1,0]
	v_pk_fma_f32 v[20:21], v[72:73], v[10:11], v[20:21]
	v_cvt_scalef32_pk_f32_fp4 v[72:73], v23, 1.0
	v_pk_fma_f32 v[20:21], v[72:73], v[12:13], v[20:21]
	v_cvt_scalef32_pk_f32_fp4 v[72:73], v23, 1.0 op_sel:[1,0,0]
	v_pk_fma_f32 v[20:21], v[72:73], v[14:15], v[20:21]
	v_cvt_scalef32_pk_f32_fp4 v[72:73], v23, 1.0 op_sel:[0,1,0]
	v_pk_fma_f32 v[20:21], v[72:73], v[16:17], v[20:21]
	v_cvt_scalef32_pk_f32_fp4 v[22:23], v23, 1.0 op_sel:[1,1,0]
	v_pk_fma_f32 v[20:21], v[22:23], v[18:19], v[20:21]
	s_waitcnt vmcnt(13)
	v_cvt_scalef32_pk_f32_fp4 v[22:23], v24, 1.0 op_sel:[1,0,0]
	v_add_f32_e32 v72, v20, v21
	v_cvt_scalef32_pk_f32_fp4 v[20:21], v24, 1.0
	v_pk_mul_f32 v[22:23], v[22:23], v[6:7]
	s_nop 0
	v_pk_fma_f32 v[20:21], v[20:21], v[4:5], v[22:23]
	v_cvt_scalef32_pk_f32_fp4 v[22:23], v24, 1.0 op_sel:[0,1,0]
	v_pk_fma_f32 v[20:21], v[22:23], v[8:9], v[20:21]
	v_cvt_scalef32_pk_f32_fp4 v[22:23], v24, 1.0 op_sel:[1,1,0]
	v_pk_fma_f32 v[20:21], v[22:23], v[10:11], v[20:21]
	v_cvt_scalef32_pk_f32_fp4 v[22:23], v25, 1.0
	v_pk_fma_f32 v[20:21], v[22:23], v[12:13], v[20:21]
	v_cvt_scalef32_pk_f32_fp4 v[22:23], v25, 1.0 op_sel:[1,0,0]
	v_pk_fma_f32 v[20:21], v[22:23], v[14:15], v[20:21]
	v_cvt_scalef32_pk_f32_fp4 v[22:23], v25, 1.0 op_sel:[0,1,0]
	v_pk_fma_f32 v[20:21], v[22:23], v[16:17], v[20:21]
	v_cvt_scalef32_pk_f32_fp4 v[22:23], v25, 1.0 op_sel:[1,1,0]
	v_pk_fma_f32 v[20:21], v[22:23], v[18:19], v[20:21]
	s_waitcnt vmcnt(12)
	v_cvt_scalef32_pk_f32_fp4 v[22:23], v26, 1.0 op_sel:[1,0,0]
	v_add_f32_e32 v24, v20, v21
	v_cvt_scalef32_pk_f32_fp4 v[20:21], v26, 1.0
	v_pk_mul_f32 v[22:23], v[22:23], v[6:7]
	s_nop 0
	v_pk_fma_f32 v[20:21], v[20:21], v[4:5], v[22:23]
	v_cvt_scalef32_pk_f32_fp4 v[22:23], v26, 1.0 op_sel:[0,1,0]
	v_pk_fma_f32 v[20:21], v[22:23], v[8:9], v[20:21]
	v_cvt_scalef32_pk_f32_fp4 v[22:23], v26, 1.0 op_sel:[1,1,0]
	v_pk_fma_f32 v[20:21], v[22:23], v[10:11], v[20:21]
	v_cvt_scalef32_pk_f32_fp4 v[22:23], v27, 1.0
	v_pk_fma_f32 v[20:21], v[22:23], v[12:13], v[20:21]
	v_cvt_scalef32_pk_f32_fp4 v[22:23], v27, 1.0 op_sel:[1,0,0]
	v_pk_fma_f32 v[20:21], v[22:23], v[14:15], v[20:21]
	v_cvt_scalef32_pk_f32_fp4 v[22:23], v27, 1.0 op_sel:[0,1,0]
	v_pk_fma_f32 v[20:21], v[22:23], v[16:17], v[20:21]
	v_cvt_scalef32_pk_f32_fp4 v[22:23], v27, 1.0 op_sel:[1,1,0]
	v_pk_fma_f32 v[20:21], v[22:23], v[18:19], v[20:21]
	s_waitcnt vmcnt(11)
	v_cvt_scalef32_pk_f32_fp4 v[22:23], v28, 1.0 op_sel:[1,0,0]
	v_add_f32_e32 v25, v20, v21
	v_cvt_scalef32_pk_f32_fp4 v[20:21], v28, 1.0
	v_pk_mul_f32 v[22:23], v[22:23], v[6:7]
	s_nop 0
	v_pk_fma_f32 v[20:21], v[20:21], v[4:5], v[22:23]
	v_cvt_scalef32_pk_f32_fp4 v[22:23], v28, 1.0 op_sel:[0,1,0]
	v_pk_fma_f32 v[20:21], v[22:23], v[8:9], v[20:21]
	v_cvt_scalef32_pk_f32_fp4 v[22:23], v28, 1.0 op_sel:[1,1,0]
	v_pk_fma_f32 v[20:21], v[22:23], v[10:11], v[20:21]
	v_cvt_scalef32_pk_f32_fp4 v[22:23], v29, 1.0
	v_pk_fma_f32 v[20:21], v[22:23], v[12:13], v[20:21]
	v_cvt_scalef32_pk_f32_fp4 v[22:23], v29, 1.0 op_sel:[1,0,0]
	v_pk_fma_f32 v[20:21], v[22:23], v[14:15], v[20:21]
	v_cvt_scalef32_pk_f32_fp4 v[22:23], v29, 1.0 op_sel:[0,1,0]
	v_pk_fma_f32 v[20:21], v[22:23], v[16:17], v[20:21]
	v_cvt_scalef32_pk_f32_fp4 v[22:23], v29, 1.0 op_sel:[1,1,0]
	v_pk_fma_f32 v[20:21], v[22:23], v[18:19], v[20:21]
	s_waitcnt vmcnt(10)
	v_cvt_scalef32_pk_f32_fp4 v[22:23], v30, 1.0 op_sel:[1,0,0]
	v_add_f32_e32 v26, v20, v21
	v_cvt_scalef32_pk_f32_fp4 v[20:21], v30, 1.0
	v_pk_mul_f32 v[22:23], v[22:23], v[6:7]
	v_add_u32_e32 v124, 2, v124
	v_pk_fma_f32 v[20:21], v[20:21], v[4:5], v[22:23]
	v_cvt_scalef32_pk_f32_fp4 v[22:23], v30, 1.0 op_sel:[0,1,0]
	v_pk_fma_f32 v[20:21], v[22:23], v[8:9], v[20:21]
	v_cvt_scalef32_pk_f32_fp4 v[22:23], v30, 1.0 op_sel:[1,1,0]
	v_pk_fma_f32 v[20:21], v[22:23], v[10:11], v[20:21]
	v_cvt_scalef32_pk_f32_fp4 v[22:23], v31, 1.0
	v_pk_fma_f32 v[20:21], v[22:23], v[12:13], v[20:21]
	v_cvt_scalef32_pk_f32_fp4 v[22:23], v31, 1.0 op_sel:[1,0,0]
	v_pk_fma_f32 v[20:21], v[22:23], v[14:15], v[20:21]
	v_cvt_scalef32_pk_f32_fp4 v[22:23], v31, 1.0 op_sel:[0,1,0]
	v_pk_fma_f32 v[20:21], v[22:23], v[16:17], v[20:21]
	v_cvt_scalef32_pk_f32_fp4 v[22:23], v31, 1.0 op_sel:[1,1,0]
	v_pk_fma_f32 v[20:21], v[22:23], v[18:19], v[20:21]
	s_waitcnt vmcnt(9)
	v_cvt_scalef32_pk_f32_fp4 v[22:23], v32, 1.0 op_sel:[1,0,0]
	v_add_f32_e32 v27, v20, v21
	v_cvt_scalef32_pk_f32_fp4 v[20:21], v32, 1.0
	v_pk_mul_f32 v[22:23], v[22:23], v[6:7]
	s_nop 0
	v_pk_fma_f32 v[20:21], v[20:21], v[4:5], v[22:23]
	v_cvt_scalef32_pk_f32_fp4 v[22:23], v32, 1.0 op_sel:[0,1,0]
	v_pk_fma_f32 v[20:21], v[22:23], v[8:9], v[20:21]
	v_cvt_scalef32_pk_f32_fp4 v[22:23], v32, 1.0 op_sel:[1,1,0]
	v_pk_fma_f32 v[20:21], v[22:23], v[10:11], v[20:21]
	v_cvt_scalef32_pk_f32_fp4 v[22:23], v33, 1.0
	v_pk_fma_f32 v[20:21], v[22:23], v[12:13], v[20:21]
	v_cvt_scalef32_pk_f32_fp4 v[22:23], v33, 1.0 op_sel:[1,0,0]
	v_pk_fma_f32 v[20:21], v[22:23], v[14:15], v[20:21]
	v_cvt_scalef32_pk_f32_fp4 v[22:23], v33, 1.0 op_sel:[0,1,0]
	v_pk_fma_f32 v[20:21], v[22:23], v[16:17], v[20:21]
	v_cvt_scalef32_pk_f32_fp4 v[22:23], v33, 1.0 op_sel:[1,1,0]
	v_pk_fma_f32 v[20:21], v[22:23], v[18:19], v[20:21]
	s_waitcnt vmcnt(8)
	v_cvt_scalef32_pk_f32_fp4 v[22:23], v34, 1.0 op_sel:[1,0,0]
	v_add_f32_e32 v28, v20, v21
	v_cvt_scalef32_pk_f32_fp4 v[20:21], v34, 1.0
	v_pk_mul_f32 v[22:23], v[22:23], v[6:7]
	s_nop 0
	v_pk_fma_f32 v[20:21], v[20:21], v[4:5], v[22:23]
	v_cvt_scalef32_pk_f32_fp4 v[22:23], v34, 1.0 op_sel:[0,1,0]
	v_pk_fma_f32 v[20:21], v[22:23], v[8:9], v[20:21]
	v_cvt_scalef32_pk_f32_fp4 v[22:23], v34, 1.0 op_sel:[1,1,0]
	v_pk_fma_f32 v[20:21], v[22:23], v[10:11], v[20:21]
	v_cvt_scalef32_pk_f32_fp4 v[22:23], v35, 1.0
	v_pk_fma_f32 v[20:21], v[22:23], v[12:13], v[20:21]
	v_cvt_scalef32_pk_f32_fp4 v[22:23], v35, 1.0 op_sel:[1,0,0]
	v_pk_fma_f32 v[20:21], v[22:23], v[14:15], v[20:21]
	v_cvt_scalef32_pk_f32_fp4 v[22:23], v35, 1.0 op_sel:[0,1,0]
	v_pk_fma_f32 v[20:21], v[22:23], v[16:17], v[20:21]
	v_cvt_scalef32_pk_f32_fp4 v[22:23], v35, 1.0 op_sel:[1,1,0]
	v_pk_fma_f32 v[20:21], v[22:23], v[18:19], v[20:21]
	s_waitcnt vmcnt(7)
	v_cvt_scalef32_pk_f32_fp4 v[22:23], v56, 1.0 op_sel:[1,0,0]
	v_add_f32_e32 v29, v20, v21
	v_cvt_scalef32_pk_f32_fp4 v[20:21], v56, 1.0
	v_pk_mul_f32 v[22:23], v[22:23], v[6:7]
	s_nop 0
	v_pk_fma_f32 v[20:21], v[20:21], v[4:5], v[22:23]
	v_cvt_scalef32_pk_f32_fp4 v[22:23], v56, 1.0 op_sel:[0,1,0]
	v_pk_fma_f32 v[20:21], v[22:23], v[8:9], v[20:21]
	v_cvt_scalef32_pk_f32_fp4 v[22:23], v56, 1.0 op_sel:[1,1,0]
	v_pk_fma_f32 v[20:21], v[22:23], v[10:11], v[20:21]
	v_cvt_scalef32_pk_f32_fp4 v[22:23], v57, 1.0
	v_pk_fma_f32 v[20:21], v[22:23], v[12:13], v[20:21]
	v_cvt_scalef32_pk_f32_fp4 v[22:23], v57, 1.0 op_sel:[1,0,0]
	v_pk_fma_f32 v[20:21], v[22:23], v[14:15], v[20:21]
	v_cvt_scalef32_pk_f32_fp4 v[22:23], v57, 1.0 op_sel:[0,1,0]
	v_pk_fma_f32 v[20:21], v[22:23], v[16:17], v[20:21]
	v_cvt_scalef32_pk_f32_fp4 v[22:23], v57, 1.0 op_sel:[1,1,0]
	v_pk_fma_f32 v[20:21], v[22:23], v[18:19], v[20:21]
	s_waitcnt vmcnt(6)
	v_cvt_scalef32_pk_f32_fp4 v[22:23], v58, 1.0 op_sel:[1,0,0]
	v_add_f32_e32 v30, v20, v21
	v_cvt_scalef32_pk_f32_fp4 v[20:21], v58, 1.0
	v_pk_mul_f32 v[22:23], v[22:23], v[6:7]
	s_nop 0
	v_pk_fma_f32 v[20:21], v[20:21], v[4:5], v[22:23]
	v_cvt_scalef32_pk_f32_fp4 v[22:23], v58, 1.0 op_sel:[0,1,0]
	v_pk_fma_f32 v[20:21], v[22:23], v[8:9], v[20:21]
	v_cvt_scalef32_pk_f32_fp4 v[22:23], v58, 1.0 op_sel:[1,1,0]
	v_pk_fma_f32 v[20:21], v[22:23], v[10:11], v[20:21]
	v_cvt_scalef32_pk_f32_fp4 v[22:23], v59, 1.0
	v_pk_fma_f32 v[20:21], v[22:23], v[12:13], v[20:21]
	v_cvt_scalef32_pk_f32_fp4 v[22:23], v59, 1.0 op_sel:[1,0,0]
	v_pk_fma_f32 v[20:21], v[22:23], v[14:15], v[20:21]
	v_cvt_scalef32_pk_f32_fp4 v[22:23], v59, 1.0 op_sel:[0,1,0]
	v_pk_fma_f32 v[20:21], v[22:23], v[16:17], v[20:21]
	v_cvt_scalef32_pk_f32_fp4 v[22:23], v59, 1.0 op_sel:[1,1,0]
	v_pk_fma_f32 v[20:21], v[22:23], v[18:19], v[20:21]
	s_waitcnt vmcnt(5)
	v_cvt_scalef32_pk_f32_fp4 v[22:23], v60, 1.0 op_sel:[1,0,0]
	v_add_f32_e32 v31, v20, v21
	v_cvt_scalef32_pk_f32_fp4 v[20:21], v60, 1.0
	v_pk_mul_f32 v[22:23], v[22:23], v[6:7]
	s_nop 0
	v_pk_fma_f32 v[20:21], v[20:21], v[4:5], v[22:23]
	v_cvt_scalef32_pk_f32_fp4 v[22:23], v60, 1.0 op_sel:[0,1,0]
	v_pk_fma_f32 v[20:21], v[22:23], v[8:9], v[20:21]
	v_cvt_scalef32_pk_f32_fp4 v[22:23], v60, 1.0 op_sel:[1,1,0]
	v_pk_fma_f32 v[20:21], v[22:23], v[10:11], v[20:21]
	v_cvt_scalef32_pk_f32_fp4 v[22:23], v61, 1.0
	v_pk_fma_f32 v[20:21], v[22:23], v[12:13], v[20:21]
	v_cvt_scalef32_pk_f32_fp4 v[22:23], v61, 1.0 op_sel:[1,0,0]
	v_pk_fma_f32 v[20:21], v[22:23], v[14:15], v[20:21]
	v_cvt_scalef32_pk_f32_fp4 v[22:23], v61, 1.0 op_sel:[0,1,0]
	v_pk_fma_f32 v[20:21], v[22:23], v[16:17], v[20:21]
	v_cvt_scalef32_pk_f32_fp4 v[22:23], v61, 1.0 op_sel:[1,1,0]
	v_pk_fma_f32 v[20:21], v[22:23], v[18:19], v[20:21]
	s_waitcnt vmcnt(4)
	v_cvt_scalef32_pk_f32_fp4 v[22:23], v62, 1.0 op_sel:[1,0,0]
	v_add_f32_e32 v32, v20, v21
	v_cvt_scalef32_pk_f32_fp4 v[20:21], v62, 1.0
	v_pk_mul_f32 v[22:23], v[22:23], v[6:7]
	s_nop 0
	v_pk_fma_f32 v[20:21], v[20:21], v[4:5], v[22:23]
	v_cvt_scalef32_pk_f32_fp4 v[22:23], v62, 1.0 op_sel:[0,1,0]
	v_pk_fma_f32 v[20:21], v[22:23], v[8:9], v[20:21]
	v_cvt_scalef32_pk_f32_fp4 v[22:23], v62, 1.0 op_sel:[1,1,0]
	v_pk_fma_f32 v[20:21], v[22:23], v[10:11], v[20:21]
	v_cvt_scalef32_pk_f32_fp4 v[22:23], v63, 1.0
	v_pk_fma_f32 v[20:21], v[22:23], v[12:13], v[20:21]
	v_cvt_scalef32_pk_f32_fp4 v[22:23], v63, 1.0 op_sel:[1,0,0]
	v_pk_fma_f32 v[20:21], v[22:23], v[14:15], v[20:21]
	v_cvt_scalef32_pk_f32_fp4 v[22:23], v63, 1.0 op_sel:[0,1,0]
	v_pk_fma_f32 v[20:21], v[22:23], v[16:17], v[20:21]
	v_cvt_scalef32_pk_f32_fp4 v[22:23], v63, 1.0 op_sel:[1,1,0]
	v_pk_fma_f32 v[20:21], v[22:23], v[18:19], v[20:21]
	s_waitcnt vmcnt(3)
	v_cvt_scalef32_pk_f32_fp4 v[22:23], v64, 1.0 op_sel:[1,0,0]
	v_add_f32_e32 v33, v20, v21
	v_cvt_scalef32_pk_f32_fp4 v[20:21], v64, 1.0
	v_pk_mul_f32 v[22:23], v[22:23], v[6:7]
	s_nop 0
	v_pk_fma_f32 v[20:21], v[20:21], v[4:5], v[22:23]
	v_cvt_scalef32_pk_f32_fp4 v[22:23], v64, 1.0 op_sel:[0,1,0]
	v_pk_fma_f32 v[20:21], v[22:23], v[8:9], v[20:21]
	v_cvt_scalef32_pk_f32_fp4 v[22:23], v64, 1.0 op_sel:[1,1,0]
	v_pk_fma_f32 v[20:21], v[22:23], v[10:11], v[20:21]
	v_cvt_scalef32_pk_f32_fp4 v[22:23], v65, 1.0
	v_pk_fma_f32 v[20:21], v[22:23], v[12:13], v[20:21]
	v_cvt_scalef32_pk_f32_fp4 v[22:23], v65, 1.0 op_sel:[1,0,0]
	v_pk_fma_f32 v[20:21], v[22:23], v[14:15], v[20:21]
	v_cvt_scalef32_pk_f32_fp4 v[22:23], v65, 1.0 op_sel:[0,1,0]
	v_pk_fma_f32 v[20:21], v[22:23], v[16:17], v[20:21]
	v_cvt_scalef32_pk_f32_fp4 v[22:23], v65, 1.0 op_sel:[1,1,0]
	v_pk_fma_f32 v[20:21], v[22:23], v[18:19], v[20:21]
	s_waitcnt vmcnt(2)
	v_cvt_scalef32_pk_f32_fp4 v[22:23], v66, 1.0 op_sel:[1,0,0]
	v_add_f32_e32 v34, v20, v21
	v_cvt_scalef32_pk_f32_fp4 v[20:21], v66, 1.0
	v_pk_mul_f32 v[22:23], v[22:23], v[6:7]
	s_nop 0
	v_pk_fma_f32 v[20:21], v[20:21], v[4:5], v[22:23]
	v_cvt_scalef32_pk_f32_fp4 v[22:23], v66, 1.0 op_sel:[0,1,0]
	v_pk_fma_f32 v[20:21], v[22:23], v[8:9], v[20:21]
	v_cvt_scalef32_pk_f32_fp4 v[22:23], v66, 1.0 op_sel:[1,1,0]
	v_pk_fma_f32 v[20:21], v[22:23], v[10:11], v[20:21]
	v_cvt_scalef32_pk_f32_fp4 v[22:23], v67, 1.0
	v_pk_fma_f32 v[20:21], v[22:23], v[12:13], v[20:21]
	v_cvt_scalef32_pk_f32_fp4 v[22:23], v67, 1.0 op_sel:[1,0,0]
	v_pk_fma_f32 v[20:21], v[22:23], v[14:15], v[20:21]
	v_cvt_scalef32_pk_f32_fp4 v[22:23], v67, 1.0 op_sel:[0,1,0]
	v_pk_fma_f32 v[20:21], v[22:23], v[16:17], v[20:21]
	v_cvt_scalef32_pk_f32_fp4 v[22:23], v67, 1.0 op_sel:[1,1,0]
	v_pk_fma_f32 v[20:21], v[22:23], v[18:19], v[20:21]
	s_waitcnt vmcnt(1)
	v_cvt_scalef32_pk_f32_fp4 v[22:23], v68, 1.0 op_sel:[1,0,0]
	v_add_f32_e32 v35, v20, v21
	v_cvt_scalef32_pk_f32_fp4 v[20:21], v68, 1.0
	v_pk_mul_f32 v[22:23], v[22:23], v[6:7]
	s_nop 0
	v_pk_fma_f32 v[20:21], v[20:21], v[4:5], v[22:23]
	v_cvt_scalef32_pk_f32_fp4 v[22:23], v68, 1.0 op_sel:[0,1,0]
	v_pk_fma_f32 v[20:21], v[22:23], v[8:9], v[20:21]
	v_cvt_scalef32_pk_f32_fp4 v[22:23], v68, 1.0 op_sel:[1,1,0]
	v_pk_fma_f32 v[20:21], v[22:23], v[10:11], v[20:21]
	v_cvt_scalef32_pk_f32_fp4 v[22:23], v69, 1.0
	v_pk_fma_f32 v[20:21], v[22:23], v[12:13], v[20:21]
	v_cvt_scalef32_pk_f32_fp4 v[22:23], v69, 1.0 op_sel:[1,0,0]
	v_pk_fma_f32 v[20:21], v[22:23], v[14:15], v[20:21]
	v_cvt_scalef32_pk_f32_fp4 v[22:23], v69, 1.0 op_sel:[0,1,0]
	v_pk_fma_f32 v[20:21], v[22:23], v[16:17], v[20:21]
	v_cvt_scalef32_pk_f32_fp4 v[22:23], v69, 1.0 op_sel:[1,1,0]
	v_pk_fma_f32 v[20:21], v[22:23], v[18:19], v[20:21]
	s_waitcnt vmcnt(0)
	v_cvt_scalef32_pk_f32_fp4 v[22:23], v70, 1.0 op_sel:[1,0,0]
	v_add_f32_e32 v56, v20, v21
	v_cvt_scalef32_pk_f32_fp4 v[20:21], v70, 1.0
	v_pk_mul_f32 v[22:23], v[22:23], v[6:7]
	s_nop 0
	v_pk_fma_f32 v[20:21], v[20:21], v[4:5], v[22:23]
	v_cvt_scalef32_pk_f32_fp4 v[22:23], v70, 1.0 op_sel:[0,1,0]
	v_pk_fma_f32 v[20:21], v[22:23], v[8:9], v[20:21]
	v_cvt_scalef32_pk_f32_fp4 v[22:23], v70, 1.0 op_sel:[1,1,0]
	v_pk_fma_f32 v[20:21], v[22:23], v[10:11], v[20:21]
	v_cvt_scalef32_pk_f32_fp4 v[22:23], v71, 1.0
	v_pk_fma_f32 v[20:21], v[22:23], v[12:13], v[20:21]
	v_cvt_scalef32_pk_f32_fp4 v[22:23], v71, 1.0 op_sel:[1,0,0]
	v_pk_fma_f32 v[20:21], v[22:23], v[14:15], v[20:21]
	v_cvt_scalef32_pk_f32_fp4 v[22:23], v71, 1.0 op_sel:[0,1,0]
	v_pk_fma_f32 v[20:21], v[22:23], v[16:17], v[20:21]
	v_cvt_scalef32_pk_f32_fp4 v[22:23], v71, 1.0 op_sel:[1,1,0]
	v_pk_fma_f32 v[20:21], v[22:23], v[18:19], v[20:21]
	v_cndmask_b32_e64 v22, v74, v30, s[0:1]
	v_add_f32_e32 v20, v20, v21
	v_cndmask_b32_e64 v21, v30, v74, s[0:1]
	v_cndmask_b32_e64 v23, v72, v31, s[0:1]
	s_nop 0
	v_add_f32_dpp v21, v22, v21 quad_perm:[1,0,3,2] row_mask:0xf bank_mask:0xf bound_ctrl:1
	v_cndmask_b32_e64 v22, v31, v72, s[0:1]
	s_nop 1
	v_add_f32_dpp v22, v23, v22 quad_perm:[1,0,3,2] row_mask:0xf bank_mask:0xf bound_ctrl:1
	v_cndmask_b32_e64 v23, v32, v24, s[0:1]
	v_cndmask_b32_e64 v24, v24, v32, s[0:1]
	s_nop 1
	v_add_f32_dpp v23, v24, v23 quad_perm:[1,0,3,2] row_mask:0xf bank_mask:0xf bound_ctrl:1
	v_cndmask_b32_e64 v24, v33, v25, s[0:1]
	v_cndmask_b32_e64 v25, v25, v33, s[0:1]
	s_nop 1
	v_add_f32_dpp v24, v25, v24 quad_perm:[1,0,3,2] row_mask:0xf bank_mask:0xf bound_ctrl:1
	v_cndmask_b32_e64 v25, v34, v26, s[0:1]
	v_cndmask_b32_e64 v26, v26, v34, s[0:1]
	s_nop 1
	v_add_f32_dpp v25, v26, v25 quad_perm:[1,0,3,2] row_mask:0xf bank_mask:0xf bound_ctrl:1
	v_cndmask_b32_e64 v26, v35, v27, s[0:1]
	v_cndmask_b32_e64 v27, v27, v35, s[0:1]
	s_nop 1
	v_add_f32_dpp v26, v27, v26 quad_perm:[1,0,3,2] row_mask:0xf bank_mask:0xf bound_ctrl:1
	v_cndmask_b32_e64 v27, v56, v28, s[0:1]
	v_cndmask_b32_e64 v28, v28, v56, s[0:1]
	s_nop 1
	v_add_f32_dpp v27, v28, v27 quad_perm:[1,0,3,2] row_mask:0xf bank_mask:0xf bound_ctrl:1
	v_cndmask_b32_e64 v28, v20, v29, s[0:1]
	v_cndmask_b32_e64 v20, v29, v20, s[0:1]
	s_nop 1
	v_add_f32_dpp v20, v20, v28 quad_perm:[1,0,3,2] row_mask:0xf bank_mask:0xf bound_ctrl:1
	v_cndmask_b32_e64 v28, v25, v21, s[4:5]
	v_cndmask_b32_e64 v21, v21, v25, s[4:5]
	v_cndmask_b32_e64 v25, v26, v22, s[4:5]
	v_cndmask_b32_e64 v22, v22, v26, s[4:5]
	v_add_f32_dpp v21, v21, v28 quad_perm:[2,3,0,1] row_mask:0xf bank_mask:0xf bound_ctrl:1
	s_nop 0
	v_add_f32_dpp v22, v22, v25 quad_perm:[2,3,0,1] row_mask:0xf bank_mask:0xf bound_ctrl:1
	v_cndmask_b32_e64 v25, v27, v23, s[4:5]
	v_cndmask_b32_e64 v23, v23, v27, s[4:5]
	s_nop 1
	v_add_f32_dpp v23, v23, v25 quad_perm:[2,3,0,1] row_mask:0xf bank_mask:0xf bound_ctrl:1
	v_cndmask_b32_e64 v25, v20, v24, s[4:5]
	v_cndmask_b32_e64 v20, v24, v20, s[4:5]
	v_cndmask_b32_e64 v24, v23, v21, s[6:7]
	v_cndmask_b32_e64 v21, v21, v23, s[6:7]
	v_add_f32_dpp v20, v20, v25 quad_perm:[2,3,0,1] row_mask:0xf bank_mask:0xf bound_ctrl:1
	v_cndmask_b32_e64 v23, v20, v22, s[6:7]
	v_cndmask_b32_e64 v20, v22, v20, s[6:7]
	v_mov_b32_dpp v21, v21 row_half_mirror row_mask:0xf bank_mask:0xf bound_ctrl:1
	s_nop 0
	v_mov_b32_dpp v20, v20 row_half_mirror row_mask:0xf bank_mask:0xf bound_ctrl:1
	v_add_f32_dpp v21, v21, v24 quad_perm:[3,2,1,0] row_mask:0xf bank_mask:0xf bound_ctrl:1
	s_nop 0
	v_add_f32_dpp v20, v20, v23 quad_perm:[3,2,1,0] row_mask:0xf bank_mask:0xf bound_ctrl:1
	v_cndmask_b32_e64 v22, v20, v21, s[8:9]
	v_cndmask_b32_e64 v20, v21, v20, s[8:9]
	s_nop 1
	v_mov_b32_dpp v20, v20 row_mirror row_mask:0xf bank_mask:0xf bound_ctrl:1
	s_nop 1
	v_add_f32_dpp v20, v20, v22 row_half_mirror row_mask:0xf bank_mask:0xf bound_ctrl:1
	ds_bpermute_b32 v21, v125, v20
	s_waitcnt lgkmcnt(0)
	v_add_f32_e32 v20, v20, v21
	ds_bpermute_b32 v21, v126, v20
	s_waitcnt lgkmcnt(0)
	v_add_f32_e32 v20, v20, v21
	v_or_b32_e32 v21, 1, v76
	v_cmp_eq_u32_e64 s[14:15], v106, v21
	v_cndmask_b32_e64 v21, v20, v77, s[12:13]
	s_and_b64 s[12:13], s[14:15], s[12:13]
	v_cndmask_b32_e64 v129, v78, v20, s[12:13]
	v_cmp_ge_u32_e64 s[12:13], v127, v115
	v_cndmask_b32_e64 v128, v77, v21, s[14:15]
	s_or_b64 s[28:29], s[12:13], s[28:29]
	s_branch .Lh3_u10_join
.Lh3_u10_hi:
	v_readlane_b32 s84, v70, 32
	v_readlane_b32 s86, v70, 33
	v_readlane_b32 s88, v70, 34
	v_readlane_b32 s90, v70, 35
	s_lshl_b32 s84, s84, 9
	s_lshl_b32 s86, s86, 9
	s_lshl_b32 s88, s88, 9
	s_lshl_b32 s90, s90, 9
	s_add_u32 s84, s93, s84
	s_addc_u32 s85, s94, 0
	s_add_u32 s86, s93, s86
	s_addc_u32 s87, s94, 0
	s_add_u32 s88, s93, s88
	s_addc_u32 s89, s94, 0
	s_add_u32 s90, s93, s90
	s_addc_u32 s91, s94, 0
	global_load_dwordx2 v[72:73], v255, s[84:85]
	global_load_dwordx2 v[74:75], v255, s[86:87]
	global_load_dwordx2 v[76:77], v255, s[88:89]
	global_load_dwordx2 v[78:79], v255, s[90:91]
	v_readlane_b32 s84, v70, 36
	v_readlane_b32 s86, v70, 37
	v_readlane_b32 s88, v70, 38
	v_readlane_b32 s90, v70, 39
	s_lshl_b32 s84, s84, 9
	s_lshl_b32 s86, s86, 9
	s_lshl_b32 s88, s88, 9
	s_lshl_b32 s90, s90, 9
	s_add_u32 s84, s93, s84
	s_addc_u32 s85, s94, 0
	s_add_u32 s86, s93, s86
	s_addc_u32 s87, s94, 0
	s_add_u32 s88, s93, s88
	s_addc_u32 s89, s94, 0
	s_add_u32 s90, s93, s90
	s_addc_u32 s91, s94, 0
	global_load_dwordx2 v[80:81], v255, s[84:85]
	global_load_dwordx2 v[82:83], v255, s[86:87]
	global_load_dwordx2 v[84:85], v255, s[88:89]
	global_load_dwordx2 v[86:87], v255, s[90:91]
	v_readlane_b32 s84, v70, 40
	v_readlane_b32 s86, v70, 41
	v_readlane_b32 s88, v70, 42
	v_readlane_b32 s90, v70, 43
	s_lshl_b32 s84, s84, 9
	s_lshl_b32 s86, s86, 9
	s_lshl_b32 s88, s88, 9
	s_lshl_b32 s90, s90, 9
	s_add_u32 s84, s93, s84
	s_addc_u32 s85, s94, 0
	s_add_u32 s86, s93, s86
	s_addc_u32 s87, s94, 0
	s_add_u32 s88, s93, s88
	s_addc_u32 s89, s94, 0
	s_add_u32 s90, s93, s90
	s_addc_u32 s91, s94, 0
	global_load_dwordx2 v[88:89], v255, s[84:85]
	global_load_dwordx2 v[90:91], v255, s[86:87]
	global_load_dwordx2 v[92:93], v255, s[88:89]
	global_load_dwordx2 v[94:95], v255, s[90:91]
	v_readlane_b32 s84, v70, 44
	v_readlane_b32 s86, v70, 45
	v_readlane_b32 s88, v70, 46
	v_readlane_b32 s90, v70, 47
	s_lshl_b32 s84, s84, 9
	s_lshl_b32 s86, s86, 9
	s_lshl_b32 s88, s88, 9
	s_lshl_b32 s90, s90, 9
	s_add_u32 s84, s93, s84
	s_addc_u32 s85, s94, 0
	s_add_u32 s86, s93, s86
	s_addc_u32 s87, s94, 0
	s_add_u32 s88, s93, s88
	s_addc_u32 s89, s94, 0
	s_add_u32 s90, s93, s90
	s_addc_u32 s91, s94, 0
	global_load_dwordx2 v[96:97], v255, s[84:85]
	global_load_dwordx2 v[98:99], v255, s[86:87]
	global_load_dwordx2 v[100:101], v255, s[88:89]
	global_load_dwordx2 v[102:103], v255, s[90:91]
	v_readlane_b32 s84, v70, 48
	v_readlane_b32 s86, v70, 49
	v_readlane_b32 s88, v70, 50
	v_readlane_b32 s90, v70, 51
	s_lshl_b32 s84, s84, 9
	s_lshl_b32 s86, s86, 9
	s_lshl_b32 s88, s88, 9
	s_lshl_b32 s90, s90, 9
	s_add_u32 s84, s93, s84
	s_addc_u32 s85, s94, 0
	s_add_u32 s86, s93, s86
	s_addc_u32 s87, s94, 0
	s_add_u32 s88, s93, s88
	s_addc_u32 s89, s94, 0
	s_add_u32 s90, s93, s90
	s_addc_u32 s91, s94, 0
	global_load_dwordx2 v[20:21], v255, s[84:85]
	global_load_dwordx2 v[22:23], v255, s[86:87]
	global_load_dwordx2 v[24:25], v255, s[88:89]
	global_load_dwordx2 v[26:27], v255, s[90:91]
	v_readlane_b32 s84, v70, 52
	v_readlane_b32 s86, v70, 53
	v_readlane_b32 s88, v70, 54
	v_readlane_b32 s90, v70, 55
	s_lshl_b32 s84, s84, 9
	s_lshl_b32 s86, s86, 9
	s_lshl_b32 s88, s88, 9
	s_lshl_b32 s90, s90, 9
	s_add_u32 s84, s93, s84
	s_addc_u32 s85, s94, 0
	s_add_u32 s86, s93, s86
	s_addc_u32 s87, s94, 0
	s_add_u32 s88, s93, s88
	s_addc_u32 s89, s94, 0
	s_add_u32 s90, s93, s90
	s_addc_u32 s91, s94, 0
	global_load_dwordx2 v[28:29], v255, s[84:85]
	global_load_dwordx2 v[30:31], v255, s[86:87]
	global_load_dwordx2 v[32:33], v255, s[88:89]
	global_load_dwordx2 v[34:35], v255, s[90:91]
	v_readlane_b32 s84, v70, 56
	v_readlane_b32 s86, v70, 57
	v_readlane_b32 s88, v70, 58
	v_readlane_b32 s90, v70, 59
	s_lshl_b32 s84, s84, 9
	s_lshl_b32 s86, s86, 9
	s_lshl_b32 s88, s88, 9
	s_lshl_b32 s90, s90, 9
	s_add_u32 s84, s93, s84
	s_addc_u32 s85, s94, 0
	s_add_u32 s86, s93, s86
	s_addc_u32 s87, s94, 0
	s_add_u32 s88, s93, s88
	s_addc_u32 s89, s94, 0
	s_add_u32 s90, s93, s90
	s_addc_u32 s91, s94, 0
	global_load_dwordx2 v[56:57], v255, s[84:85]
	global_load_dwordx2 v[58:59], v255, s[86:87]
	global_load_dwordx2 v[60:61], v255, s[88:89]
	global_load_dwordx2 v[62:63], v255, s[90:91]
	v_readlane_b32 s84, v70, 60
	v_readlane_b32 s86, v70, 61
	v_readlane_b32 s88, v70, 62
	v_readlane_b32 s90, v70, 63
	s_lshl_b32 s84, s84, 9
	s_lshl_b32 s86, s86, 9
	s_lshl_b32 s88, s88, 9
	s_lshl_b32 s90, s90, 9
	s_add_u32 s84, s93, s84
	s_addc_u32 s85, s94, 0
	s_add_u32 s86, s93, s86
	s_addc_u32 s87, s94, 0
	s_add_u32 s88, s93, s88
	s_addc_u32 s89, s94, 0
	s_add_u32 s90, s93, s90
	s_addc_u32 s91, s94, 0
	global_load_dwordx2 v[64:65], v255, s[84:85]
	global_load_dwordx2 v[66:67], v255, s[86:87]
	global_load_dwordx2 v[68:69], v255, s[88:89]
	global_load_dwordx2 v[70:71], v255, s[90:91]
	s_waitcnt vmcnt(31)
	v_cvt_scalef32_pk_f32_fp4 v[132:133], v72, 1.0 op_sel:[1,0,0]
	s_nop 0
	v_cvt_scalef32_pk_f32_fp4 v[130:131], v72, 1.0
	v_pk_mul_f32 v[132:133], v[132:133], v[6:7]
	s_nop 0
	v_pk_fma_f32 v[130:131], v[130:131], v[4:5], v[132:133]
	v_cvt_scalef32_pk_f32_fp4 v[132:133], v72, 1.0 op_sel:[0,1,0]
	v_pk_fma_f32 v[130:131], v[132:133], v[8:9], v[130:131]
	v_cvt_scalef32_pk_f32_fp4 v[132:133], v72, 1.0 op_sel:[1,1,0]
	v_pk_fma_f32 v[130:131], v[132:133], v[10:11], v[130:131]
	v_cvt_scalef32_pk_f32_fp4 v[132:133], v73, 1.0
	v_pk_fma_f32 v[130:131], v[132:133], v[12:13], v[130:131]
	v_cvt_scalef32_pk_f32_fp4 v[132:133], v73, 1.0 op_sel:[1,0,0]
	v_pk_fma_f32 v[130:131], v[132:133], v[14:15], v[130:131]
	v_cvt_scalef32_pk_f32_fp4 v[132:133], v73, 1.0 op_sel:[0,1,0]
	v_pk_fma_f32 v[130:131], v[132:133], v[16:17], v[130:131]
	v_cvt_scalef32_pk_f32_fp4 v[72:73], v73, 1.0 op_sel:[1,1,0]
	v_pk_fma_f32 v[72:73], v[72:73], v[18:19], v[130:131]
	s_waitcnt vmcnt(30)
	v_cvt_scalef32_pk_f32_fp4 v[130:131], v74, 1.0 op_sel:[1,0,0]
	v_add_f32_e32 v132, v72, v73
	v_cvt_scalef32_pk_f32_fp4 v[72:73], v74, 1.0
	v_pk_mul_f32 v[130:131], v[130:131], v[6:7]
	s_nop 0
	v_pk_fma_f32 v[72:73], v[72:73], v[4:5], v[130:131]
	v_cvt_scalef32_pk_f32_fp4 v[130:131], v74, 1.0 op_sel:[0,1,0]
	v_pk_fma_f32 v[72:73], v[130:131], v[8:9], v[72:73]
	v_cvt_scalef32_pk_f32_fp4 v[130:131], v74, 1.0 op_sel:[1,1,0]
	v_pk_fma_f32 v[72:73], v[130:131], v[10:11], v[72:73]
	v_cvt_scalef32_pk_f32_fp4 v[130:131], v75, 1.0
	v_pk_fma_f32 v[72:73], v[130:131], v[12:13], v[72:73]
	v_cvt_scalef32_pk_f32_fp4 v[130:131], v75, 1.0 op_sel:[1,0,0]
	v_pk_fma_f32 v[72:73], v[130:131], v[14:15], v[72:73]
	v_cvt_scalef32_pk_f32_fp4 v[130:131], v75, 1.0 op_sel:[0,1,0]
	v_pk_fma_f32 v[72:73], v[130:131], v[16:17], v[72:73]
	v_cvt_scalef32_pk_f32_fp4 v[74:75], v75, 1.0 op_sel:[1,1,0]
	v_pk_fma_f32 v[72:73], v[74:75], v[18:19], v[72:73]
	s_waitcnt vmcnt(29)
	v_cvt_scalef32_pk_f32_fp4 v[74:75], v76, 1.0 op_sel:[1,0,0]
	v_add_f32_e32 v130, v72, v73
	v_cvt_scalef32_pk_f32_fp4 v[72:73], v76, 1.0
	v_pk_mul_f32 v[74:75], v[74:75], v[6:7]
	s_nop 0
	v_pk_fma_f32 v[72:73], v[72:73], v[4:5], v[74:75]
	v_cvt_scalef32_pk_f32_fp4 v[74:75], v76, 1.0 op_sel:[0,1,0]
	v_pk_fma_f32 v[72:73], v[74:75], v[8:9], v[72:73]
	v_cvt_scalef32_pk_f32_fp4 v[74:75], v76, 1.0 op_sel:[1,1,0]
	v_pk_fma_f32 v[72:73], v[74:75], v[10:11], v[72:73]
	v_cvt_scalef32_pk_f32_fp4 v[74:75], v77, 1.0
	v_pk_fma_f32 v[72:73], v[74:75], v[12:13], v[72:73]
	v_cvt_scalef32_pk_f32_fp4 v[74:75], v77, 1.0 op_sel:[1,0,0]
	v_pk_fma_f32 v[72:73], v[74:75], v[14:15], v[72:73]
	v_cvt_scalef32_pk_f32_fp4 v[74:75], v77, 1.0 op_sel:[0,1,0]
	v_pk_fma_f32 v[72:73], v[74:75], v[16:17], v[72:73]
	v_cvt_scalef32_pk_f32_fp4 v[74:75], v77, 1.0 op_sel:[1,1,0]
	v_pk_fma_f32 v[72:73], v[74:75], v[18:19], v[72:73]
	s_waitcnt vmcnt(28)
	v_cvt_scalef32_pk_f32_fp4 v[74:75], v78, 1.0 op_sel:[1,0,0]
	v_add_f32_e32 v76, v72, v73
	v_cvt_scalef32_pk_f32_fp4 v[72:73], v78, 1.0
	v_pk_mul_f32 v[74:75], v[74:75], v[6:7]
	s_nop 0
	v_pk_fma_f32 v[72:73], v[72:73], v[4:5], v[74:75]
	v_cvt_scalef32_pk_f32_fp4 v[74:75], v78, 1.0 op_sel:[0,1,0]
	v_pk_fma_f32 v[72:73], v[74:75], v[8:9], v[72:73]
	v_cvt_scalef32_pk_f32_fp4 v[74:75], v78, 1.0 op_sel:[1,1,0]
	v_pk_fma_f32 v[72:73], v[74:75], v[10:11], v[72:73]
	v_cvt_scalef32_pk_f32_fp4 v[74:75], v79, 1.0
	v_pk_fma_f32 v[72:73], v[74:75], v[12:13], v[72:73]
	v_cvt_scalef32_pk_f32_fp4 v[74:75], v79, 1.0 op_sel:[1,0,0]
	v_pk_fma_f32 v[72:73], v[74:75], v[14:15], v[72:73]
	v_cvt_scalef32_pk_f32_fp4 v[74:75], v79, 1.0 op_sel:[0,1,0]
	v_pk_fma_f32 v[72:73], v[74:75], v[16:17], v[72:73]
	v_cvt_scalef32_pk_f32_fp4 v[74:75], v79, 1.0 op_sel:[1,1,0]
	v_pk_fma_f32 v[72:73], v[74:75], v[18:19], v[72:73]
	s_waitcnt vmcnt(27)
	v_cvt_scalef32_pk_f32_fp4 v[74:75], v80, 1.0 op_sel:[1,0,0]
	v_add_f32_e32 v77, v72, v73
	v_cvt_scalef32_pk_f32_fp4 v[72:73], v80, 1.0
	v_pk_mul_f32 v[74:75], v[74:75], v[6:7]
	s_nop 0
	v_pk_fma_f32 v[72:73], v[72:73], v[4:5], v[74:75]
	v_cvt_scalef32_pk_f32_fp4 v[74:75], v80, 1.0 op_sel:[0,1,0]
	v_pk_fma_f32 v[72:73], v[74:75], v[8:9], v[72:73]
	v_cvt_scalef32_pk_f32_fp4 v[74:75], v80, 1.0 op_sel:[1,1,0]
	v_pk_fma_f32 v[72:73], v[74:75], v[10:11], v[72:73]
	v_cvt_scalef32_pk_f32_fp4 v[74:75], v81, 1.0
	v_pk_fma_f32 v[72:73], v[74:75], v[12:13], v[72:73]
	v_cvt_scalef32_pk_f32_fp4 v[74:75], v81, 1.0 op_sel:[1,0,0]
	v_pk_fma_f32 v[72:73], v[74:75], v[14:15], v[72:73]
	v_cvt_scalef32_pk_f32_fp4 v[74:75], v81, 1.0 op_sel:[0,1,0]
	v_pk_fma_f32 v[72:73], v[74:75], v[16:17], v[72:73]
	v_cvt_scalef32_pk_f32_fp4 v[74:75], v81, 1.0 op_sel:[1,1,0]
	v_pk_fma_f32 v[72:73], v[74:75], v[18:19], v[72:73]
	s_waitcnt vmcnt(26)
	v_cvt_scalef32_pk_f32_fp4 v[74:75], v82, 1.0 op_sel:[1,0,0]
	v_add_f32_e32 v78, v72, v73
	v_cvt_scalef32_pk_f32_fp4 v[72:73], v82, 1.0
	v_pk_mul_f32 v[74:75], v[74:75], v[6:7]
	s_nop 0
	v_pk_fma_f32 v[72:73], v[72:73], v[4:5], v[74:75]
	v_cvt_scalef32_pk_f32_fp4 v[74:75], v82, 1.0 op_sel:[0,1,0]
	v_pk_fma_f32 v[72:73], v[74:75], v[8:9], v[72:73]
	v_cvt_scalef32_pk_f32_fp4 v[74:75], v82, 1.0 op_sel:[1,1,0]
	v_pk_fma_f32 v[72:73], v[74:75], v[10:11], v[72:73]
	v_cvt_scalef32_pk_f32_fp4 v[74:75], v83, 1.0
	v_pk_fma_f32 v[72:73], v[74:75], v[12:13], v[72:73]
	v_cvt_scalef32_pk_f32_fp4 v[74:75], v83, 1.0 op_sel:[1,0,0]
	v_pk_fma_f32 v[72:73], v[74:75], v[14:15], v[72:73]
	v_cvt_scalef32_pk_f32_fp4 v[74:75], v83, 1.0 op_sel:[0,1,0]
	v_pk_fma_f32 v[72:73], v[74:75], v[16:17], v[72:73]
	v_cvt_scalef32_pk_f32_fp4 v[74:75], v83, 1.0 op_sel:[1,1,0]
	v_pk_fma_f32 v[72:73], v[74:75], v[18:19], v[72:73]
	s_waitcnt vmcnt(25)
	v_cvt_scalef32_pk_f32_fp4 v[74:75], v84, 1.0 op_sel:[1,0,0]
	v_add_f32_e32 v79, v72, v73
	v_cvt_scalef32_pk_f32_fp4 v[72:73], v84, 1.0
	v_pk_mul_f32 v[74:75], v[74:75], v[6:7]
	s_nop 0
	v_pk_fma_f32 v[72:73], v[72:73], v[4:5], v[74:75]
	v_cvt_scalef32_pk_f32_fp4 v[74:75], v84, 1.0 op_sel:[0,1,0]
	v_pk_fma_f32 v[72:73], v[74:75], v[8:9], v[72:73]
	v_cvt_scalef32_pk_f32_fp4 v[74:75], v84, 1.0 op_sel:[1,1,0]
	v_pk_fma_f32 v[72:73], v[74:75], v[10:11], v[72:73]
	v_cvt_scalef32_pk_f32_fp4 v[74:75], v85, 1.0
	v_pk_fma_f32 v[72:73], v[74:75], v[12:13], v[72:73]
	v_cvt_scalef32_pk_f32_fp4 v[74:75], v85, 1.0 op_sel:[1,0,0]
	v_pk_fma_f32 v[72:73], v[74:75], v[14:15], v[72:73]
	v_cvt_scalef32_pk_f32_fp4 v[74:75], v85, 1.0 op_sel:[0,1,0]
	v_pk_fma_f32 v[72:73], v[74:75], v[16:17], v[72:73]
	v_cvt_scalef32_pk_f32_fp4 v[74:75], v85, 1.0 op_sel:[1,1,0]
	v_pk_fma_f32 v[72:73], v[74:75], v[18:19], v[72:73]
	s_waitcnt vmcnt(24)
	v_cvt_scalef32_pk_f32_fp4 v[74:75], v86, 1.0 op_sel:[1,0,0]
	v_add_f32_e32 v80, v72, v73
	v_cvt_scalef32_pk_f32_fp4 v[72:73], v86, 1.0
	v_pk_mul_f32 v[74:75], v[74:75], v[6:7]
	s_nop 0
	v_pk_fma_f32 v[72:73], v[72:73], v[4:5], v[74:75]
	v_cvt_scalef32_pk_f32_fp4 v[74:75], v86, 1.0 op_sel:[0,1,0]
	v_pk_fma_f32 v[72:73], v[74:75], v[8:9], v[72:73]
	v_cvt_scalef32_pk_f32_fp4 v[74:75], v86, 1.0 op_sel:[1,1,0]
	v_pk_fma_f32 v[72:73], v[74:75], v[10:11], v[72:73]
	v_cvt_scalef32_pk_f32_fp4 v[74:75], v87, 1.0
	v_pk_fma_f32 v[72:73], v[74:75], v[12:13], v[72:73]
	v_cvt_scalef32_pk_f32_fp4 v[74:75], v87, 1.0 op_sel:[1,0,0]
	v_pk_fma_f32 v[72:73], v[74:75], v[14:15], v[72:73]
	v_cvt_scalef32_pk_f32_fp4 v[74:75], v87, 1.0 op_sel:[0,1,0]
	v_pk_fma_f32 v[72:73], v[74:75], v[16:17], v[72:73]
	v_cvt_scalef32_pk_f32_fp4 v[74:75], v87, 1.0 op_sel:[1,1,0]
	v_pk_fma_f32 v[72:73], v[74:75], v[18:19], v[72:73]
	s_waitcnt vmcnt(23)
	v_cvt_scalef32_pk_f32_fp4 v[74:75], v88, 1.0 op_sel:[1,0,0]
	v_add_f32_e32 v81, v72, v73
	v_cvt_scalef32_pk_f32_fp4 v[72:73], v88, 1.0
	v_pk_mul_f32 v[74:75], v[74:75], v[6:7]
	s_nop 0
	v_pk_fma_f32 v[72:73], v[72:73], v[4:5], v[74:75]
	v_cvt_scalef32_pk_f32_fp4 v[74:75], v88, 1.0 op_sel:[0,1,0]
	v_pk_fma_f32 v[72:73], v[74:75], v[8:9], v[72:73]
	v_cvt_scalef32_pk_f32_fp4 v[74:75], v88, 1.0 op_sel:[1,1,0]
	v_pk_fma_f32 v[72:73], v[74:75], v[10:11], v[72:73]
	v_cvt_scalef32_pk_f32_fp4 v[74:75], v89, 1.0
	v_pk_fma_f32 v[72:73], v[74:75], v[12:13], v[72:73]
	v_cvt_scalef32_pk_f32_fp4 v[74:75], v89, 1.0 op_sel:[1,0,0]
	v_pk_fma_f32 v[72:73], v[74:75], v[14:15], v[72:73]
	v_cvt_scalef32_pk_f32_fp4 v[74:75], v89, 1.0 op_sel:[0,1,0]
	v_pk_fma_f32 v[72:73], v[74:75], v[16:17], v[72:73]
	v_cvt_scalef32_pk_f32_fp4 v[74:75], v89, 1.0 op_sel:[1,1,0]
	v_pk_fma_f32 v[72:73], v[74:75], v[18:19], v[72:73]
	s_waitcnt vmcnt(22)
	v_cvt_scalef32_pk_f32_fp4 v[74:75], v90, 1.0 op_sel:[1,0,0]
	v_add_f32_e32 v82, v72, v73
	v_cvt_scalef32_pk_f32_fp4 v[72:73], v90, 1.0
	v_pk_mul_f32 v[74:75], v[74:75], v[6:7]
	s_nop 0
	v_pk_fma_f32 v[72:73], v[72:73], v[4:5], v[74:75]
	v_cvt_scalef32_pk_f32_fp4 v[74:75], v90, 1.0 op_sel:[0,1,0]
	v_pk_fma_f32 v[72:73], v[74:75], v[8:9], v[72:73]
	v_cvt_scalef32_pk_f32_fp4 v[74:75], v90, 1.0 op_sel:[1,1,0]
	v_pk_fma_f32 v[72:73], v[74:75], v[10:11], v[72:73]
	v_cvt_scalef32_pk_f32_fp4 v[74:75], v91, 1.0
	v_pk_fma_f32 v[72:73], v[74:75], v[12:13], v[72:73]
	v_cvt_scalef32_pk_f32_fp4 v[74:75], v91, 1.0 op_sel:[1,0,0]
	v_pk_fma_f32 v[72:73], v[74:75], v[14:15], v[72:73]
	v_cvt_scalef32_pk_f32_fp4 v[74:75], v91, 1.0 op_sel:[0,1,0]
	v_pk_fma_f32 v[72:73], v[74:75], v[16:17], v[72:73]
	v_cvt_scalef32_pk_f32_fp4 v[74:75], v91, 1.0 op_sel:[1,1,0]
	v_pk_fma_f32 v[72:73], v[74:75], v[18:19], v[72:73]
	s_waitcnt vmcnt(21)
	v_cvt_scalef32_pk_f32_fp4 v[74:75], v92, 1.0 op_sel:[1,0,0]
	v_add_f32_e32 v83, v72, v73
	v_cvt_scalef32_pk_f32_fp4 v[72:73], v92, 1.0
	v_pk_mul_f32 v[74:75], v[74:75], v[6:7]
	s_nop 0
	v_pk_fma_f32 v[72:73], v[72:73], v[4:5], v[74:75]
	v_cvt_scalef32_pk_f32_fp4 v[74:75], v92, 1.0 op_sel:[0,1,0]
	v_pk_fma_f32 v[72:73], v[74:75], v[8:9], v[72:73]
	v_cvt_scalef32_pk_f32_fp4 v[74:75], v92, 1.0 op_sel:[1,1,0]
	v_pk_fma_f32 v[72:73], v[74:75], v[10:11], v[72:73]
	v_cvt_scalef32_pk_f32_fp4 v[74:75], v93, 1.0
	v_pk_fma_f32 v[72:73], v[74:75], v[12:13], v[72:73]
	v_cvt_scalef32_pk_f32_fp4 v[74:75], v93, 1.0 op_sel:[1,0,0]
	v_pk_fma_f32 v[72:73], v[74:75], v[14:15], v[72:73]
	v_cvt_scalef32_pk_f32_fp4 v[74:75], v93, 1.0 op_sel:[0,1,0]
	v_pk_fma_f32 v[72:73], v[74:75], v[16:17], v[72:73]
	v_cvt_scalef32_pk_f32_fp4 v[74:75], v93, 1.0 op_sel:[1,1,0]
	v_pk_fma_f32 v[72:73], v[74:75], v[18:19], v[72:73]
	s_waitcnt vmcnt(20)
	v_cvt_scalef32_pk_f32_fp4 v[74:75], v94, 1.0 op_sel:[1,0,0]
	v_add_f32_e32 v84, v72, v73
	v_cvt_scalef32_pk_f32_fp4 v[72:73], v94, 1.0
	v_pk_mul_f32 v[74:75], v[74:75], v[6:7]
	s_nop 0
	v_pk_fma_f32 v[72:73], v[72:73], v[4:5], v[74:75]
	v_cvt_scalef32_pk_f32_fp4 v[74:75], v94, 1.0 op_sel:[0,1,0]
	v_pk_fma_f32 v[72:73], v[74:75], v[8:9], v[72:73]
	v_cvt_scalef32_pk_f32_fp4 v[74:75], v94, 1.0 op_sel:[1,1,0]
	v_pk_fma_f32 v[72:73], v[74:75], v[10:11], v[72:73]
	v_cvt_scalef32_pk_f32_fp4 v[74:75], v95, 1.0
	v_pk_fma_f32 v[72:73], v[74:75], v[12:13], v[72:73]
	v_cvt_scalef32_pk_f32_fp4 v[74:75], v95, 1.0 op_sel:[1,0,0]
	v_pk_fma_f32 v[72:73], v[74:75], v[14:15], v[72:73]
	v_cvt_scalef32_pk_f32_fp4 v[74:75], v95, 1.0 op_sel:[0,1,0]
	v_pk_fma_f32 v[72:73], v[74:75], v[16:17], v[72:73]
	v_cvt_scalef32_pk_f32_fp4 v[74:75], v95, 1.0 op_sel:[1,1,0]
	v_pk_fma_f32 v[72:73], v[74:75], v[18:19], v[72:73]
	s_waitcnt vmcnt(19)
	v_cvt_scalef32_pk_f32_fp4 v[74:75], v96, 1.0 op_sel:[1,0,0]
	v_add_f32_e32 v85, v72, v73
	v_cvt_scalef32_pk_f32_fp4 v[72:73], v96, 1.0
	v_pk_mul_f32 v[74:75], v[74:75], v[6:7]
	s_nop 0
	v_pk_fma_f32 v[72:73], v[72:73], v[4:5], v[74:75]
	v_cvt_scalef32_pk_f32_fp4 v[74:75], v96, 1.0 op_sel:[0,1,0]
	v_pk_fma_f32 v[72:73], v[74:75], v[8:9], v[72:73]
	v_cvt_scalef32_pk_f32_fp4 v[74:75], v96, 1.0 op_sel:[1,1,0]
	v_pk_fma_f32 v[72:73], v[74:75], v[10:11], v[72:73]
	v_cvt_scalef32_pk_f32_fp4 v[74:75], v97, 1.0
	v_pk_fma_f32 v[72:73], v[74:75], v[12:13], v[72:73]
	v_cvt_scalef32_pk_f32_fp4 v[74:75], v97, 1.0 op_sel:[1,0,0]
	v_pk_fma_f32 v[72:73], v[74:75], v[14:15], v[72:73]
	v_cvt_scalef32_pk_f32_fp4 v[74:75], v97, 1.0 op_sel:[0,1,0]
	v_pk_fma_f32 v[72:73], v[74:75], v[16:17], v[72:73]
	v_cvt_scalef32_pk_f32_fp4 v[74:75], v97, 1.0 op_sel:[1,1,0]
	v_pk_fma_f32 v[72:73], v[74:75], v[18:19], v[72:73]
	s_waitcnt vmcnt(18)
	v_cvt_scalef32_pk_f32_fp4 v[74:75], v98, 1.0 op_sel:[1,0,0]
	v_add_f32_e32 v86, v72, v73
	v_cvt_scalef32_pk_f32_fp4 v[72:73], v98, 1.0
	v_pk_mul_f32 v[74:75], v[74:75], v[6:7]
	s_nop 0
	v_pk_fma_f32 v[72:73], v[72:73], v[4:5], v[74:75]
	v_cvt_scalef32_pk_f32_fp4 v[74:75], v98, 1.0 op_sel:[0,1,0]
	v_pk_fma_f32 v[72:73], v[74:75], v[8:9], v[72:73]
	v_cvt_scalef32_pk_f32_fp4 v[74:75], v98, 1.0 op_sel:[1,1,0]
	v_pk_fma_f32 v[72:73], v[74:75], v[10:11], v[72:73]
	v_cvt_scalef32_pk_f32_fp4 v[74:75], v99, 1.0
	v_pk_fma_f32 v[72:73], v[74:75], v[12:13], v[72:73]
	v_cvt_scalef32_pk_f32_fp4 v[74:75], v99, 1.0 op_sel:[1,0,0]
	v_pk_fma_f32 v[72:73], v[74:75], v[14:15], v[72:73]
	v_cvt_scalef32_pk_f32_fp4 v[74:75], v99, 1.0 op_sel:[0,1,0]
	v_pk_fma_f32 v[72:73], v[74:75], v[16:17], v[72:73]
	v_cvt_scalef32_pk_f32_fp4 v[74:75], v99, 1.0 op_sel:[1,1,0]
	v_pk_fma_f32 v[72:73], v[74:75], v[18:19], v[72:73]
	s_waitcnt vmcnt(17)
	v_cvt_scalef32_pk_f32_fp4 v[74:75], v100, 1.0 op_sel:[1,0,0]
	v_add_f32_e32 v87, v72, v73
	v_cvt_scalef32_pk_f32_fp4 v[72:73], v100, 1.0
	v_pk_mul_f32 v[74:75], v[74:75], v[6:7]
	s_nop 0
	v_pk_fma_f32 v[72:73], v[72:73], v[4:5], v[74:75]
	v_cvt_scalef32_pk_f32_fp4 v[74:75], v100, 1.0 op_sel:[0,1,0]
	v_pk_fma_f32 v[72:73], v[74:75], v[8:9], v[72:73]
	v_cvt_scalef32_pk_f32_fp4 v[74:75], v100, 1.0 op_sel:[1,1,0]
	v_pk_fma_f32 v[72:73], v[74:75], v[10:11], v[72:73]
	v_cvt_scalef32_pk_f32_fp4 v[74:75], v101, 1.0
	v_pk_fma_f32 v[72:73], v[74:75], v[12:13], v[72:73]
	v_cvt_scalef32_pk_f32_fp4 v[74:75], v101, 1.0 op_sel:[1,0,0]
	v_pk_fma_f32 v[72:73], v[74:75], v[14:15], v[72:73]
	v_cvt_scalef32_pk_f32_fp4 v[74:75], v101, 1.0 op_sel:[0,1,0]
	v_pk_fma_f32 v[72:73], v[74:75], v[16:17], v[72:73]
	v_cvt_scalef32_pk_f32_fp4 v[74:75], v101, 1.0 op_sel:[1,1,0]
	v_pk_fma_f32 v[72:73], v[74:75], v[18:19], v[72:73]
	s_waitcnt vmcnt(16)
	v_cvt_scalef32_pk_f32_fp4 v[74:75], v102, 1.0 op_sel:[1,0,0]
	v_add_f32_e32 v88, v72, v73
	v_cvt_scalef32_pk_f32_fp4 v[72:73], v102, 1.0
	v_pk_mul_f32 v[74:75], v[74:75], v[6:7]
	s_nop 0
	v_pk_fma_f32 v[72:73], v[72:73], v[4:5], v[74:75]
	v_cvt_scalef32_pk_f32_fp4 v[74:75], v102, 1.0 op_sel:[0,1,0]
	v_pk_fma_f32 v[72:73], v[74:75], v[8:9], v[72:73]
	v_cvt_scalef32_pk_f32_fp4 v[74:75], v102, 1.0 op_sel:[1,1,0]
	v_pk_fma_f32 v[72:73], v[74:75], v[10:11], v[72:73]
	v_cvt_scalef32_pk_f32_fp4 v[74:75], v103, 1.0
	v_pk_fma_f32 v[72:73], v[74:75], v[12:13], v[72:73]
	v_cvt_scalef32_pk_f32_fp4 v[74:75], v103, 1.0 op_sel:[1,0,0]
	v_pk_fma_f32 v[72:73], v[74:75], v[14:15], v[72:73]
	v_cvt_scalef32_pk_f32_fp4 v[74:75], v103, 1.0 op_sel:[0,1,0]
	v_pk_fma_f32 v[72:73], v[74:75], v[16:17], v[72:73]
	v_cvt_scalef32_pk_f32_fp4 v[74:75], v103, 1.0 op_sel:[1,1,0]
	v_pk_fma_f32 v[72:73], v[74:75], v[18:19], v[72:73]
	v_cndmask_b32_e64 v74, v132, v82, s[0:1]
	v_add_f32_e32 v72, v72, v73
	v_cndmask_b32_e64 v73, v82, v132, s[0:1]
	v_cndmask_b32_e64 v75, v130, v83, s[0:1]
	s_nop 0
	v_add_f32_dpp v73, v74, v73 quad_perm:[1,0,3,2] row_mask:0xf bank_mask:0xf bound_ctrl:1
	v_cndmask_b32_e64 v74, v83, v130, s[0:1]
	v_add_u32_e32 v127, 32, v127
	s_nop 0
	v_add_f32_dpp v74, v75, v74 quad_perm:[1,0,3,2] row_mask:0xf bank_mask:0xf bound_ctrl:1
	v_cndmask_b32_e64 v75, v84, v76, s[0:1]
	v_cndmask_b32_e64 v76, v76, v84, s[0:1]
	s_nop 1
	v_add_f32_dpp v75, v76, v75 quad_perm:[1,0,3,2] row_mask:0xf bank_mask:0xf bound_ctrl:1
	v_cndmask_b32_e64 v76, v85, v77, s[0:1]
	v_cndmask_b32_e64 v77, v77, v85, s[0:1]
	s_nop 1
	v_add_f32_dpp v76, v77, v76 quad_perm:[1,0,3,2] row_mask:0xf bank_mask:0xf bound_ctrl:1
	v_cndmask_b32_e64 v77, v86, v78, s[0:1]
	v_cndmask_b32_e64 v78, v78, v86, s[0:1]
	s_nop 1
	v_add_f32_dpp v77, v78, v77 quad_perm:[1,0,3,2] row_mask:0xf bank_mask:0xf bound_ctrl:1
	v_cndmask_b32_e64 v78, v87, v79, s[0:1]
	v_cndmask_b32_e64 v79, v79, v87, s[0:1]
	s_nop 0
	s_nop 0
	v_add_f32_dpp v78, v79, v78 quad_perm:[1,0,3,2] row_mask:0xf bank_mask:0xf bound_ctrl:1
	v_cndmask_b32_e64 v79, v88, v80, s[0:1]
	v_cndmask_b32_e64 v80, v80, v88, s[0:1]
	s_nop 1
	v_add_f32_dpp v79, v80, v79 quad_perm:[1,0,3,2] row_mask:0xf bank_mask:0xf bound_ctrl:1
	v_cndmask_b32_e64 v80, v72, v81, s[0:1]
	v_cndmask_b32_e64 v72, v81, v72, s[0:1]
	s_nop 1
	v_add_f32_dpp v72, v72, v80 quad_perm:[1,0,3,2] row_mask:0xf bank_mask:0xf bound_ctrl:1
	v_cndmask_b32_e64 v80, v77, v73, s[4:5]
	v_cndmask_b32_e64 v73, v73, v77, s[4:5]
	v_cndmask_b32_e64 v77, v78, v74, s[4:5]
	v_cndmask_b32_e64 v74, v74, v78, s[4:5]
	v_add_f32_dpp v73, v73, v80 quad_perm:[2,3,0,1] row_mask:0xf bank_mask:0xf bound_ctrl:1
	s_nop 0
	v_add_f32_dpp v74, v74, v77 quad_perm:[2,3,0,1] row_mask:0xf bank_mask:0xf bound_ctrl:1
	v_cndmask_b32_e64 v77, v79, v75, s[4:5]
	v_cndmask_b32_e64 v75, v75, v79, s[4:5]
	s_nop 0
	s_nop 0
	v_add_f32_dpp v75, v75, v77 quad_perm:[2,3,0,1] row_mask:0xf bank_mask:0xf bound_ctrl:1
	v_cndmask_b32_e64 v77, v72, v76, s[4:5]
	v_cndmask_b32_e64 v72, v76, v72, s[4:5]
	v_cndmask_b32_e64 v76, v75, v73, s[6:7]
	v_cndmask_b32_e64 v73, v73, v75, s[6:7]
	v_add_f32_dpp v72, v72, v77 quad_perm:[2,3,0,1] row_mask:0xf bank_mask:0xf bound_ctrl:1
	v_cndmask_b32_e64 v75, v72, v74, s[6:7]
	v_cndmask_b32_e64 v72, v74, v72, s[6:7]
	v_mov_b32_dpp v73, v73 row_half_mirror row_mask:0xf bank_mask:0xf bound_ctrl:1
	s_nop 0
	v_mov_b32_dpp v72, v72 row_half_mirror row_mask:0xf bank_mask:0xf bound_ctrl:1
	v_add_f32_dpp v73, v73, v76 quad_perm:[3,2,1,0] row_mask:0xf bank_mask:0xf bound_ctrl:1
	s_nop 0
	v_add_f32_dpp v72, v72, v75 quad_perm:[3,2,1,0] row_mask:0xf bank_mask:0xf bound_ctrl:1
	v_cndmask_b32_e64 v74, v72, v73, s[8:9]
	v_cndmask_b32_e64 v72, v73, v72, s[8:9]
	s_nop 1
	v_mov_b32_dpp v72, v72 row_mirror row_mask:0xf bank_mask:0xf bound_ctrl:1
	v_and_b32_e32 v76, 2, v124
	s_nop 0
	v_add_f32_dpp v72, v72, v74 row_half_mirror row_mask:0xf bank_mask:0xf bound_ctrl:1
	ds_bpermute_b32 v73, v125, v72
	v_cmp_eq_u32_e64 s[14:15], v106, v76
	s_waitcnt lgkmcnt(0)
	v_add_f32_e32 v72, v72, v73
	ds_bpermute_b32 v73, v126, v72
	s_waitcnt vmcnt(15)
	v_cvt_scalef32_pk_f32_fp4 v[74:75], v20, 1.0 op_sel:[1,0,0]
	v_pk_mul_f32 v[74:75], v[74:75], v[6:7]
	s_waitcnt lgkmcnt(0)
	v_add_f32_e32 v72, v72, v73
	v_cndmask_b32_e64 v73, v72, v128, s[12:13]
	v_cndmask_b32_e64 v77, v128, v73, s[14:15]
	s_and_b64 s[14:15], s[14:15], s[12:13]
	v_cndmask_b32_e64 v78, v129, v72, s[14:15]
	v_cvt_scalef32_pk_f32_fp4 v[72:73], v20, 1.0
	v_pk_fma_f32 v[72:73], v[72:73], v[4:5], v[74:75]
	v_cvt_scalef32_pk_f32_fp4 v[74:75], v20, 1.0 op_sel:[0,1,0]
	v_pk_fma_f32 v[72:73], v[74:75], v[8:9], v[72:73]
	v_cvt_scalef32_pk_f32_fp4 v[74:75], v20, 1.0 op_sel:[1,1,0]
	v_pk_fma_f32 v[72:73], v[74:75], v[10:11], v[72:73]
	v_cvt_scalef32_pk_f32_fp4 v[74:75], v21, 1.0
	v_pk_fma_f32 v[72:73], v[74:75], v[12:13], v[72:73]
	v_cvt_scalef32_pk_f32_fp4 v[74:75], v21, 1.0 op_sel:[1,0,0]
	v_pk_fma_f32 v[72:73], v[74:75], v[14:15], v[72:73]
	v_cvt_scalef32_pk_f32_fp4 v[74:75], v21, 1.0 op_sel:[0,1,0]
	v_pk_fma_f32 v[72:73], v[74:75], v[16:17], v[72:73]
	v_cvt_scalef32_pk_f32_fp4 v[20:21], v21, 1.0 op_sel:[1,1,0]
	v_pk_fma_f32 v[20:21], v[20:21], v[18:19], v[72:73]
	s_waitcnt vmcnt(14)
	v_cvt_scalef32_pk_f32_fp4 v[72:73], v22, 1.0 op_sel:[1,0,0]
	v_add_f32_e32 v74, v20, v21
	v_cvt_scalef32_pk_f32_fp4 v[20:21], v22, 1.0
	v_pk_mul_f32 v[72:73], v[72:73], v[6:7]
	s_nop 0
	v_pk_fma_f32 v[20:21], v[20:21], v[4:5], v[72:73]
	v_cvt_scalef32_pk_f32_fp4 v[72:73], v22, 1.0 op_sel:[0,1,0]
	v_pk_fma_f32 v[20:21], v[72:73], v[8:9], v[20:21]
	v_cvt_scalef32_pk_f32_fp4 v[72:73], v22, 1.0 op_sel:[1,1,0]
	v_pk_fma_f32 v[20:21], v[72:73], v[10:11], v[20:21]
	v_cvt_scalef32_pk_f32_fp4 v[72:73], v23, 1.0
	v_pk_fma_f32 v[20:21], v[72:73], v[12:13], v[20:21]
	v_cvt_scalef32_pk_f32_fp4 v[72:73], v23, 1.0 op_sel:[1,0,0]
	v_pk_fma_f32 v[20:21], v[72:73], v[14:15], v[20:21]
	v_cvt_scalef32_pk_f32_fp4 v[72:73], v23, 1.0 op_sel:[0,1,0]
	v_pk_fma_f32 v[20:21], v[72:73], v[16:17], v[20:21]
	v_cvt_scalef32_pk_f32_fp4 v[22:23], v23, 1.0 op_sel:[1,1,0]
	v_pk_fma_f32 v[20:21], v[22:23], v[18:19], v[20:21]
	s_waitcnt vmcnt(13)
	v_cvt_scalef32_pk_f32_fp4 v[22:23], v24, 1.0 op_sel:[1,0,0]
	v_add_f32_e32 v72, v20, v21
	v_cvt_scalef32_pk_f32_fp4 v[20:21], v24, 1.0
	v_pk_mul_f32 v[22:23], v[22:23], v[6:7]
	s_nop 0
	v_pk_fma_f32 v[20:21], v[20:21], v[4:5], v[22:23]
	v_cvt_scalef32_pk_f32_fp4 v[22:23], v24, 1.0 op_sel:[0,1,0]
	v_pk_fma_f32 v[20:21], v[22:23], v[8:9], v[20:21]
	v_cvt_scalef32_pk_f32_fp4 v[22:23], v24, 1.0 op_sel:[1,1,0]
	v_pk_fma_f32 v[20:21], v[22:23], v[10:11], v[20:21]
	v_cvt_scalef32_pk_f32_fp4 v[22:23], v25, 1.0
	v_pk_fma_f32 v[20:21], v[22:23], v[12:13], v[20:21]
	v_cvt_scalef32_pk_f32_fp4 v[22:23], v25, 1.0 op_sel:[1,0,0]
	v_pk_fma_f32 v[20:21], v[22:23], v[14:15], v[20:21]
	v_cvt_scalef32_pk_f32_fp4 v[22:23], v25, 1.0 op_sel:[0,1,0]
	v_pk_fma_f32 v[20:21], v[22:23], v[16:17], v[20:21]
	v_cvt_scalef32_pk_f32_fp4 v[22:23], v25, 1.0 op_sel:[1,1,0]
	v_pk_fma_f32 v[20:21], v[22:23], v[18:19], v[20:21]
	s_waitcnt vmcnt(12)
	v_cvt_scalef32_pk_f32_fp4 v[22:23], v26, 1.0 op_sel:[1,0,0]
	v_add_f32_e32 v24, v20, v21
	v_cvt_scalef32_pk_f32_fp4 v[20:21], v26, 1.0
	v_pk_mul_f32 v[22:23], v[22:23], v[6:7]
	s_nop 0
	v_pk_fma_f32 v[20:21], v[20:21], v[4:5], v[22:23]
	v_cvt_scalef32_pk_f32_fp4 v[22:23], v26, 1.0 op_sel:[0,1,0]
	v_pk_fma_f32 v[20:21], v[22:23], v[8:9], v[20:21]
	v_cvt_scalef32_pk_f32_fp4 v[22:23], v26, 1.0 op_sel:[1,1,0]
	v_pk_fma_f32 v[20:21], v[22:23], v[10:11], v[20:21]
	v_cvt_scalef32_pk_f32_fp4 v[22:23], v27, 1.0
	v_pk_fma_f32 v[20:21], v[22:23], v[12:13], v[20:21]
	v_cvt_scalef32_pk_f32_fp4 v[22:23], v27, 1.0 op_sel:[1,0,0]
	v_pk_fma_f32 v[20:21], v[22:23], v[14:15], v[20:21]
	v_cvt_scalef32_pk_f32_fp4 v[22:23], v27, 1.0 op_sel:[0,1,0]
	v_pk_fma_f32 v[20:21], v[22:23], v[16:17], v[20:21]
	v_cvt_scalef32_pk_f32_fp4 v[22:23], v27, 1.0 op_sel:[1,1,0]
	v_pk_fma_f32 v[20:21], v[22:23], v[18:19], v[20:21]
	s_waitcnt vmcnt(11)
	v_cvt_scalef32_pk_f32_fp4 v[22:23], v28, 1.0 op_sel:[1,0,0]
	v_add_f32_e32 v25, v20, v21
	v_cvt_scalef32_pk_f32_fp4 v[20:21], v28, 1.0
	v_pk_mul_f32 v[22:23], v[22:23], v[6:7]
	s_nop 0
	v_pk_fma_f32 v[20:21], v[20:21], v[4:5], v[22:23]
	v_cvt_scalef32_pk_f32_fp4 v[22:23], v28, 1.0 op_sel:[0,1,0]
	v_pk_fma_f32 v[20:21], v[22:23], v[8:9], v[20:21]
	v_cvt_scalef32_pk_f32_fp4 v[22:23], v28, 1.0 op_sel:[1,1,0]
	v_pk_fma_f32 v[20:21], v[22:23], v[10:11], v[20:21]
	v_cvt_scalef32_pk_f32_fp4 v[22:23], v29, 1.0
	v_pk_fma_f32 v[20:21], v[22:23], v[12:13], v[20:21]
	v_cvt_scalef32_pk_f32_fp4 v[22:23], v29, 1.0 op_sel:[1,0,0]
	v_pk_fma_f32 v[20:21], v[22:23], v[14:15], v[20:21]
	v_cvt_scalef32_pk_f32_fp4 v[22:23], v29, 1.0 op_sel:[0,1,0]
	v_pk_fma_f32 v[20:21], v[22:23], v[16:17], v[20:21]
	v_cvt_scalef32_pk_f32_fp4 v[22:23], v29, 1.0 op_sel:[1,1,0]
	v_pk_fma_f32 v[20:21], v[22:23], v[18:19], v[20:21]
	s_waitcnt vmcnt(10)
	v_cvt_scalef32_pk_f32_fp4 v[22:23], v30, 1.0 op_sel:[1,0,0]
	v_add_f32_e32 v26, v20, v21
	v_cvt_scalef32_pk_f32_fp4 v[20:21], v30, 1.0
	v_pk_mul_f32 v[22:23], v[22:23], v[6:7]
	v_add_u32_e32 v124, 2, v124
	v_pk_fma_f32 v[20:21], v[20:21], v[4:5], v[22:23]
	v_cvt_scalef32_pk_f32_fp4 v[22:23], v30, 1.0 op_sel:[0,1,0]
	v_pk_fma_f32 v[20:21], v[22:23], v[8:9], v[20:21]
	v_cvt_scalef32_pk_f32_fp4 v[22:23], v30, 1.0 op_sel:[1,1,0]
	v_pk_fma_f32 v[20:21], v[22:23], v[10:11], v[20:21]
	v_cvt_scalef32_pk_f32_fp4 v[22:23], v31, 1.0
	v_pk_fma_f32 v[20:21], v[22:23], v[12:13], v[20:21]
	v_cvt_scalef32_pk_f32_fp4 v[22:23], v31, 1.0 op_sel:[1,0,0]
	v_pk_fma_f32 v[20:21], v[22:23], v[14:15], v[20:21]
	v_cvt_scalef32_pk_f32_fp4 v[22:23], v31, 1.0 op_sel:[0,1,0]
	v_pk_fma_f32 v[20:21], v[22:23], v[16:17], v[20:21]
	v_cvt_scalef32_pk_f32_fp4 v[22:23], v31, 1.0 op_sel:[1,1,0]
	v_pk_fma_f32 v[20:21], v[22:23], v[18:19], v[20:21]
	s_waitcnt vmcnt(9)
	v_cvt_scalef32_pk_f32_fp4 v[22:23], v32, 1.0 op_sel:[1,0,0]
	v_add_f32_e32 v27, v20, v21
	v_cvt_scalef32_pk_f32_fp4 v[20:21], v32, 1.0
	v_pk_mul_f32 v[22:23], v[22:23], v[6:7]
	s_nop 0
	v_pk_fma_f32 v[20:21], v[20:21], v[4:5], v[22:23]
	v_cvt_scalef32_pk_f32_fp4 v[22:23], v32, 1.0 op_sel:[0,1,0]
	v_pk_fma_f32 v[20:21], v[22:23], v[8:9], v[20:21]
	v_cvt_scalef32_pk_f32_fp4 v[22:23], v32, 1.0 op_sel:[1,1,0]
	v_pk_fma_f32 v[20:21], v[22:23], v[10:11], v[20:21]
	v_cvt_scalef32_pk_f32_fp4 v[22:23], v33, 1.0
	v_pk_fma_f32 v[20:21], v[22:23], v[12:13], v[20:21]
	v_cvt_scalef32_pk_f32_fp4 v[22:23], v33, 1.0 op_sel:[1,0,0]
	v_pk_fma_f32 v[20:21], v[22:23], v[14:15], v[20:21]
	v_cvt_scalef32_pk_f32_fp4 v[22:23], v33, 1.0 op_sel:[0,1,0]
	v_pk_fma_f32 v[20:21], v[22:23], v[16:17], v[20:21]
	v_cvt_scalef32_pk_f32_fp4 v[22:23], v33, 1.0 op_sel:[1,1,0]
	v_pk_fma_f32 v[20:21], v[22:23], v[18:19], v[20:21]
	s_waitcnt vmcnt(8)
	v_cvt_scalef32_pk_f32_fp4 v[22:23], v34, 1.0 op_sel:[1,0,0]
	v_add_f32_e32 v28, v20, v21
	v_cvt_scalef32_pk_f32_fp4 v[20:21], v34, 1.0
	v_pk_mul_f32 v[22:23], v[22:23], v[6:7]
	s_nop 0
	v_pk_fma_f32 v[20:21], v[20:21], v[4:5], v[22:23]
	v_cvt_scalef32_pk_f32_fp4 v[22:23], v34, 1.0 op_sel:[0,1,0]
	v_pk_fma_f32 v[20:21], v[22:23], v[8:9], v[20:21]
	v_cvt_scalef32_pk_f32_fp4 v[22:23], v34, 1.0 op_sel:[1,1,0]
	v_pk_fma_f32 v[20:21], v[22:23], v[10:11], v[20:21]
	v_cvt_scalef32_pk_f32_fp4 v[22:23], v35, 1.0
	v_pk_fma_f32 v[20:21], v[22:23], v[12:13], v[20:21]
	v_cvt_scalef32_pk_f32_fp4 v[22:23], v35, 1.0 op_sel:[1,0,0]
	v_pk_fma_f32 v[20:21], v[22:23], v[14:15], v[20:21]
	v_cvt_scalef32_pk_f32_fp4 v[22:23], v35, 1.0 op_sel:[0,1,0]
	v_pk_fma_f32 v[20:21], v[22:23], v[16:17], v[20:21]
	v_cvt_scalef32_pk_f32_fp4 v[22:23], v35, 1.0 op_sel:[1,1,0]
	v_pk_fma_f32 v[20:21], v[22:23], v[18:19], v[20:21]
	s_waitcnt vmcnt(7)
	v_cvt_scalef32_pk_f32_fp4 v[22:23], v56, 1.0 op_sel:[1,0,0]
	v_add_f32_e32 v29, v20, v21
	v_cvt_scalef32_pk_f32_fp4 v[20:21], v56, 1.0
	v_pk_mul_f32 v[22:23], v[22:23], v[6:7]
	s_nop 0
	v_pk_fma_f32 v[20:21], v[20:21], v[4:5], v[22:23]
	v_cvt_scalef32_pk_f32_fp4 v[22:23], v56, 1.0 op_sel:[0,1,0]
	v_pk_fma_f32 v[20:21], v[22:23], v[8:9], v[20:21]
	v_cvt_scalef32_pk_f32_fp4 v[22:23], v56, 1.0 op_sel:[1,1,0]
	v_pk_fma_f32 v[20:21], v[22:23], v[10:11], v[20:21]
	v_cvt_scalef32_pk_f32_fp4 v[22:23], v57, 1.0
	v_pk_fma_f32 v[20:21], v[22:23], v[12:13], v[20:21]
	v_cvt_scalef32_pk_f32_fp4 v[22:23], v57, 1.0 op_sel:[1,0,0]
	v_pk_fma_f32 v[20:21], v[22:23], v[14:15], v[20:21]
	v_cvt_scalef32_pk_f32_fp4 v[22:23], v57, 1.0 op_sel:[0,1,0]
	v_pk_fma_f32 v[20:21], v[22:23], v[16:17], v[20:21]
	v_cvt_scalef32_pk_f32_fp4 v[22:23], v57, 1.0 op_sel:[1,1,0]
	v_pk_fma_f32 v[20:21], v[22:23], v[18:19], v[20:21]
	s_waitcnt vmcnt(6)
	v_cvt_scalef32_pk_f32_fp4 v[22:23], v58, 1.0 op_sel:[1,0,0]
	v_add_f32_e32 v30, v20, v21
	v_cvt_scalef32_pk_f32_fp4 v[20:21], v58, 1.0
	v_pk_mul_f32 v[22:23], v[22:23], v[6:7]
	s_nop 0
	v_pk_fma_f32 v[20:21], v[20:21], v[4:5], v[22:23]
	v_cvt_scalef32_pk_f32_fp4 v[22:23], v58, 1.0 op_sel:[0,1,0]
	v_pk_fma_f32 v[20:21], v[22:23], v[8:9], v[20:21]
	v_cvt_scalef32_pk_f32_fp4 v[22:23], v58, 1.0 op_sel:[1,1,0]
	v_pk_fma_f32 v[20:21], v[22:23], v[10:11], v[20:21]
	v_cvt_scalef32_pk_f32_fp4 v[22:23], v59, 1.0
	v_pk_fma_f32 v[20:21], v[22:23], v[12:13], v[20:21]
	v_cvt_scalef32_pk_f32_fp4 v[22:23], v59, 1.0 op_sel:[1,0,0]
	v_pk_fma_f32 v[20:21], v[22:23], v[14:15], v[20:21]
	v_cvt_scalef32_pk_f32_fp4 v[22:23], v59, 1.0 op_sel:[0,1,0]
	v_pk_fma_f32 v[20:21], v[22:23], v[16:17], v[20:21]
	v_cvt_scalef32_pk_f32_fp4 v[22:23], v59, 1.0 op_sel:[1,1,0]
	v_pk_fma_f32 v[20:21], v[22:23], v[18:19], v[20:21]
	s_waitcnt vmcnt(5)
	v_cvt_scalef32_pk_f32_fp4 v[22:23], v60, 1.0 op_sel:[1,0,0]
	v_add_f32_e32 v31, v20, v21
	v_cvt_scalef32_pk_f32_fp4 v[20:21], v60, 1.0
	v_pk_mul_f32 v[22:23], v[22:23], v[6:7]
	s_nop 0
	v_pk_fma_f32 v[20:21], v[20:21], v[4:5], v[22:23]
	v_cvt_scalef32_pk_f32_fp4 v[22:23], v60, 1.0 op_sel:[0,1,0]
	v_pk_fma_f32 v[20:21], v[22:23], v[8:9], v[20:21]
	v_cvt_scalef32_pk_f32_fp4 v[22:23], v60, 1.0 op_sel:[1,1,0]
	v_pk_fma_f32 v[20:21], v[22:23], v[10:11], v[20:21]
	v_cvt_scalef32_pk_f32_fp4 v[22:23], v61, 1.0
	v_pk_fma_f32 v[20:21], v[22:23], v[12:13], v[20:21]
	v_cvt_scalef32_pk_f32_fp4 v[22:23], v61, 1.0 op_sel:[1,0,0]
	v_pk_fma_f32 v[20:21], v[22:23], v[14:15], v[20:21]
	v_cvt_scalef32_pk_f32_fp4 v[22:23], v61, 1.0 op_sel:[0,1,0]
	v_pk_fma_f32 v[20:21], v[22:23], v[16:17], v[20:21]
	v_cvt_scalef32_pk_f32_fp4 v[22:23], v61, 1.0 op_sel:[1,1,0]
	v_pk_fma_f32 v[20:21], v[22:23], v[18:19], v[20:21]
	s_waitcnt vmcnt(4)
	v_cvt_scalef32_pk_f32_fp4 v[22:23], v62, 1.0 op_sel:[1,0,0]
	v_add_f32_e32 v32, v20, v21
	v_cvt_scalef32_pk_f32_fp4 v[20:21], v62, 1.0
	v_pk_mul_f32 v[22:23], v[22:23], v[6:7]
	s_nop 0
	v_pk_fma_f32 v[20:21], v[20:21], v[4:5], v[22:23]
	v_cvt_scalef32_pk_f32_fp4 v[22:23], v62, 1.0 op_sel:[0,1,0]
	v_pk_fma_f32 v[20:21], v[22:23], v[8:9], v[20:21]
	v_cvt_scalef32_pk_f32_fp4 v[22:23], v62, 1.0 op_sel:[1,1,0]
	v_pk_fma_f32 v[20:21], v[22:23], v[10:11], v[20:21]
	v_cvt_scalef32_pk_f32_fp4 v[22:23], v63, 1.0
	v_pk_fma_f32 v[20:21], v[22:23], v[12:13], v[20:21]
	v_cvt_scalef32_pk_f32_fp4 v[22:23], v63, 1.0 op_sel:[1,0,0]
	v_pk_fma_f32 v[20:21], v[22:23], v[14:15], v[20:21]
	v_cvt_scalef32_pk_f32_fp4 v[22:23], v63, 1.0 op_sel:[0,1,0]
	v_pk_fma_f32 v[20:21], v[22:23], v[16:17], v[20:21]
	v_cvt_scalef32_pk_f32_fp4 v[22:23], v63, 1.0 op_sel:[1,1,0]
	v_pk_fma_f32 v[20:21], v[22:23], v[18:19], v[20:21]
	s_waitcnt vmcnt(3)
	v_cvt_scalef32_pk_f32_fp4 v[22:23], v64, 1.0 op_sel:[1,0,0]
	v_add_f32_e32 v33, v20, v21
	v_cvt_scalef32_pk_f32_fp4 v[20:21], v64, 1.0
	v_pk_mul_f32 v[22:23], v[22:23], v[6:7]
	s_nop 0
	v_pk_fma_f32 v[20:21], v[20:21], v[4:5], v[22:23]
	v_cvt_scalef32_pk_f32_fp4 v[22:23], v64, 1.0 op_sel:[0,1,0]
	v_pk_fma_f32 v[20:21], v[22:23], v[8:9], v[20:21]
	v_cvt_scalef32_pk_f32_fp4 v[22:23], v64, 1.0 op_sel:[1,1,0]
	v_pk_fma_f32 v[20:21], v[22:23], v[10:11], v[20:21]
	v_cvt_scalef32_pk_f32_fp4 v[22:23], v65, 1.0
	v_pk_fma_f32 v[20:21], v[22:23], v[12:13], v[20:21]
	v_cvt_scalef32_pk_f32_fp4 v[22:23], v65, 1.0 op_sel:[1,0,0]
	v_pk_fma_f32 v[20:21], v[22:23], v[14:15], v[20:21]
	v_cvt_scalef32_pk_f32_fp4 v[22:23], v65, 1.0 op_sel:[0,1,0]
	v_pk_fma_f32 v[20:21], v[22:23], v[16:17], v[20:21]
	v_cvt_scalef32_pk_f32_fp4 v[22:23], v65, 1.0 op_sel:[1,1,0]
	v_pk_fma_f32 v[20:21], v[22:23], v[18:19], v[20:21]
	s_waitcnt vmcnt(2)
	v_cvt_scalef32_pk_f32_fp4 v[22:23], v66, 1.0 op_sel:[1,0,0]
	v_add_f32_e32 v34, v20, v21
	v_cvt_scalef32_pk_f32_fp4 v[20:21], v66, 1.0
	v_pk_mul_f32 v[22:23], v[22:23], v[6:7]
	s_nop 0
	v_pk_fma_f32 v[20:21], v[20:21], v[4:5], v[22:23]
	v_cvt_scalef32_pk_f32_fp4 v[22:23], v66, 1.0 op_sel:[0,1,0]
	v_pk_fma_f32 v[20:21], v[22:23], v[8:9], v[20:21]
	v_cvt_scalef32_pk_f32_fp4 v[22:23], v66, 1.0 op_sel:[1,1,0]
	v_pk_fma_f32 v[20:21], v[22:23], v[10:11], v[20:21]
	v_cvt_scalef32_pk_f32_fp4 v[22:23], v67, 1.0
	v_pk_fma_f32 v[20:21], v[22:23], v[12:13], v[20:21]
	v_cvt_scalef32_pk_f32_fp4 v[22:23], v67, 1.0 op_sel:[1,0,0]
	v_pk_fma_f32 v[20:21], v[22:23], v[14:15], v[20:21]
	v_cvt_scalef32_pk_f32_fp4 v[22:23], v67, 1.0 op_sel:[0,1,0]
	v_pk_fma_f32 v[20:21], v[22:23], v[16:17], v[20:21]
	v_cvt_scalef32_pk_f32_fp4 v[22:23], v67, 1.0 op_sel:[1,1,0]
	v_pk_fma_f32 v[20:21], v[22:23], v[18:19], v[20:21]
	s_waitcnt vmcnt(1)
	v_cvt_scalef32_pk_f32_fp4 v[22:23], v68, 1.0 op_sel:[1,0,0]
	v_add_f32_e32 v35, v20, v21
	v_cvt_scalef32_pk_f32_fp4 v[20:21], v68, 1.0
	v_pk_mul_f32 v[22:23], v[22:23], v[6:7]
	s_nop 0
	v_pk_fma_f32 v[20:21], v[20:21], v[4:5], v[22:23]
	v_cvt_scalef32_pk_f32_fp4 v[22:23], v68, 1.0 op_sel:[0,1,0]
	v_pk_fma_f32 v[20:21], v[22:23], v[8:9], v[20:21]
	v_cvt_scalef32_pk_f32_fp4 v[22:23], v68, 1.0 op_sel:[1,1,0]
	v_pk_fma_f32 v[20:21], v[22:23], v[10:11], v[20:21]
	v_cvt_scalef32_pk_f32_fp4 v[22:23], v69, 1.0
	v_pk_fma_f32 v[20:21], v[22:23], v[12:13], v[20:21]
	v_cvt_scalef32_pk_f32_fp4 v[22:23], v69, 1.0 op_sel:[1,0,0]
	v_pk_fma_f32 v[20:21], v[22:23], v[14:15], v[20:21]
	v_cvt_scalef32_pk_f32_fp4 v[22:23], v69, 1.0 op_sel:[0,1,0]
	v_pk_fma_f32 v[20:21], v[22:23], v[16:17], v[20:21]
	v_cvt_scalef32_pk_f32_fp4 v[22:23], v69, 1.0 op_sel:[1,1,0]
	v_pk_fma_f32 v[20:21], v[22:23], v[18:19], v[20:21]
	s_waitcnt vmcnt(0)
	v_cvt_scalef32_pk_f32_fp4 v[22:23], v70, 1.0 op_sel:[1,0,0]
	v_add_f32_e32 v56, v20, v21
	v_cvt_scalef32_pk_f32_fp4 v[20:21], v70, 1.0
	v_pk_mul_f32 v[22:23], v[22:23], v[6:7]
	s_nop 0
	v_pk_fma_f32 v[20:21], v[20:21], v[4:5], v[22:23]
	v_cvt_scalef32_pk_f32_fp4 v[22:23], v70, 1.0 op_sel:[0,1,0]
	v_pk_fma_f32 v[20:21], v[22:23], v[8:9], v[20:21]
	v_cvt_scalef32_pk_f32_fp4 v[22:23], v70, 1.0 op_sel:[1,1,0]
	v_pk_fma_f32 v[20:21], v[22:23], v[10:11], v[20:21]
	v_cvt_scalef32_pk_f32_fp4 v[22:23], v71, 1.0
	v_pk_fma_f32 v[20:21], v[22:23], v[12:13], v[20:21]
	v_cvt_scalef32_pk_f32_fp4 v[22:23], v71, 1.0 op_sel:[1,0,0]
	v_pk_fma_f32 v[20:21], v[22:23], v[14:15], v[20:21]
	v_cvt_scalef32_pk_f32_fp4 v[22:23], v71, 1.0 op_sel:[0,1,0]
	v_pk_fma_f32 v[20:21], v[22:23], v[16:17], v[20:21]
	v_cvt_scalef32_pk_f32_fp4 v[22:23], v71, 1.0 op_sel:[1,1,0]
	v_pk_fma_f32 v[20:21], v[22:23], v[18:19], v[20:21]
	v_cndmask_b32_e64 v22, v74, v30, s[0:1]
	v_add_f32_e32 v20, v20, v21
	v_cndmask_b32_e64 v21, v30, v74, s[0:1]
	v_cndmask_b32_e64 v23, v72, v31, s[0:1]
	s_nop 0
	v_add_f32_dpp v21, v22, v21 quad_perm:[1,0,3,2] row_mask:0xf bank_mask:0xf bound_ctrl:1
	v_cndmask_b32_e64 v22, v31, v72, s[0:1]
	s_nop 1
	v_add_f32_dpp v22, v23, v22 quad_perm:[1,0,3,2] row_mask:0xf bank_mask:0xf bound_ctrl:1
	v_cndmask_b32_e64 v23, v32, v24, s[0:1]
	v_cndmask_b32_e64 v24, v24, v32, s[0:1]
	s_nop 1
	v_add_f32_dpp v23, v24, v23 quad_perm:[1,0,3,2] row_mask:0xf bank_mask:0xf bound_ctrl:1
	v_cndmask_b32_e64 v24, v33, v25, s[0:1]
	v_cndmask_b32_e64 v25, v25, v33, s[0:1]
	s_nop 1
	v_add_f32_dpp v24, v25, v24 quad_perm:[1,0,3,2] row_mask:0xf bank_mask:0xf bound_ctrl:1
	v_cndmask_b32_e64 v25, v34, v26, s[0:1]
	v_cndmask_b32_e64 v26, v26, v34, s[0:1]
	s_nop 1
	v_add_f32_dpp v25, v26, v25 quad_perm:[1,0,3,2] row_mask:0xf bank_mask:0xf bound_ctrl:1
	v_cndmask_b32_e64 v26, v35, v27, s[0:1]
	v_cndmask_b32_e64 v27, v27, v35, s[0:1]
	s_nop 1
	v_add_f32_dpp v26, v27, v26 quad_perm:[1,0,3,2] row_mask:0xf bank_mask:0xf bound_ctrl:1
	v_cndmask_b32_e64 v27, v56, v28, s[0:1]
	v_cndmask_b32_e64 v28, v28, v56, s[0:1]
	s_nop 1
	v_add_f32_dpp v27, v28, v27 quad_perm:[1,0,3,2] row_mask:0xf bank_mask:0xf bound_ctrl:1
	v_cndmask_b32_e64 v28, v20, v29, s[0:1]
	v_cndmask_b32_e64 v20, v29, v20, s[0:1]
	s_nop 1
	v_add_f32_dpp v20, v20, v28 quad_perm:[1,0,3,2] row_mask:0xf bank_mask:0xf bound_ctrl:1
	v_cndmask_b32_e64 v28, v25, v21, s[4:5]
	v_cndmask_b32_e64 v21, v21, v25, s[4:5]
	v_cndmask_b32_e64 v25, v26, v22, s[4:5]
	v_cndmask_b32_e64 v22, v22, v26, s[4:5]
	v_add_f32_dpp v21, v21, v28 quad_perm:[2,3,0,1] row_mask:0xf bank_mask:0xf bound_ctrl:1
	s_nop 0
	v_add_f32_dpp v22, v22, v25 quad_perm:[2,3,0,1] row_mask:0xf bank_mask:0xf bound_ctrl:1
	v_cndmask_b32_e64 v25, v27, v23, s[4:5]
	v_cndmask_b32_e64 v23, v23, v27, s[4:5]
	s_nop 1
	v_add_f32_dpp v23, v23, v25 quad_perm:[2,3,0,1] row_mask:0xf bank_mask:0xf bound_ctrl:1
	v_cndmask_b32_e64 v25, v20, v24, s[4:5]
	v_cndmask_b32_e64 v20, v24, v20, s[4:5]
	v_cndmask_b32_e64 v24, v23, v21, s[6:7]
	v_cndmask_b32_e64 v21, v21, v23, s[6:7]
	v_add_f32_dpp v20, v20, v25 quad_perm:[2,3,0,1] row_mask:0xf bank_mask:0xf bound_ctrl:1
	v_cndmask_b32_e64 v23, v20, v22, s[6:7]
	v_cndmask_b32_e64 v20, v22, v20, s[6:7]
	v_mov_b32_dpp v21, v21 row_half_mirror row_mask:0xf bank_mask:0xf bound_ctrl:1
	s_nop 0
	v_mov_b32_dpp v20, v20 row_half_mirror row_mask:0xf bank_mask:0xf bound_ctrl:1
	v_add_f32_dpp v21, v21, v24 quad_perm:[3,2,1,0] row_mask:0xf bank_mask:0xf bound_ctrl:1
	s_nop 0
	v_add_f32_dpp v20, v20, v23 quad_perm:[3,2,1,0] row_mask:0xf bank_mask:0xf bound_ctrl:1
	v_cndmask_b32_e64 v22, v20, v21, s[8:9]
	v_cndmask_b32_e64 v20, v21, v20, s[8:9]
	s_nop 1
	v_mov_b32_dpp v20, v20 row_mirror row_mask:0xf bank_mask:0xf bound_ctrl:1
	s_nop 1
	v_add_f32_dpp v20, v20, v22 row_half_mirror row_mask:0xf bank_mask:0xf bound_ctrl:1
	ds_bpermute_b32 v21, v125, v20
	s_waitcnt lgkmcnt(0)
	v_add_f32_e32 v20, v20, v21
	ds_bpermute_b32 v21, v126, v20
	s_waitcnt lgkmcnt(0)
	v_add_f32_e32 v20, v20, v21
	v_or_b32_e32 v21, 1, v76
	v_cmp_eq_u32_e64 s[14:15], v106, v21
	v_cndmask_b32_e64 v21, v20, v77, s[12:13]
	s_and_b64 s[12:13], s[14:15], s[12:13]
	v_cndmask_b32_e64 v129, v78, v20, s[12:13]
	v_cmp_ge_u32_e64 s[12:13], v127, v115
	v_cndmask_b32_e64 v128, v77, v21, s[14:15]
	s_or_b64 s[28:29], s[12:13], s[28:29]

.LBB0_2112:
	v_cmp_gt_u32_e32 vcc, 64, v116
	s_nop 1
	v_cndmask_b32_e32 v102, v118, v117, vcc
	v_readfirstlane_b32 s92, v116
	v_readfirstlane_b32 s93, v40
	v_readfirstlane_b32 s94, v41
	s_nop 1
	v_subrev_u32_e32 v255, s93, v40
	s_nop 1
	s_and_b32 s92, s92, 32
	s_cbranch_scc1 .Lh3_v10_hi
	v_readlane_b32 s84, v102, 0
	v_readlane_b32 s86, v102, 1
	v_readlane_b32 s88, v102, 2
	v_readlane_b32 s90, v102, 3
	s_lshl_b32 s84, s84, 9
	s_lshl_b32 s86, s86, 9
	s_lshl_b32 s88, s88, 9
	s_lshl_b32 s90, s90, 9
	s_add_u32 s84, s93, s84
	s_addc_u32 s85, s94, 0
	s_add_u32 s86, s93, s86
	s_addc_u32 s87, s94, 0
	s_add_u32 s88, s93, s88
	s_addc_u32 s89, s94, 0
	s_add_u32 s90, s93, s90
	s_addc_u32 s91, s94, 0
	global_load_dwordx2 v[20:21], v255, s[84:85]
	global_load_dwordx2 v[22:23], v255, s[86:87]
	global_load_dwordx2 v[24:25], v255, s[88:89]
	global_load_dwordx2 v[26:27], v255, s[90:91]
	v_readlane_b32 s84, v102, 4
	v_readlane_b32 s86, v102, 5
	v_readlane_b32 s88, v102, 6
	v_readlane_b32 s90, v102, 7
	s_lshl_b32 s84, s84, 9
	s_lshl_b32 s86, s86, 9
	s_lshl_b32 s88, s88, 9
	s_lshl_b32 s90, s90, 9
	s_add_u32 s84, s93, s84
	s_addc_u32 s85, s94, 0
	s_add_u32 s86, s93, s86
	s_addc_u32 s87, s94, 0
	s_add_u32 s88, s93, s88
	s_addc_u32 s89, s94, 0
	s_add_u32 s90, s93, s90
	s_addc_u32 s91, s94, 0
	global_load_dwordx2 v[28:29], v255, s[84:85]
	global_load_dwordx2 v[30:31], v255, s[86:87]
	global_load_dwordx2 v[32:33], v255, s[88:89]
	global_load_dwordx2 v[34:35], v255, s[90:91]
	v_readlane_b32 s84, v102, 8
	v_readlane_b32 s86, v102, 9
	v_readlane_b32 s88, v102, 10
	v_readlane_b32 s90, v102, 11
	s_lshl_b32 s84, s84, 9
	s_lshl_b32 s86, s86, 9
	s_lshl_b32 s88, s88, 9
	s_lshl_b32 s90, s90, 9
	s_add_u32 s84, s93, s84
	s_addc_u32 s85, s94, 0
	s_add_u32 s86, s93, s86
	s_addc_u32 s87, s94, 0
	s_add_u32 s88, s93, s88
	s_addc_u32 s89, s94, 0
	s_add_u32 s90, s93, s90
	s_addc_u32 s91, s94, 0
	global_load_dwordx2 v[56:57], v255, s[84:85]
	global_load_dwordx2 v[58:59], v255, s[86:87]
	global_load_dwordx2 v[60:61], v255, s[88:89]
	global_load_dwordx2 v[62:63], v255, s[90:91]
	v_readlane_b32 s84, v102, 12
	v_readlane_b32 s86, v102, 13
	v_readlane_b32 s88, v102, 14
	v_readlane_b32 s90, v102, 15
	s_lshl_b32 s84, s84, 9
	s_lshl_b32 s86, s86, 9
	s_lshl_b32 s88, s88, 9
	s_lshl_b32 s90, s90, 9
	s_add_u32 s84, s93, s84
	s_addc_u32 s85, s94, 0
	s_add_u32 s86, s93, s86
	s_addc_u32 s87, s94, 0
	s_add_u32 s88, s93, s88
	s_addc_u32 s89, s94, 0
	s_add_u32 s90, s93, s90
	s_addc_u32 s91, s94, 0
	global_load_dwordx2 v[64:65], v255, s[84:85]
	global_load_dwordx2 v[66:67], v255, s[86:87]
	global_load_dwordx2 v[68:69], v255, s[88:89]
	global_load_dwordx2 v[70:71], v255, s[90:91]
	v_readlane_b32 s84, v102, 16
	v_readlane_b32 s86, v102, 17
	v_readlane_b32 s88, v102, 18
	v_readlane_b32 s90, v102, 19
	s_lshl_b32 s84, s84, 9
	s_lshl_b32 s86, s86, 9
	s_lshl_b32 s88, s88, 9
	s_lshl_b32 s90, s90, 9
	s_add_u32 s84, s93, s84
	s_addc_u32 s85, s94, 0
	s_add_u32 s86, s93, s86
	s_addc_u32 s87, s94, 0
	s_add_u32 s88, s93, s88
	s_addc_u32 s89, s94, 0
	s_add_u32 s90, s93, s90
	s_addc_u32 s91, s94, 0
	global_load_dwordx2 v[72:73], v255, s[84:85]
	global_load_dwordx2 v[74:75], v255, s[86:87]
	global_load_dwordx2 v[76:77], v255, s[88:89]
	global_load_dwordx2 v[78:79], v255, s[90:91]
	v_readlane_b32 s84, v102, 20
	v_readlane_b32 s86, v102, 21
	v_readlane_b32 s88, v102, 22
	v_readlane_b32 s90, v102, 23
	s_lshl_b32 s84, s84, 9
	s_lshl_b32 s86, s86, 9
	s_lshl_b32 s88, s88, 9
	s_lshl_b32 s90, s90, 9
	s_add_u32 s84, s93, s84
	s_addc_u32 s85, s94, 0
	s_add_u32 s86, s93, s86
	s_addc_u32 s87, s94, 0
	s_add_u32 s88, s93, s88
	s_addc_u32 s89, s94, 0
	s_add_u32 s90, s93, s90
	s_addc_u32 s91, s94, 0
	global_load_dwordx2 v[80:81], v255, s[84:85]
	global_load_dwordx2 v[82:83], v255, s[86:87]
	global_load_dwordx2 v[84:85], v255, s[88:89]
	global_load_dwordx2 v[86:87], v255, s[90:91]
	v_readlane_b32 s84, v102, 24
	v_readlane_b32 s86, v102, 25
	v_readlane_b32 s88, v102, 26
	v_readlane_b32 s90, v102, 27
	s_lshl_b32 s84, s84, 9
	s_lshl_b32 s86, s86, 9
	s_lshl_b32 s88, s88, 9
	s_lshl_b32 s90, s90, 9
	s_add_u32 s84, s93, s84
	s_addc_u32 s85, s94, 0
	s_add_u32 s86, s93, s86
	s_addc_u32 s87, s94, 0
	s_add_u32 s88, s93, s88
	s_addc_u32 s89, s94, 0
	s_add_u32 s90, s93, s90
	s_addc_u32 s91, s94, 0
	global_load_dwordx2 v[88:89], v255, s[84:85]
	global_load_dwordx2 v[90:91], v255, s[86:87]
	global_load_dwordx2 v[92:93], v255, s[88:89]
	global_load_dwordx2 v[94:95], v255, s[90:91]
	v_readlane_b32 s84, v102, 28
	v_readlane_b32 s86, v102, 29
	v_readlane_b32 s88, v102, 30
	v_readlane_b32 s90, v102, 31
	s_lshl_b32 s84, s84, 9
	s_lshl_b32 s86, s86, 9
	s_lshl_b32 s88, s88, 9
	s_lshl_b32 s90, s90, 9
	s_add_u32 s84, s93, s84
	s_addc_u32 s85, s94, 0
	s_add_u32 s86, s93, s86
	s_addc_u32 s87, s94, 0
	s_add_u32 s88, s93, s88
	s_addc_u32 s89, s94, 0
	s_add_u32 s90, s93, s90
	s_addc_u32 s91, s94, 0
	global_load_dwordx2 v[96:97], v255, s[84:85]
	global_load_dwordx2 v[98:99], v255, s[86:87]
	global_load_dwordx2 v[100:101], v255, s[88:89]
	global_load_dwordx2 v[102:103], v255, s[90:91]
	v_cndmask_b32_e32 v127, v3, v119, vcc
	s_waitcnt vmcnt(31)
	v_cvt_scalef32_pk_f32_fp4 v[130:131], v20, 1.0
	v_readlane_b32 s28, v127, 2
	v_readlane_b32 s2, v127, 3
	v_add_u32_e32 v116, 32, v116
	v_cmp_ge_u32_e32 vcc, v116, v115
	s_nop 0
	s_nop 0
	s_nop 0
	v_readlane_b32 s64, v127, 0
	s_or_b64 s[14:15], vcc, s[14:15]
	s_nop 0
	v_pk_fma_f32 v[4:5], v[130:131], s[64:65], v[4:5] op_sel_hi:[1,0,1]
	v_cvt_scalef32_pk_f32_fp4 v[130:131], v20, 1.0 op_sel:[1,0,0]
	v_pk_fma_f32 v[6:7], s[64:65], v[130:131], v[6:7] op_sel_hi:[0,1,1]
	v_cvt_scalef32_pk_f32_fp4 v[130:131], v20, 1.0 op_sel:[0,1,0]
	v_pk_fma_f32 v[8:9], s[64:65], v[130:131], v[8:9] op_sel_hi:[0,1,1]
	v_cvt_scalef32_pk_f32_fp4 v[130:131], v20, 1.0 op_sel:[1,1,0]
	v_pk_fma_f32 v[10:11], s[64:65], v[130:131], v[10:11] op_sel_hi:[0,1,1]
	v_cvt_scalef32_pk_f32_fp4 v[130:131], v21, 1.0
	v_pk_fma_f32 v[12:13], s[64:65], v[130:131], v[12:13] op_sel_hi:[0,1,1]
	v_cvt_scalef32_pk_f32_fp4 v[130:131], v21, 1.0 op_sel:[1,0,0]
	v_pk_fma_f32 v[14:15], s[64:65], v[130:131], v[14:15] op_sel_hi:[0,1,1]
	v_cvt_scalef32_pk_f32_fp4 v[130:131], v21, 1.0 op_sel:[0,1,0]
	v_cvt_scalef32_pk_f32_fp4 v[20:21], v21, 1.0 op_sel:[1,1,0]
	v_pk_fma_f32 v[16:17], s[64:65], v[130:131], v[16:17] op_sel_hi:[0,1,1]
	v_pk_fma_f32 v[18:19], s[64:65], v[20:21], v[18:19] op_sel_hi:[0,1,1]
	v_readlane_b32 s64, v127, 8
	s_waitcnt vmcnt(30)
	v_cvt_scalef32_pk_f32_fp4 v[20:21], v22, 1.0
	v_pk_fma_f32 v[4:5], v[20:21], s[64:65], v[4:5] op_sel_hi:[1,0,1]
	v_cvt_scalef32_pk_f32_fp4 v[20:21], v22, 1.0 op_sel:[1,0,0]
	v_pk_fma_f32 v[6:7], s[64:65], v[20:21], v[6:7] op_sel_hi:[0,1,1]
	v_cvt_scalef32_pk_f32_fp4 v[20:21], v22, 1.0 op_sel:[0,1,0]
	v_pk_fma_f32 v[8:9], s[64:65], v[20:21], v[8:9] op_sel_hi:[0,1,1]
	v_cvt_scalef32_pk_f32_fp4 v[20:21], v22, 1.0 op_sel:[1,1,0]
	v_pk_fma_f32 v[10:11], s[64:65], v[20:21], v[10:11] op_sel_hi:[0,1,1]
	v_cvt_scalef32_pk_f32_fp4 v[20:21], v23, 1.0
	v_pk_fma_f32 v[12:13], s[64:65], v[20:21], v[12:13] op_sel_hi:[0,1,1]
	v_cvt_scalef32_pk_f32_fp4 v[20:21], v23, 1.0 op_sel:[1,0,0]
	v_pk_fma_f32 v[14:15], s[64:65], v[20:21], v[14:15] op_sel_hi:[0,1,1]
	v_cvt_scalef32_pk_f32_fp4 v[20:21], v23, 1.0 op_sel:[0,1,0]
	v_pk_fma_f32 v[16:17], s[64:65], v[20:21], v[16:17] op_sel_hi:[0,1,1]
	v_cvt_scalef32_pk_f32_fp4 v[20:21], v23, 1.0 op_sel:[1,1,0]
	v_pk_fma_f32 v[18:19], s[64:65], v[20:21], v[18:19] op_sel_hi:[0,1,1]
	v_readlane_b32 s64, v127, 4
	s_waitcnt vmcnt(29)
	v_cvt_scalef32_pk_f32_fp4 v[20:21], v24, 1.0
	v_pk_fma_f32 v[4:5], v[20:21], s[64:65], v[4:5] op_sel_hi:[1,0,1]
	v_cvt_scalef32_pk_f32_fp4 v[20:21], v24, 1.0 op_sel:[1,0,0]
	v_pk_fma_f32 v[6:7], s[64:65], v[20:21], v[6:7] op_sel_hi:[0,1,1]
	v_cvt_scalef32_pk_f32_fp4 v[20:21], v24, 1.0 op_sel:[0,1,0]
	v_pk_fma_f32 v[8:9], s[64:65], v[20:21], v[8:9] op_sel_hi:[0,1,1]
	v_cvt_scalef32_pk_f32_fp4 v[20:21], v24, 1.0 op_sel:[1,1,0]
	v_pk_fma_f32 v[10:11], s[64:65], v[20:21], v[10:11] op_sel_hi:[0,1,1]
	v_cvt_scalef32_pk_f32_fp4 v[20:21], v25, 1.0
	v_pk_fma_f32 v[12:13], s[64:65], v[20:21], v[12:13] op_sel_hi:[0,1,1]
	v_cvt_scalef32_pk_f32_fp4 v[20:21], v25, 1.0 op_sel:[1,0,0]
	v_pk_fma_f32 v[14:15], s[64:65], v[20:21], v[14:15] op_sel_hi:[0,1,1]
	v_cvt_scalef32_pk_f32_fp4 v[20:21], v25, 1.0 op_sel:[0,1,0]
	v_pk_fma_f32 v[16:17], s[64:65], v[20:21], v[16:17] op_sel_hi:[0,1,1]
	v_cvt_scalef32_pk_f32_fp4 v[20:21], v25, 1.0 op_sel:[1,1,0]
	v_pk_fma_f32 v[18:19], s[64:65], v[20:21], v[18:19] op_sel_hi:[0,1,1]
	v_readlane_b32 s64, v127, 12
	s_waitcnt vmcnt(28)
	v_cvt_scalef32_pk_f32_fp4 v[20:21], v26, 1.0
	v_pk_fma_f32 v[4:5], v[20:21], s[64:65], v[4:5] op_sel_hi:[1,0,1]
	v_cvt_scalef32_pk_f32_fp4 v[20:21], v26, 1.0 op_sel:[1,0,0]
	v_pk_fma_f32 v[6:7], s[64:65], v[20:21], v[6:7] op_sel_hi:[0,1,1]
	v_cvt_scalef32_pk_f32_fp4 v[20:21], v26, 1.0 op_sel:[0,1,0]
	v_pk_fma_f32 v[8:9], s[64:65], v[20:21], v[8:9] op_sel_hi:[0,1,1]
	v_cvt_scalef32_pk_f32_fp4 v[20:21], v26, 1.0 op_sel:[1,1,0]
	v_pk_fma_f32 v[10:11], s[64:65], v[20:21], v[10:11] op_sel_hi:[0,1,1]
	v_cvt_scalef32_pk_f32_fp4 v[20:21], v27, 1.0
	v_pk_fma_f32 v[12:13], s[64:65], v[20:21], v[12:13] op_sel_hi:[0,1,1]
	v_cvt_scalef32_pk_f32_fp4 v[20:21], v27, 1.0 op_sel:[1,0,0]
	v_pk_fma_f32 v[14:15], s[64:65], v[20:21], v[14:15] op_sel_hi:[0,1,1]
	v_cvt_scalef32_pk_f32_fp4 v[20:21], v27, 1.0 op_sel:[0,1,0]
	v_pk_fma_f32 v[16:17], s[64:65], v[20:21], v[16:17] op_sel_hi:[0,1,1]
	v_cvt_scalef32_pk_f32_fp4 v[20:21], v27, 1.0 op_sel:[1,1,0]
	v_pk_fma_f32 v[18:19], s[64:65], v[20:21], v[18:19] op_sel_hi:[0,1,1]
	s_waitcnt vmcnt(27)
	v_cvt_scalef32_pk_f32_fp4 v[20:21], v28, 1.0
	v_pk_fma_f32 v[4:5], v[20:21], s[28:29], v[4:5] op_sel_hi:[1,0,1]
	v_cvt_scalef32_pk_f32_fp4 v[20:21], v28, 1.0 op_sel:[1,0,0]
	v_pk_fma_f32 v[6:7], s[28:29], v[20:21], v[6:7] op_sel_hi:[0,1,1]
	v_cvt_scalef32_pk_f32_fp4 v[20:21], v28, 1.0 op_sel:[0,1,0]
	v_pk_fma_f32 v[8:9], s[28:29], v[20:21], v[8:9] op_sel_hi:[0,1,1]
	v_cvt_scalef32_pk_f32_fp4 v[20:21], v28, 1.0 op_sel:[1,1,0]
	v_pk_fma_f32 v[10:11], s[28:29], v[20:21], v[10:11] op_sel_hi:[0,1,1]
	v_cvt_scalef32_pk_f32_fp4 v[20:21], v29, 1.0
	v_pk_fma_f32 v[12:13], s[28:29], v[20:21], v[12:13] op_sel_hi:[0,1,1]
	v_cvt_scalef32_pk_f32_fp4 v[20:21], v29, 1.0 op_sel:[1,0,0]
	v_pk_fma_f32 v[14:15], s[28:29], v[20:21], v[14:15] op_sel_hi:[0,1,1]
	v_cvt_scalef32_pk_f32_fp4 v[20:21], v29, 1.0 op_sel:[0,1,0]
	v_pk_fma_f32 v[16:17], s[28:29], v[20:21], v[16:17] op_sel_hi:[0,1,1]
	v_cvt_scalef32_pk_f32_fp4 v[20:21], v29, 1.0 op_sel:[1,1,0]
	v_pk_fma_f32 v[18:19], s[28:29], v[20:21], v[18:19] op_sel_hi:[0,1,1]
	v_readlane_b32 s28, v127, 10
	s_waitcnt vmcnt(26)
	v_cvt_scalef32_pk_f32_fp4 v[20:21], v30, 1.0
	v_pk_fma_f32 v[4:5], v[20:21], s[28:29], v[4:5] op_sel_hi:[1,0,1]
	v_cvt_scalef32_pk_f32_fp4 v[20:21], v30, 1.0 op_sel:[1,0,0]
	v_pk_fma_f32 v[6:7], s[28:29], v[20:21], v[6:7] op_sel_hi:[0,1,1]
	v_cvt_scalef32_pk_f32_fp4 v[20:21], v30, 1.0 op_sel:[0,1,0]
	v_pk_fma_f32 v[8:9], s[28:29], v[20:21], v[8:9] op_sel_hi:[0,1,1]
	v_cvt_scalef32_pk_f32_fp4 v[20:21], v30, 1.0 op_sel:[1,1,0]
	v_pk_fma_f32 v[10:11], s[28:29], v[20:21], v[10:11] op_sel_hi:[0,1,1]
	v_cvt_scalef32_pk_f32_fp4 v[20:21], v31, 1.0
	v_pk_fma_f32 v[12:13], s[28:29], v[20:21], v[12:13] op_sel_hi:[0,1,1]
	v_cvt_scalef32_pk_f32_fp4 v[20:21], v31, 1.0 op_sel:[1,0,0]
	v_pk_fma_f32 v[14:15], s[28:29], v[20:21], v[14:15] op_sel_hi:[0,1,1]
	v_cvt_scalef32_pk_f32_fp4 v[20:21], v31, 1.0 op_sel:[0,1,0]
	v_pk_fma_f32 v[16:17], s[28:29], v[20:21], v[16:17] op_sel_hi:[0,1,1]
	v_cvt_scalef32_pk_f32_fp4 v[20:21], v31, 1.0 op_sel:[1,1,0]
	v_pk_fma_f32 v[18:19], s[28:29], v[20:21], v[18:19] op_sel_hi:[0,1,1]
	v_readlane_b32 s28, v127, 6
	s_waitcnt vmcnt(25)
	v_cvt_scalef32_pk_f32_fp4 v[20:21], v32, 1.0
	v_pk_fma_f32 v[4:5], v[20:21], s[28:29], v[4:5] op_sel_hi:[1,0,1]
	v_cvt_scalef32_pk_f32_fp4 v[20:21], v32, 1.0 op_sel:[1,0,0]
	v_pk_fma_f32 v[6:7], s[28:29], v[20:21], v[6:7] op_sel_hi:[0,1,1]
	v_cvt_scalef32_pk_f32_fp4 v[20:21], v32, 1.0 op_sel:[0,1,0]
	v_pk_fma_f32 v[8:9], s[28:29], v[20:21], v[8:9] op_sel_hi:[0,1,1]
	v_cvt_scalef32_pk_f32_fp4 v[20:21], v32, 1.0 op_sel:[1,1,0]
	v_pk_fma_f32 v[10:11], s[28:29], v[20:21], v[10:11] op_sel_hi:[0,1,1]
	v_cvt_scalef32_pk_f32_fp4 v[20:21], v33, 1.0
	v_pk_fma_f32 v[12:13], s[28:29], v[20:21], v[12:13] op_sel_hi:[0,1,1]
	v_cvt_scalef32_pk_f32_fp4 v[20:21], v33, 1.0 op_sel:[1,0,0]
	v_pk_fma_f32 v[14:15], s[28:29], v[20:21], v[14:15] op_sel_hi:[0,1,1]
	v_cvt_scalef32_pk_f32_fp4 v[20:21], v33, 1.0 op_sel:[0,1,0]
	v_pk_fma_f32 v[16:17], s[28:29], v[20:21], v[16:17] op_sel_hi:[0,1,1]
	v_cvt_scalef32_pk_f32_fp4 v[20:21], v33, 1.0 op_sel:[1,1,0]
	v_pk_fma_f32 v[18:19], s[28:29], v[20:21], v[18:19] op_sel_hi:[0,1,1]
	v_readlane_b32 s28, v127, 14
	s_waitcnt vmcnt(24)
	v_cvt_scalef32_pk_f32_fp4 v[20:21], v34, 1.0
	v_pk_fma_f32 v[4:5], v[20:21], s[28:29], v[4:5] op_sel_hi:[1,0,1]
	v_cvt_scalef32_pk_f32_fp4 v[20:21], v34, 1.0 op_sel:[1,0,0]
	v_pk_fma_f32 v[6:7], s[28:29], v[20:21], v[6:7] op_sel_hi:[0,1,1]
	v_cvt_scalef32_pk_f32_fp4 v[20:21], v34, 1.0 op_sel:[0,1,0]
	v_pk_fma_f32 v[8:9], s[28:29], v[20:21], v[8:9] op_sel_hi:[0,1,1]
	v_cvt_scalef32_pk_f32_fp4 v[20:21], v34, 1.0 op_sel:[1,1,0]
	v_pk_fma_f32 v[10:11], s[28:29], v[20:21], v[10:11] op_sel_hi:[0,1,1]
	v_cvt_scalef32_pk_f32_fp4 v[20:21], v35, 1.0
	v_pk_fma_f32 v[12:13], s[28:29], v[20:21], v[12:13] op_sel_hi:[0,1,1]
	v_cvt_scalef32_pk_f32_fp4 v[20:21], v35, 1.0 op_sel:[1,0,0]
	v_pk_fma_f32 v[14:15], s[28:29], v[20:21], v[14:15] op_sel_hi:[0,1,1]
	v_cvt_scalef32_pk_f32_fp4 v[20:21], v35, 1.0 op_sel:[0,1,0]
	v_pk_fma_f32 v[16:17], s[28:29], v[20:21], v[16:17] op_sel_hi:[0,1,1]
	v_cvt_scalef32_pk_f32_fp4 v[20:21], v35, 1.0 op_sel:[1,1,0]
	v_pk_fma_f32 v[18:19], s[28:29], v[20:21], v[18:19] op_sel_hi:[0,1,1]
	v_readlane_b32 s28, v127, 1
	s_waitcnt vmcnt(23)
	v_cvt_scalef32_pk_f32_fp4 v[20:21], v56, 1.0
	v_pk_fma_f32 v[4:5], v[20:21], s[28:29], v[4:5] op_sel_hi:[1,0,1]
	v_cvt_scalef32_pk_f32_fp4 v[20:21], v56, 1.0 op_sel:[1,0,0]
	v_pk_fma_f32 v[6:7], s[28:29], v[20:21], v[6:7] op_sel_hi:[0,1,1]
	v_cvt_scalef32_pk_f32_fp4 v[20:21], v56, 1.0 op_sel:[0,1,0]
	v_pk_fma_f32 v[8:9], s[28:29], v[20:21], v[8:9] op_sel_hi:[0,1,1]
	v_cvt_scalef32_pk_f32_fp4 v[20:21], v56, 1.0 op_sel:[1,1,0]
	v_pk_fma_f32 v[10:11], s[28:29], v[20:21], v[10:11] op_sel_hi:[0,1,1]
	v_cvt_scalef32_pk_f32_fp4 v[20:21], v57, 1.0
	v_pk_fma_f32 v[12:13], s[28:29], v[20:21], v[12:13] op_sel_hi:[0,1,1]
	v_cvt_scalef32_pk_f32_fp4 v[20:21], v57, 1.0 op_sel:[1,0,0]
	v_pk_fma_f32 v[14:15], s[28:29], v[20:21], v[14:15] op_sel_hi:[0,1,1]
	v_cvt_scalef32_pk_f32_fp4 v[20:21], v57, 1.0 op_sel:[0,1,0]
	v_pk_fma_f32 v[16:17], s[28:29], v[20:21], v[16:17] op_sel_hi:[0,1,1]
	v_cvt_scalef32_pk_f32_fp4 v[20:21], v57, 1.0 op_sel:[1,1,0]
	v_pk_fma_f32 v[18:19], s[28:29], v[20:21], v[18:19] op_sel_hi:[0,1,1]
	v_readlane_b32 s28, v127, 9
	s_waitcnt vmcnt(22)
	v_cvt_scalef32_pk_f32_fp4 v[20:21], v58, 1.0
	v_pk_fma_f32 v[4:5], v[20:21], s[28:29], v[4:5] op_sel_hi:[1,0,1]
	v_cvt_scalef32_pk_f32_fp4 v[20:21], v58, 1.0 op_sel:[1,0,0]
	v_pk_fma_f32 v[6:7], s[28:29], v[20:21], v[6:7] op_sel_hi:[0,1,1]
	v_cvt_scalef32_pk_f32_fp4 v[20:21], v58, 1.0 op_sel:[0,1,0]
	v_pk_fma_f32 v[8:9], s[28:29], v[20:21], v[8:9] op_sel_hi:[0,1,1]
	v_cvt_scalef32_pk_f32_fp4 v[20:21], v58, 1.0 op_sel:[1,1,0]
	v_pk_fma_f32 v[10:11], s[28:29], v[20:21], v[10:11] op_sel_hi:[0,1,1]
	v_cvt_scalef32_pk_f32_fp4 v[20:21], v59, 1.0
	v_pk_fma_f32 v[12:13], s[28:29], v[20:21], v[12:13] op_sel_hi:[0,1,1]
	v_cvt_scalef32_pk_f32_fp4 v[20:21], v59, 1.0 op_sel:[1,0,0]
	v_pk_fma_f32 v[14:15], s[28:29], v[20:21], v[14:15] op_sel_hi:[0,1,1]
	v_cvt_scalef32_pk_f32_fp4 v[20:21], v59, 1.0 op_sel:[0,1,0]
	v_pk_fma_f32 v[16:17], s[28:29], v[20:21], v[16:17] op_sel_hi:[0,1,1]
	v_cvt_scalef32_pk_f32_fp4 v[20:21], v59, 1.0 op_sel:[1,1,0]
	v_pk_fma_f32 v[18:19], s[28:29], v[20:21], v[18:19] op_sel_hi:[0,1,1]
	v_readlane_b32 s28, v127, 5
	s_waitcnt vmcnt(21)
	v_cvt_scalef32_pk_f32_fp4 v[20:21], v60, 1.0
	v_pk_fma_f32 v[4:5], v[20:21], s[28:29], v[4:5] op_sel_hi:[1,0,1]
	v_cvt_scalef32_pk_f32_fp4 v[20:21], v60, 1.0 op_sel:[1,0,0]
	v_pk_fma_f32 v[6:7], s[28:29], v[20:21], v[6:7] op_sel_hi:[0,1,1]
	v_cvt_scalef32_pk_f32_fp4 v[20:21], v60, 1.0 op_sel:[0,1,0]
	v_pk_fma_f32 v[8:9], s[28:29], v[20:21], v[8:9] op_sel_hi:[0,1,1]
	v_cvt_scalef32_pk_f32_fp4 v[20:21], v60, 1.0 op_sel:[1,1,0]
	v_pk_fma_f32 v[10:11], s[28:29], v[20:21], v[10:11] op_sel_hi:[0,1,1]
	v_cvt_scalef32_pk_f32_fp4 v[20:21], v61, 1.0
	v_pk_fma_f32 v[12:13], s[28:29], v[20:21], v[12:13] op_sel_hi:[0,1,1]
	v_cvt_scalef32_pk_f32_fp4 v[20:21], v61, 1.0 op_sel:[1,0,0]
	v_pk_fma_f32 v[14:15], s[28:29], v[20:21], v[14:15] op_sel_hi:[0,1,1]
	v_cvt_scalef32_pk_f32_fp4 v[20:21], v61, 1.0 op_sel:[0,1,0]
	v_pk_fma_f32 v[16:17], s[28:29], v[20:21], v[16:17] op_sel_hi:[0,1,1]
	v_cvt_scalef32_pk_f32_fp4 v[20:21], v61, 1.0 op_sel:[1,1,0]
	v_pk_fma_f32 v[18:19], s[28:29], v[20:21], v[18:19] op_sel_hi:[0,1,1]
	v_readlane_b32 s28, v127, 13
	s_waitcnt vmcnt(20)
	v_cvt_scalef32_pk_f32_fp4 v[20:21], v62, 1.0
	v_pk_fma_f32 v[4:5], v[20:21], s[28:29], v[4:5] op_sel_hi:[1,0,1]
	v_cvt_scalef32_pk_f32_fp4 v[20:21], v62, 1.0 op_sel:[1,0,0]
	v_pk_fma_f32 v[6:7], s[28:29], v[20:21], v[6:7] op_sel_hi:[0,1,1]
	v_cvt_scalef32_pk_f32_fp4 v[20:21], v62, 1.0 op_sel:[0,1,0]
	v_pk_fma_f32 v[8:9], s[28:29], v[20:21], v[8:9] op_sel_hi:[0,1,1]
	v_cvt_scalef32_pk_f32_fp4 v[20:21], v62, 1.0 op_sel:[1,1,0]
	v_pk_fma_f32 v[10:11], s[28:29], v[20:21], v[10:11] op_sel_hi:[0,1,1]
	v_cvt_scalef32_pk_f32_fp4 v[20:21], v63, 1.0
	v_pk_fma_f32 v[12:13], s[28:29], v[20:21], v[12:13] op_sel_hi:[0,1,1]
	v_cvt_scalef32_pk_f32_fp4 v[20:21], v63, 1.0 op_sel:[1,0,0]
	v_pk_fma_f32 v[14:15], s[28:29], v[20:21], v[14:15] op_sel_hi:[0,1,1]
	v_cvt_scalef32_pk_f32_fp4 v[20:21], v63, 1.0 op_sel:[0,1,0]
	v_pk_fma_f32 v[16:17], s[28:29], v[20:21], v[16:17] op_sel_hi:[0,1,1]
	v_cvt_scalef32_pk_f32_fp4 v[20:21], v63, 1.0 op_sel:[1,1,0]
	v_pk_fma_f32 v[18:19], s[28:29], v[20:21], v[18:19] op_sel_hi:[0,1,1]
	s_waitcnt vmcnt(19)
	v_cvt_scalef32_pk_f32_fp4 v[20:21], v64, 1.0
	v_pk_fma_f32 v[4:5], v[20:21], s[2:3], v[4:5] op_sel_hi:[1,0,1]
	v_cvt_scalef32_pk_f32_fp4 v[20:21], v64, 1.0 op_sel:[1,0,0]
	v_pk_fma_f32 v[6:7], s[2:3], v[20:21], v[6:7] op_sel_hi:[0,1,1]
	v_cvt_scalef32_pk_f32_fp4 v[20:21], v64, 1.0 op_sel:[0,1,0]
	v_pk_fma_f32 v[8:9], s[2:3], v[20:21], v[8:9] op_sel_hi:[0,1,1]
	v_cvt_scalef32_pk_f32_fp4 v[20:21], v64, 1.0 op_sel:[1,1,0]
	v_pk_fma_f32 v[10:11], s[2:3], v[20:21], v[10:11] op_sel_hi:[0,1,1]
	v_cvt_scalef32_pk_f32_fp4 v[20:21], v65, 1.0
	v_pk_fma_f32 v[12:13], s[2:3], v[20:21], v[12:13] op_sel_hi:[0,1,1]
	v_cvt_scalef32_pk_f32_fp4 v[20:21], v65, 1.0 op_sel:[1,0,0]
	v_pk_fma_f32 v[14:15], s[2:3], v[20:21], v[14:15] op_sel_hi:[0,1,1]
	v_cvt_scalef32_pk_f32_fp4 v[20:21], v65, 1.0 op_sel:[0,1,0]
	v_pk_fma_f32 v[16:17], s[2:3], v[20:21], v[16:17] op_sel_hi:[0,1,1]
	v_cvt_scalef32_pk_f32_fp4 v[20:21], v65, 1.0 op_sel:[1,1,0]
	v_pk_fma_f32 v[18:19], s[2:3], v[20:21], v[18:19] op_sel_hi:[0,1,1]
	v_readlane_b32 s2, v127, 11
	s_waitcnt vmcnt(18)
	v_cvt_scalef32_pk_f32_fp4 v[20:21], v66, 1.0
	v_pk_fma_f32 v[4:5], v[20:21], s[2:3], v[4:5] op_sel_hi:[1,0,1]
	v_cvt_scalef32_pk_f32_fp4 v[20:21], v66, 1.0 op_sel:[1,0,0]
	v_pk_fma_f32 v[6:7], s[2:3], v[20:21], v[6:7] op_sel_hi:[0,1,1]
	v_cvt_scalef32_pk_f32_fp4 v[20:21], v66, 1.0 op_sel:[0,1,0]
	v_pk_fma_f32 v[8:9], s[2:3], v[20:21], v[8:9] op_sel_hi:[0,1,1]
	v_cvt_scalef32_pk_f32_fp4 v[20:21], v66, 1.0 op_sel:[1,1,0]
	v_pk_fma_f32 v[10:11], s[2:3], v[20:21], v[10:11] op_sel_hi:[0,1,1]
	v_cvt_scalef32_pk_f32_fp4 v[20:21], v67, 1.0
	v_pk_fma_f32 v[12:13], s[2:3], v[20:21], v[12:13] op_sel_hi:[0,1,1]
	v_cvt_scalef32_pk_f32_fp4 v[20:21], v67, 1.0 op_sel:[1,0,0]
	v_pk_fma_f32 v[14:15], s[2:3], v[20:21], v[14:15] op_sel_hi:[0,1,1]
	v_cvt_scalef32_pk_f32_fp4 v[20:21], v67, 1.0 op_sel:[0,1,0]
	v_pk_fma_f32 v[16:17], s[2:3], v[20:21], v[16:17] op_sel_hi:[0,1,1]
	v_cvt_scalef32_pk_f32_fp4 v[20:21], v67, 1.0 op_sel:[1,1,0]
	v_pk_fma_f32 v[18:19], s[2:3], v[20:21], v[18:19] op_sel_hi:[0,1,1]
	v_readlane_b32 s2, v127, 7
	s_waitcnt vmcnt(17)
	v_cvt_scalef32_pk_f32_fp4 v[20:21], v68, 1.0
	v_pk_fma_f32 v[4:5], v[20:21], s[2:3], v[4:5] op_sel_hi:[1,0,1]
	v_cvt_scalef32_pk_f32_fp4 v[20:21], v68, 1.0 op_sel:[1,0,0]
	v_pk_fma_f32 v[6:7], s[2:3], v[20:21], v[6:7] op_sel_hi:[0,1,1]
	v_cvt_scalef32_pk_f32_fp4 v[20:21], v68, 1.0 op_sel:[0,1,0]
	v_pk_fma_f32 v[8:9], s[2:3], v[20:21], v[8:9] op_sel_hi:[0,1,1]
	v_cvt_scalef32_pk_f32_fp4 v[20:21], v68, 1.0 op_sel:[1,1,0]
	v_pk_fma_f32 v[10:11], s[2:3], v[20:21], v[10:11] op_sel_hi:[0,1,1]
	v_cvt_scalef32_pk_f32_fp4 v[20:21], v69, 1.0
	v_pk_fma_f32 v[12:13], s[2:3], v[20:21], v[12:13] op_sel_hi:[0,1,1]
	v_cvt_scalef32_pk_f32_fp4 v[20:21], v69, 1.0 op_sel:[1,0,0]
	v_pk_fma_f32 v[14:15], s[2:3], v[20:21], v[14:15] op_sel_hi:[0,1,1]
	v_cvt_scalef32_pk_f32_fp4 v[20:21], v69, 1.0 op_sel:[0,1,0]
	v_pk_fma_f32 v[16:17], s[2:3], v[20:21], v[16:17] op_sel_hi:[0,1,1]
	v_cvt_scalef32_pk_f32_fp4 v[20:21], v69, 1.0 op_sel:[1,1,0]
	v_pk_fma_f32 v[18:19], s[2:3], v[20:21], v[18:19] op_sel_hi:[0,1,1]
	v_readlane_b32 s2, v127, 15
	s_waitcnt vmcnt(16)
	v_cvt_scalef32_pk_f32_fp4 v[20:21], v70, 1.0
	v_pk_fma_f32 v[4:5], v[20:21], s[2:3], v[4:5] op_sel_hi:[1,0,1]
	v_cvt_scalef32_pk_f32_fp4 v[20:21], v70, 1.0 op_sel:[1,0,0]
	v_pk_fma_f32 v[6:7], s[2:3], v[20:21], v[6:7] op_sel_hi:[0,1,1]
	v_cvt_scalef32_pk_f32_fp4 v[20:21], v70, 1.0 op_sel:[0,1,0]
	v_pk_fma_f32 v[8:9], s[2:3], v[20:21], v[8:9] op_sel_hi:[0,1,1]
	v_cvt_scalef32_pk_f32_fp4 v[20:21], v70, 1.0 op_sel:[1,1,0]
	v_pk_fma_f32 v[10:11], s[2:3], v[20:21], v[10:11] op_sel_hi:[0,1,1]
	v_cvt_scalef32_pk_f32_fp4 v[20:21], v71, 1.0
	v_pk_fma_f32 v[12:13], s[2:3], v[20:21], v[12:13] op_sel_hi:[0,1,1]
	v_cvt_scalef32_pk_f32_fp4 v[20:21], v71, 1.0 op_sel:[1,0,0]
	v_pk_fma_f32 v[14:15], s[2:3], v[20:21], v[14:15] op_sel_hi:[0,1,1]
	v_cvt_scalef32_pk_f32_fp4 v[20:21], v71, 1.0 op_sel:[0,1,0]
	v_pk_fma_f32 v[16:17], s[2:3], v[20:21], v[16:17] op_sel_hi:[0,1,1]
	v_cvt_scalef32_pk_f32_fp4 v[20:21], v71, 1.0 op_sel:[1,1,0]
	v_pk_fma_f32 v[18:19], s[2:3], v[20:21], v[18:19] op_sel_hi:[0,1,1]
	v_readlane_b32 s2, v127, 16
	s_waitcnt vmcnt(15)
	v_cvt_scalef32_pk_f32_fp4 v[20:21], v72, 1.0
	v_pk_fma_f32 v[4:5], v[20:21], s[2:3], v[4:5] op_sel_hi:[1,0,1]
	v_cvt_scalef32_pk_f32_fp4 v[20:21], v72, 1.0 op_sel:[1,0,0]
	v_pk_fma_f32 v[6:7], s[2:3], v[20:21], v[6:7] op_sel_hi:[0,1,1]
	v_cvt_scalef32_pk_f32_fp4 v[20:21], v72, 1.0 op_sel:[0,1,0]
	v_pk_fma_f32 v[8:9], s[2:3], v[20:21], v[8:9] op_sel_hi:[0,1,1]
	v_cvt_scalef32_pk_f32_fp4 v[20:21], v72, 1.0 op_sel:[1,1,0]
	v_pk_fma_f32 v[10:11], s[2:3], v[20:21], v[10:11] op_sel_hi:[0,1,1]
	v_cvt_scalef32_pk_f32_fp4 v[20:21], v73, 1.0
	v_pk_fma_f32 v[12:13], s[2:3], v[20:21], v[12:13] op_sel_hi:[0,1,1]
	v_cvt_scalef32_pk_f32_fp4 v[20:21], v73, 1.0 op_sel:[1,0,0]
	v_pk_fma_f32 v[14:15], s[2:3], v[20:21], v[14:15] op_sel_hi:[0,1,1]
	v_cvt_scalef32_pk_f32_fp4 v[20:21], v73, 1.0 op_sel:[0,1,0]
	v_pk_fma_f32 v[16:17], s[2:3], v[20:21], v[16:17] op_sel_hi:[0,1,1]
	v_cvt_scalef32_pk_f32_fp4 v[20:21], v73, 1.0 op_sel:[1,1,0]
	v_pk_fma_f32 v[18:19], s[2:3], v[20:21], v[18:19] op_sel_hi:[0,1,1]
	v_readlane_b32 s2, v127, 24
	s_waitcnt vmcnt(14)
	v_cvt_scalef32_pk_f32_fp4 v[20:21], v74, 1.0
	v_pk_fma_f32 v[4:5], v[20:21], s[2:3], v[4:5] op_sel_hi:[1,0,1]
	v_cvt_scalef32_pk_f32_fp4 v[20:21], v74, 1.0 op_sel:[1,0,0]
	v_pk_fma_f32 v[6:7], s[2:3], v[20:21], v[6:7] op_sel_hi:[0,1,1]
	v_cvt_scalef32_pk_f32_fp4 v[20:21], v74, 1.0 op_sel:[0,1,0]
	v_pk_fma_f32 v[8:9], s[2:3], v[20:21], v[8:9] op_sel_hi:[0,1,1]
	v_cvt_scalef32_pk_f32_fp4 v[20:21], v74, 1.0 op_sel:[1,1,0]
	v_pk_fma_f32 v[10:11], s[2:3], v[20:21], v[10:11] op_sel_hi:[0,1,1]
	v_cvt_scalef32_pk_f32_fp4 v[20:21], v75, 1.0
	v_pk_fma_f32 v[12:13], s[2:3], v[20:21], v[12:13] op_sel_hi:[0,1,1]
	v_cvt_scalef32_pk_f32_fp4 v[20:21], v75, 1.0 op_sel:[1,0,0]
	v_pk_fma_f32 v[14:15], s[2:3], v[20:21], v[14:15] op_sel_hi:[0,1,1]
	v_cvt_scalef32_pk_f32_fp4 v[20:21], v75, 1.0 op_sel:[0,1,0]
	v_pk_fma_f32 v[16:17], s[2:3], v[20:21], v[16:17] op_sel_hi:[0,1,1]
	v_cvt_scalef32_pk_f32_fp4 v[20:21], v75, 1.0 op_sel:[1,1,0]
	v_pk_fma_f32 v[18:19], s[2:3], v[20:21], v[18:19] op_sel_hi:[0,1,1]
	v_readlane_b32 s2, v127, 20
	s_waitcnt vmcnt(13)
	v_cvt_scalef32_pk_f32_fp4 v[20:21], v76, 1.0
	v_pk_fma_f32 v[4:5], v[20:21], s[2:3], v[4:5] op_sel_hi:[1,0,1]
	v_cvt_scalef32_pk_f32_fp4 v[20:21], v76, 1.0 op_sel:[1,0,0]
	v_pk_fma_f32 v[6:7], s[2:3], v[20:21], v[6:7] op_sel_hi:[0,1,1]
	v_cvt_scalef32_pk_f32_fp4 v[20:21], v76, 1.0 op_sel:[0,1,0]
	v_pk_fma_f32 v[8:9], s[2:3], v[20:21], v[8:9] op_sel_hi:[0,1,1]
	v_cvt_scalef32_pk_f32_fp4 v[20:21], v76, 1.0 op_sel:[1,1,0]
	v_pk_fma_f32 v[10:11], s[2:3], v[20:21], v[10:11] op_sel_hi:[0,1,1]
	v_cvt_scalef32_pk_f32_fp4 v[20:21], v77, 1.0
	v_pk_fma_f32 v[12:13], s[2:3], v[20:21], v[12:13] op_sel_hi:[0,1,1]
	v_cvt_scalef32_pk_f32_fp4 v[20:21], v77, 1.0 op_sel:[1,0,0]
	v_pk_fma_f32 v[14:15], s[2:3], v[20:21], v[14:15] op_sel_hi:[0,1,1]
	v_cvt_scalef32_pk_f32_fp4 v[20:21], v77, 1.0 op_sel:[0,1,0]
	v_pk_fma_f32 v[16:17], s[2:3], v[20:21], v[16:17] op_sel_hi:[0,1,1]
	v_cvt_scalef32_pk_f32_fp4 v[20:21], v77, 1.0 op_sel:[1,1,0]
	v_pk_fma_f32 v[18:19], s[2:3], v[20:21], v[18:19] op_sel_hi:[0,1,1]
	v_readlane_b32 s2, v127, 28
	s_waitcnt vmcnt(12)
	v_cvt_scalef32_pk_f32_fp4 v[20:21], v78, 1.0
	v_pk_fma_f32 v[4:5], v[20:21], s[2:3], v[4:5] op_sel_hi:[1,0,1]
	v_cvt_scalef32_pk_f32_fp4 v[20:21], v78, 1.0 op_sel:[1,0,0]
	v_pk_fma_f32 v[6:7], s[2:3], v[20:21], v[6:7] op_sel_hi:[0,1,1]
	v_cvt_scalef32_pk_f32_fp4 v[20:21], v78, 1.0 op_sel:[0,1,0]
	v_pk_fma_f32 v[8:9], s[2:3], v[20:21], v[8:9] op_sel_hi:[0,1,1]
	v_cvt_scalef32_pk_f32_fp4 v[20:21], v78, 1.0 op_sel:[1,1,0]
	v_pk_fma_f32 v[10:11], s[2:3], v[20:21], v[10:11] op_sel_hi:[0,1,1]
	v_cvt_scalef32_pk_f32_fp4 v[20:21], v79, 1.0
	v_pk_fma_f32 v[12:13], s[2:3], v[20:21], v[12:13] op_sel_hi:[0,1,1]
	v_cvt_scalef32_pk_f32_fp4 v[20:21], v79, 1.0 op_sel:[1,0,0]
	v_pk_fma_f32 v[14:15], s[2:3], v[20:21], v[14:15] op_sel_hi:[0,1,1]
	v_cvt_scalef32_pk_f32_fp4 v[20:21], v79, 1.0 op_sel:[0,1,0]
	v_pk_fma_f32 v[16:17], s[2:3], v[20:21], v[16:17] op_sel_hi:[0,1,1]
	v_cvt_scalef32_pk_f32_fp4 v[20:21], v79, 1.0 op_sel:[1,1,0]
	v_pk_fma_f32 v[18:19], s[2:3], v[20:21], v[18:19] op_sel_hi:[0,1,1]
	v_readlane_b32 s2, v127, 18
	s_waitcnt vmcnt(11)
	v_cvt_scalef32_pk_f32_fp4 v[20:21], v80, 1.0
	v_pk_fma_f32 v[4:5], v[20:21], s[2:3], v[4:5] op_sel_hi:[1,0,1]
	v_cvt_scalef32_pk_f32_fp4 v[20:21], v80, 1.0 op_sel:[1,0,0]
	v_pk_fma_f32 v[6:7], s[2:3], v[20:21], v[6:7] op_sel_hi:[0,1,1]
	v_cvt_scalef32_pk_f32_fp4 v[20:21], v80, 1.0 op_sel:[0,1,0]
	v_pk_fma_f32 v[8:9], s[2:3], v[20:21], v[8:9] op_sel_hi:[0,1,1]
	v_cvt_scalef32_pk_f32_fp4 v[20:21], v80, 1.0 op_sel:[1,1,0]
	v_pk_fma_f32 v[10:11], s[2:3], v[20:21], v[10:11] op_sel_hi:[0,1,1]
	v_cvt_scalef32_pk_f32_fp4 v[20:21], v81, 1.0
	v_pk_fma_f32 v[12:13], s[2:3], v[20:21], v[12:13] op_sel_hi:[0,1,1]
	v_cvt_scalef32_pk_f32_fp4 v[20:21], v81, 1.0 op_sel:[1,0,0]
	v_pk_fma_f32 v[14:15], s[2:3], v[20:21], v[14:15] op_sel_hi:[0,1,1]
	v_cvt_scalef32_pk_f32_fp4 v[20:21], v81, 1.0 op_sel:[0,1,0]
	v_pk_fma_f32 v[16:17], s[2:3], v[20:21], v[16:17] op_sel_hi:[0,1,1]
	v_cvt_scalef32_pk_f32_fp4 v[20:21], v81, 1.0 op_sel:[1,1,0]
	v_pk_fma_f32 v[18:19], s[2:3], v[20:21], v[18:19] op_sel_hi:[0,1,1]
	v_readlane_b32 s2, v127, 26
	s_waitcnt vmcnt(10)
	v_cvt_scalef32_pk_f32_fp4 v[20:21], v82, 1.0
	v_pk_fma_f32 v[4:5], v[20:21], s[2:3], v[4:5] op_sel_hi:[1,0,1]
	v_cvt_scalef32_pk_f32_fp4 v[20:21], v82, 1.0 op_sel:[1,0,0]
	v_pk_fma_f32 v[6:7], s[2:3], v[20:21], v[6:7] op_sel_hi:[0,1,1]
	v_cvt_scalef32_pk_f32_fp4 v[20:21], v82, 1.0 op_sel:[0,1,0]
	v_pk_fma_f32 v[8:9], s[2:3], v[20:21], v[8:9] op_sel_hi:[0,1,1]
	v_cvt_scalef32_pk_f32_fp4 v[20:21], v82, 1.0 op_sel:[1,1,0]
	v_pk_fma_f32 v[10:11], s[2:3], v[20:21], v[10:11] op_sel_hi:[0,1,1]
	v_cvt_scalef32_pk_f32_fp4 v[20:21], v83, 1.0
	v_pk_fma_f32 v[12:13], s[2:3], v[20:21], v[12:13] op_sel_hi:[0,1,1]
	v_cvt_scalef32_pk_f32_fp4 v[20:21], v83, 1.0 op_sel:[1,0,0]
	v_pk_fma_f32 v[14:15], s[2:3], v[20:21], v[14:15] op_sel_hi:[0,1,1]
	v_cvt_scalef32_pk_f32_fp4 v[20:21], v83, 1.0 op_sel:[0,1,0]
	v_pk_fma_f32 v[16:17], s[2:3], v[20:21], v[16:17] op_sel_hi:[0,1,1]
	v_cvt_scalef32_pk_f32_fp4 v[20:21], v83, 1.0 op_sel:[1,1,0]
	v_pk_fma_f32 v[18:19], s[2:3], v[20:21], v[18:19] op_sel_hi:[0,1,1]
	v_readlane_b32 s2, v127, 22
	s_waitcnt vmcnt(9)
	v_cvt_scalef32_pk_f32_fp4 v[20:21], v84, 1.0
	v_pk_fma_f32 v[4:5], v[20:21], s[2:3], v[4:5] op_sel_hi:[1,0,1]
	v_cvt_scalef32_pk_f32_fp4 v[20:21], v84, 1.0 op_sel:[1,0,0]
	v_pk_fma_f32 v[6:7], s[2:3], v[20:21], v[6:7] op_sel_hi:[0,1,1]
	v_cvt_scalef32_pk_f32_fp4 v[20:21], v84, 1.0 op_sel:[0,1,0]
	v_pk_fma_f32 v[8:9], s[2:3], v[20:21], v[8:9] op_sel_hi:[0,1,1]
	v_cvt_scalef32_pk_f32_fp4 v[20:21], v84, 1.0 op_sel:[1,1,0]
	v_pk_fma_f32 v[10:11], s[2:3], v[20:21], v[10:11] op_sel_hi:[0,1,1]
	v_cvt_scalef32_pk_f32_fp4 v[20:21], v85, 1.0
	v_pk_fma_f32 v[12:13], s[2:3], v[20:21], v[12:13] op_sel_hi:[0,1,1]
	v_cvt_scalef32_pk_f32_fp4 v[20:21], v85, 1.0 op_sel:[1,0,0]
	v_pk_fma_f32 v[14:15], s[2:3], v[20:21], v[14:15] op_sel_hi:[0,1,1]
	v_cvt_scalef32_pk_f32_fp4 v[20:21], v85, 1.0 op_sel:[0,1,0]
	v_pk_fma_f32 v[16:17], s[2:3], v[20:21], v[16:17] op_sel_hi:[0,1,1]
	v_cvt_scalef32_pk_f32_fp4 v[20:21], v85, 1.0 op_sel:[1,1,0]
	v_pk_fma_f32 v[18:19], s[2:3], v[20:21], v[18:19] op_sel_hi:[0,1,1]
	v_readlane_b32 s2, v127, 30
	s_waitcnt vmcnt(8)
	v_cvt_scalef32_pk_f32_fp4 v[20:21], v86, 1.0
	v_pk_fma_f32 v[4:5], v[20:21], s[2:3], v[4:5] op_sel_hi:[1,0,1]
	v_cvt_scalef32_pk_f32_fp4 v[20:21], v86, 1.0 op_sel:[1,0,0]
	v_pk_fma_f32 v[6:7], s[2:3], v[20:21], v[6:7] op_sel_hi:[0,1,1]
	v_cvt_scalef32_pk_f32_fp4 v[20:21], v86, 1.0 op_sel:[0,1,0]
	v_pk_fma_f32 v[8:9], s[2:3], v[20:21], v[8:9] op_sel_hi:[0,1,1]
	v_cvt_scalef32_pk_f32_fp4 v[20:21], v86, 1.0 op_sel:[1,1,0]
	v_pk_fma_f32 v[10:11], s[2:3], v[20:21], v[10:11] op_sel_hi:[0,1,1]
	v_cvt_scalef32_pk_f32_fp4 v[20:21], v87, 1.0
	v_pk_fma_f32 v[12:13], s[2:3], v[20:21], v[12:13] op_sel_hi:[0,1,1]
	v_cvt_scalef32_pk_f32_fp4 v[20:21], v87, 1.0 op_sel:[1,0,0]
	v_pk_fma_f32 v[14:15], s[2:3], v[20:21], v[14:15] op_sel_hi:[0,1,1]
	v_cvt_scalef32_pk_f32_fp4 v[20:21], v87, 1.0 op_sel:[0,1,0]
	v_pk_fma_f32 v[16:17], s[2:3], v[20:21], v[16:17] op_sel_hi:[0,1,1]
	v_cvt_scalef32_pk_f32_fp4 v[20:21], v87, 1.0 op_sel:[1,1,0]
	v_pk_fma_f32 v[18:19], s[2:3], v[20:21], v[18:19] op_sel_hi:[0,1,1]
	s_waitcnt vmcnt(7)
	v_cvt_scalef32_pk_f32_fp4 v[20:21], v88, 1.0
	s_nop 1
	v_readlane_b32 s2, v127, 17
	s_nop 1
	v_pk_fma_f32 v[4:5], v[20:21], s[2:3], v[4:5] op_sel_hi:[1,0,1]
	v_cvt_scalef32_pk_f32_fp4 v[20:21], v88, 1.0 op_sel:[1,0,0]
	v_pk_fma_f32 v[6:7], s[2:3], v[20:21], v[6:7] op_sel_hi:[0,1,1]
	v_cvt_scalef32_pk_f32_fp4 v[20:21], v88, 1.0 op_sel:[0,1,0]
	v_pk_fma_f32 v[8:9], s[2:3], v[20:21], v[8:9] op_sel_hi:[0,1,1]
	v_cvt_scalef32_pk_f32_fp4 v[20:21], v88, 1.0 op_sel:[1,1,0]
	v_pk_fma_f32 v[10:11], s[2:3], v[20:21], v[10:11] op_sel_hi:[0,1,1]
	v_cvt_scalef32_pk_f32_fp4 v[20:21], v89, 1.0
	v_pk_fma_f32 v[12:13], s[2:3], v[20:21], v[12:13] op_sel_hi:[0,1,1]
	v_cvt_scalef32_pk_f32_fp4 v[20:21], v89, 1.0 op_sel:[1,0,0]
	v_pk_fma_f32 v[14:15], s[2:3], v[20:21], v[14:15] op_sel_hi:[0,1,1]
	v_cvt_scalef32_pk_f32_fp4 v[20:21], v89, 1.0 op_sel:[0,1,0]
	v_pk_fma_f32 v[16:17], s[2:3], v[20:21], v[16:17] op_sel_hi:[0,1,1]
	v_cvt_scalef32_pk_f32_fp4 v[20:21], v89, 1.0 op_sel:[1,1,0]
	v_pk_fma_f32 v[18:19], s[2:3], v[20:21], v[18:19] op_sel_hi:[0,1,1]
	s_waitcnt vmcnt(6)
	v_cvt_scalef32_pk_f32_fp4 v[20:21], v90, 1.0
	s_nop 1
	v_readlane_b32 s2, v127, 25
	s_nop 1
	v_pk_fma_f32 v[4:5], v[20:21], s[2:3], v[4:5] op_sel_hi:[1,0,1]
	v_cvt_scalef32_pk_f32_fp4 v[20:21], v90, 1.0 op_sel:[1,0,0]
	v_pk_fma_f32 v[6:7], s[2:3], v[20:21], v[6:7] op_sel_hi:[0,1,1]
	v_cvt_scalef32_pk_f32_fp4 v[20:21], v90, 1.0 op_sel:[0,1,0]
	v_pk_fma_f32 v[8:9], s[2:3], v[20:21], v[8:9] op_sel_hi:[0,1,1]
	v_cvt_scalef32_pk_f32_fp4 v[20:21], v90, 1.0 op_sel:[1,1,0]
	v_pk_fma_f32 v[10:11], s[2:3], v[20:21], v[10:11] op_sel_hi:[0,1,1]
	v_cvt_scalef32_pk_f32_fp4 v[20:21], v91, 1.0
	v_pk_fma_f32 v[12:13], s[2:3], v[20:21], v[12:13] op_sel_hi:[0,1,1]
	v_cvt_scalef32_pk_f32_fp4 v[20:21], v91, 1.0 op_sel:[1,0,0]
	v_pk_fma_f32 v[14:15], s[2:3], v[20:21], v[14:15] op_sel_hi:[0,1,1]
	v_cvt_scalef32_pk_f32_fp4 v[20:21], v91, 1.0 op_sel:[0,1,0]
	v_pk_fma_f32 v[16:17], s[2:3], v[20:21], v[16:17] op_sel_hi:[0,1,1]
	v_cvt_scalef32_pk_f32_fp4 v[20:21], v91, 1.0 op_sel:[1,1,0]
	v_pk_fma_f32 v[18:19], s[2:3], v[20:21], v[18:19] op_sel_hi:[0,1,1]
	s_waitcnt vmcnt(5)
	v_cvt_scalef32_pk_f32_fp4 v[20:21], v92, 1.0
	s_nop 1
	v_readlane_b32 s2, v127, 21
	s_nop 1
	v_pk_fma_f32 v[4:5], v[20:21], s[2:3], v[4:5] op_sel_hi:[1,0,1]
	v_cvt_scalef32_pk_f32_fp4 v[20:21], v92, 1.0 op_sel:[1,0,0]
	v_pk_fma_f32 v[6:7], s[2:3], v[20:21], v[6:7] op_sel_hi:[0,1,1]
	v_cvt_scalef32_pk_f32_fp4 v[20:21], v92, 1.0 op_sel:[0,1,0]
	v_pk_fma_f32 v[8:9], s[2:3], v[20:21], v[8:9] op_sel_hi:[0,1,1]
	v_cvt_scalef32_pk_f32_fp4 v[20:21], v92, 1.0 op_sel:[1,1,0]
	v_pk_fma_f32 v[10:11], s[2:3], v[20:21], v[10:11] op_sel_hi:[0,1,1]
	v_cvt_scalef32_pk_f32_fp4 v[20:21], v93, 1.0
	v_pk_fma_f32 v[12:13], s[2:3], v[20:21], v[12:13] op_sel_hi:[0,1,1]
	v_cvt_scalef32_pk_f32_fp4 v[20:21], v93, 1.0 op_sel:[1,0,0]
	v_pk_fma_f32 v[14:15], s[2:3], v[20:21], v[14:15] op_sel_hi:[0,1,1]
	v_cvt_scalef32_pk_f32_fp4 v[20:21], v93, 1.0 op_sel:[0,1,0]
	v_pk_fma_f32 v[16:17], s[2:3], v[20:21], v[16:17] op_sel_hi:[0,1,1]
	v_cvt_scalef32_pk_f32_fp4 v[20:21], v93, 1.0 op_sel:[1,1,0]
	v_pk_fma_f32 v[18:19], s[2:3], v[20:21], v[18:19] op_sel_hi:[0,1,1]
	s_waitcnt vmcnt(4)
	v_cvt_scalef32_pk_f32_fp4 v[20:21], v94, 1.0
	s_nop 1
	v_readlane_b32 s2, v127, 29
	s_nop 1
	v_pk_fma_f32 v[4:5], v[20:21], s[2:3], v[4:5] op_sel_hi:[1,0,1]
	v_cvt_scalef32_pk_f32_fp4 v[20:21], v94, 1.0 op_sel:[1,0,0]
	v_pk_fma_f32 v[6:7], s[2:3], v[20:21], v[6:7] op_sel_hi:[0,1,1]
	v_cvt_scalef32_pk_f32_fp4 v[20:21], v94, 1.0 op_sel:[0,1,0]
	v_pk_fma_f32 v[8:9], s[2:3], v[20:21], v[8:9] op_sel_hi:[0,1,1]
	v_cvt_scalef32_pk_f32_fp4 v[20:21], v94, 1.0 op_sel:[1,1,0]
	v_pk_fma_f32 v[10:11], s[2:3], v[20:21], v[10:11] op_sel_hi:[0,1,1]
	v_cvt_scalef32_pk_f32_fp4 v[20:21], v95, 1.0
	v_pk_fma_f32 v[12:13], s[2:3], v[20:21], v[12:13] op_sel_hi:[0,1,1]
	v_cvt_scalef32_pk_f32_fp4 v[20:21], v95, 1.0 op_sel:[1,0,0]
	v_pk_fma_f32 v[14:15], s[2:3], v[20:21], v[14:15] op_sel_hi:[0,1,1]
	v_cvt_scalef32_pk_f32_fp4 v[20:21], v95, 1.0 op_sel:[0,1,0]
	v_pk_fma_f32 v[16:17], s[2:3], v[20:21], v[16:17] op_sel_hi:[0,1,1]
	v_cvt_scalef32_pk_f32_fp4 v[20:21], v95, 1.0 op_sel:[1,1,0]
	v_pk_fma_f32 v[18:19], s[2:3], v[20:21], v[18:19] op_sel_hi:[0,1,1]
	s_waitcnt vmcnt(3)
	v_cvt_scalef32_pk_f32_fp4 v[20:21], v96, 1.0
	s_nop 1
	v_readlane_b32 s2, v127, 19
	s_nop 1
	v_pk_fma_f32 v[4:5], v[20:21], s[2:3], v[4:5] op_sel_hi:[1,0,1]
	v_cvt_scalef32_pk_f32_fp4 v[20:21], v96, 1.0 op_sel:[1,0,0]
	v_pk_fma_f32 v[6:7], s[2:3], v[20:21], v[6:7] op_sel_hi:[0,1,1]
	v_cvt_scalef32_pk_f32_fp4 v[20:21], v96, 1.0 op_sel:[0,1,0]
	v_pk_fma_f32 v[8:9], s[2:3], v[20:21], v[8:9] op_sel_hi:[0,1,1]
	v_cvt_scalef32_pk_f32_fp4 v[20:21], v96, 1.0 op_sel:[1,1,0]
	v_pk_fma_f32 v[10:11], s[2:3], v[20:21], v[10:11] op_sel_hi:[0,1,1]
	v_cvt_scalef32_pk_f32_fp4 v[20:21], v97, 1.0
	v_pk_fma_f32 v[12:13], s[2:3], v[20:21], v[12:13] op_sel_hi:[0,1,1]
	v_cvt_scalef32_pk_f32_fp4 v[20:21], v97, 1.0 op_sel:[1,0,0]
	v_pk_fma_f32 v[14:15], s[2:3], v[20:21], v[14:15] op_sel_hi:[0,1,1]
	v_cvt_scalef32_pk_f32_fp4 v[20:21], v97, 1.0 op_sel:[0,1,0]
	v_pk_fma_f32 v[16:17], s[2:3], v[20:21], v[16:17] op_sel_hi:[0,1,1]
	v_cvt_scalef32_pk_f32_fp4 v[20:21], v97, 1.0 op_sel:[1,1,0]
	v_pk_fma_f32 v[18:19], s[2:3], v[20:21], v[18:19] op_sel_hi:[0,1,1]
	s_waitcnt vmcnt(2)
	v_cvt_scalef32_pk_f32_fp4 v[20:21], v98, 1.0
	s_nop 1
	v_readlane_b32 s2, v127, 27
	s_nop 1
	v_pk_fma_f32 v[4:5], v[20:21], s[2:3], v[4:5] op_sel_hi:[1,0,1]
	v_cvt_scalef32_pk_f32_fp4 v[20:21], v98, 1.0 op_sel:[1,0,0]
	v_pk_fma_f32 v[6:7], s[2:3], v[20:21], v[6:7] op_sel_hi:[0,1,1]
	v_cvt_scalef32_pk_f32_fp4 v[20:21], v98, 1.0 op_sel:[0,1,0]
	v_pk_fma_f32 v[8:9], s[2:3], v[20:21], v[8:9] op_sel_hi:[0,1,1]
	v_cvt_scalef32_pk_f32_fp4 v[20:21], v98, 1.0 op_sel:[1,1,0]
	v_pk_fma_f32 v[10:11], s[2:3], v[20:21], v[10:11] op_sel_hi:[0,1,1]
	v_cvt_scalef32_pk_f32_fp4 v[20:21], v99, 1.0
	v_pk_fma_f32 v[12:13], s[2:3], v[20:21], v[12:13] op_sel_hi:[0,1,1]
	v_cvt_scalef32_pk_f32_fp4 v[20:21], v99, 1.0 op_sel:[1,0,0]
	v_pk_fma_f32 v[14:15], s[2:3], v[20:21], v[14:15] op_sel_hi:[0,1,1]
	v_cvt_scalef32_pk_f32_fp4 v[20:21], v99, 1.0 op_sel:[0,1,0]
	v_pk_fma_f32 v[16:17], s[2:3], v[20:21], v[16:17] op_sel_hi:[0,1,1]
	v_cvt_scalef32_pk_f32_fp4 v[20:21], v99, 1.0 op_sel:[1,1,0]
	v_pk_fma_f32 v[18:19], s[2:3], v[20:21], v[18:19] op_sel_hi:[0,1,1]
	s_waitcnt vmcnt(1)
	v_cvt_scalef32_pk_f32_fp4 v[20:21], v100, 1.0
	s_nop 1
	v_readlane_b32 s2, v127, 23
	s_nop 1
	v_pk_fma_f32 v[4:5], v[20:21], s[2:3], v[4:5] op_sel_hi:[1,0,1]
	v_cvt_scalef32_pk_f32_fp4 v[20:21], v100, 1.0 op_sel:[1,0,0]
	v_pk_fma_f32 v[6:7], s[2:3], v[20:21], v[6:7] op_sel_hi:[0,1,1]
	v_cvt_scalef32_pk_f32_fp4 v[20:21], v100, 1.0 op_sel:[0,1,0]
	v_pk_fma_f32 v[8:9], s[2:3], v[20:21], v[8:9] op_sel_hi:[0,1,1]
	v_cvt_scalef32_pk_f32_fp4 v[20:21], v100, 1.0 op_sel:[1,1,0]
	v_pk_fma_f32 v[10:11], s[2:3], v[20:21], v[10:11] op_sel_hi:[0,1,1]
	v_cvt_scalef32_pk_f32_fp4 v[20:21], v101, 1.0
	v_pk_fma_f32 v[12:13], s[2:3], v[20:21], v[12:13] op_sel_hi:[0,1,1]
	v_cvt_scalef32_pk_f32_fp4 v[20:21], v101, 1.0 op_sel:[1,0,0]
	v_pk_fma_f32 v[14:15], s[2:3], v[20:21], v[14:15] op_sel_hi:[0,1,1]
	v_cvt_scalef32_pk_f32_fp4 v[20:21], v101, 1.0 op_sel:[0,1,0]
	v_pk_fma_f32 v[16:17], s[2:3], v[20:21], v[16:17] op_sel_hi:[0,1,1]
	v_cvt_scalef32_pk_f32_fp4 v[20:21], v101, 1.0 op_sel:[1,1,0]
	v_pk_fma_f32 v[18:19], s[2:3], v[20:21], v[18:19] op_sel_hi:[0,1,1]
	s_waitcnt vmcnt(0)
	v_cvt_scalef32_pk_f32_fp4 v[20:21], v102, 1.0
	s_nop 1
	v_readlane_b32 s2, v127, 31
	s_nop 1
	v_pk_fma_f32 v[4:5], v[20:21], s[2:3], v[4:5] op_sel_hi:[1,0,1]
	v_cvt_scalef32_pk_f32_fp4 v[20:21], v102, 1.0 op_sel:[1,0,0]
	v_pk_fma_f32 v[6:7], s[2:3], v[20:21], v[6:7] op_sel_hi:[0,1,1]
	v_cvt_scalef32_pk_f32_fp4 v[20:21], v102, 1.0 op_sel:[0,1,0]
	v_pk_fma_f32 v[8:9], s[2:3], v[20:21], v[8:9] op_sel_hi:[0,1,1]
	v_cvt_scalef32_pk_f32_fp4 v[20:21], v102, 1.0 op_sel:[1,1,0]
	v_pk_fma_f32 v[10:11], s[2:3], v[20:21], v[10:11] op_sel_hi:[0,1,1]
	v_cvt_scalef32_pk_f32_fp4 v[20:21], v103, 1.0
	v_pk_fma_f32 v[12:13], s[2:3], v[20:21], v[12:13] op_sel_hi:[0,1,1]
	v_cvt_scalef32_pk_f32_fp4 v[20:21], v103, 1.0 op_sel:[1,0,0]
	v_pk_fma_f32 v[14:15], s[2:3], v[20:21], v[14:15] op_sel_hi:[0,1,1]
	v_cvt_scalef32_pk_f32_fp4 v[20:21], v103, 1.0 op_sel:[0,1,0]
	v_pk_fma_f32 v[16:17], s[2:3], v[20:21], v[16:17] op_sel_hi:[0,1,1]
	v_cvt_scalef32_pk_f32_fp4 v[20:21], v103, 1.0 op_sel:[1,1,0]
	v_pk_fma_f32 v[18:19], s[2:3], v[20:21], v[18:19] op_sel_hi:[0,1,1]
	s_branch .Lh3_v10_join
.Lh3_v10_hi:
	v_readlane_b32 s84, v102, 32
	v_readlane_b32 s86, v102, 33
	v_readlane_b32 s88, v102, 34
	v_readlane_b32 s90, v102, 35
	s_lshl_b32 s84, s84, 9
	s_lshl_b32 s86, s86, 9
	s_lshl_b32 s88, s88, 9
	s_lshl_b32 s90, s90, 9
	s_add_u32 s84, s93, s84
	s_addc_u32 s85, s94, 0
	s_add_u32 s86, s93, s86
	s_addc_u32 s87, s94, 0
	s_add_u32 s88, s93, s88
	s_addc_u32 s89, s94, 0
	s_add_u32 s90, s93, s90
	s_addc_u32 s91, s94, 0
	global_load_dwordx2 v[20:21], v255, s[84:85]
	global_load_dwordx2 v[22:23], v255, s[86:87]
	global_load_dwordx2 v[24:25], v255, s[88:89]
	global_load_dwordx2 v[26:27], v255, s[90:91]
	v_readlane_b32 s84, v102, 36
	v_readlane_b32 s86, v102, 37
	v_readlane_b32 s88, v102, 38
	v_readlane_b32 s90, v102, 39
	s_lshl_b32 s84, s84, 9
	s_lshl_b32 s86, s86, 9
	s_lshl_b32 s88, s88, 9
	s_lshl_b32 s90, s90, 9
	s_add_u32 s84, s93, s84
	s_addc_u32 s85, s94, 0
	s_add_u32 s86, s93, s86
	s_addc_u32 s87, s94, 0
	s_add_u32 s88, s93, s88
	s_addc_u32 s89, s94, 0
	s_add_u32 s90, s93, s90
	s_addc_u32 s91, s94, 0
	global_load_dwordx2 v[28:29], v255, s[84:85]
	global_load_dwordx2 v[30:31], v255, s[86:87]
	global_load_dwordx2 v[32:33], v255, s[88:89]
	global_load_dwordx2 v[34:35], v255, s[90:91]
	v_readlane_b32 s84, v102, 40
	v_readlane_b32 s86, v102, 41
	v_readlane_b32 s88, v102, 42
	v_readlane_b32 s90, v102, 43
	s_lshl_b32 s84, s84, 9
	s_lshl_b32 s86, s86, 9
	s_lshl_b32 s88, s88, 9
	s_lshl_b32 s90, s90, 9
	s_add_u32 s84, s93, s84
	s_addc_u32 s85, s94, 0
	s_add_u32 s86, s93, s86
	s_addc_u32 s87, s94, 0
	s_add_u32 s88, s93, s88
	s_addc_u32 s89, s94, 0
	s_add_u32 s90, s93, s90
	s_addc_u32 s91, s94, 0
	global_load_dwordx2 v[56:57], v255, s[84:85]
	global_load_dwordx2 v[58:59], v255, s[86:87]
	global_load_dwordx2 v[60:61], v255, s[88:89]
	global_load_dwordx2 v[62:63], v255, s[90:91]
	v_readlane_b32 s84, v102, 44
	v_readlane_b32 s86, v102, 45
	v_readlane_b32 s88, v102, 46
	v_readlane_b32 s90, v102, 47
	s_lshl_b32 s84, s84, 9
	s_lshl_b32 s86, s86, 9
	s_lshl_b32 s88, s88, 9
	s_lshl_b32 s90, s90, 9
	s_add_u32 s84, s93, s84
	s_addc_u32 s85, s94, 0
	s_add_u32 s86, s93, s86
	s_addc_u32 s87, s94, 0
	s_add_u32 s88, s93, s88
	s_addc_u32 s89, s94, 0
	s_add_u32 s90, s93, s90
	s_addc_u32 s91, s94, 0
	global_load_dwordx2 v[64:65], v255, s[84:85]
	global_load_dwordx2 v[66:67], v255, s[86:87]
	global_load_dwordx2 v[68:69], v255, s[88:89]
	global_load_dwordx2 v[70:71], v255, s[90:91]
	v_readlane_b32 s84, v102, 48
	v_readlane_b32 s86, v102, 49
	v_readlane_b32 s88, v102, 50
	v_readlane_b32 s90, v102, 51
	s_lshl_b32 s84, s84, 9
	s_lshl_b32 s86, s86, 9
	s_lshl_b32 s88, s88, 9
	s_lshl_b32 s90, s90, 9
	s_add_u32 s84, s93, s84
	s_addc_u32 s85, s94, 0
	s_add_u32 s86, s93, s86
	s_addc_u32 s87, s94, 0
	s_add_u32 s88, s93, s88
	s_addc_u32 s89, s94, 0
	s_add_u32 s90, s93, s90
	s_addc_u32 s91, s94, 0
	global_load_dwordx2 v[72:73], v255, s[84:85]
	global_load_dwordx2 v[74:75], v255, s[86:87]
	global_load_dwordx2 v[76:77], v255, s[88:89]
	global_load_dwordx2 v[78:79], v255, s[90:91]
	v_readlane_b32 s84, v102, 52
	v_readlane_b32 s86, v102, 53
	v_readlane_b32 s88, v102, 54
	v_readlane_b32 s90, v102, 55
	s_lshl_b32 s84, s84, 9
	s_lshl_b32 s86, s86, 9
	s_lshl_b32 s88, s88, 9
	s_lshl_b32 s90, s90, 9
	s_add_u32 s84, s93, s84
	s_addc_u32 s85, s94, 0
	s_add_u32 s86, s93, s86
	s_addc_u32 s87, s94, 0
	s_add_u32 s88, s93, s88
	s_addc_u32 s89, s94, 0
	s_add_u32 s90, s93, s90
	s_addc_u32 s91, s94, 0
	global_load_dwordx2 v[80:81], v255, s[84:85]
	global_load_dwordx2 v[82:83], v255, s[86:87]
	global_load_dwordx2 v[84:85], v255, s[88:89]
	global_load_dwordx2 v[86:87], v255, s[90:91]
	v_readlane_b32 s84, v102, 56
	v_readlane_b32 s86, v102, 57
	v_readlane_b32 s88, v102, 58
	v_readlane_b32 s90, v102, 59
	s_lshl_b32 s84, s84, 9
	s_lshl_b32 s86, s86, 9
	s_lshl_b32 s88, s88, 9
	s_lshl_b32 s90, s90, 9
	s_add_u32 s84, s93, s84
	s_addc_u32 s85, s94, 0
	s_add_u32 s86, s93, s86
	s_addc_u32 s87, s94, 0
	s_add_u32 s88, s93, s88
	s_addc_u32 s89, s94, 0
	s_add_u32 s90, s93, s90
	s_addc_u32 s91, s94, 0
	global_load_dwordx2 v[88:89], v255, s[84:85]
	global_load_dwordx2 v[90:91], v255, s[86:87]
	global_load_dwordx2 v[92:93], v255, s[88:89]
	global_load_dwordx2 v[94:95], v255, s[90:91]
	v_readlane_b32 s84, v102, 60
	v_readlane_b32 s86, v102, 61
	v_readlane_b32 s88, v102, 62
	v_readlane_b32 s90, v102, 63
	s_lshl_b32 s84, s84, 9
	s_lshl_b32 s86, s86, 9
	s_lshl_b32 s88, s88, 9
	s_lshl_b32 s90, s90, 9
	s_add_u32 s84, s93, s84
	s_addc_u32 s85, s94, 0
	s_add_u32 s86, s93, s86
	s_addc_u32 s87, s94, 0
	s_add_u32 s88, s93, s88
	s_addc_u32 s89, s94, 0
	s_add_u32 s90, s93, s90
	s_addc_u32 s91, s94, 0
	global_load_dwordx2 v[96:97], v255, s[84:85]
	global_load_dwordx2 v[98:99], v255, s[86:87]
	global_load_dwordx2 v[100:101], v255, s[88:89]
	global_load_dwordx2 v[102:103], v255, s[90:91]
	v_cndmask_b32_e32 v127, v3, v119, vcc
	s_waitcnt vmcnt(31)
	v_cvt_scalef32_pk_f32_fp4 v[130:131], v20, 1.0
	v_readlane_b32 s28, v127, 34
	v_readlane_b32 s2, v127, 35
	v_add_u32_e32 v116, 32, v116
	v_cmp_ge_u32_e32 vcc, v116, v115
	s_nop 0
	s_nop 0
	s_nop 0
	v_readlane_b32 s64, v127, 32
	s_or_b64 s[14:15], vcc, s[14:15]
	s_nop 0
	v_pk_fma_f32 v[4:5], v[130:131], s[64:65], v[4:5] op_sel_hi:[1,0,1]
	v_cvt_scalef32_pk_f32_fp4 v[130:131], v20, 1.0 op_sel:[1,0,0]
	v_pk_fma_f32 v[6:7], s[64:65], v[130:131], v[6:7] op_sel_hi:[0,1,1]
	v_cvt_scalef32_pk_f32_fp4 v[130:131], v20, 1.0 op_sel:[0,1,0]
	v_pk_fma_f32 v[8:9], s[64:65], v[130:131], v[8:9] op_sel_hi:[0,1,1]
	v_cvt_scalef32_pk_f32_fp4 v[130:131], v20, 1.0 op_sel:[1,1,0]
	v_pk_fma_f32 v[10:11], s[64:65], v[130:131], v[10:11] op_sel_hi:[0,1,1]
	v_cvt_scalef32_pk_f32_fp4 v[130:131], v21, 1.0
	v_pk_fma_f32 v[12:13], s[64:65], v[130:131], v[12:13] op_sel_hi:[0,1,1]
	v_cvt_scalef32_pk_f32_fp4 v[130:131], v21, 1.0 op_sel:[1,0,0]
	v_pk_fma_f32 v[14:15], s[64:65], v[130:131], v[14:15] op_sel_hi:[0,1,1]
	v_cvt_scalef32_pk_f32_fp4 v[130:131], v21, 1.0 op_sel:[0,1,0]
	v_cvt_scalef32_pk_f32_fp4 v[20:21], v21, 1.0 op_sel:[1,1,0]
	v_pk_fma_f32 v[16:17], s[64:65], v[130:131], v[16:17] op_sel_hi:[0,1,1]
	v_pk_fma_f32 v[18:19], s[64:65], v[20:21], v[18:19] op_sel_hi:[0,1,1]
	v_readlane_b32 s64, v127, 40
	s_waitcnt vmcnt(30)
	v_cvt_scalef32_pk_f32_fp4 v[20:21], v22, 1.0
	v_pk_fma_f32 v[4:5], v[20:21], s[64:65], v[4:5] op_sel_hi:[1,0,1]
	v_cvt_scalef32_pk_f32_fp4 v[20:21], v22, 1.0 op_sel:[1,0,0]
	v_pk_fma_f32 v[6:7], s[64:65], v[20:21], v[6:7] op_sel_hi:[0,1,1]
	v_cvt_scalef32_pk_f32_fp4 v[20:21], v22, 1.0 op_sel:[0,1,0]
	v_pk_fma_f32 v[8:9], s[64:65], v[20:21], v[8:9] op_sel_hi:[0,1,1]
	v_cvt_scalef32_pk_f32_fp4 v[20:21], v22, 1.0 op_sel:[1,1,0]
	v_pk_fma_f32 v[10:11], s[64:65], v[20:21], v[10:11] op_sel_hi:[0,1,1]
	v_cvt_scalef32_pk_f32_fp4 v[20:21], v23, 1.0
	v_pk_fma_f32 v[12:13], s[64:65], v[20:21], v[12:13] op_sel_hi:[0,1,1]
	v_cvt_scalef32_pk_f32_fp4 v[20:21], v23, 1.0 op_sel:[1,0,0]
	v_pk_fma_f32 v[14:15], s[64:65], v[20:21], v[14:15] op_sel_hi:[0,1,1]
	v_cvt_scalef32_pk_f32_fp4 v[20:21], v23, 1.0 op_sel:[0,1,0]
	v_pk_fma_f32 v[16:17], s[64:65], v[20:21], v[16:17] op_sel_hi:[0,1,1]
	v_cvt_scalef32_pk_f32_fp4 v[20:21], v23, 1.0 op_sel:[1,1,0]
	v_pk_fma_f32 v[18:19], s[64:65], v[20:21], v[18:19] op_sel_hi:[0,1,1]
	v_readlane_b32 s64, v127, 36
	s_waitcnt vmcnt(29)
	v_cvt_scalef32_pk_f32_fp4 v[20:21], v24, 1.0
	v_pk_fma_f32 v[4:5], v[20:21], s[64:65], v[4:5] op_sel_hi:[1,0,1]
	v_cvt_scalef32_pk_f32_fp4 v[20:21], v24, 1.0 op_sel:[1,0,0]
	v_pk_fma_f32 v[6:7], s[64:65], v[20:21], v[6:7] op_sel_hi:[0,1,1]
	v_cvt_scalef32_pk_f32_fp4 v[20:21], v24, 1.0 op_sel:[0,1,0]
	v_pk_fma_f32 v[8:9], s[64:65], v[20:21], v[8:9] op_sel_hi:[0,1,1]
	v_cvt_scalef32_pk_f32_fp4 v[20:21], v24, 1.0 op_sel:[1,1,0]
	v_pk_fma_f32 v[10:11], s[64:65], v[20:21], v[10:11] op_sel_hi:[0,1,1]
	v_cvt_scalef32_pk_f32_fp4 v[20:21], v25, 1.0
	v_pk_fma_f32 v[12:13], s[64:65], v[20:21], v[12:13] op_sel_hi:[0,1,1]
	v_cvt_scalef32_pk_f32_fp4 v[20:21], v25, 1.0 op_sel:[1,0,0]
	v_pk_fma_f32 v[14:15], s[64:65], v[20:21], v[14:15] op_sel_hi:[0,1,1]
	v_cvt_scalef32_pk_f32_fp4 v[20:21], v25, 1.0 op_sel:[0,1,0]
	v_pk_fma_f32 v[16:17], s[64:65], v[20:21], v[16:17] op_sel_hi:[0,1,1]
	v_cvt_scalef32_pk_f32_fp4 v[20:21], v25, 1.0 op_sel:[1,1,0]
	v_pk_fma_f32 v[18:19], s[64:65], v[20:21], v[18:19] op_sel_hi:[0,1,1]
	v_readlane_b32 s64, v127, 44
	s_waitcnt vmcnt(28)
	v_cvt_scalef32_pk_f32_fp4 v[20:21], v26, 1.0
	v_pk_fma_f32 v[4:5], v[20:21], s[64:65], v[4:5] op_sel_hi:[1,0,1]
	v_cvt_scalef32_pk_f32_fp4 v[20:21], v26, 1.0 op_sel:[1,0,0]
	v_pk_fma_f32 v[6:7], s[64:65], v[20:21], v[6:7] op_sel_hi:[0,1,1]
	v_cvt_scalef32_pk_f32_fp4 v[20:21], v26, 1.0 op_sel:[0,1,0]
	v_pk_fma_f32 v[8:9], s[64:65], v[20:21], v[8:9] op_sel_hi:[0,1,1]
	v_cvt_scalef32_pk_f32_fp4 v[20:21], v26, 1.0 op_sel:[1,1,0]
	v_pk_fma_f32 v[10:11], s[64:65], v[20:21], v[10:11] op_sel_hi:[0,1,1]
	v_cvt_scalef32_pk_f32_fp4 v[20:21], v27, 1.0
	v_pk_fma_f32 v[12:13], s[64:65], v[20:21], v[12:13] op_sel_hi:[0,1,1]
	v_cvt_scalef32_pk_f32_fp4 v[20:21], v27, 1.0 op_sel:[1,0,0]
	v_pk_fma_f32 v[14:15], s[64:65], v[20:21], v[14:15] op_sel_hi:[0,1,1]
	v_cvt_scalef32_pk_f32_fp4 v[20:21], v27, 1.0 op_sel:[0,1,0]
	v_pk_fma_f32 v[16:17], s[64:65], v[20:21], v[16:17] op_sel_hi:[0,1,1]
	v_cvt_scalef32_pk_f32_fp4 v[20:21], v27, 1.0 op_sel:[1,1,0]
	v_pk_fma_f32 v[18:19], s[64:65], v[20:21], v[18:19] op_sel_hi:[0,1,1]
	s_waitcnt vmcnt(27)
	v_cvt_scalef32_pk_f32_fp4 v[20:21], v28, 1.0
	v_pk_fma_f32 v[4:5], v[20:21], s[28:29], v[4:5] op_sel_hi:[1,0,1]
	v_cvt_scalef32_pk_f32_fp4 v[20:21], v28, 1.0 op_sel:[1,0,0]
	v_pk_fma_f32 v[6:7], s[28:29], v[20:21], v[6:7] op_sel_hi:[0,1,1]
	v_cvt_scalef32_pk_f32_fp4 v[20:21], v28, 1.0 op_sel:[0,1,0]
	v_pk_fma_f32 v[8:9], s[28:29], v[20:21], v[8:9] op_sel_hi:[0,1,1]
	v_cvt_scalef32_pk_f32_fp4 v[20:21], v28, 1.0 op_sel:[1,1,0]
	v_pk_fma_f32 v[10:11], s[28:29], v[20:21], v[10:11] op_sel_hi:[0,1,1]
	v_cvt_scalef32_pk_f32_fp4 v[20:21], v29, 1.0
	v_pk_fma_f32 v[12:13], s[28:29], v[20:21], v[12:13] op_sel_hi:[0,1,1]
	v_cvt_scalef32_pk_f32_fp4 v[20:21], v29, 1.0 op_sel:[1,0,0]
	v_pk_fma_f32 v[14:15], s[28:29], v[20:21], v[14:15] op_sel_hi:[0,1,1]
	v_cvt_scalef32_pk_f32_fp4 v[20:21], v29, 1.0 op_sel:[0,1,0]
	v_pk_fma_f32 v[16:17], s[28:29], v[20:21], v[16:17] op_sel_hi:[0,1,1]
	v_cvt_scalef32_pk_f32_fp4 v[20:21], v29, 1.0 op_sel:[1,1,0]
	v_pk_fma_f32 v[18:19], s[28:29], v[20:21], v[18:19] op_sel_hi:[0,1,1]
	v_readlane_b32 s28, v127, 42
	s_waitcnt vmcnt(26)
	v_cvt_scalef32_pk_f32_fp4 v[20:21], v30, 1.0
	v_pk_fma_f32 v[4:5], v[20:21], s[28:29], v[4:5] op_sel_hi:[1,0,1]
	v_cvt_scalef32_pk_f32_fp4 v[20:21], v30, 1.0 op_sel:[1,0,0]
	v_pk_fma_f32 v[6:7], s[28:29], v[20:21], v[6:7] op_sel_hi:[0,1,1]
	v_cvt_scalef32_pk_f32_fp4 v[20:21], v30, 1.0 op_sel:[0,1,0]
	v_pk_fma_f32 v[8:9], s[28:29], v[20:21], v[8:9] op_sel_hi:[0,1,1]
	v_cvt_scalef32_pk_f32_fp4 v[20:21], v30, 1.0 op_sel:[1,1,0]
	v_pk_fma_f32 v[10:11], s[28:29], v[20:21], v[10:11] op_sel_hi:[0,1,1]
	v_cvt_scalef32_pk_f32_fp4 v[20:21], v31, 1.0
	v_pk_fma_f32 v[12:13], s[28:29], v[20:21], v[12:13] op_sel_hi:[0,1,1]
	v_cvt_scalef32_pk_f32_fp4 v[20:21], v31, 1.0 op_sel:[1,0,0]
	v_pk_fma_f32 v[14:15], s[28:29], v[20:21], v[14:15] op_sel_hi:[0,1,1]
	v_cvt_scalef32_pk_f32_fp4 v[20:21], v31, 1.0 op_sel:[0,1,0]
	v_pk_fma_f32 v[16:17], s[28:29], v[20:21], v[16:17] op_sel_hi:[0,1,1]
	v_cvt_scalef32_pk_f32_fp4 v[20:21], v31, 1.0 op_sel:[1,1,0]
	v_pk_fma_f32 v[18:19], s[28:29], v[20:21], v[18:19] op_sel_hi:[0,1,1]
	v_readlane_b32 s28, v127, 38
	s_waitcnt vmcnt(25)
	v_cvt_scalef32_pk_f32_fp4 v[20:21], v32, 1.0
	v_pk_fma_f32 v[4:5], v[20:21], s[28:29], v[4:5] op_sel_hi:[1,0,1]
	v_cvt_scalef32_pk_f32_fp4 v[20:21], v32, 1.0 op_sel:[1,0,0]
	v_pk_fma_f32 v[6:7], s[28:29], v[20:21], v[6:7] op_sel_hi:[0,1,1]
	v_cvt_scalef32_pk_f32_fp4 v[20:21], v32, 1.0 op_sel:[0,1,0]
	v_pk_fma_f32 v[8:9], s[28:29], v[20:21], v[8:9] op_sel_hi:[0,1,1]
	v_cvt_scalef32_pk_f32_fp4 v[20:21], v32, 1.0 op_sel:[1,1,0]
	v_pk_fma_f32 v[10:11], s[28:29], v[20:21], v[10:11] op_sel_hi:[0,1,1]
	v_cvt_scalef32_pk_f32_fp4 v[20:21], v33, 1.0
	v_pk_fma_f32 v[12:13], s[28:29], v[20:21], v[12:13] op_sel_hi:[0,1,1]
	v_cvt_scalef32_pk_f32_fp4 v[20:21], v33, 1.0 op_sel:[1,0,0]
	v_pk_fma_f32 v[14:15], s[28:29], v[20:21], v[14:15] op_sel_hi:[0,1,1]
	v_cvt_scalef32_pk_f32_fp4 v[20:21], v33, 1.0 op_sel:[0,1,0]
	v_pk_fma_f32 v[16:17], s[28:29], v[20:21], v[16:17] op_sel_hi:[0,1,1]
	v_cvt_scalef32_pk_f32_fp4 v[20:21], v33, 1.0 op_sel:[1,1,0]
	v_pk_fma_f32 v[18:19], s[28:29], v[20:21], v[18:19] op_sel_hi:[0,1,1]
	v_readlane_b32 s28, v127, 46
	s_waitcnt vmcnt(24)
	v_cvt_scalef32_pk_f32_fp4 v[20:21], v34, 1.0
	v_pk_fma_f32 v[4:5], v[20:21], s[28:29], v[4:5] op_sel_hi:[1,0,1]
	v_cvt_scalef32_pk_f32_fp4 v[20:21], v34, 1.0 op_sel:[1,0,0]
	v_pk_fma_f32 v[6:7], s[28:29], v[20:21], v[6:7] op_sel_hi:[0,1,1]
	v_cvt_scalef32_pk_f32_fp4 v[20:21], v34, 1.0 op_sel:[0,1,0]
	v_pk_fma_f32 v[8:9], s[28:29], v[20:21], v[8:9] op_sel_hi:[0,1,1]
	v_cvt_scalef32_pk_f32_fp4 v[20:21], v34, 1.0 op_sel:[1,1,0]
	v_pk_fma_f32 v[10:11], s[28:29], v[20:21], v[10:11] op_sel_hi:[0,1,1]
	v_cvt_scalef32_pk_f32_fp4 v[20:21], v35, 1.0
	v_pk_fma_f32 v[12:13], s[28:29], v[20:21], v[12:13] op_sel_hi:[0,1,1]
	v_cvt_scalef32_pk_f32_fp4 v[20:21], v35, 1.0 op_sel:[1,0,0]
	v_pk_fma_f32 v[14:15], s[28:29], v[20:21], v[14:15] op_sel_hi:[0,1,1]
	v_cvt_scalef32_pk_f32_fp4 v[20:21], v35, 1.0 op_sel:[0,1,0]
	v_pk_fma_f32 v[16:17], s[28:29], v[20:21], v[16:17] op_sel_hi:[0,1,1]
	v_cvt_scalef32_pk_f32_fp4 v[20:21], v35, 1.0 op_sel:[1,1,0]
	v_pk_fma_f32 v[18:19], s[28:29], v[20:21], v[18:19] op_sel_hi:[0,1,1]
	v_readlane_b32 s28, v127, 33
	s_waitcnt vmcnt(23)
	v_cvt_scalef32_pk_f32_fp4 v[20:21], v56, 1.0
	v_pk_fma_f32 v[4:5], v[20:21], s[28:29], v[4:5] op_sel_hi:[1,0,1]
	v_cvt_scalef32_pk_f32_fp4 v[20:21], v56, 1.0 op_sel:[1,0,0]
	v_pk_fma_f32 v[6:7], s[28:29], v[20:21], v[6:7] op_sel_hi:[0,1,1]
	v_cvt_scalef32_pk_f32_fp4 v[20:21], v56, 1.0 op_sel:[0,1,0]
	v_pk_fma_f32 v[8:9], s[28:29], v[20:21], v[8:9] op_sel_hi:[0,1,1]
	v_cvt_scalef32_pk_f32_fp4 v[20:21], v56, 1.0 op_sel:[1,1,0]
	v_pk_fma_f32 v[10:11], s[28:29], v[20:21], v[10:11] op_sel_hi:[0,1,1]
	v_cvt_scalef32_pk_f32_fp4 v[20:21], v57, 1.0
	v_pk_fma_f32 v[12:13], s[28:29], v[20:21], v[12:13] op_sel_hi:[0,1,1]
	v_cvt_scalef32_pk_f32_fp4 v[20:21], v57, 1.0 op_sel:[1,0,0]
	v_pk_fma_f32 v[14:15], s[28:29], v[20:21], v[14:15] op_sel_hi:[0,1,1]
	v_cvt_scalef32_pk_f32_fp4 v[20:21], v57, 1.0 op_sel:[0,1,0]
	v_pk_fma_f32 v[16:17], s[28:29], v[20:21], v[16:17] op_sel_hi:[0,1,1]
	v_cvt_scalef32_pk_f32_fp4 v[20:21], v57, 1.0 op_sel:[1,1,0]
	v_pk_fma_f32 v[18:19], s[28:29], v[20:21], v[18:19] op_sel_hi:[0,1,1]
	v_readlane_b32 s28, v127, 41
	s_waitcnt vmcnt(22)
	v_cvt_scalef32_pk_f32_fp4 v[20:21], v58, 1.0
	v_pk_fma_f32 v[4:5], v[20:21], s[28:29], v[4:5] op_sel_hi:[1,0,1]
	v_cvt_scalef32_pk_f32_fp4 v[20:21], v58, 1.0 op_sel:[1,0,0]
	v_pk_fma_f32 v[6:7], s[28:29], v[20:21], v[6:7] op_sel_hi:[0,1,1]
	v_cvt_scalef32_pk_f32_fp4 v[20:21], v58, 1.0 op_sel:[0,1,0]
	v_pk_fma_f32 v[8:9], s[28:29], v[20:21], v[8:9] op_sel_hi:[0,1,1]
	v_cvt_scalef32_pk_f32_fp4 v[20:21], v58, 1.0 op_sel:[1,1,0]
	v_pk_fma_f32 v[10:11], s[28:29], v[20:21], v[10:11] op_sel_hi:[0,1,1]
	v_cvt_scalef32_pk_f32_fp4 v[20:21], v59, 1.0
	v_pk_fma_f32 v[12:13], s[28:29], v[20:21], v[12:13] op_sel_hi:[0,1,1]
	v_cvt_scalef32_pk_f32_fp4 v[20:21], v59, 1.0 op_sel:[1,0,0]
	v_pk_fma_f32 v[14:15], s[28:29], v[20:21], v[14:15] op_sel_hi:[0,1,1]
	v_cvt_scalef32_pk_f32_fp4 v[20:21], v59, 1.0 op_sel:[0,1,0]
	v_pk_fma_f32 v[16:17], s[28:29], v[20:21], v[16:17] op_sel_hi:[0,1,1]
	v_cvt_scalef32_pk_f32_fp4 v[20:21], v59, 1.0 op_sel:[1,1,0]
	v_pk_fma_f32 v[18:19], s[28:29], v[20:21], v[18:19] op_sel_hi:[0,1,1]
	v_readlane_b32 s28, v127, 37
	s_waitcnt vmcnt(21)
	v_cvt_scalef32_pk_f32_fp4 v[20:21], v60, 1.0
	v_pk_fma_f32 v[4:5], v[20:21], s[28:29], v[4:5] op_sel_hi:[1,0,1]
	v_cvt_scalef32_pk_f32_fp4 v[20:21], v60, 1.0 op_sel:[1,0,0]
	v_pk_fma_f32 v[6:7], s[28:29], v[20:21], v[6:7] op_sel_hi:[0,1,1]
	v_cvt_scalef32_pk_f32_fp4 v[20:21], v60, 1.0 op_sel:[0,1,0]
	v_pk_fma_f32 v[8:9], s[28:29], v[20:21], v[8:9] op_sel_hi:[0,1,1]
	v_cvt_scalef32_pk_f32_fp4 v[20:21], v60, 1.0 op_sel:[1,1,0]
	v_pk_fma_f32 v[10:11], s[28:29], v[20:21], v[10:11] op_sel_hi:[0,1,1]
	v_cvt_scalef32_pk_f32_fp4 v[20:21], v61, 1.0
	v_pk_fma_f32 v[12:13], s[28:29], v[20:21], v[12:13] op_sel_hi:[0,1,1]
	v_cvt_scalef32_pk_f32_fp4 v[20:21], v61, 1.0 op_sel:[1,0,0]
	v_pk_fma_f32 v[14:15], s[28:29], v[20:21], v[14:15] op_sel_hi:[0,1,1]
	v_cvt_scalef32_pk_f32_fp4 v[20:21], v61, 1.0 op_sel:[0,1,0]
	v_pk_fma_f32 v[16:17], s[28:29], v[20:21], v[16:17] op_sel_hi:[0,1,1]
	v_cvt_scalef32_pk_f32_fp4 v[20:21], v61, 1.0 op_sel:[1,1,0]
	v_pk_fma_f32 v[18:19], s[28:29], v[20:21], v[18:19] op_sel_hi:[0,1,1]
	v_readlane_b32 s28, v127, 45
	s_waitcnt vmcnt(20)
	v_cvt_scalef32_pk_f32_fp4 v[20:21], v62, 1.0
	v_pk_fma_f32 v[4:5], v[20:21], s[28:29], v[4:5] op_sel_hi:[1,0,1]
	v_cvt_scalef32_pk_f32_fp4 v[20:21], v62, 1.0 op_sel:[1,0,0]
	v_pk_fma_f32 v[6:7], s[28:29], v[20:21], v[6:7] op_sel_hi:[0,1,1]
	v_cvt_scalef32_pk_f32_fp4 v[20:21], v62, 1.0 op_sel:[0,1,0]
	v_pk_fma_f32 v[8:9], s[28:29], v[20:21], v[8:9] op_sel_hi:[0,1,1]
	v_cvt_scalef32_pk_f32_fp4 v[20:21], v62, 1.0 op_sel:[1,1,0]
	v_pk_fma_f32 v[10:11], s[28:29], v[20:21], v[10:11] op_sel_hi:[0,1,1]
	v_cvt_scalef32_pk_f32_fp4 v[20:21], v63, 1.0
	v_pk_fma_f32 v[12:13], s[28:29], v[20:21], v[12:13] op_sel_hi:[0,1,1]
	v_cvt_scalef32_pk_f32_fp4 v[20:21], v63, 1.0 op_sel:[1,0,0]
	v_pk_fma_f32 v[14:15], s[28:29], v[20:21], v[14:15] op_sel_hi:[0,1,1]
	v_cvt_scalef32_pk_f32_fp4 v[20:21], v63, 1.0 op_sel:[0,1,0]
	v_pk_fma_f32 v[16:17], s[28:29], v[20:21], v[16:17] op_sel_hi:[0,1,1]
	v_cvt_scalef32_pk_f32_fp4 v[20:21], v63, 1.0 op_sel:[1,1,0]
	v_pk_fma_f32 v[18:19], s[28:29], v[20:21], v[18:19] op_sel_hi:[0,1,1]
	s_waitcnt vmcnt(19)
	v_cvt_scalef32_pk_f32_fp4 v[20:21], v64, 1.0
	v_pk_fma_f32 v[4:5], v[20:21], s[2:3], v[4:5] op_sel_hi:[1,0,1]
	v_cvt_scalef32_pk_f32_fp4 v[20:21], v64, 1.0 op_sel:[1,0,0]
	v_pk_fma_f32 v[6:7], s[2:3], v[20:21], v[6:7] op_sel_hi:[0,1,1]
	v_cvt_scalef32_pk_f32_fp4 v[20:21], v64, 1.0 op_sel:[0,1,0]
	v_pk_fma_f32 v[8:9], s[2:3], v[20:21], v[8:9] op_sel_hi:[0,1,1]
	v_cvt_scalef32_pk_f32_fp4 v[20:21], v64, 1.0 op_sel:[1,1,0]
	v_pk_fma_f32 v[10:11], s[2:3], v[20:21], v[10:11] op_sel_hi:[0,1,1]
	v_cvt_scalef32_pk_f32_fp4 v[20:21], v65, 1.0
	v_pk_fma_f32 v[12:13], s[2:3], v[20:21], v[12:13] op_sel_hi:[0,1,1]
	v_cvt_scalef32_pk_f32_fp4 v[20:21], v65, 1.0 op_sel:[1,0,0]
	v_pk_fma_f32 v[14:15], s[2:3], v[20:21], v[14:15] op_sel_hi:[0,1,1]
	v_cvt_scalef32_pk_f32_fp4 v[20:21], v65, 1.0 op_sel:[0,1,0]
	v_pk_fma_f32 v[16:17], s[2:3], v[20:21], v[16:17] op_sel_hi:[0,1,1]
	v_cvt_scalef32_pk_f32_fp4 v[20:21], v65, 1.0 op_sel:[1,1,0]
	v_pk_fma_f32 v[18:19], s[2:3], v[20:21], v[18:19] op_sel_hi:[0,1,1]
	v_readlane_b32 s2, v127, 43
	s_waitcnt vmcnt(18)
	v_cvt_scalef32_pk_f32_fp4 v[20:21], v66, 1.0
	v_pk_fma_f32 v[4:5], v[20:21], s[2:3], v[4:5] op_sel_hi:[1,0,1]
	v_cvt_scalef32_pk_f32_fp4 v[20:21], v66, 1.0 op_sel:[1,0,0]
	v_pk_fma_f32 v[6:7], s[2:3], v[20:21], v[6:7] op_sel_hi:[0,1,1]
	v_cvt_scalef32_pk_f32_fp4 v[20:21], v66, 1.0 op_sel:[0,1,0]
	v_pk_fma_f32 v[8:9], s[2:3], v[20:21], v[8:9] op_sel_hi:[0,1,1]
	v_cvt_scalef32_pk_f32_fp4 v[20:21], v66, 1.0 op_sel:[1,1,0]
	v_pk_fma_f32 v[10:11], s[2:3], v[20:21], v[10:11] op_sel_hi:[0,1,1]
	v_cvt_scalef32_pk_f32_fp4 v[20:21], v67, 1.0
	v_pk_fma_f32 v[12:13], s[2:3], v[20:21], v[12:13] op_sel_hi:[0,1,1]
	v_cvt_scalef32_pk_f32_fp4 v[20:21], v67, 1.0 op_sel:[1,0,0]
	v_pk_fma_f32 v[14:15], s[2:3], v[20:21], v[14:15] op_sel_hi:[0,1,1]
	v_cvt_scalef32_pk_f32_fp4 v[20:21], v67, 1.0 op_sel:[0,1,0]
	v_pk_fma_f32 v[16:17], s[2:3], v[20:21], v[16:17] op_sel_hi:[0,1,1]
	v_cvt_scalef32_pk_f32_fp4 v[20:21], v67, 1.0 op_sel:[1,1,0]
	v_pk_fma_f32 v[18:19], s[2:3], v[20:21], v[18:19] op_sel_hi:[0,1,1]
	v_readlane_b32 s2, v127, 39
	s_waitcnt vmcnt(17)
	v_cvt_scalef32_pk_f32_fp4 v[20:21], v68, 1.0
	v_pk_fma_f32 v[4:5], v[20:21], s[2:3], v[4:5] op_sel_hi:[1,0,1]
	v_cvt_scalef32_pk_f32_fp4 v[20:21], v68, 1.0 op_sel:[1,0,0]
	v_pk_fma_f32 v[6:7], s[2:3], v[20:21], v[6:7] op_sel_hi:[0,1,1]
	v_cvt_scalef32_pk_f32_fp4 v[20:21], v68, 1.0 op_sel:[0,1,0]
	v_pk_fma_f32 v[8:9], s[2:3], v[20:21], v[8:9] op_sel_hi:[0,1,1]
	v_cvt_scalef32_pk_f32_fp4 v[20:21], v68, 1.0 op_sel:[1,1,0]
	v_pk_fma_f32 v[10:11], s[2:3], v[20:21], v[10:11] op_sel_hi:[0,1,1]
	v_cvt_scalef32_pk_f32_fp4 v[20:21], v69, 1.0
	v_pk_fma_f32 v[12:13], s[2:3], v[20:21], v[12:13] op_sel_hi:[0,1,1]
	v_cvt_scalef32_pk_f32_fp4 v[20:21], v69, 1.0 op_sel:[1,0,0]
	v_pk_fma_f32 v[14:15], s[2:3], v[20:21], v[14:15] op_sel_hi:[0,1,1]
	v_cvt_scalef32_pk_f32_fp4 v[20:21], v69, 1.0 op_sel:[0,1,0]
	v_pk_fma_f32 v[16:17], s[2:3], v[20:21], v[16:17] op_sel_hi:[0,1,1]
	v_cvt_scalef32_pk_f32_fp4 v[20:21], v69, 1.0 op_sel:[1,1,0]
	v_pk_fma_f32 v[18:19], s[2:3], v[20:21], v[18:19] op_sel_hi:[0,1,1]
	v_readlane_b32 s2, v127, 47
	s_waitcnt vmcnt(16)
	v_cvt_scalef32_pk_f32_fp4 v[20:21], v70, 1.0
	v_pk_fma_f32 v[4:5], v[20:21], s[2:3], v[4:5] op_sel_hi:[1,0,1]
	v_cvt_scalef32_pk_f32_fp4 v[20:21], v70, 1.0 op_sel:[1,0,0]
	v_pk_fma_f32 v[6:7], s[2:3], v[20:21], v[6:7] op_sel_hi:[0,1,1]
	v_cvt_scalef32_pk_f32_fp4 v[20:21], v70, 1.0 op_sel:[0,1,0]
	v_pk_fma_f32 v[8:9], s[2:3], v[20:21], v[8:9] op_sel_hi:[0,1,1]
	v_cvt_scalef32_pk_f32_fp4 v[20:21], v70, 1.0 op_sel:[1,1,0]
	v_pk_fma_f32 v[10:11], s[2:3], v[20:21], v[10:11] op_sel_hi:[0,1,1]
	v_cvt_scalef32_pk_f32_fp4 v[20:21], v71, 1.0
	v_pk_fma_f32 v[12:13], s[2:3], v[20:21], v[12:13] op_sel_hi:[0,1,1]
	v_cvt_scalef32_pk_f32_fp4 v[20:21], v71, 1.0 op_sel:[1,0,0]
	v_pk_fma_f32 v[14:15], s[2:3], v[20:21], v[14:15] op_sel_hi:[0,1,1]
	v_cvt_scalef32_pk_f32_fp4 v[20:21], v71, 1.0 op_sel:[0,1,0]
	v_pk_fma_f32 v[16:17], s[2:3], v[20:21], v[16:17] op_sel_hi:[0,1,1]
	v_cvt_scalef32_pk_f32_fp4 v[20:21], v71, 1.0 op_sel:[1,1,0]
	v_pk_fma_f32 v[18:19], s[2:3], v[20:21], v[18:19] op_sel_hi:[0,1,1]
	v_readlane_b32 s2, v127, 48
	s_waitcnt vmcnt(15)
	v_cvt_scalef32_pk_f32_fp4 v[20:21], v72, 1.0
	v_pk_fma_f32 v[4:5], v[20:21], s[2:3], v[4:5] op_sel_hi:[1,0,1]
	v_cvt_scalef32_pk_f32_fp4 v[20:21], v72, 1.0 op_sel:[1,0,0]
	v_pk_fma_f32 v[6:7], s[2:3], v[20:21], v[6:7] op_sel_hi:[0,1,1]
	v_cvt_scalef32_pk_f32_fp4 v[20:21], v72, 1.0 op_sel:[0,1,0]
	v_pk_fma_f32 v[8:9], s[2:3], v[20:21], v[8:9] op_sel_hi:[0,1,1]
	v_cvt_scalef32_pk_f32_fp4 v[20:21], v72, 1.0 op_sel:[1,1,0]
	v_pk_fma_f32 v[10:11], s[2:3], v[20:21], v[10:11] op_sel_hi:[0,1,1]
	v_cvt_scalef32_pk_f32_fp4 v[20:21], v73, 1.0
	v_pk_fma_f32 v[12:13], s[2:3], v[20:21], v[12:13] op_sel_hi:[0,1,1]
	v_cvt_scalef32_pk_f32_fp4 v[20:21], v73, 1.0 op_sel:[1,0,0]
	v_pk_fma_f32 v[14:15], s[2:3], v[20:21], v[14:15] op_sel_hi:[0,1,1]
	v_cvt_scalef32_pk_f32_fp4 v[20:21], v73, 1.0 op_sel:[0,1,0]
	v_pk_fma_f32 v[16:17], s[2:3], v[20:21], v[16:17] op_sel_hi:[0,1,1]
	v_cvt_scalef32_pk_f32_fp4 v[20:21], v73, 1.0 op_sel:[1,1,0]
	v_pk_fma_f32 v[18:19], s[2:3], v[20:21], v[18:19] op_sel_hi:[0,1,1]
	v_readlane_b32 s2, v127, 56
	s_waitcnt vmcnt(14)
	v_cvt_scalef32_pk_f32_fp4 v[20:21], v74, 1.0
	v_pk_fma_f32 v[4:5], v[20:21], s[2:3], v[4:5] op_sel_hi:[1,0,1]
	v_cvt_scalef32_pk_f32_fp4 v[20:21], v74, 1.0 op_sel:[1,0,0]
	v_pk_fma_f32 v[6:7], s[2:3], v[20:21], v[6:7] op_sel_hi:[0,1,1]
	v_cvt_scalef32_pk_f32_fp4 v[20:21], v74, 1.0 op_sel:[0,1,0]
	v_pk_fma_f32 v[8:9], s[2:3], v[20:21], v[8:9] op_sel_hi:[0,1,1]
	v_cvt_scalef32_pk_f32_fp4 v[20:21], v74, 1.0 op_sel:[1,1,0]
	v_pk_fma_f32 v[10:11], s[2:3], v[20:21], v[10:11] op_sel_hi:[0,1,1]
	v_cvt_scalef32_pk_f32_fp4 v[20:21], v75, 1.0
	v_pk_fma_f32 v[12:13], s[2:3], v[20:21], v[12:13] op_sel_hi:[0,1,1]
	v_cvt_scalef32_pk_f32_fp4 v[20:21], v75, 1.0 op_sel:[1,0,0]
	v_pk_fma_f32 v[14:15], s[2:3], v[20:21], v[14:15] op_sel_hi:[0,1,1]
	v_cvt_scalef32_pk_f32_fp4 v[20:21], v75, 1.0 op_sel:[0,1,0]
	v_pk_fma_f32 v[16:17], s[2:3], v[20:21], v[16:17] op_sel_hi:[0,1,1]
	v_cvt_scalef32_pk_f32_fp4 v[20:21], v75, 1.0 op_sel:[1,1,0]
	v_pk_fma_f32 v[18:19], s[2:3], v[20:21], v[18:19] op_sel_hi:[0,1,1]
	v_readlane_b32 s2, v127, 52
	s_waitcnt vmcnt(13)
	v_cvt_scalef32_pk_f32_fp4 v[20:21], v76, 1.0
	v_pk_fma_f32 v[4:5], v[20:21], s[2:3], v[4:5] op_sel_hi:[1,0,1]
	v_cvt_scalef32_pk_f32_fp4 v[20:21], v76, 1.0 op_sel:[1,0,0]
	v_pk_fma_f32 v[6:7], s[2:3], v[20:21], v[6:7] op_sel_hi:[0,1,1]
	v_cvt_scalef32_pk_f32_fp4 v[20:21], v76, 1.0 op_sel:[0,1,0]
	v_pk_fma_f32 v[8:9], s[2:3], v[20:21], v[8:9] op_sel_hi:[0,1,1]
	v_cvt_scalef32_pk_f32_fp4 v[20:21], v76, 1.0 op_sel:[1,1,0]
	v_pk_fma_f32 v[10:11], s[2:3], v[20:21], v[10:11] op_sel_hi:[0,1,1]
	v_cvt_scalef32_pk_f32_fp4 v[20:21], v77, 1.0
	v_pk_fma_f32 v[12:13], s[2:3], v[20:21], v[12:13] op_sel_hi:[0,1,1]
	v_cvt_scalef32_pk_f32_fp4 v[20:21], v77, 1.0 op_sel:[1,0,0]
	v_pk_fma_f32 v[14:15], s[2:3], v[20:21], v[14:15] op_sel_hi:[0,1,1]
	v_cvt_scalef32_pk_f32_fp4 v[20:21], v77, 1.0 op_sel:[0,1,0]
	v_pk_fma_f32 v[16:17], s[2:3], v[20:21], v[16:17] op_sel_hi:[0,1,1]
	v_cvt_scalef32_pk_f32_fp4 v[20:21], v77, 1.0 op_sel:[1,1,0]
	v_pk_fma_f32 v[18:19], s[2:3], v[20:21], v[18:19] op_sel_hi:[0,1,1]
	v_readlane_b32 s2, v127, 60
	s_waitcnt vmcnt(12)
	v_cvt_scalef32_pk_f32_fp4 v[20:21], v78, 1.0
	v_pk_fma_f32 v[4:5], v[20:21], s[2:3], v[4:5] op_sel_hi:[1,0,1]
	v_cvt_scalef32_pk_f32_fp4 v[20:21], v78, 1.0 op_sel:[1,0,0]
	v_pk_fma_f32 v[6:7], s[2:3], v[20:21], v[6:7] op_sel_hi:[0,1,1]
	v_cvt_scalef32_pk_f32_fp4 v[20:21], v78, 1.0 op_sel:[0,1,0]
	v_pk_fma_f32 v[8:9], s[2:3], v[20:21], v[8:9] op_sel_hi:[0,1,1]
	v_cvt_scalef32_pk_f32_fp4 v[20:21], v78, 1.0 op_sel:[1,1,0]
	v_pk_fma_f32 v[10:11], s[2:3], v[20:21], v[10:11] op_sel_hi:[0,1,1]
	v_cvt_scalef32_pk_f32_fp4 v[20:21], v79, 1.0
	v_pk_fma_f32 v[12:13], s[2:3], v[20:21], v[12:13] op_sel_hi:[0,1,1]
	v_cvt_scalef32_pk_f32_fp4 v[20:21], v79, 1.0 op_sel:[1,0,0]
	v_pk_fma_f32 v[14:15], s[2:3], v[20:21], v[14:15] op_sel_hi:[0,1,1]
	v_cvt_scalef32_pk_f32_fp4 v[20:21], v79, 1.0 op_sel:[0,1,0]
	v_pk_fma_f32 v[16:17], s[2:3], v[20:21], v[16:17] op_sel_hi:[0,1,1]
	v_cvt_scalef32_pk_f32_fp4 v[20:21], v79, 1.0 op_sel:[1,1,0]
	v_pk_fma_f32 v[18:19], s[2:3], v[20:21], v[18:19] op_sel_hi:[0,1,1]
	v_readlane_b32 s2, v127, 50
	s_waitcnt vmcnt(11)
	v_cvt_scalef32_pk_f32_fp4 v[20:21], v80, 1.0
	v_pk_fma_f32 v[4:5], v[20:21], s[2:3], v[4:5] op_sel_hi:[1,0,1]
	v_cvt_scalef32_pk_f32_fp4 v[20:21], v80, 1.0 op_sel:[1,0,0]
	v_pk_fma_f32 v[6:7], s[2:3], v[20:21], v[6:7] op_sel_hi:[0,1,1]
	v_cvt_scalef32_pk_f32_fp4 v[20:21], v80, 1.0 op_sel:[0,1,0]
	v_pk_fma_f32 v[8:9], s[2:3], v[20:21], v[8:9] op_sel_hi:[0,1,1]
	v_cvt_scalef32_pk_f32_fp4 v[20:21], v80, 1.0 op_sel:[1,1,0]
	v_pk_fma_f32 v[10:11], s[2:3], v[20:21], v[10:11] op_sel_hi:[0,1,1]
	v_cvt_scalef32_pk_f32_fp4 v[20:21], v81, 1.0
	v_pk_fma_f32 v[12:13], s[2:3], v[20:21], v[12:13] op_sel_hi:[0,1,1]
	v_cvt_scalef32_pk_f32_fp4 v[20:21], v81, 1.0 op_sel:[1,0,0]
	v_pk_fma_f32 v[14:15], s[2:3], v[20:21], v[14:15] op_sel_hi:[0,1,1]
	v_cvt_scalef32_pk_f32_fp4 v[20:21], v81, 1.0 op_sel:[0,1,0]
	v_pk_fma_f32 v[16:17], s[2:3], v[20:21], v[16:17] op_sel_hi:[0,1,1]
	v_cvt_scalef32_pk_f32_fp4 v[20:21], v81, 1.0 op_sel:[1,1,0]
	v_pk_fma_f32 v[18:19], s[2:3], v[20:21], v[18:19] op_sel_hi:[0,1,1]
	v_readlane_b32 s2, v127, 58
	s_waitcnt vmcnt(10)
	v_cvt_scalef32_pk_f32_fp4 v[20:21], v82, 1.0
	v_pk_fma_f32 v[4:5], v[20:21], s[2:3], v[4:5] op_sel_hi:[1,0,1]
	v_cvt_scalef32_pk_f32_fp4 v[20:21], v82, 1.0 op_sel:[1,0,0]
	v_pk_fma_f32 v[6:7], s[2:3], v[20:21], v[6:7] op_sel_hi:[0,1,1]
	v_cvt_scalef32_pk_f32_fp4 v[20:21], v82, 1.0 op_sel:[0,1,0]
	v_pk_fma_f32 v[8:9], s[2:3], v[20:21], v[8:9] op_sel_hi:[0,1,1]
	v_cvt_scalef32_pk_f32_fp4 v[20:21], v82, 1.0 op_sel:[1,1,0]
	v_pk_fma_f32 v[10:11], s[2:3], v[20:21], v[10:11] op_sel_hi:[0,1,1]
	v_cvt_scalef32_pk_f32_fp4 v[20:21], v83, 1.0
	v_pk_fma_f32 v[12:13], s[2:3], v[20:21], v[12:13] op_sel_hi:[0,1,1]
	v_cvt_scalef32_pk_f32_fp4 v[20:21], v83, 1.0 op_sel:[1,0,0]
	v_pk_fma_f32 v[14:15], s[2:3], v[20:21], v[14:15] op_sel_hi:[0,1,1]
	v_cvt_scalef32_pk_f32_fp4 v[20:21], v83, 1.0 op_sel:[0,1,0]
	v_pk_fma_f32 v[16:17], s[2:3], v[20:21], v[16:17] op_sel_hi:[0,1,1]
	v_cvt_scalef32_pk_f32_fp4 v[20:21], v83, 1.0 op_sel:[1,1,0]
	v_pk_fma_f32 v[18:19], s[2:3], v[20:21], v[18:19] op_sel_hi:[0,1,1]
	v_readlane_b32 s2, v127, 54
	s_waitcnt vmcnt(9)
	v_cvt_scalef32_pk_f32_fp4 v[20:21], v84, 1.0
	v_pk_fma_f32 v[4:5], v[20:21], s[2:3], v[4:5] op_sel_hi:[1,0,1]
	v_cvt_scalef32_pk_f32_fp4 v[20:21], v84, 1.0 op_sel:[1,0,0]
	v_pk_fma_f32 v[6:7], s[2:3], v[20:21], v[6:7] op_sel_hi:[0,1,1]
	v_cvt_scalef32_pk_f32_fp4 v[20:21], v84, 1.0 op_sel:[0,1,0]
	v_pk_fma_f32 v[8:9], s[2:3], v[20:21], v[8:9] op_sel_hi:[0,1,1]
	v_cvt_scalef32_pk_f32_fp4 v[20:21], v84, 1.0 op_sel:[1,1,0]
	v_pk_fma_f32 v[10:11], s[2:3], v[20:21], v[10:11] op_sel_hi:[0,1,1]
	v_cvt_scalef32_pk_f32_fp4 v[20:21], v85, 1.0
	v_pk_fma_f32 v[12:13], s[2:3], v[20:21], v[12:13] op_sel_hi:[0,1,1]
	v_cvt_scalef32_pk_f32_fp4 v[20:21], v85, 1.0 op_sel:[1,0,0]
	v_pk_fma_f32 v[14:15], s[2:3], v[20:21], v[14:15] op_sel_hi:[0,1,1]
	v_cvt_scalef32_pk_f32_fp4 v[20:21], v85, 1.0 op_sel:[0,1,0]
	v_pk_fma_f32 v[16:17], s[2:3], v[20:21], v[16:17] op_sel_hi:[0,1,1]
	v_cvt_scalef32_pk_f32_fp4 v[20:21], v85, 1.0 op_sel:[1,1,0]
	v_pk_fma_f32 v[18:19], s[2:3], v[20:21], v[18:19] op_sel_hi:[0,1,1]
	v_readlane_b32 s2, v127, 62
	s_waitcnt vmcnt(8)
	v_cvt_scalef32_pk_f32_fp4 v[20:21], v86, 1.0
	v_pk_fma_f32 v[4:5], v[20:21], s[2:3], v[4:5] op_sel_hi:[1,0,1]
	v_cvt_scalef32_pk_f32_fp4 v[20:21], v86, 1.0 op_sel:[1,0,0]
	v_pk_fma_f32 v[6:7], s[2:3], v[20:21], v[6:7] op_sel_hi:[0,1,1]
	v_cvt_scalef32_pk_f32_fp4 v[20:21], v86, 1.0 op_sel:[0,1,0]
	v_pk_fma_f32 v[8:9], s[2:3], v[20:21], v[8:9] op_sel_hi:[0,1,1]
	v_cvt_scalef32_pk_f32_fp4 v[20:21], v86, 1.0 op_sel:[1,1,0]
	v_pk_fma_f32 v[10:11], s[2:3], v[20:21], v[10:11] op_sel_hi:[0,1,1]
	v_cvt_scalef32_pk_f32_fp4 v[20:21], v87, 1.0
	v_pk_fma_f32 v[12:13], s[2:3], v[20:21], v[12:13] op_sel_hi:[0,1,1]
	v_cvt_scalef32_pk_f32_fp4 v[20:21], v87, 1.0 op_sel:[1,0,0]
	v_pk_fma_f32 v[14:15], s[2:3], v[20:21], v[14:15] op_sel_hi:[0,1,1]
	v_cvt_scalef32_pk_f32_fp4 v[20:21], v87, 1.0 op_sel:[0,1,0]
	v_pk_fma_f32 v[16:17], s[2:3], v[20:21], v[16:17] op_sel_hi:[0,1,1]
	v_cvt_scalef32_pk_f32_fp4 v[20:21], v87, 1.0 op_sel:[1,1,0]
	v_pk_fma_f32 v[18:19], s[2:3], v[20:21], v[18:19] op_sel_hi:[0,1,1]
	s_waitcnt vmcnt(7)
	v_cvt_scalef32_pk_f32_fp4 v[20:21], v88, 1.0
	s_nop 1
	v_readlane_b32 s2, v127, 49
	s_nop 1
	v_pk_fma_f32 v[4:5], v[20:21], s[2:3], v[4:5] op_sel_hi:[1,0,1]
	v_cvt_scalef32_pk_f32_fp4 v[20:21], v88, 1.0 op_sel:[1,0,0]
	v_pk_fma_f32 v[6:7], s[2:3], v[20:21], v[6:7] op_sel_hi:[0,1,1]
	v_cvt_scalef32_pk_f32_fp4 v[20:21], v88, 1.0 op_sel:[0,1,0]
	v_pk_fma_f32 v[8:9], s[2:3], v[20:21], v[8:9] op_sel_hi:[0,1,1]
	v_cvt_scalef32_pk_f32_fp4 v[20:21], v88, 1.0 op_sel:[1,1,0]
	v_pk_fma_f32 v[10:11], s[2:3], v[20:21], v[10:11] op_sel_hi:[0,1,1]
	v_cvt_scalef32_pk_f32_fp4 v[20:21], v89, 1.0
	v_pk_fma_f32 v[12:13], s[2:3], v[20:21], v[12:13] op_sel_hi:[0,1,1]
	v_cvt_scalef32_pk_f32_fp4 v[20:21], v89, 1.0 op_sel:[1,0,0]
	v_pk_fma_f32 v[14:15], s[2:3], v[20:21], v[14:15] op_sel_hi:[0,1,1]
	v_cvt_scalef32_pk_f32_fp4 v[20:21], v89, 1.0 op_sel:[0,1,0]
	v_pk_fma_f32 v[16:17], s[2:3], v[20:21], v[16:17] op_sel_hi:[0,1,1]
	v_cvt_scalef32_pk_f32_fp4 v[20:21], v89, 1.0 op_sel:[1,1,0]
	v_pk_fma_f32 v[18:19], s[2:3], v[20:21], v[18:19] op_sel_hi:[0,1,1]
	s_waitcnt vmcnt(6)
	v_cvt_scalef32_pk_f32_fp4 v[20:21], v90, 1.0
	s_nop 1
	v_readlane_b32 s2, v127, 57
	s_nop 1
	v_pk_fma_f32 v[4:5], v[20:21], s[2:3], v[4:5] op_sel_hi:[1,0,1]
	v_cvt_scalef32_pk_f32_fp4 v[20:21], v90, 1.0 op_sel:[1,0,0]
	v_pk_fma_f32 v[6:7], s[2:3], v[20:21], v[6:7] op_sel_hi:[0,1,1]
	v_cvt_scalef32_pk_f32_fp4 v[20:21], v90, 1.0 op_sel:[0,1,0]
	v_pk_fma_f32 v[8:9], s[2:3], v[20:21], v[8:9] op_sel_hi:[0,1,1]
	v_cvt_scalef32_pk_f32_fp4 v[20:21], v90, 1.0 op_sel:[1,1,0]
	v_pk_fma_f32 v[10:11], s[2:3], v[20:21], v[10:11] op_sel_hi:[0,1,1]
	v_cvt_scalef32_pk_f32_fp4 v[20:21], v91, 1.0
	v_pk_fma_f32 v[12:13], s[2:3], v[20:21], v[12:13] op_sel_hi:[0,1,1]
	v_cvt_scalef32_pk_f32_fp4 v[20:21], v91, 1.0 op_sel:[1,0,0]
	v_pk_fma_f32 v[14:15], s[2:3], v[20:21], v[14:15] op_sel_hi:[0,1,1]
	v_cvt_scalef32_pk_f32_fp4 v[20:21], v91, 1.0 op_sel:[0,1,0]
	v_pk_fma_f32 v[16:17], s[2:3], v[20:21], v[16:17] op_sel_hi:[0,1,1]
	v_cvt_scalef32_pk_f32_fp4 v[20:21], v91, 1.0 op_sel:[1,1,0]
	v_pk_fma_f32 v[18:19], s[2:3], v[20:21], v[18:19] op_sel_hi:[0,1,1]
	s_waitcnt vmcnt(5)
	v_cvt_scalef32_pk_f32_fp4 v[20:21], v92, 1.0
	s_nop 1
	v_readlane_b32 s2, v127, 53
	s_nop 1
	v_pk_fma_f32 v[4:5], v[20:21], s[2:3], v[4:5] op_sel_hi:[1,0,1]
	v_cvt_scalef32_pk_f32_fp4 v[20:21], v92, 1.0 op_sel:[1,0,0]
	v_pk_fma_f32 v[6:7], s[2:3], v[20:21], v[6:7] op_sel_hi:[0,1,1]
	v_cvt_scalef32_pk_f32_fp4 v[20:21], v92, 1.0 op_sel:[0,1,0]
	v_pk_fma_f32 v[8:9], s[2:3], v[20:21], v[8:9] op_sel_hi:[0,1,1]
	v_cvt_scalef32_pk_f32_fp4 v[20:21], v92, 1.0 op_sel:[1,1,0]
	v_pk_fma_f32 v[10:11], s[2:3], v[20:21], v[10:11] op_sel_hi:[0,1,1]
	v_cvt_scalef32_pk_f32_fp4 v[20:21], v93, 1.0
	v_pk_fma_f32 v[12:13], s[2:3], v[20:21], v[12:13] op_sel_hi:[0,1,1]
	v_cvt_scalef32_pk_f32_fp4 v[20:21], v93, 1.0 op_sel:[1,0,0]
	v_pk_fma_f32 v[14:15], s[2:3], v[20:21], v[14:15] op_sel_hi:[0,1,1]
	v_cvt_scalef32_pk_f32_fp4 v[20:21], v93, 1.0 op_sel:[0,1,0]
	v_pk_fma_f32 v[16:17], s[2:3], v[20:21], v[16:17] op_sel_hi:[0,1,1]
	v_cvt_scalef32_pk_f32_fp4 v[20:21], v93, 1.0 op_sel:[1,1,0]
	v_pk_fma_f32 v[18:19], s[2:3], v[20:21], v[18:19] op_sel_hi:[0,1,1]
	s_waitcnt vmcnt(4)
	v_cvt_scalef32_pk_f32_fp4 v[20:21], v94, 1.0
	s_nop 1
	v_readlane_b32 s2, v127, 61
	s_nop 1
	v_pk_fma_f32 v[4:5], v[20:21], s[2:3], v[4:5] op_sel_hi:[1,0,1]
	v_cvt_scalef32_pk_f32_fp4 v[20:21], v94, 1.0 op_sel:[1,0,0]
	v_pk_fma_f32 v[6:7], s[2:3], v[20:21], v[6:7] op_sel_hi:[0,1,1]
	v_cvt_scalef32_pk_f32_fp4 v[20:21], v94, 1.0 op_sel:[0,1,0]
	v_pk_fma_f32 v[8:9], s[2:3], v[20:21], v[8:9] op_sel_hi:[0,1,1]
	v_cvt_scalef32_pk_f32_fp4 v[20:21], v94, 1.0 op_sel:[1,1,0]
	v_pk_fma_f32 v[10:11], s[2:3], v[20:21], v[10:11] op_sel_hi:[0,1,1]
	v_cvt_scalef32_pk_f32_fp4 v[20:21], v95, 1.0
	v_pk_fma_f32 v[12:13], s[2:3], v[20:21], v[12:13] op_sel_hi:[0,1,1]
	v_cvt_scalef32_pk_f32_fp4 v[20:21], v95, 1.0 op_sel:[1,0,0]
	v_pk_fma_f32 v[14:15], s[2:3], v[20:21], v[14:15] op_sel_hi:[0,1,1]
	v_cvt_scalef32_pk_f32_fp4 v[20:21], v95, 1.0 op_sel:[0,1,0]
	v_pk_fma_f32 v[16:17], s[2:3], v[20:21], v[16:17] op_sel_hi:[0,1,1]
	v_cvt_scalef32_pk_f32_fp4 v[20:21], v95, 1.0 op_sel:[1,1,0]
	v_pk_fma_f32 v[18:19], s[2:3], v[20:21], v[18:19] op_sel_hi:[0,1,1]
	s_waitcnt vmcnt(3)
	v_cvt_scalef32_pk_f32_fp4 v[20:21], v96, 1.0
	s_nop 1
	v_readlane_b32 s2, v127, 51
	s_nop 1
	v_pk_fma_f32 v[4:5], v[20:21], s[2:3], v[4:5] op_sel_hi:[1,0,1]
	v_cvt_scalef32_pk_f32_fp4 v[20:21], v96, 1.0 op_sel:[1,0,0]
	v_pk_fma_f32 v[6:7], s[2:3], v[20:21], v[6:7] op_sel_hi:[0,1,1]
	v_cvt_scalef32_pk_f32_fp4 v[20:21], v96, 1.0 op_sel:[0,1,0]
	v_pk_fma_f32 v[8:9], s[2:3], v[20:21], v[8:9] op_sel_hi:[0,1,1]
	v_cvt_scalef32_pk_f32_fp4 v[20:21], v96, 1.0 op_sel:[1,1,0]
	v_pk_fma_f32 v[10:11], s[2:3], v[20:21], v[10:11] op_sel_hi:[0,1,1]
	v_cvt_scalef32_pk_f32_fp4 v[20:21], v97, 1.0
	v_pk_fma_f32 v[12:13], s[2:3], v[20:21], v[12:13] op_sel_hi:[0,1,1]
	v_cvt_scalef32_pk_f32_fp4 v[20:21], v97, 1.0 op_sel:[1,0,0]
	v_pk_fma_f32 v[14:15], s[2:3], v[20:21], v[14:15] op_sel_hi:[0,1,1]
	v_cvt_scalef32_pk_f32_fp4 v[20:21], v97, 1.0 op_sel:[0,1,0]
	v_pk_fma_f32 v[16:17], s[2:3], v[20:21], v[16:17] op_sel_hi:[0,1,1]
	v_cvt_scalef32_pk_f32_fp4 v[20:21], v97, 1.0 op_sel:[1,1,0]
	v_pk_fma_f32 v[18:19], s[2:3], v[20:21], v[18:19] op_sel_hi:[0,1,1]
	s_waitcnt vmcnt(2)
	v_cvt_scalef32_pk_f32_fp4 v[20:21], v98, 1.0
	s_nop 1
	v_readlane_b32 s2, v127, 59
	s_nop 1
	v_pk_fma_f32 v[4:5], v[20:21], s[2:3], v[4:5] op_sel_hi:[1,0,1]
	v_cvt_scalef32_pk_f32_fp4 v[20:21], v98, 1.0 op_sel:[1,0,0]
	v_pk_fma_f32 v[6:7], s[2:3], v[20:21], v[6:7] op_sel_hi:[0,1,1]
	v_cvt_scalef32_pk_f32_fp4 v[20:21], v98, 1.0 op_sel:[0,1,0]
	v_pk_fma_f32 v[8:9], s[2:3], v[20:21], v[8:9] op_sel_hi:[0,1,1]
	v_cvt_scalef32_pk_f32_fp4 v[20:21], v98, 1.0 op_sel:[1,1,0]
	v_pk_fma_f32 v[10:11], s[2:3], v[20:21], v[10:11] op_sel_hi:[0,1,1]
	v_cvt_scalef32_pk_f32_fp4 v[20:21], v99, 1.0
	v_pk_fma_f32 v[12:13], s[2:3], v[20:21], v[12:13] op_sel_hi:[0,1,1]
	v_cvt_scalef32_pk_f32_fp4 v[20:21], v99, 1.0 op_sel:[1,0,0]
	v_pk_fma_f32 v[14:15], s[2:3], v[20:21], v[14:15] op_sel_hi:[0,1,1]
	v_cvt_scalef32_pk_f32_fp4 v[20:21], v99, 1.0 op_sel:[0,1,0]
	v_pk_fma_f32 v[16:17], s[2:3], v[20:21], v[16:17] op_sel_hi:[0,1,1]
	v_cvt_scalef32_pk_f32_fp4 v[20:21], v99, 1.0 op_sel:[1,1,0]
	v_pk_fma_f32 v[18:19], s[2:3], v[20:21], v[18:19] op_sel_hi:[0,1,1]
	s_waitcnt vmcnt(1)
	v_cvt_scalef32_pk_f32_fp4 v[20:21], v100, 1.0
	s_nop 1
	v_readlane_b32 s2, v127, 55
	s_nop 1
	v_pk_fma_f32 v[4:5], v[20:21], s[2:3], v[4:5] op_sel_hi:[1,0,1]
	v_cvt_scalef32_pk_f32_fp4 v[20:21], v100, 1.0 op_sel:[1,0,0]
	v_pk_fma_f32 v[6:7], s[2:3], v[20:21], v[6:7] op_sel_hi:[0,1,1]
	v_cvt_scalef32_pk_f32_fp4 v[20:21], v100, 1.0 op_sel:[0,1,0]
	v_pk_fma_f32 v[8:9], s[2:3], v[20:21], v[8:9] op_sel_hi:[0,1,1]
	v_cvt_scalef32_pk_f32_fp4 v[20:21], v100, 1.0 op_sel:[1,1,0]
	v_pk_fma_f32 v[10:11], s[2:3], v[20:21], v[10:11] op_sel_hi:[0,1,1]
	v_cvt_scalef32_pk_f32_fp4 v[20:21], v101, 1.0
	v_pk_fma_f32 v[12:13], s[2:3], v[20:21], v[12:13] op_sel_hi:[0,1,1]
	v_cvt_scalef32_pk_f32_fp4 v[20:21], v101, 1.0 op_sel:[1,0,0]
	v_pk_fma_f32 v[14:15], s[2:3], v[20:21], v[14:15] op_sel_hi:[0,1,1]
	v_cvt_scalef32_pk_f32_fp4 v[20:21], v101, 1.0 op_sel:[0,1,0]
	v_pk_fma_f32 v[16:17], s[2:3], v[20:21], v[16:17] op_sel_hi:[0,1,1]
	v_cvt_scalef32_pk_f32_fp4 v[20:21], v101, 1.0 op_sel:[1,1,0]
	v_pk_fma_f32 v[18:19], s[2:3], v[20:21], v[18:19] op_sel_hi:[0,1,1]
	s_waitcnt vmcnt(0)
	v_cvt_scalef32_pk_f32_fp4 v[20:21], v102, 1.0
	s_nop 1
	v_readlane_b32 s2, v127, 63
	s_nop 1
	v_pk_fma_f32 v[4:5], v[20:21], s[2:3], v[4:5] op_sel_hi:[1,0,1]
	v_cvt_scalef32_pk_f32_fp4 v[20:21], v102, 1.0 op_sel:[1,0,0]
	v_pk_fma_f32 v[6:7], s[2:3], v[20:21], v[6:7] op_sel_hi:[0,1,1]
	v_cvt_scalef32_pk_f32_fp4 v[20:21], v102, 1.0 op_sel:[0,1,0]
	v_pk_fma_f32 v[8:9], s[2:3], v[20:21], v[8:9] op_sel_hi:[0,1,1]
	v_cvt_scalef32_pk_f32_fp4 v[20:21], v102, 1.0 op_sel:[1,1,0]
	v_pk_fma_f32 v[10:11], s[2:3], v[20:21], v[10:11] op_sel_hi:[0,1,1]
	v_cvt_scalef32_pk_f32_fp4 v[20:21], v103, 1.0
	v_pk_fma_f32 v[12:13], s[2:3], v[20:21], v[12:13] op_sel_hi:[0,1,1]
	v_cvt_scalef32_pk_f32_fp4 v[20:21], v103, 1.0 op_sel:[1,0,0]
	v_pk_fma_f32 v[14:15], s[2:3], v[20:21], v[14:15] op_sel_hi:[0,1,1]
	v_cvt_scalef32_pk_f32_fp4 v[20:21], v103, 1.0 op_sel:[0,1,0]
	v_pk_fma_f32 v[16:17], s[2:3], v[20:21], v[16:17] op_sel_hi:[0,1,1]
	v_cvt_scalef32_pk_f32_fp4 v[20:21], v103, 1.0 op_sel:[1,1,0]
	v_pk_fma_f32 v[18:19], s[2:3], v[20:21], v[18:19] op_sel_hi:[0,1,1]

.LBB0_3301:
	v_cmp_gt_u32_e64 s[10:11], 64, v126
	s_nop 1
	v_cndmask_b32_e64 v70, v117, v53, s[10:11]
	v_readfirstlane_b32 s92, v126
	v_readfirstlane_b32 s93, v36
	v_readfirstlane_b32 s94, v37
	s_nop 1
	v_subrev_u32_e32 v255, s93, v36
	s_nop 1
	s_and_b32 s92, s92, 32
	s_cbranch_scc1 .Lh2_u19_hi
	v_readlane_b32 s84, v70, 0
	v_readlane_b32 s86, v70, 1
	v_readlane_b32 s88, v70, 2
	v_readlane_b32 s90, v70, 3
	s_lshl_b32 s84, s84, 9
	s_lshl_b32 s86, s86, 9
	s_lshl_b32 s88, s88, 9
	s_lshl_b32 s90, s90, 9
	s_add_u32 s84, s93, s84
	s_addc_u32 s85, s94, 0
	s_add_u32 s86, s93, s86
	s_addc_u32 s87, s94, 0
	s_add_u32 s88, s93, s88
	s_addc_u32 s89, s94, 0
	s_add_u32 s90, s93, s90
	s_addc_u32 s91, s94, 0
	global_load_dwordx2 v[72:73], v255, s[84:85]
	global_load_dwordx2 v[74:75], v255, s[86:87]
	global_load_dwordx2 v[76:77], v255, s[88:89]
	global_load_dwordx2 v[78:79], v255, s[90:91]
	v_readlane_b32 s84, v70, 4
	v_readlane_b32 s86, v70, 5
	v_readlane_b32 s88, v70, 6
	v_readlane_b32 s90, v70, 7
	s_lshl_b32 s84, s84, 9
	s_lshl_b32 s86, s86, 9
	s_lshl_b32 s88, s88, 9
	s_lshl_b32 s90, s90, 9
	s_add_u32 s84, s93, s84
	s_addc_u32 s85, s94, 0
	s_add_u32 s86, s93, s86
	s_addc_u32 s87, s94, 0
	s_add_u32 s88, s93, s88
	s_addc_u32 s89, s94, 0
	s_add_u32 s90, s93, s90
	s_addc_u32 s91, s94, 0
	global_load_dwordx2 v[80:81], v255, s[84:85]
	global_load_dwordx2 v[82:83], v255, s[86:87]
	global_load_dwordx2 v[84:85], v255, s[88:89]
	global_load_dwordx2 v[86:87], v255, s[90:91]
	v_readlane_b32 s84, v70, 8
	v_readlane_b32 s86, v70, 9
	v_readlane_b32 s88, v70, 10
	v_readlane_b32 s90, v70, 11
	s_lshl_b32 s84, s84, 9
	s_lshl_b32 s86, s86, 9
	s_lshl_b32 s88, s88, 9
	s_lshl_b32 s90, s90, 9
	s_add_u32 s84, s93, s84
	s_addc_u32 s85, s94, 0
	s_add_u32 s86, s93, s86
	s_addc_u32 s87, s94, 0
	s_add_u32 s88, s93, s88
	s_addc_u32 s89, s94, 0
	s_add_u32 s90, s93, s90
	s_addc_u32 s91, s94, 0
	global_load_dwordx2 v[88:89], v255, s[84:85]
	global_load_dwordx2 v[90:91], v255, s[86:87]
	global_load_dwordx2 v[92:93], v255, s[88:89]
	global_load_dwordx2 v[94:95], v255, s[90:91]
	v_readlane_b32 s84, v70, 12
	v_readlane_b32 s86, v70, 13
	v_readlane_b32 s88, v70, 14
	v_readlane_b32 s90, v70, 15
	s_lshl_b32 s84, s84, 9
	s_lshl_b32 s86, s86, 9
	s_lshl_b32 s88, s88, 9
	s_lshl_b32 s90, s90, 9
	s_add_u32 s84, s93, s84
	s_addc_u32 s85, s94, 0
	s_add_u32 s86, s93, s86
	s_addc_u32 s87, s94, 0
	s_add_u32 s88, s93, s88
	s_addc_u32 s89, s94, 0
	s_add_u32 s90, s93, s90
	s_addc_u32 s91, s94, 0
	global_load_dwordx2 v[96:97], v255, s[84:85]
	global_load_dwordx2 v[98:99], v255, s[86:87]
	global_load_dwordx2 v[100:101], v255, s[88:89]
	global_load_dwordx2 v[102:103], v255, s[90:91]
	v_readlane_b32 s84, v70, 16
	v_readlane_b32 s86, v70, 17
	v_readlane_b32 s88, v70, 18
	v_readlane_b32 s90, v70, 19
	s_lshl_b32 s84, s84, 9
	s_lshl_b32 s86, s86, 9
	s_lshl_b32 s88, s88, 9
	s_lshl_b32 s90, s90, 9
	s_add_u32 s84, s93, s84
	s_addc_u32 s85, s94, 0
	s_add_u32 s86, s93, s86
	s_addc_u32 s87, s94, 0
	s_add_u32 s88, s93, s88
	s_addc_u32 s89, s94, 0
	s_add_u32 s90, s93, s90
	s_addc_u32 s91, s94, 0
	global_load_dwordx2 v[18:19], v255, s[84:85]
	global_load_dwordx2 v[20:21], v255, s[86:87]
	global_load_dwordx2 v[22:23], v255, s[88:89]
	global_load_dwordx2 v[24:25], v255, s[90:91]
	v_readlane_b32 s84, v70, 20
	v_readlane_b32 s86, v70, 21
	v_readlane_b32 s88, v70, 22
	v_readlane_b32 s90, v70, 23
	s_lshl_b32 s84, s84, 9
	s_lshl_b32 s86, s86, 9
	s_lshl_b32 s88, s88, 9
	s_lshl_b32 s90, s90, 9
	s_add_u32 s84, s93, s84
	s_addc_u32 s85, s94, 0
	s_add_u32 s86, s93, s86
	s_addc_u32 s87, s94, 0
	s_add_u32 s88, s93, s88
	s_addc_u32 s89, s94, 0
	s_add_u32 s90, s93, s90
	s_addc_u32 s91, s94, 0
	global_load_dwordx2 v[26:27], v255, s[84:85]
	global_load_dwordx2 v[28:29], v255, s[86:87]
	global_load_dwordx2 v[30:31], v255, s[88:89]
	global_load_dwordx2 v[32:33], v255, s[90:91]
	v_readlane_b32 s84, v70, 24
	v_readlane_b32 s86, v70, 25
	v_readlane_b32 s88, v70, 26
	v_readlane_b32 s90, v70, 27
	s_lshl_b32 s84, s84, 9
	s_lshl_b32 s86, s86, 9
	s_lshl_b32 s88, s88, 9
	s_lshl_b32 s90, s90, 9
	s_add_u32 s84, s93, s84
	s_addc_u32 s85, s94, 0
	s_add_u32 s86, s93, s86
	s_addc_u32 s87, s94, 0
	s_add_u32 s88, s93, s88
	s_addc_u32 s89, s94, 0
	s_add_u32 s90, s93, s90
	s_addc_u32 s91, s94, 0
	global_load_dwordx2 v[56:57], v255, s[84:85]
	global_load_dwordx2 v[58:59], v255, s[86:87]
	global_load_dwordx2 v[60:61], v255, s[88:89]
	global_load_dwordx2 v[62:63], v255, s[90:91]
	v_readlane_b32 s84, v70, 28
	v_readlane_b32 s86, v70, 29
	v_readlane_b32 s88, v70, 30
	v_readlane_b32 s90, v70, 31
	s_lshl_b32 s84, s84, 9
	s_lshl_b32 s86, s86, 9
	s_lshl_b32 s88, s88, 9
	s_lshl_b32 s90, s90, 9
	s_add_u32 s84, s93, s84
	s_addc_u32 s85, s94, 0
	s_add_u32 s86, s93, s86
	s_addc_u32 s87, s94, 0
	s_add_u32 s88, s93, s88
	s_addc_u32 s89, s94, 0
	s_add_u32 s90, s93, s90
	s_addc_u32 s91, s94, 0
	global_load_dwordx2 v[64:65], v255, s[84:85]
	global_load_dwordx2 v[66:67], v255, s[86:87]
	global_load_dwordx2 v[68:69], v255, s[88:89]
	global_load_dwordx2 v[70:71], v255, s[90:91]
	s_branch .Lh2_u19_join
.Lh2_u19_hi:
	v_readlane_b32 s84, v70, 32
	v_readlane_b32 s86, v70, 33
	v_readlane_b32 s88, v70, 34
	v_readlane_b32 s90, v70, 35
	s_lshl_b32 s84, s84, 9
	s_lshl_b32 s86, s86, 9
	s_lshl_b32 s88, s88, 9
	s_lshl_b32 s90, s90, 9
	s_add_u32 s84, s93, s84
	s_addc_u32 s85, s94, 0
	s_add_u32 s86, s93, s86
	s_addc_u32 s87, s94, 0
	s_add_u32 s88, s93, s88
	s_addc_u32 s89, s94, 0
	s_add_u32 s90, s93, s90
	s_addc_u32 s91, s94, 0
	global_load_dwordx2 v[72:73], v255, s[84:85]
	global_load_dwordx2 v[74:75], v255, s[86:87]
	global_load_dwordx2 v[76:77], v255, s[88:89]
	global_load_dwordx2 v[78:79], v255, s[90:91]
	v_readlane_b32 s84, v70, 36
	v_readlane_b32 s86, v70, 37
	v_readlane_b32 s88, v70, 38
	v_readlane_b32 s90, v70, 39
	s_lshl_b32 s84, s84, 9
	s_lshl_b32 s86, s86, 9
	s_lshl_b32 s88, s88, 9
	s_lshl_b32 s90, s90, 9
	s_add_u32 s84, s93, s84
	s_addc_u32 s85, s94, 0
	s_add_u32 s86, s93, s86
	s_addc_u32 s87, s94, 0
	s_add_u32 s88, s93, s88
	s_addc_u32 s89, s94, 0
	s_add_u32 s90, s93, s90
	s_addc_u32 s91, s94, 0
	global_load_dwordx2 v[80:81], v255, s[84:85]
	global_load_dwordx2 v[82:83], v255, s[86:87]
	global_load_dwordx2 v[84:85], v255, s[88:89]
	global_load_dwordx2 v[86:87], v255, s[90:91]
	v_readlane_b32 s84, v70, 40
	v_readlane_b32 s86, v70, 41
	v_readlane_b32 s88, v70, 42
	v_readlane_b32 s90, v70, 43
	s_lshl_b32 s84, s84, 9
	s_lshl_b32 s86, s86, 9
	s_lshl_b32 s88, s88, 9
	s_lshl_b32 s90, s90, 9
	s_add_u32 s84, s93, s84
	s_addc_u32 s85, s94, 0
	s_add_u32 s86, s93, s86
	s_addc_u32 s87, s94, 0
	s_add_u32 s88, s93, s88
	s_addc_u32 s89, s94, 0
	s_add_u32 s90, s93, s90
	s_addc_u32 s91, s94, 0
	global_load_dwordx2 v[88:89], v255, s[84:85]
	global_load_dwordx2 v[90:91], v255, s[86:87]
	global_load_dwordx2 v[92:93], v255, s[88:89]
	global_load_dwordx2 v[94:95], v255, s[90:91]
	v_readlane_b32 s84, v70, 44
	v_readlane_b32 s86, v70, 45
	v_readlane_b32 s88, v70, 46
	v_readlane_b32 s90, v70, 47
	s_lshl_b32 s84, s84, 9
	s_lshl_b32 s86, s86, 9
	s_lshl_b32 s88, s88, 9
	s_lshl_b32 s90, s90, 9
	s_add_u32 s84, s93, s84
	s_addc_u32 s85, s94, 0
	s_add_u32 s86, s93, s86
	s_addc_u32 s87, s94, 0
	s_add_u32 s88, s93, s88
	s_addc_u32 s89, s94, 0
	s_add_u32 s90, s93, s90
	s_addc_u32 s91, s94, 0
	global_load_dwordx2 v[96:97], v255, s[84:85]
	global_load_dwordx2 v[98:99], v255, s[86:87]
	global_load_dwordx2 v[100:101], v255, s[88:89]
	global_load_dwordx2 v[102:103], v255, s[90:91]
	v_readlane_b32 s84, v70, 48
	v_readlane_b32 s86, v70, 49
	v_readlane_b32 s88, v70, 50
	v_readlane_b32 s90, v70, 51
	s_lshl_b32 s84, s84, 9
	s_lshl_b32 s86, s86, 9
	s_lshl_b32 s88, s88, 9
	s_lshl_b32 s90, s90, 9
	s_add_u32 s84, s93, s84
	s_addc_u32 s85, s94, 0
	s_add_u32 s86, s93, s86
	s_addc_u32 s87, s94, 0
	s_add_u32 s88, s93, s88
	s_addc_u32 s89, s94, 0
	s_add_u32 s90, s93, s90
	s_addc_u32 s91, s94, 0
	global_load_dwordx2 v[18:19], v255, s[84:85]
	global_load_dwordx2 v[20:21], v255, s[86:87]
	global_load_dwordx2 v[22:23], v255, s[88:89]
	global_load_dwordx2 v[24:25], v255, s[90:91]
	v_readlane_b32 s84, v70, 52
	v_readlane_b32 s86, v70, 53
	v_readlane_b32 s88, v70, 54
	v_readlane_b32 s90, v70, 55
	s_lshl_b32 s84, s84, 9
	s_lshl_b32 s86, s86, 9
	s_lshl_b32 s88, s88, 9
	s_lshl_b32 s90, s90, 9
	s_add_u32 s84, s93, s84
	s_addc_u32 s85, s94, 0
	s_add_u32 s86, s93, s86
	s_addc_u32 s87, s94, 0
	s_add_u32 s88, s93, s88
	s_addc_u32 s89, s94, 0
	s_add_u32 s90, s93, s90
	s_addc_u32 s91, s94, 0
	global_load_dwordx2 v[26:27], v255, s[84:85]
	global_load_dwordx2 v[28:29], v255, s[86:87]
	global_load_dwordx2 v[30:31], v255, s[88:89]
	global_load_dwordx2 v[32:33], v255, s[90:91]
	v_readlane_b32 s84, v70, 56
	v_readlane_b32 s86, v70, 57
	v_readlane_b32 s88, v70, 58
	v_readlane_b32 s90, v70, 59
	s_lshl_b32 s84, s84, 9
	s_lshl_b32 s86, s86, 9
	s_lshl_b32 s88, s88, 9
	s_lshl_b32 s90, s90, 9
	s_add_u32 s84, s93, s84
	s_addc_u32 s85, s94, 0
	s_add_u32 s86, s93, s86
	s_addc_u32 s87, s94, 0
	s_add_u32 s88, s93, s88
	s_addc_u32 s89, s94, 0
	s_add_u32 s90, s93, s90
	s_addc_u32 s91, s94, 0
	global_load_dwordx2 v[56:57], v255, s[84:85]
	global_load_dwordx2 v[58:59], v255, s[86:87]
	global_load_dwordx2 v[60:61], v255, s[88:89]
	global_load_dwordx2 v[62:63], v255, s[90:91]
	v_readlane_b32 s84, v70, 60
	v_readlane_b32 s86, v70, 61
	v_readlane_b32 s88, v70, 62
	v_readlane_b32 s90, v70, 63
	s_lshl_b32 s84, s84, 9
	s_lshl_b32 s86, s86, 9
	s_lshl_b32 s88, s88, 9
	s_lshl_b32 s90, s90, 9
	s_add_u32 s84, s93, s84
	s_addc_u32 s85, s94, 0
	s_add_u32 s86, s93, s86
	s_addc_u32 s87, s94, 0
	s_add_u32 s88, s93, s88
	s_addc_u32 s89, s94, 0
	s_add_u32 s90, s93, s90
	s_addc_u32 s91, s94, 0
	global_load_dwordx2 v[64:65], v255, s[84:85]
	global_load_dwordx2 v[66:67], v255, s[86:87]
	global_load_dwordx2 v[68:69], v255, s[88:89]
	global_load_dwordx2 v[70:71], v255, s[90:91]

.LBB0_3313:
	v_cmp_gt_u32_e32 vcc, 64, v116
	s_nop 1
	v_cndmask_b32_e32 v102, v117, v53, vcc
	v_readfirstlane_b32 s92, v116
	v_readfirstlane_b32 s93, v38
	v_readfirstlane_b32 s94, v39
	s_nop 1
	v_subrev_u32_e32 v255, s93, v38
	s_nop 1
	s_and_b32 s92, s92, 32
	s_cbranch_scc1 .Lh3_v19_hi
	v_readlane_b32 s84, v102, 0
	v_readlane_b32 s86, v102, 1
	v_readlane_b32 s88, v102, 2
	v_readlane_b32 s90, v102, 3
	s_lshl_b32 s84, s84, 9
	s_lshl_b32 s86, s86, 9
	s_lshl_b32 s88, s88, 9
	s_lshl_b32 s90, s90, 9
	s_add_u32 s84, s93, s84
	s_addc_u32 s85, s94, 0
	s_add_u32 s86, s93, s86
	s_addc_u32 s87, s94, 0
	s_add_u32 s88, s93, s88
	s_addc_u32 s89, s94, 0
	s_add_u32 s90, s93, s90
	s_addc_u32 s91, s94, 0
	global_load_dwordx2 v[18:19], v255, s[84:85]
	global_load_dwordx2 v[20:21], v255, s[86:87]
	global_load_dwordx2 v[22:23], v255, s[88:89]
	global_load_dwordx2 v[24:25], v255, s[90:91]
	v_readlane_b32 s84, v102, 4
	v_readlane_b32 s86, v102, 5
	v_readlane_b32 s88, v102, 6
	v_readlane_b32 s90, v102, 7
	s_lshl_b32 s84, s84, 9
	s_lshl_b32 s86, s86, 9
	s_lshl_b32 s88, s88, 9
	s_lshl_b32 s90, s90, 9
	s_add_u32 s84, s93, s84
	s_addc_u32 s85, s94, 0
	s_add_u32 s86, s93, s86
	s_addc_u32 s87, s94, 0
	s_add_u32 s88, s93, s88
	s_addc_u32 s89, s94, 0
	s_add_u32 s90, s93, s90
	s_addc_u32 s91, s94, 0
	global_load_dwordx2 v[26:27], v255, s[84:85]
	global_load_dwordx2 v[28:29], v255, s[86:87]
	global_load_dwordx2 v[30:31], v255, s[88:89]
	global_load_dwordx2 v[32:33], v255, s[90:91]
	v_readlane_b32 s84, v102, 8
	v_readlane_b32 s86, v102, 9
	v_readlane_b32 s88, v102, 10
	v_readlane_b32 s90, v102, 11
	s_lshl_b32 s84, s84, 9
	s_lshl_b32 s86, s86, 9
	s_lshl_b32 s88, s88, 9
	s_lshl_b32 s90, s90, 9
	s_add_u32 s84, s93, s84
	s_addc_u32 s85, s94, 0
	s_add_u32 s86, s93, s86
	s_addc_u32 s87, s94, 0
	s_add_u32 s88, s93, s88
	s_addc_u32 s89, s94, 0
	s_add_u32 s90, s93, s90
	s_addc_u32 s91, s94, 0
	global_load_dwordx2 v[56:57], v255, s[84:85]
	global_load_dwordx2 v[58:59], v255, s[86:87]
	global_load_dwordx2 v[60:61], v255, s[88:89]
	global_load_dwordx2 v[62:63], v255, s[90:91]
	v_readlane_b32 s84, v102, 12
	v_readlane_b32 s86, v102, 13
	v_readlane_b32 s88, v102, 14
	v_readlane_b32 s90, v102, 15
	s_lshl_b32 s84, s84, 9
	s_lshl_b32 s86, s86, 9
	s_lshl_b32 s88, s88, 9
	s_lshl_b32 s90, s90, 9
	s_add_u32 s84, s93, s84
	s_addc_u32 s85, s94, 0
	s_add_u32 s86, s93, s86
	s_addc_u32 s87, s94, 0
	s_add_u32 s88, s93, s88
	s_addc_u32 s89, s94, 0
	s_add_u32 s90, s93, s90
	s_addc_u32 s91, s94, 0
	global_load_dwordx2 v[64:65], v255, s[84:85]
	global_load_dwordx2 v[66:67], v255, s[86:87]
	global_load_dwordx2 v[68:69], v255, s[88:89]
	global_load_dwordx2 v[70:71], v255, s[90:91]
	v_readlane_b32 s84, v102, 16
	v_readlane_b32 s86, v102, 17
	v_readlane_b32 s88, v102, 18
	v_readlane_b32 s90, v102, 19
	s_lshl_b32 s84, s84, 9
	s_lshl_b32 s86, s86, 9
	s_lshl_b32 s88, s88, 9
	s_lshl_b32 s90, s90, 9
	s_add_u32 s84, s93, s84
	s_addc_u32 s85, s94, 0
	s_add_u32 s86, s93, s86
	s_addc_u32 s87, s94, 0
	s_add_u32 s88, s93, s88
	s_addc_u32 s89, s94, 0
	s_add_u32 s90, s93, s90
	s_addc_u32 s91, s94, 0
	global_load_dwordx2 v[72:73], v255, s[84:85]
	global_load_dwordx2 v[74:75], v255, s[86:87]
	global_load_dwordx2 v[76:77], v255, s[88:89]
	global_load_dwordx2 v[78:79], v255, s[90:91]
	v_readlane_b32 s84, v102, 20
	v_readlane_b32 s86, v102, 21
	v_readlane_b32 s88, v102, 22
	v_readlane_b32 s90, v102, 23
	s_lshl_b32 s84, s84, 9
	s_lshl_b32 s86, s86, 9
	s_lshl_b32 s88, s88, 9
	s_lshl_b32 s90, s90, 9
	s_add_u32 s84, s93, s84
	s_addc_u32 s85, s94, 0
	s_add_u32 s86, s93, s86
	s_addc_u32 s87, s94, 0
	s_add_u32 s88, s93, s88
	s_addc_u32 s89, s94, 0
	s_add_u32 s90, s93, s90
	s_addc_u32 s91, s94, 0
	global_load_dwordx2 v[80:81], v255, s[84:85]
	global_load_dwordx2 v[82:83], v255, s[86:87]
	global_load_dwordx2 v[84:85], v255, s[88:89]
	global_load_dwordx2 v[86:87], v255, s[90:91]
	v_readlane_b32 s84, v102, 24
	v_readlane_b32 s86, v102, 25
	v_readlane_b32 s88, v102, 26
	v_readlane_b32 s90, v102, 27
	s_lshl_b32 s84, s84, 9
	s_lshl_b32 s86, s86, 9
	s_lshl_b32 s88, s88, 9
	s_lshl_b32 s90, s90, 9
	s_add_u32 s84, s93, s84
	s_addc_u32 s85, s94, 0
	s_add_u32 s86, s93, s86
	s_addc_u32 s87, s94, 0
	s_add_u32 s88, s93, s88
	s_addc_u32 s89, s94, 0
	s_add_u32 s90, s93, s90
	s_addc_u32 s91, s94, 0
	global_load_dwordx2 v[88:89], v255, s[84:85]
	global_load_dwordx2 v[90:91], v255, s[86:87]
	global_load_dwordx2 v[92:93], v255, s[88:89]
	global_load_dwordx2 v[94:95], v255, s[90:91]
	v_readlane_b32 s84, v102, 28
	v_readlane_b32 s86, v102, 29
	v_readlane_b32 s88, v102, 30
	v_readlane_b32 s90, v102, 31
	s_lshl_b32 s84, s84, 9
	s_lshl_b32 s86, s86, 9
	s_lshl_b32 s88, s88, 9
	s_lshl_b32 s90, s90, 9
	s_add_u32 s84, s93, s84
	s_addc_u32 s85, s94, 0
	s_add_u32 s86, s93, s86
	s_addc_u32 s87, s94, 0
	s_add_u32 s88, s93, s88
	s_addc_u32 s89, s94, 0
	s_add_u32 s90, s93, s90
	s_addc_u32 s91, s94, 0
	global_load_dwordx2 v[96:97], v255, s[84:85]
	global_load_dwordx2 v[98:99], v255, s[86:87]
	global_load_dwordx2 v[100:101], v255, s[88:89]
	global_load_dwordx2 v[102:103], v255, s[90:91]
	v_cndmask_b32_e32 v126, v1, v118, vcc
	s_nop 0
	v_readlane_b32 s48, v126, 0
	s_waitcnt vmcnt(31)
	v_cvt_scalef32_pk_f32_fp4 v[128:129], v18, 1.0
	v_pk_fma_f32 v[2:3], v[128:129], s[48:49], v[2:3] op_sel_hi:[1,0,1]
	v_cvt_scalef32_pk_f32_fp4 v[128:129], v18, 1.0 op_sel:[1,0,0]
	v_pk_fma_f32 v[4:5], s[48:49], v[128:129], v[4:5] op_sel_hi:[0,1,1]
	v_cvt_scalef32_pk_f32_fp4 v[128:129], v18, 1.0 op_sel:[0,1,0]
	v_pk_fma_f32 v[6:7], s[48:49], v[128:129], v[6:7] op_sel_hi:[0,1,1]
	v_cvt_scalef32_pk_f32_fp4 v[128:129], v18, 1.0 op_sel:[1,1,0]
	v_pk_fma_f32 v[8:9], s[48:49], v[128:129], v[8:9] op_sel_hi:[0,1,1]
	v_cvt_scalef32_pk_f32_fp4 v[128:129], v19, 1.0
	v_pk_fma_f32 v[10:11], s[48:49], v[128:129], v[10:11] op_sel_hi:[0,1,1]
	v_cvt_scalef32_pk_f32_fp4 v[128:129], v19, 1.0 op_sel:[1,0,0]
	v_pk_fma_f32 v[12:13], s[48:49], v[128:129], v[12:13] op_sel_hi:[0,1,1]
	v_cvt_scalef32_pk_f32_fp4 v[128:129], v19, 1.0 op_sel:[0,1,0]
	v_cvt_scalef32_pk_f32_fp4 v[18:19], v19, 1.0 op_sel:[1,1,0]
	v_pk_fma_f32 v[14:15], s[48:49], v[128:129], v[14:15] op_sel_hi:[0,1,1]
	v_pk_fma_f32 v[16:17], s[48:49], v[18:19], v[16:17] op_sel_hi:[0,1,1]
	v_readlane_b32 s48, v126, 8
	s_waitcnt vmcnt(30)
	v_cvt_scalef32_pk_f32_fp4 v[18:19], v20, 1.0
	v_pk_fma_f32 v[2:3], v[18:19], s[48:49], v[2:3] op_sel_hi:[1,0,1]
	v_cvt_scalef32_pk_f32_fp4 v[18:19], v20, 1.0 op_sel:[1,0,0]
	v_pk_fma_f32 v[4:5], s[48:49], v[18:19], v[4:5] op_sel_hi:[0,1,1]
	v_cvt_scalef32_pk_f32_fp4 v[18:19], v20, 1.0 op_sel:[0,1,0]
	v_pk_fma_f32 v[6:7], s[48:49], v[18:19], v[6:7] op_sel_hi:[0,1,1]
	v_cvt_scalef32_pk_f32_fp4 v[18:19], v20, 1.0 op_sel:[1,1,0]
	v_pk_fma_f32 v[8:9], s[48:49], v[18:19], v[8:9] op_sel_hi:[0,1,1]
	v_cvt_scalef32_pk_f32_fp4 v[18:19], v21, 1.0
	v_pk_fma_f32 v[10:11], s[48:49], v[18:19], v[10:11] op_sel_hi:[0,1,1]
	v_cvt_scalef32_pk_f32_fp4 v[18:19], v21, 1.0 op_sel:[1,0,0]
	v_pk_fma_f32 v[12:13], s[48:49], v[18:19], v[12:13] op_sel_hi:[0,1,1]
	v_cvt_scalef32_pk_f32_fp4 v[18:19], v21, 1.0 op_sel:[0,1,0]
	v_pk_fma_f32 v[14:15], s[48:49], v[18:19], v[14:15] op_sel_hi:[0,1,1]
	v_cvt_scalef32_pk_f32_fp4 v[18:19], v21, 1.0 op_sel:[1,1,0]
	v_pk_fma_f32 v[16:17], s[48:49], v[18:19], v[16:17] op_sel_hi:[0,1,1]
	v_readlane_b32 s48, v126, 4
	s_waitcnt vmcnt(29)
	v_cvt_scalef32_pk_f32_fp4 v[18:19], v22, 1.0
	v_pk_fma_f32 v[2:3], v[18:19], s[48:49], v[2:3] op_sel_hi:[1,0,1]
	v_cvt_scalef32_pk_f32_fp4 v[18:19], v22, 1.0 op_sel:[1,0,0]
	v_pk_fma_f32 v[4:5], s[48:49], v[18:19], v[4:5] op_sel_hi:[0,1,1]
	v_cvt_scalef32_pk_f32_fp4 v[18:19], v22, 1.0 op_sel:[0,1,0]
	v_pk_fma_f32 v[6:7], s[48:49], v[18:19], v[6:7] op_sel_hi:[0,1,1]
	v_cvt_scalef32_pk_f32_fp4 v[18:19], v22, 1.0 op_sel:[1,1,0]
	v_pk_fma_f32 v[8:9], s[48:49], v[18:19], v[8:9] op_sel_hi:[0,1,1]
	v_cvt_scalef32_pk_f32_fp4 v[18:19], v23, 1.0
	v_pk_fma_f32 v[10:11], s[48:49], v[18:19], v[10:11] op_sel_hi:[0,1,1]
	v_cvt_scalef32_pk_f32_fp4 v[18:19], v23, 1.0 op_sel:[1,0,0]
	v_pk_fma_f32 v[12:13], s[48:49], v[18:19], v[12:13] op_sel_hi:[0,1,1]
	v_cvt_scalef32_pk_f32_fp4 v[18:19], v23, 1.0 op_sel:[0,1,0]
	v_pk_fma_f32 v[14:15], s[48:49], v[18:19], v[14:15] op_sel_hi:[0,1,1]
	v_cvt_scalef32_pk_f32_fp4 v[18:19], v23, 1.0 op_sel:[1,1,0]
	v_pk_fma_f32 v[16:17], s[48:49], v[18:19], v[16:17] op_sel_hi:[0,1,1]
	v_readlane_b32 s48, v126, 12
	s_waitcnt vmcnt(28)
	v_cvt_scalef32_pk_f32_fp4 v[18:19], v24, 1.0
	v_pk_fma_f32 v[2:3], v[18:19], s[48:49], v[2:3] op_sel_hi:[1,0,1]
	v_cvt_scalef32_pk_f32_fp4 v[18:19], v24, 1.0 op_sel:[1,0,0]
	v_pk_fma_f32 v[4:5], s[48:49], v[18:19], v[4:5] op_sel_hi:[0,1,1]
	v_cvt_scalef32_pk_f32_fp4 v[18:19], v24, 1.0 op_sel:[0,1,0]
	v_pk_fma_f32 v[6:7], s[48:49], v[18:19], v[6:7] op_sel_hi:[0,1,1]
	v_cvt_scalef32_pk_f32_fp4 v[18:19], v24, 1.0 op_sel:[1,1,0]
	v_pk_fma_f32 v[8:9], s[48:49], v[18:19], v[8:9] op_sel_hi:[0,1,1]
	v_cvt_scalef32_pk_f32_fp4 v[18:19], v25, 1.0
	v_pk_fma_f32 v[10:11], s[48:49], v[18:19], v[10:11] op_sel_hi:[0,1,1]
	v_cvt_scalef32_pk_f32_fp4 v[18:19], v25, 1.0 op_sel:[1,0,0]
	v_pk_fma_f32 v[12:13], s[48:49], v[18:19], v[12:13] op_sel_hi:[0,1,1]
	v_cvt_scalef32_pk_f32_fp4 v[18:19], v25, 1.0 op_sel:[0,1,0]
	v_pk_fma_f32 v[14:15], s[48:49], v[18:19], v[14:15] op_sel_hi:[0,1,1]
	v_cvt_scalef32_pk_f32_fp4 v[18:19], v25, 1.0 op_sel:[1,1,0]
	v_pk_fma_f32 v[16:17], s[48:49], v[18:19], v[16:17] op_sel_hi:[0,1,1]
	v_readlane_b32 s48, v126, 2
	s_waitcnt vmcnt(27)
	v_cvt_scalef32_pk_f32_fp4 v[18:19], v26, 1.0
	v_pk_fma_f32 v[2:3], v[18:19], s[48:49], v[2:3] op_sel_hi:[1,0,1]
	v_cvt_scalef32_pk_f32_fp4 v[18:19], v26, 1.0 op_sel:[1,0,0]
	v_pk_fma_f32 v[4:5], s[48:49], v[18:19], v[4:5] op_sel_hi:[0,1,1]
	v_cvt_scalef32_pk_f32_fp4 v[18:19], v26, 1.0 op_sel:[0,1,0]
	v_pk_fma_f32 v[6:7], s[48:49], v[18:19], v[6:7] op_sel_hi:[0,1,1]
	v_cvt_scalef32_pk_f32_fp4 v[18:19], v26, 1.0 op_sel:[1,1,0]
	v_pk_fma_f32 v[8:9], s[48:49], v[18:19], v[8:9] op_sel_hi:[0,1,1]
	v_cvt_scalef32_pk_f32_fp4 v[18:19], v27, 1.0
	v_pk_fma_f32 v[10:11], s[48:49], v[18:19], v[10:11] op_sel_hi:[0,1,1]
	v_cvt_scalef32_pk_f32_fp4 v[18:19], v27, 1.0 op_sel:[1,0,0]
	v_pk_fma_f32 v[12:13], s[48:49], v[18:19], v[12:13] op_sel_hi:[0,1,1]
	v_cvt_scalef32_pk_f32_fp4 v[18:19], v27, 1.0 op_sel:[0,1,0]
	v_pk_fma_f32 v[14:15], s[48:49], v[18:19], v[14:15] op_sel_hi:[0,1,1]
	v_cvt_scalef32_pk_f32_fp4 v[18:19], v27, 1.0 op_sel:[1,1,0]
	v_pk_fma_f32 v[16:17], s[48:49], v[18:19], v[16:17] op_sel_hi:[0,1,1]
	v_readlane_b32 s48, v126, 10
	s_waitcnt vmcnt(26)
	v_cvt_scalef32_pk_f32_fp4 v[18:19], v28, 1.0
	v_pk_fma_f32 v[2:3], v[18:19], s[48:49], v[2:3] op_sel_hi:[1,0,1]
	v_cvt_scalef32_pk_f32_fp4 v[18:19], v28, 1.0 op_sel:[1,0,0]
	v_pk_fma_f32 v[4:5], s[48:49], v[18:19], v[4:5] op_sel_hi:[0,1,1]
	v_cvt_scalef32_pk_f32_fp4 v[18:19], v28, 1.0 op_sel:[0,1,0]
	v_pk_fma_f32 v[6:7], s[48:49], v[18:19], v[6:7] op_sel_hi:[0,1,1]
	v_cvt_scalef32_pk_f32_fp4 v[18:19], v28, 1.0 op_sel:[1,1,0]
	v_pk_fma_f32 v[8:9], s[48:49], v[18:19], v[8:9] op_sel_hi:[0,1,1]
	v_cvt_scalef32_pk_f32_fp4 v[18:19], v29, 1.0
	v_pk_fma_f32 v[10:11], s[48:49], v[18:19], v[10:11] op_sel_hi:[0,1,1]
	v_cvt_scalef32_pk_f32_fp4 v[18:19], v29, 1.0 op_sel:[1,0,0]
	v_pk_fma_f32 v[12:13], s[48:49], v[18:19], v[12:13] op_sel_hi:[0,1,1]
	v_cvt_scalef32_pk_f32_fp4 v[18:19], v29, 1.0 op_sel:[0,1,0]
	v_pk_fma_f32 v[14:15], s[48:49], v[18:19], v[14:15] op_sel_hi:[0,1,1]
	v_cvt_scalef32_pk_f32_fp4 v[18:19], v29, 1.0 op_sel:[1,1,0]
	v_pk_fma_f32 v[16:17], s[48:49], v[18:19], v[16:17] op_sel_hi:[0,1,1]
	v_readlane_b32 s48, v126, 6
	s_waitcnt vmcnt(25)
	v_cvt_scalef32_pk_f32_fp4 v[18:19], v30, 1.0
	v_pk_fma_f32 v[2:3], v[18:19], s[48:49], v[2:3] op_sel_hi:[1,0,1]
	v_cvt_scalef32_pk_f32_fp4 v[18:19], v30, 1.0 op_sel:[1,0,0]
	v_pk_fma_f32 v[4:5], s[48:49], v[18:19], v[4:5] op_sel_hi:[0,1,1]
	v_cvt_scalef32_pk_f32_fp4 v[18:19], v30, 1.0 op_sel:[0,1,0]
	v_pk_fma_f32 v[6:7], s[48:49], v[18:19], v[6:7] op_sel_hi:[0,1,1]
	v_cvt_scalef32_pk_f32_fp4 v[18:19], v30, 1.0 op_sel:[1,1,0]
	v_pk_fma_f32 v[8:9], s[48:49], v[18:19], v[8:9] op_sel_hi:[0,1,1]
	v_cvt_scalef32_pk_f32_fp4 v[18:19], v31, 1.0
	v_pk_fma_f32 v[10:11], s[48:49], v[18:19], v[10:11] op_sel_hi:[0,1,1]
	v_cvt_scalef32_pk_f32_fp4 v[18:19], v31, 1.0 op_sel:[1,0,0]
	v_pk_fma_f32 v[12:13], s[48:49], v[18:19], v[12:13] op_sel_hi:[0,1,1]
	v_cvt_scalef32_pk_f32_fp4 v[18:19], v31, 1.0 op_sel:[0,1,0]
	v_pk_fma_f32 v[14:15], s[48:49], v[18:19], v[14:15] op_sel_hi:[0,1,1]
	v_cvt_scalef32_pk_f32_fp4 v[18:19], v31, 1.0 op_sel:[1,1,0]
	v_pk_fma_f32 v[16:17], s[48:49], v[18:19], v[16:17] op_sel_hi:[0,1,1]
	v_readlane_b32 s48, v126, 14
	s_waitcnt vmcnt(24)
	v_cvt_scalef32_pk_f32_fp4 v[18:19], v32, 1.0
	v_pk_fma_f32 v[2:3], v[18:19], s[48:49], v[2:3] op_sel_hi:[1,0,1]
	v_cvt_scalef32_pk_f32_fp4 v[18:19], v32, 1.0 op_sel:[1,0,0]
	v_pk_fma_f32 v[4:5], s[48:49], v[18:19], v[4:5] op_sel_hi:[0,1,1]
	v_cvt_scalef32_pk_f32_fp4 v[18:19], v32, 1.0 op_sel:[0,1,0]
	v_pk_fma_f32 v[6:7], s[48:49], v[18:19], v[6:7] op_sel_hi:[0,1,1]
	v_cvt_scalef32_pk_f32_fp4 v[18:19], v32, 1.0 op_sel:[1,1,0]
	v_pk_fma_f32 v[8:9], s[48:49], v[18:19], v[8:9] op_sel_hi:[0,1,1]
	v_cvt_scalef32_pk_f32_fp4 v[18:19], v33, 1.0
	v_pk_fma_f32 v[10:11], s[48:49], v[18:19], v[10:11] op_sel_hi:[0,1,1]
	v_cvt_scalef32_pk_f32_fp4 v[18:19], v33, 1.0 op_sel:[1,0,0]
	v_pk_fma_f32 v[12:13], s[48:49], v[18:19], v[12:13] op_sel_hi:[0,1,1]
	v_cvt_scalef32_pk_f32_fp4 v[18:19], v33, 1.0 op_sel:[0,1,0]
	v_pk_fma_f32 v[14:15], s[48:49], v[18:19], v[14:15] op_sel_hi:[0,1,1]
	v_cvt_scalef32_pk_f32_fp4 v[18:19], v33, 1.0 op_sel:[1,1,0]
	v_pk_fma_f32 v[16:17], s[48:49], v[18:19], v[16:17] op_sel_hi:[0,1,1]
	v_readlane_b32 s48, v126, 1
	s_waitcnt vmcnt(23)
	v_cvt_scalef32_pk_f32_fp4 v[18:19], v56, 1.0
	v_pk_fma_f32 v[2:3], v[18:19], s[48:49], v[2:3] op_sel_hi:[1,0,1]
	v_cvt_scalef32_pk_f32_fp4 v[18:19], v56, 1.0 op_sel:[1,0,0]
	v_pk_fma_f32 v[4:5], s[48:49], v[18:19], v[4:5] op_sel_hi:[0,1,1]
	v_cvt_scalef32_pk_f32_fp4 v[18:19], v56, 1.0 op_sel:[0,1,0]
	v_pk_fma_f32 v[6:7], s[48:49], v[18:19], v[6:7] op_sel_hi:[0,1,1]
	v_cvt_scalef32_pk_f32_fp4 v[18:19], v56, 1.0 op_sel:[1,1,0]
	v_pk_fma_f32 v[8:9], s[48:49], v[18:19], v[8:9] op_sel_hi:[0,1,1]
	v_cvt_scalef32_pk_f32_fp4 v[18:19], v57, 1.0
	v_pk_fma_f32 v[10:11], s[48:49], v[18:19], v[10:11] op_sel_hi:[0,1,1]
	v_cvt_scalef32_pk_f32_fp4 v[18:19], v57, 1.0 op_sel:[1,0,0]
	v_pk_fma_f32 v[12:13], s[48:49], v[18:19], v[12:13] op_sel_hi:[0,1,1]
	v_cvt_scalef32_pk_f32_fp4 v[18:19], v57, 1.0 op_sel:[0,1,0]
	v_pk_fma_f32 v[14:15], s[48:49], v[18:19], v[14:15] op_sel_hi:[0,1,1]
	v_cvt_scalef32_pk_f32_fp4 v[18:19], v57, 1.0 op_sel:[1,1,0]
	v_pk_fma_f32 v[16:17], s[48:49], v[18:19], v[16:17] op_sel_hi:[0,1,1]
	v_readlane_b32 s48, v126, 9
	s_waitcnt vmcnt(22)
	v_cvt_scalef32_pk_f32_fp4 v[18:19], v58, 1.0
	v_pk_fma_f32 v[2:3], v[18:19], s[48:49], v[2:3] op_sel_hi:[1,0,1]
	v_cvt_scalef32_pk_f32_fp4 v[18:19], v58, 1.0 op_sel:[1,0,0]
	v_pk_fma_f32 v[4:5], s[48:49], v[18:19], v[4:5] op_sel_hi:[0,1,1]
	v_cvt_scalef32_pk_f32_fp4 v[18:19], v58, 1.0 op_sel:[0,1,0]
	v_pk_fma_f32 v[6:7], s[48:49], v[18:19], v[6:7] op_sel_hi:[0,1,1]
	v_cvt_scalef32_pk_f32_fp4 v[18:19], v58, 1.0 op_sel:[1,1,0]
	v_pk_fma_f32 v[8:9], s[48:49], v[18:19], v[8:9] op_sel_hi:[0,1,1]
	v_cvt_scalef32_pk_f32_fp4 v[18:19], v59, 1.0
	v_pk_fma_f32 v[10:11], s[48:49], v[18:19], v[10:11] op_sel_hi:[0,1,1]
	v_cvt_scalef32_pk_f32_fp4 v[18:19], v59, 1.0 op_sel:[1,0,0]
	v_pk_fma_f32 v[12:13], s[48:49], v[18:19], v[12:13] op_sel_hi:[0,1,1]
	v_cvt_scalef32_pk_f32_fp4 v[18:19], v59, 1.0 op_sel:[0,1,0]
	v_pk_fma_f32 v[14:15], s[48:49], v[18:19], v[14:15] op_sel_hi:[0,1,1]
	v_cvt_scalef32_pk_f32_fp4 v[18:19], v59, 1.0 op_sel:[1,1,0]
	v_pk_fma_f32 v[16:17], s[48:49], v[18:19], v[16:17] op_sel_hi:[0,1,1]
	v_readlane_b32 s48, v126, 5
	s_waitcnt vmcnt(21)
	v_cvt_scalef32_pk_f32_fp4 v[18:19], v60, 1.0
	v_pk_fma_f32 v[2:3], v[18:19], s[48:49], v[2:3] op_sel_hi:[1,0,1]
	v_cvt_scalef32_pk_f32_fp4 v[18:19], v60, 1.0 op_sel:[1,0,0]
	v_pk_fma_f32 v[4:5], s[48:49], v[18:19], v[4:5] op_sel_hi:[0,1,1]
	v_cvt_scalef32_pk_f32_fp4 v[18:19], v60, 1.0 op_sel:[0,1,0]
	v_pk_fma_f32 v[6:7], s[48:49], v[18:19], v[6:7] op_sel_hi:[0,1,1]
	v_cvt_scalef32_pk_f32_fp4 v[18:19], v60, 1.0 op_sel:[1,1,0]
	v_pk_fma_f32 v[8:9], s[48:49], v[18:19], v[8:9] op_sel_hi:[0,1,1]
	v_cvt_scalef32_pk_f32_fp4 v[18:19], v61, 1.0
	v_pk_fma_f32 v[10:11], s[48:49], v[18:19], v[10:11] op_sel_hi:[0,1,1]
	v_cvt_scalef32_pk_f32_fp4 v[18:19], v61, 1.0 op_sel:[1,0,0]
	v_pk_fma_f32 v[12:13], s[48:49], v[18:19], v[12:13] op_sel_hi:[0,1,1]
	v_cvt_scalef32_pk_f32_fp4 v[18:19], v61, 1.0 op_sel:[0,1,0]
	v_pk_fma_f32 v[14:15], s[48:49], v[18:19], v[14:15] op_sel_hi:[0,1,1]
	v_cvt_scalef32_pk_f32_fp4 v[18:19], v61, 1.0 op_sel:[1,1,0]
	v_pk_fma_f32 v[16:17], s[48:49], v[18:19], v[16:17] op_sel_hi:[0,1,1]
	v_readlane_b32 s48, v126, 13
	s_waitcnt vmcnt(20)
	v_cvt_scalef32_pk_f32_fp4 v[18:19], v62, 1.0
	v_pk_fma_f32 v[2:3], v[18:19], s[48:49], v[2:3] op_sel_hi:[1,0,1]
	v_cvt_scalef32_pk_f32_fp4 v[18:19], v62, 1.0 op_sel:[1,0,0]
	v_pk_fma_f32 v[4:5], s[48:49], v[18:19], v[4:5] op_sel_hi:[0,1,1]
	v_cvt_scalef32_pk_f32_fp4 v[18:19], v62, 1.0 op_sel:[0,1,0]
	v_pk_fma_f32 v[6:7], s[48:49], v[18:19], v[6:7] op_sel_hi:[0,1,1]
	v_cvt_scalef32_pk_f32_fp4 v[18:19], v62, 1.0 op_sel:[1,1,0]
	v_pk_fma_f32 v[8:9], s[48:49], v[18:19], v[8:9] op_sel_hi:[0,1,1]
	v_cvt_scalef32_pk_f32_fp4 v[18:19], v63, 1.0
	v_pk_fma_f32 v[10:11], s[48:49], v[18:19], v[10:11] op_sel_hi:[0,1,1]
	v_cvt_scalef32_pk_f32_fp4 v[18:19], v63, 1.0 op_sel:[1,0,0]
	v_pk_fma_f32 v[12:13], s[48:49], v[18:19], v[12:13] op_sel_hi:[0,1,1]
	v_cvt_scalef32_pk_f32_fp4 v[18:19], v63, 1.0 op_sel:[0,1,0]
	v_pk_fma_f32 v[14:15], s[48:49], v[18:19], v[14:15] op_sel_hi:[0,1,1]
	v_cvt_scalef32_pk_f32_fp4 v[18:19], v63, 1.0 op_sel:[1,1,0]
	v_pk_fma_f32 v[16:17], s[48:49], v[18:19], v[16:17] op_sel_hi:[0,1,1]
	v_readlane_b32 s24, v126, 3
	s_waitcnt vmcnt(19)
	v_cvt_scalef32_pk_f32_fp4 v[18:19], v64, 1.0
	v_pk_fma_f32 v[2:3], v[18:19], s[24:25], v[2:3] op_sel_hi:[1,0,1]
	v_cvt_scalef32_pk_f32_fp4 v[18:19], v64, 1.0 op_sel:[1,0,0]
	v_pk_fma_f32 v[4:5], s[24:25], v[18:19], v[4:5] op_sel_hi:[0,1,1]
	v_cvt_scalef32_pk_f32_fp4 v[18:19], v64, 1.0 op_sel:[0,1,0]
	v_pk_fma_f32 v[6:7], s[24:25], v[18:19], v[6:7] op_sel_hi:[0,1,1]
	v_cvt_scalef32_pk_f32_fp4 v[18:19], v64, 1.0 op_sel:[1,1,0]
	v_pk_fma_f32 v[8:9], s[24:25], v[18:19], v[8:9] op_sel_hi:[0,1,1]
	v_cvt_scalef32_pk_f32_fp4 v[18:19], v65, 1.0
	v_pk_fma_f32 v[10:11], s[24:25], v[18:19], v[10:11] op_sel_hi:[0,1,1]
	v_cvt_scalef32_pk_f32_fp4 v[18:19], v65, 1.0 op_sel:[1,0,0]
	v_pk_fma_f32 v[12:13], s[24:25], v[18:19], v[12:13] op_sel_hi:[0,1,1]
	v_cvt_scalef32_pk_f32_fp4 v[18:19], v65, 1.0 op_sel:[0,1,0]
	v_pk_fma_f32 v[14:15], s[24:25], v[18:19], v[14:15] op_sel_hi:[0,1,1]
	v_cvt_scalef32_pk_f32_fp4 v[18:19], v65, 1.0 op_sel:[1,1,0]
	v_pk_fma_f32 v[16:17], s[24:25], v[18:19], v[16:17] op_sel_hi:[0,1,1]
	v_readlane_b32 s24, v126, 11
	s_waitcnt vmcnt(18)
	v_cvt_scalef32_pk_f32_fp4 v[18:19], v66, 1.0
	v_pk_fma_f32 v[2:3], v[18:19], s[24:25], v[2:3] op_sel_hi:[1,0,1]
	v_cvt_scalef32_pk_f32_fp4 v[18:19], v66, 1.0 op_sel:[1,0,0]
	v_pk_fma_f32 v[4:5], s[24:25], v[18:19], v[4:5] op_sel_hi:[0,1,1]
	v_cvt_scalef32_pk_f32_fp4 v[18:19], v66, 1.0 op_sel:[0,1,0]
	v_pk_fma_f32 v[6:7], s[24:25], v[18:19], v[6:7] op_sel_hi:[0,1,1]
	v_cvt_scalef32_pk_f32_fp4 v[18:19], v66, 1.0 op_sel:[1,1,0]
	v_pk_fma_f32 v[8:9], s[24:25], v[18:19], v[8:9] op_sel_hi:[0,1,1]
	v_cvt_scalef32_pk_f32_fp4 v[18:19], v67, 1.0
	v_pk_fma_f32 v[10:11], s[24:25], v[18:19], v[10:11] op_sel_hi:[0,1,1]
	v_cvt_scalef32_pk_f32_fp4 v[18:19], v67, 1.0 op_sel:[1,0,0]
	v_pk_fma_f32 v[12:13], s[24:25], v[18:19], v[12:13] op_sel_hi:[0,1,1]
	v_cvt_scalef32_pk_f32_fp4 v[18:19], v67, 1.0 op_sel:[0,1,0]
	v_pk_fma_f32 v[14:15], s[24:25], v[18:19], v[14:15] op_sel_hi:[0,1,1]
	v_cvt_scalef32_pk_f32_fp4 v[18:19], v67, 1.0 op_sel:[1,1,0]
	v_pk_fma_f32 v[16:17], s[24:25], v[18:19], v[16:17] op_sel_hi:[0,1,1]
	v_readlane_b32 s24, v126, 7
	s_waitcnt vmcnt(17)
	v_cvt_scalef32_pk_f32_fp4 v[18:19], v68, 1.0
	v_pk_fma_f32 v[2:3], v[18:19], s[24:25], v[2:3] op_sel_hi:[1,0,1]
	v_cvt_scalef32_pk_f32_fp4 v[18:19], v68, 1.0 op_sel:[1,0,0]
	v_pk_fma_f32 v[4:5], s[24:25], v[18:19], v[4:5] op_sel_hi:[0,1,1]
	v_cvt_scalef32_pk_f32_fp4 v[18:19], v68, 1.0 op_sel:[0,1,0]
	v_pk_fma_f32 v[6:7], s[24:25], v[18:19], v[6:7] op_sel_hi:[0,1,1]
	v_cvt_scalef32_pk_f32_fp4 v[18:19], v68, 1.0 op_sel:[1,1,0]
	v_pk_fma_f32 v[8:9], s[24:25], v[18:19], v[8:9] op_sel_hi:[0,1,1]
	v_cvt_scalef32_pk_f32_fp4 v[18:19], v69, 1.0
	v_pk_fma_f32 v[10:11], s[24:25], v[18:19], v[10:11] op_sel_hi:[0,1,1]
	v_cvt_scalef32_pk_f32_fp4 v[18:19], v69, 1.0 op_sel:[1,0,0]
	v_pk_fma_f32 v[12:13], s[24:25], v[18:19], v[12:13] op_sel_hi:[0,1,1]
	v_cvt_scalef32_pk_f32_fp4 v[18:19], v69, 1.0 op_sel:[0,1,0]
	v_pk_fma_f32 v[14:15], s[24:25], v[18:19], v[14:15] op_sel_hi:[0,1,1]
	v_cvt_scalef32_pk_f32_fp4 v[18:19], v69, 1.0 op_sel:[1,1,0]
	v_pk_fma_f32 v[16:17], s[24:25], v[18:19], v[16:17] op_sel_hi:[0,1,1]
	v_readlane_b32 s24, v126, 15
	s_waitcnt vmcnt(16)
	v_cvt_scalef32_pk_f32_fp4 v[18:19], v70, 1.0
	v_pk_fma_f32 v[2:3], v[18:19], s[24:25], v[2:3] op_sel_hi:[1,0,1]
	v_cvt_scalef32_pk_f32_fp4 v[18:19], v70, 1.0 op_sel:[1,0,0]
	v_pk_fma_f32 v[4:5], s[24:25], v[18:19], v[4:5] op_sel_hi:[0,1,1]
	v_cvt_scalef32_pk_f32_fp4 v[18:19], v70, 1.0 op_sel:[0,1,0]
	v_pk_fma_f32 v[6:7], s[24:25], v[18:19], v[6:7] op_sel_hi:[0,1,1]
	v_cvt_scalef32_pk_f32_fp4 v[18:19], v70, 1.0 op_sel:[1,1,0]
	v_pk_fma_f32 v[8:9], s[24:25], v[18:19], v[8:9] op_sel_hi:[0,1,1]
	v_cvt_scalef32_pk_f32_fp4 v[18:19], v71, 1.0
	v_pk_fma_f32 v[10:11], s[24:25], v[18:19], v[10:11] op_sel_hi:[0,1,1]
	v_cvt_scalef32_pk_f32_fp4 v[18:19], v71, 1.0 op_sel:[1,0,0]
	v_pk_fma_f32 v[12:13], s[24:25], v[18:19], v[12:13] op_sel_hi:[0,1,1]
	v_cvt_scalef32_pk_f32_fp4 v[18:19], v71, 1.0 op_sel:[0,1,0]
	v_pk_fma_f32 v[14:15], s[24:25], v[18:19], v[14:15] op_sel_hi:[0,1,1]
	v_cvt_scalef32_pk_f32_fp4 v[18:19], v71, 1.0 op_sel:[1,1,0]
	v_pk_fma_f32 v[16:17], s[24:25], v[18:19], v[16:17] op_sel_hi:[0,1,1]
	v_readlane_b32 s24, v126, 16
	s_waitcnt vmcnt(15)
	v_cvt_scalef32_pk_f32_fp4 v[18:19], v72, 1.0
	v_pk_fma_f32 v[2:3], v[18:19], s[24:25], v[2:3] op_sel_hi:[1,0,1]
	v_cvt_scalef32_pk_f32_fp4 v[18:19], v72, 1.0 op_sel:[1,0,0]
	v_pk_fma_f32 v[4:5], s[24:25], v[18:19], v[4:5] op_sel_hi:[0,1,1]
	v_cvt_scalef32_pk_f32_fp4 v[18:19], v72, 1.0 op_sel:[0,1,0]
	v_pk_fma_f32 v[6:7], s[24:25], v[18:19], v[6:7] op_sel_hi:[0,1,1]
	v_cvt_scalef32_pk_f32_fp4 v[18:19], v72, 1.0 op_sel:[1,1,0]
	v_pk_fma_f32 v[8:9], s[24:25], v[18:19], v[8:9] op_sel_hi:[0,1,1]
	v_cvt_scalef32_pk_f32_fp4 v[18:19], v73, 1.0
	v_pk_fma_f32 v[10:11], s[24:25], v[18:19], v[10:11] op_sel_hi:[0,1,1]
	v_cvt_scalef32_pk_f32_fp4 v[18:19], v73, 1.0 op_sel:[1,0,0]
	v_pk_fma_f32 v[12:13], s[24:25], v[18:19], v[12:13] op_sel_hi:[0,1,1]
	v_cvt_scalef32_pk_f32_fp4 v[18:19], v73, 1.0 op_sel:[0,1,0]
	v_pk_fma_f32 v[14:15], s[24:25], v[18:19], v[14:15] op_sel_hi:[0,1,1]
	v_cvt_scalef32_pk_f32_fp4 v[18:19], v73, 1.0 op_sel:[1,1,0]
	v_pk_fma_f32 v[16:17], s[24:25], v[18:19], v[16:17] op_sel_hi:[0,1,1]
	v_readlane_b32 s24, v126, 24
	s_waitcnt vmcnt(14)
	v_cvt_scalef32_pk_f32_fp4 v[18:19], v74, 1.0
	v_pk_fma_f32 v[2:3], v[18:19], s[24:25], v[2:3] op_sel_hi:[1,0,1]
	v_cvt_scalef32_pk_f32_fp4 v[18:19], v74, 1.0 op_sel:[1,0,0]
	v_pk_fma_f32 v[4:5], s[24:25], v[18:19], v[4:5] op_sel_hi:[0,1,1]
	v_cvt_scalef32_pk_f32_fp4 v[18:19], v74, 1.0 op_sel:[0,1,0]
	v_pk_fma_f32 v[6:7], s[24:25], v[18:19], v[6:7] op_sel_hi:[0,1,1]
	v_cvt_scalef32_pk_f32_fp4 v[18:19], v74, 1.0 op_sel:[1,1,0]
	v_pk_fma_f32 v[8:9], s[24:25], v[18:19], v[8:9] op_sel_hi:[0,1,1]
	v_cvt_scalef32_pk_f32_fp4 v[18:19], v75, 1.0
	v_pk_fma_f32 v[10:11], s[24:25], v[18:19], v[10:11] op_sel_hi:[0,1,1]
	v_cvt_scalef32_pk_f32_fp4 v[18:19], v75, 1.0 op_sel:[1,0,0]
	v_pk_fma_f32 v[12:13], s[24:25], v[18:19], v[12:13] op_sel_hi:[0,1,1]
	v_cvt_scalef32_pk_f32_fp4 v[18:19], v75, 1.0 op_sel:[0,1,0]
	v_pk_fma_f32 v[14:15], s[24:25], v[18:19], v[14:15] op_sel_hi:[0,1,1]
	v_cvt_scalef32_pk_f32_fp4 v[18:19], v75, 1.0 op_sel:[1,1,0]
	v_pk_fma_f32 v[16:17], s[24:25], v[18:19], v[16:17] op_sel_hi:[0,1,1]
	v_readlane_b32 s24, v126, 20
	s_waitcnt vmcnt(13)
	v_cvt_scalef32_pk_f32_fp4 v[18:19], v76, 1.0
	v_pk_fma_f32 v[2:3], v[18:19], s[24:25], v[2:3] op_sel_hi:[1,0,1]
	v_cvt_scalef32_pk_f32_fp4 v[18:19], v76, 1.0 op_sel:[1,0,0]
	v_pk_fma_f32 v[4:5], s[24:25], v[18:19], v[4:5] op_sel_hi:[0,1,1]
	v_cvt_scalef32_pk_f32_fp4 v[18:19], v76, 1.0 op_sel:[0,1,0]
	v_pk_fma_f32 v[6:7], s[24:25], v[18:19], v[6:7] op_sel_hi:[0,1,1]
	v_cvt_scalef32_pk_f32_fp4 v[18:19], v76, 1.0 op_sel:[1,1,0]
	v_pk_fma_f32 v[8:9], s[24:25], v[18:19], v[8:9] op_sel_hi:[0,1,1]
	v_cvt_scalef32_pk_f32_fp4 v[18:19], v77, 1.0
	v_pk_fma_f32 v[10:11], s[24:25], v[18:19], v[10:11] op_sel_hi:[0,1,1]
	v_cvt_scalef32_pk_f32_fp4 v[18:19], v77, 1.0 op_sel:[1,0,0]
	v_pk_fma_f32 v[12:13], s[24:25], v[18:19], v[12:13] op_sel_hi:[0,1,1]
	v_cvt_scalef32_pk_f32_fp4 v[18:19], v77, 1.0 op_sel:[0,1,0]
	v_pk_fma_f32 v[14:15], s[24:25], v[18:19], v[14:15] op_sel_hi:[0,1,1]
	v_cvt_scalef32_pk_f32_fp4 v[18:19], v77, 1.0 op_sel:[1,1,0]
	v_pk_fma_f32 v[16:17], s[24:25], v[18:19], v[16:17] op_sel_hi:[0,1,1]
	v_readlane_b32 s24, v126, 28
	s_waitcnt vmcnt(12)
	v_cvt_scalef32_pk_f32_fp4 v[18:19], v78, 1.0
	v_pk_fma_f32 v[2:3], v[18:19], s[24:25], v[2:3] op_sel_hi:[1,0,1]
	v_cvt_scalef32_pk_f32_fp4 v[18:19], v78, 1.0 op_sel:[1,0,0]
	v_pk_fma_f32 v[4:5], s[24:25], v[18:19], v[4:5] op_sel_hi:[0,1,1]
	v_cvt_scalef32_pk_f32_fp4 v[18:19], v78, 1.0 op_sel:[0,1,0]
	v_pk_fma_f32 v[6:7], s[24:25], v[18:19], v[6:7] op_sel_hi:[0,1,1]
	v_cvt_scalef32_pk_f32_fp4 v[18:19], v78, 1.0 op_sel:[1,1,0]
	v_pk_fma_f32 v[8:9], s[24:25], v[18:19], v[8:9] op_sel_hi:[0,1,1]
	v_cvt_scalef32_pk_f32_fp4 v[18:19], v79, 1.0
	v_pk_fma_f32 v[10:11], s[24:25], v[18:19], v[10:11] op_sel_hi:[0,1,1]
	v_cvt_scalef32_pk_f32_fp4 v[18:19], v79, 1.0 op_sel:[1,0,0]
	v_pk_fma_f32 v[12:13], s[24:25], v[18:19], v[12:13] op_sel_hi:[0,1,1]
	v_cvt_scalef32_pk_f32_fp4 v[18:19], v79, 1.0 op_sel:[0,1,0]
	v_pk_fma_f32 v[14:15], s[24:25], v[18:19], v[14:15] op_sel_hi:[0,1,1]
	v_cvt_scalef32_pk_f32_fp4 v[18:19], v79, 1.0 op_sel:[1,1,0]
	v_pk_fma_f32 v[16:17], s[24:25], v[18:19], v[16:17] op_sel_hi:[0,1,1]
	v_readlane_b32 s24, v126, 18
	s_waitcnt vmcnt(11)
	v_cvt_scalef32_pk_f32_fp4 v[18:19], v80, 1.0
	v_pk_fma_f32 v[2:3], v[18:19], s[24:25], v[2:3] op_sel_hi:[1,0,1]
	v_cvt_scalef32_pk_f32_fp4 v[18:19], v80, 1.0 op_sel:[1,0,0]
	v_pk_fma_f32 v[4:5], s[24:25], v[18:19], v[4:5] op_sel_hi:[0,1,1]
	v_cvt_scalef32_pk_f32_fp4 v[18:19], v80, 1.0 op_sel:[0,1,0]
	v_pk_fma_f32 v[6:7], s[24:25], v[18:19], v[6:7] op_sel_hi:[0,1,1]
	v_cvt_scalef32_pk_f32_fp4 v[18:19], v80, 1.0 op_sel:[1,1,0]
	v_pk_fma_f32 v[8:9], s[24:25], v[18:19], v[8:9] op_sel_hi:[0,1,1]
	v_cvt_scalef32_pk_f32_fp4 v[18:19], v81, 1.0
	v_pk_fma_f32 v[10:11], s[24:25], v[18:19], v[10:11] op_sel_hi:[0,1,1]
	v_cvt_scalef32_pk_f32_fp4 v[18:19], v81, 1.0 op_sel:[1,0,0]
	v_pk_fma_f32 v[12:13], s[24:25], v[18:19], v[12:13] op_sel_hi:[0,1,1]
	v_cvt_scalef32_pk_f32_fp4 v[18:19], v81, 1.0 op_sel:[0,1,0]
	v_pk_fma_f32 v[14:15], s[24:25], v[18:19], v[14:15] op_sel_hi:[0,1,1]
	v_cvt_scalef32_pk_f32_fp4 v[18:19], v81, 1.0 op_sel:[1,1,0]
	v_pk_fma_f32 v[16:17], s[24:25], v[18:19], v[16:17] op_sel_hi:[0,1,1]
	v_readlane_b32 s24, v126, 26
	s_waitcnt vmcnt(10)
	v_cvt_scalef32_pk_f32_fp4 v[18:19], v82, 1.0
	v_pk_fma_f32 v[2:3], v[18:19], s[24:25], v[2:3] op_sel_hi:[1,0,1]
	v_cvt_scalef32_pk_f32_fp4 v[18:19], v82, 1.0 op_sel:[1,0,0]
	v_pk_fma_f32 v[4:5], s[24:25], v[18:19], v[4:5] op_sel_hi:[0,1,1]
	v_cvt_scalef32_pk_f32_fp4 v[18:19], v82, 1.0 op_sel:[0,1,0]
	v_pk_fma_f32 v[6:7], s[24:25], v[18:19], v[6:7] op_sel_hi:[0,1,1]
	v_cvt_scalef32_pk_f32_fp4 v[18:19], v82, 1.0 op_sel:[1,1,0]
	v_pk_fma_f32 v[8:9], s[24:25], v[18:19], v[8:9] op_sel_hi:[0,1,1]
	v_cvt_scalef32_pk_f32_fp4 v[18:19], v83, 1.0
	v_pk_fma_f32 v[10:11], s[24:25], v[18:19], v[10:11] op_sel_hi:[0,1,1]
	v_cvt_scalef32_pk_f32_fp4 v[18:19], v83, 1.0 op_sel:[1,0,0]
	v_pk_fma_f32 v[12:13], s[24:25], v[18:19], v[12:13] op_sel_hi:[0,1,1]
	v_cvt_scalef32_pk_f32_fp4 v[18:19], v83, 1.0 op_sel:[0,1,0]
	v_pk_fma_f32 v[14:15], s[24:25], v[18:19], v[14:15] op_sel_hi:[0,1,1]
	v_cvt_scalef32_pk_f32_fp4 v[18:19], v83, 1.0 op_sel:[1,1,0]
	v_pk_fma_f32 v[16:17], s[24:25], v[18:19], v[16:17] op_sel_hi:[0,1,1]
	v_readlane_b32 s24, v126, 22
	s_waitcnt vmcnt(9)
	v_cvt_scalef32_pk_f32_fp4 v[18:19], v84, 1.0
	v_add_u32_e32 v116, 32, v116
	v_pk_fma_f32 v[2:3], v[18:19], s[24:25], v[2:3] op_sel_hi:[1,0,1]
	v_cvt_scalef32_pk_f32_fp4 v[18:19], v84, 1.0 op_sel:[1,0,0]
	v_pk_fma_f32 v[4:5], s[24:25], v[18:19], v[4:5] op_sel_hi:[0,1,1]
	v_cvt_scalef32_pk_f32_fp4 v[18:19], v84, 1.0 op_sel:[0,1,0]
	v_pk_fma_f32 v[6:7], s[24:25], v[18:19], v[6:7] op_sel_hi:[0,1,1]
	v_cvt_scalef32_pk_f32_fp4 v[18:19], v84, 1.0 op_sel:[1,1,0]
	v_pk_fma_f32 v[8:9], s[24:25], v[18:19], v[8:9] op_sel_hi:[0,1,1]
	v_cvt_scalef32_pk_f32_fp4 v[18:19], v85, 1.0
	v_pk_fma_f32 v[10:11], s[24:25], v[18:19], v[10:11] op_sel_hi:[0,1,1]
	v_cvt_scalef32_pk_f32_fp4 v[18:19], v85, 1.0 op_sel:[1,0,0]
	v_pk_fma_f32 v[12:13], s[24:25], v[18:19], v[12:13] op_sel_hi:[0,1,1]
	v_cvt_scalef32_pk_f32_fp4 v[18:19], v85, 1.0 op_sel:[0,1,0]
	v_pk_fma_f32 v[14:15], s[24:25], v[18:19], v[14:15] op_sel_hi:[0,1,1]
	v_cvt_scalef32_pk_f32_fp4 v[18:19], v85, 1.0 op_sel:[1,1,0]
	v_pk_fma_f32 v[16:17], s[24:25], v[18:19], v[16:17] op_sel_hi:[0,1,1]
	v_readlane_b32 s24, v126, 30
	s_waitcnt vmcnt(8)
	v_cvt_scalef32_pk_f32_fp4 v[18:19], v86, 1.0
	v_cmp_ge_u32_e32 vcc, v116, v51
	v_pk_fma_f32 v[2:3], v[18:19], s[24:25], v[2:3] op_sel_hi:[1,0,1]
	v_cvt_scalef32_pk_f32_fp4 v[18:19], v86, 1.0 op_sel:[1,0,0]
	v_pk_fma_f32 v[4:5], s[24:25], v[18:19], v[4:5] op_sel_hi:[0,1,1]
	v_cvt_scalef32_pk_f32_fp4 v[18:19], v86, 1.0 op_sel:[0,1,0]
	v_pk_fma_f32 v[6:7], s[24:25], v[18:19], v[6:7] op_sel_hi:[0,1,1]
	v_cvt_scalef32_pk_f32_fp4 v[18:19], v86, 1.0 op_sel:[1,1,0]
	v_pk_fma_f32 v[8:9], s[24:25], v[18:19], v[8:9] op_sel_hi:[0,1,1]
	v_cvt_scalef32_pk_f32_fp4 v[18:19], v87, 1.0
	v_pk_fma_f32 v[10:11], s[24:25], v[18:19], v[10:11] op_sel_hi:[0,1,1]
	v_cvt_scalef32_pk_f32_fp4 v[18:19], v87, 1.0 op_sel:[1,0,0]
	v_pk_fma_f32 v[12:13], s[24:25], v[18:19], v[12:13] op_sel_hi:[0,1,1]
	v_cvt_scalef32_pk_f32_fp4 v[18:19], v87, 1.0 op_sel:[0,1,0]
	v_pk_fma_f32 v[14:15], s[24:25], v[18:19], v[14:15] op_sel_hi:[0,1,1]
	v_cvt_scalef32_pk_f32_fp4 v[18:19], v87, 1.0 op_sel:[1,1,0]
	v_pk_fma_f32 v[16:17], s[24:25], v[18:19], v[16:17] op_sel_hi:[0,1,1]
	s_waitcnt vmcnt(7)
	v_cvt_scalef32_pk_f32_fp4 v[18:19], v88, 1.0
	s_or_b64 s[12:13], vcc, s[12:13]
	s_nop 0
	v_readlane_b32 s24, v126, 17
	s_nop 1
	v_pk_fma_f32 v[2:3], v[18:19], s[24:25], v[2:3] op_sel_hi:[1,0,1]
	v_cvt_scalef32_pk_f32_fp4 v[18:19], v88, 1.0 op_sel:[1,0,0]
	v_pk_fma_f32 v[4:5], s[24:25], v[18:19], v[4:5] op_sel_hi:[0,1,1]
	v_cvt_scalef32_pk_f32_fp4 v[18:19], v88, 1.0 op_sel:[0,1,0]
	v_pk_fma_f32 v[6:7], s[24:25], v[18:19], v[6:7] op_sel_hi:[0,1,1]
	v_cvt_scalef32_pk_f32_fp4 v[18:19], v88, 1.0 op_sel:[1,1,0]
	v_pk_fma_f32 v[8:9], s[24:25], v[18:19], v[8:9] op_sel_hi:[0,1,1]
	v_cvt_scalef32_pk_f32_fp4 v[18:19], v89, 1.0
	v_pk_fma_f32 v[10:11], s[24:25], v[18:19], v[10:11] op_sel_hi:[0,1,1]
	v_cvt_scalef32_pk_f32_fp4 v[18:19], v89, 1.0 op_sel:[1,0,0]
	v_pk_fma_f32 v[12:13], s[24:25], v[18:19], v[12:13] op_sel_hi:[0,1,1]
	v_cvt_scalef32_pk_f32_fp4 v[18:19], v89, 1.0 op_sel:[0,1,0]
	v_pk_fma_f32 v[14:15], s[24:25], v[18:19], v[14:15] op_sel_hi:[0,1,1]
	v_cvt_scalef32_pk_f32_fp4 v[18:19], v89, 1.0 op_sel:[1,1,0]
	v_pk_fma_f32 v[16:17], s[24:25], v[18:19], v[16:17] op_sel_hi:[0,1,1]
	s_waitcnt vmcnt(6)
	v_cvt_scalef32_pk_f32_fp4 v[18:19], v90, 1.0
	s_nop 1
	v_readlane_b32 s24, v126, 25
	s_nop 1
	v_pk_fma_f32 v[2:3], v[18:19], s[24:25], v[2:3] op_sel_hi:[1,0,1]
	v_cvt_scalef32_pk_f32_fp4 v[18:19], v90, 1.0 op_sel:[1,0,0]
	v_pk_fma_f32 v[4:5], s[24:25], v[18:19], v[4:5] op_sel_hi:[0,1,1]
	v_cvt_scalef32_pk_f32_fp4 v[18:19], v90, 1.0 op_sel:[0,1,0]
	v_pk_fma_f32 v[6:7], s[24:25], v[18:19], v[6:7] op_sel_hi:[0,1,1]
	v_cvt_scalef32_pk_f32_fp4 v[18:19], v90, 1.0 op_sel:[1,1,0]
	v_pk_fma_f32 v[8:9], s[24:25], v[18:19], v[8:9] op_sel_hi:[0,1,1]
	v_cvt_scalef32_pk_f32_fp4 v[18:19], v91, 1.0
	v_pk_fma_f32 v[10:11], s[24:25], v[18:19], v[10:11] op_sel_hi:[0,1,1]
	v_cvt_scalef32_pk_f32_fp4 v[18:19], v91, 1.0 op_sel:[1,0,0]
	v_pk_fma_f32 v[12:13], s[24:25], v[18:19], v[12:13] op_sel_hi:[0,1,1]
	v_cvt_scalef32_pk_f32_fp4 v[18:19], v91, 1.0 op_sel:[0,1,0]
	v_pk_fma_f32 v[14:15], s[24:25], v[18:19], v[14:15] op_sel_hi:[0,1,1]
	v_cvt_scalef32_pk_f32_fp4 v[18:19], v91, 1.0 op_sel:[1,1,0]
	v_pk_fma_f32 v[16:17], s[24:25], v[18:19], v[16:17] op_sel_hi:[0,1,1]
	s_waitcnt vmcnt(5)
	v_cvt_scalef32_pk_f32_fp4 v[18:19], v92, 1.0
	s_nop 1
	v_readlane_b32 s24, v126, 21
	s_nop 1
	v_pk_fma_f32 v[2:3], v[18:19], s[24:25], v[2:3] op_sel_hi:[1,0,1]
	v_cvt_scalef32_pk_f32_fp4 v[18:19], v92, 1.0 op_sel:[1,0,0]
	v_pk_fma_f32 v[4:5], s[24:25], v[18:19], v[4:5] op_sel_hi:[0,1,1]
	v_cvt_scalef32_pk_f32_fp4 v[18:19], v92, 1.0 op_sel:[0,1,0]
	v_pk_fma_f32 v[6:7], s[24:25], v[18:19], v[6:7] op_sel_hi:[0,1,1]
	v_cvt_scalef32_pk_f32_fp4 v[18:19], v92, 1.0 op_sel:[1,1,0]
	v_pk_fma_f32 v[8:9], s[24:25], v[18:19], v[8:9] op_sel_hi:[0,1,1]
	v_cvt_scalef32_pk_f32_fp4 v[18:19], v93, 1.0
	v_pk_fma_f32 v[10:11], s[24:25], v[18:19], v[10:11] op_sel_hi:[0,1,1]
	v_cvt_scalef32_pk_f32_fp4 v[18:19], v93, 1.0 op_sel:[1,0,0]
	v_pk_fma_f32 v[12:13], s[24:25], v[18:19], v[12:13] op_sel_hi:[0,1,1]
	v_cvt_scalef32_pk_f32_fp4 v[18:19], v93, 1.0 op_sel:[0,1,0]
	v_pk_fma_f32 v[14:15], s[24:25], v[18:19], v[14:15] op_sel_hi:[0,1,1]
	v_cvt_scalef32_pk_f32_fp4 v[18:19], v93, 1.0 op_sel:[1,1,0]
	v_pk_fma_f32 v[16:17], s[24:25], v[18:19], v[16:17] op_sel_hi:[0,1,1]
	s_waitcnt vmcnt(4)
	v_cvt_scalef32_pk_f32_fp4 v[18:19], v94, 1.0
	s_nop 1
	v_readlane_b32 s24, v126, 29
	s_nop 1
	v_pk_fma_f32 v[2:3], v[18:19], s[24:25], v[2:3] op_sel_hi:[1,0,1]
	v_cvt_scalef32_pk_f32_fp4 v[18:19], v94, 1.0 op_sel:[1,0,0]
	v_pk_fma_f32 v[4:5], s[24:25], v[18:19], v[4:5] op_sel_hi:[0,1,1]
	v_cvt_scalef32_pk_f32_fp4 v[18:19], v94, 1.0 op_sel:[0,1,0]
	v_pk_fma_f32 v[6:7], s[24:25], v[18:19], v[6:7] op_sel_hi:[0,1,1]
	v_cvt_scalef32_pk_f32_fp4 v[18:19], v94, 1.0 op_sel:[1,1,0]
	v_pk_fma_f32 v[8:9], s[24:25], v[18:19], v[8:9] op_sel_hi:[0,1,1]
	v_cvt_scalef32_pk_f32_fp4 v[18:19], v95, 1.0
	v_pk_fma_f32 v[10:11], s[24:25], v[18:19], v[10:11] op_sel_hi:[0,1,1]
	v_cvt_scalef32_pk_f32_fp4 v[18:19], v95, 1.0 op_sel:[1,0,0]
	v_pk_fma_f32 v[12:13], s[24:25], v[18:19], v[12:13] op_sel_hi:[0,1,1]
	v_cvt_scalef32_pk_f32_fp4 v[18:19], v95, 1.0 op_sel:[0,1,0]
	v_pk_fma_f32 v[14:15], s[24:25], v[18:19], v[14:15] op_sel_hi:[0,1,1]
	v_cvt_scalef32_pk_f32_fp4 v[18:19], v95, 1.0 op_sel:[1,1,0]
	v_pk_fma_f32 v[16:17], s[24:25], v[18:19], v[16:17] op_sel_hi:[0,1,1]
	s_waitcnt vmcnt(3)
	v_cvt_scalef32_pk_f32_fp4 v[18:19], v96, 1.0
	s_nop 1
	v_readlane_b32 s24, v126, 19
	s_nop 1
	v_pk_fma_f32 v[2:3], v[18:19], s[24:25], v[2:3] op_sel_hi:[1,0,1]
	v_cvt_scalef32_pk_f32_fp4 v[18:19], v96, 1.0 op_sel:[1,0,0]
	v_pk_fma_f32 v[4:5], s[24:25], v[18:19], v[4:5] op_sel_hi:[0,1,1]
	v_cvt_scalef32_pk_f32_fp4 v[18:19], v96, 1.0 op_sel:[0,1,0]
	v_pk_fma_f32 v[6:7], s[24:25], v[18:19], v[6:7] op_sel_hi:[0,1,1]
	v_cvt_scalef32_pk_f32_fp4 v[18:19], v96, 1.0 op_sel:[1,1,0]
	v_pk_fma_f32 v[8:9], s[24:25], v[18:19], v[8:9] op_sel_hi:[0,1,1]
	v_cvt_scalef32_pk_f32_fp4 v[18:19], v97, 1.0
	v_pk_fma_f32 v[10:11], s[24:25], v[18:19], v[10:11] op_sel_hi:[0,1,1]
	v_cvt_scalef32_pk_f32_fp4 v[18:19], v97, 1.0 op_sel:[1,0,0]
	v_pk_fma_f32 v[12:13], s[24:25], v[18:19], v[12:13] op_sel_hi:[0,1,1]
	v_cvt_scalef32_pk_f32_fp4 v[18:19], v97, 1.0 op_sel:[0,1,0]
	v_pk_fma_f32 v[14:15], s[24:25], v[18:19], v[14:15] op_sel_hi:[0,1,1]
	v_cvt_scalef32_pk_f32_fp4 v[18:19], v97, 1.0 op_sel:[1,1,0]
	v_pk_fma_f32 v[16:17], s[24:25], v[18:19], v[16:17] op_sel_hi:[0,1,1]
	s_waitcnt vmcnt(2)
	v_cvt_scalef32_pk_f32_fp4 v[18:19], v98, 1.0
	s_nop 1
	v_readlane_b32 s24, v126, 27
	s_nop 1
	v_pk_fma_f32 v[2:3], v[18:19], s[24:25], v[2:3] op_sel_hi:[1,0,1]
	v_cvt_scalef32_pk_f32_fp4 v[18:19], v98, 1.0 op_sel:[1,0,0]
	v_pk_fma_f32 v[4:5], s[24:25], v[18:19], v[4:5] op_sel_hi:[0,1,1]
	v_cvt_scalef32_pk_f32_fp4 v[18:19], v98, 1.0 op_sel:[0,1,0]
	v_pk_fma_f32 v[6:7], s[24:25], v[18:19], v[6:7] op_sel_hi:[0,1,1]
	v_cvt_scalef32_pk_f32_fp4 v[18:19], v98, 1.0 op_sel:[1,1,0]
	v_pk_fma_f32 v[8:9], s[24:25], v[18:19], v[8:9] op_sel_hi:[0,1,1]
	v_cvt_scalef32_pk_f32_fp4 v[18:19], v99, 1.0
	v_pk_fma_f32 v[10:11], s[24:25], v[18:19], v[10:11] op_sel_hi:[0,1,1]
	v_cvt_scalef32_pk_f32_fp4 v[18:19], v99, 1.0 op_sel:[1,0,0]
	v_pk_fma_f32 v[12:13], s[24:25], v[18:19], v[12:13] op_sel_hi:[0,1,1]
	v_cvt_scalef32_pk_f32_fp4 v[18:19], v99, 1.0 op_sel:[0,1,0]
	v_pk_fma_f32 v[14:15], s[24:25], v[18:19], v[14:15] op_sel_hi:[0,1,1]
	v_cvt_scalef32_pk_f32_fp4 v[18:19], v99, 1.0 op_sel:[1,1,0]
	v_pk_fma_f32 v[16:17], s[24:25], v[18:19], v[16:17] op_sel_hi:[0,1,1]
	s_waitcnt vmcnt(1)
	v_cvt_scalef32_pk_f32_fp4 v[18:19], v100, 1.0
	s_nop 1
	v_readlane_b32 s24, v126, 23
	s_nop 1
	v_pk_fma_f32 v[2:3], v[18:19], s[24:25], v[2:3] op_sel_hi:[1,0,1]
	v_cvt_scalef32_pk_f32_fp4 v[18:19], v100, 1.0 op_sel:[1,0,0]
	v_pk_fma_f32 v[4:5], s[24:25], v[18:19], v[4:5] op_sel_hi:[0,1,1]
	v_cvt_scalef32_pk_f32_fp4 v[18:19], v100, 1.0 op_sel:[0,1,0]
	v_pk_fma_f32 v[6:7], s[24:25], v[18:19], v[6:7] op_sel_hi:[0,1,1]
	v_cvt_scalef32_pk_f32_fp4 v[18:19], v100, 1.0 op_sel:[1,1,0]
	v_pk_fma_f32 v[8:9], s[24:25], v[18:19], v[8:9] op_sel_hi:[0,1,1]
	v_cvt_scalef32_pk_f32_fp4 v[18:19], v101, 1.0
	v_pk_fma_f32 v[10:11], s[24:25], v[18:19], v[10:11] op_sel_hi:[0,1,1]
	v_cvt_scalef32_pk_f32_fp4 v[18:19], v101, 1.0 op_sel:[1,0,0]
	v_pk_fma_f32 v[12:13], s[24:25], v[18:19], v[12:13] op_sel_hi:[0,1,1]
	v_cvt_scalef32_pk_f32_fp4 v[18:19], v101, 1.0 op_sel:[0,1,0]
	v_pk_fma_f32 v[14:15], s[24:25], v[18:19], v[14:15] op_sel_hi:[0,1,1]
	v_cvt_scalef32_pk_f32_fp4 v[18:19], v101, 1.0 op_sel:[1,1,0]
	v_pk_fma_f32 v[16:17], s[24:25], v[18:19], v[16:17] op_sel_hi:[0,1,1]
	s_waitcnt vmcnt(0)
	v_cvt_scalef32_pk_f32_fp4 v[18:19], v102, 1.0
	s_nop 1
	v_readlane_b32 s24, v126, 31
	s_nop 1
	v_pk_fma_f32 v[2:3], v[18:19], s[24:25], v[2:3] op_sel_hi:[1,0,1]
	v_cvt_scalef32_pk_f32_fp4 v[18:19], v102, 1.0 op_sel:[1,0,0]
	v_pk_fma_f32 v[4:5], s[24:25], v[18:19], v[4:5] op_sel_hi:[0,1,1]
	v_cvt_scalef32_pk_f32_fp4 v[18:19], v102, 1.0 op_sel:[0,1,0]
	v_pk_fma_f32 v[6:7], s[24:25], v[18:19], v[6:7] op_sel_hi:[0,1,1]
	v_cvt_scalef32_pk_f32_fp4 v[18:19], v102, 1.0 op_sel:[1,1,0]
	v_pk_fma_f32 v[8:9], s[24:25], v[18:19], v[8:9] op_sel_hi:[0,1,1]
	v_cvt_scalef32_pk_f32_fp4 v[18:19], v103, 1.0
	v_pk_fma_f32 v[10:11], s[24:25], v[18:19], v[10:11] op_sel_hi:[0,1,1]
	v_cvt_scalef32_pk_f32_fp4 v[18:19], v103, 1.0 op_sel:[1,0,0]
	v_pk_fma_f32 v[12:13], s[24:25], v[18:19], v[12:13] op_sel_hi:[0,1,1]
	v_cvt_scalef32_pk_f32_fp4 v[18:19], v103, 1.0 op_sel:[0,1,0]
	v_pk_fma_f32 v[14:15], s[24:25], v[18:19], v[14:15] op_sel_hi:[0,1,1]
	v_cvt_scalef32_pk_f32_fp4 v[18:19], v103, 1.0 op_sel:[1,1,0]
	v_pk_fma_f32 v[16:17], s[24:25], v[18:19], v[16:17] op_sel_hi:[0,1,1]
	s_branch .Lh3_v19_join
.Lh3_v19_hi:
	v_readlane_b32 s84, v102, 32
	v_readlane_b32 s86, v102, 33
	v_readlane_b32 s88, v102, 34
	v_readlane_b32 s90, v102, 35
	s_lshl_b32 s84, s84, 9
	s_lshl_b32 s86, s86, 9
	s_lshl_b32 s88, s88, 9
	s_lshl_b32 s90, s90, 9
	s_add_u32 s84, s93, s84
	s_addc_u32 s85, s94, 0
	s_add_u32 s86, s93, s86
	s_addc_u32 s87, s94, 0
	s_add_u32 s88, s93, s88
	s_addc_u32 s89, s94, 0
	s_add_u32 s90, s93, s90
	s_addc_u32 s91, s94, 0
	global_load_dwordx2 v[18:19], v255, s[84:85]
	global_load_dwordx2 v[20:21], v255, s[86:87]
	global_load_dwordx2 v[22:23], v255, s[88:89]
	global_load_dwordx2 v[24:25], v255, s[90:91]
	v_readlane_b32 s84, v102, 36
	v_readlane_b32 s86, v102, 37
	v_readlane_b32 s88, v102, 38
	v_readlane_b32 s90, v102, 39
	s_lshl_b32 s84, s84, 9
	s_lshl_b32 s86, s86, 9
	s_lshl_b32 s88, s88, 9
	s_lshl_b32 s90, s90, 9
	s_add_u32 s84, s93, s84
	s_addc_u32 s85, s94, 0
	s_add_u32 s86, s93, s86
	s_addc_u32 s87, s94, 0
	s_add_u32 s88, s93, s88
	s_addc_u32 s89, s94, 0
	s_add_u32 s90, s93, s90
	s_addc_u32 s91, s94, 0
	global_load_dwordx2 v[26:27], v255, s[84:85]
	global_load_dwordx2 v[28:29], v255, s[86:87]
	global_load_dwordx2 v[30:31], v255, s[88:89]
	global_load_dwordx2 v[32:33], v255, s[90:91]
	v_readlane_b32 s84, v102, 40
	v_readlane_b32 s86, v102, 41
	v_readlane_b32 s88, v102, 42
	v_readlane_b32 s90, v102, 43
	s_lshl_b32 s84, s84, 9
	s_lshl_b32 s86, s86, 9
	s_lshl_b32 s88, s88, 9
	s_lshl_b32 s90, s90, 9
	s_add_u32 s84, s93, s84
	s_addc_u32 s85, s94, 0
	s_add_u32 s86, s93, s86
	s_addc_u32 s87, s94, 0
	s_add_u32 s88, s93, s88
	s_addc_u32 s89, s94, 0
	s_add_u32 s90, s93, s90
	s_addc_u32 s91, s94, 0
	global_load_dwordx2 v[56:57], v255, s[84:85]
	global_load_dwordx2 v[58:59], v255, s[86:87]
	global_load_dwordx2 v[60:61], v255, s[88:89]
	global_load_dwordx2 v[62:63], v255, s[90:91]
	v_readlane_b32 s84, v102, 44
	v_readlane_b32 s86, v102, 45
	v_readlane_b32 s88, v102, 46
	v_readlane_b32 s90, v102, 47
	s_lshl_b32 s84, s84, 9
	s_lshl_b32 s86, s86, 9
	s_lshl_b32 s88, s88, 9
	s_lshl_b32 s90, s90, 9
	s_add_u32 s84, s93, s84
	s_addc_u32 s85, s94, 0
	s_add_u32 s86, s93, s86
	s_addc_u32 s87, s94, 0
	s_add_u32 s88, s93, s88
	s_addc_u32 s89, s94, 0
	s_add_u32 s90, s93, s90
	s_addc_u32 s91, s94, 0
	global_load_dwordx2 v[64:65], v255, s[84:85]
	global_load_dwordx2 v[66:67], v255, s[86:87]
	global_load_dwordx2 v[68:69], v255, s[88:89]
	global_load_dwordx2 v[70:71], v255, s[90:91]
	v_readlane_b32 s84, v102, 48
	v_readlane_b32 s86, v102, 49
	v_readlane_b32 s88, v102, 50
	v_readlane_b32 s90, v102, 51
	s_lshl_b32 s84, s84, 9
	s_lshl_b32 s86, s86, 9
	s_lshl_b32 s88, s88, 9
	s_lshl_b32 s90, s90, 9
	s_add_u32 s84, s93, s84
	s_addc_u32 s85, s94, 0
	s_add_u32 s86, s93, s86
	s_addc_u32 s87, s94, 0
	s_add_u32 s88, s93, s88
	s_addc_u32 s89, s94, 0
	s_add_u32 s90, s93, s90
	s_addc_u32 s91, s94, 0
	global_load_dwordx2 v[72:73], v255, s[84:85]
	global_load_dwordx2 v[74:75], v255, s[86:87]
	global_load_dwordx2 v[76:77], v255, s[88:89]
	global_load_dwordx2 v[78:79], v255, s[90:91]
	v_readlane_b32 s84, v102, 52
	v_readlane_b32 s86, v102, 53
	v_readlane_b32 s88, v102, 54
	v_readlane_b32 s90, v102, 55
	s_lshl_b32 s84, s84, 9
	s_lshl_b32 s86, s86, 9
	s_lshl_b32 s88, s88, 9
	s_lshl_b32 s90, s90, 9
	s_add_u32 s84, s93, s84
	s_addc_u32 s85, s94, 0
	s_add_u32 s86, s93, s86
	s_addc_u32 s87, s94, 0
	s_add_u32 s88, s93, s88
	s_addc_u32 s89, s94, 0
	s_add_u32 s90, s93, s90
	s_addc_u32 s91, s94, 0
	global_load_dwordx2 v[80:81], v255, s[84:85]
	global_load_dwordx2 v[82:83], v255, s[86:87]
	global_load_dwordx2 v[84:85], v255, s[88:89]
	global_load_dwordx2 v[86:87], v255, s[90:91]
	v_readlane_b32 s84, v102, 56
	v_readlane_b32 s86, v102, 57
	v_readlane_b32 s88, v102, 58
	v_readlane_b32 s90, v102, 59
	s_lshl_b32 s84, s84, 9
	s_lshl_b32 s86, s86, 9
	s_lshl_b32 s88, s88, 9
	s_lshl_b32 s90, s90, 9
	s_add_u32 s84, s93, s84
	s_addc_u32 s85, s94, 0
	s_add_u32 s86, s93, s86
	s_addc_u32 s87, s94, 0
	s_add_u32 s88, s93, s88
	s_addc_u32 s89, s94, 0
	s_add_u32 s90, s93, s90
	s_addc_u32 s91, s94, 0
	global_load_dwordx2 v[88:89], v255, s[84:85]
	global_load_dwordx2 v[90:91], v255, s[86:87]
	global_load_dwordx2 v[92:93], v255, s[88:89]
	global_load_dwordx2 v[94:95], v255, s[90:91]
	v_readlane_b32 s84, v102, 60
	v_readlane_b32 s86, v102, 61
	v_readlane_b32 s88, v102, 62
	v_readlane_b32 s90, v102, 63
	s_lshl_b32 s84, s84, 9
	s_lshl_b32 s86, s86, 9
	s_lshl_b32 s88, s88, 9
	s_lshl_b32 s90, s90, 9
	s_add_u32 s84, s93, s84
	s_addc_u32 s85, s94, 0
	s_add_u32 s86, s93, s86
	s_addc_u32 s87, s94, 0
	s_add_u32 s88, s93, s88
	s_addc_u32 s89, s94, 0
	s_add_u32 s90, s93, s90
	s_addc_u32 s91, s94, 0
	global_load_dwordx2 v[96:97], v255, s[84:85]
	global_load_dwordx2 v[98:99], v255, s[86:87]
	global_load_dwordx2 v[100:101], v255, s[88:89]
	global_load_dwordx2 v[102:103], v255, s[90:91]
	v_cndmask_b32_e32 v126, v1, v118, vcc
	s_nop 0
	v_readlane_b32 s48, v126, 32
	s_waitcnt vmcnt(31)
	v_cvt_scalef32_pk_f32_fp4 v[128:129], v18, 1.0
	v_pk_fma_f32 v[2:3], v[128:129], s[48:49], v[2:3] op_sel_hi:[1,0,1]
	v_cvt_scalef32_pk_f32_fp4 v[128:129], v18, 1.0 op_sel:[1,0,0]
	v_pk_fma_f32 v[4:5], s[48:49], v[128:129], v[4:5] op_sel_hi:[0,1,1]
	v_cvt_scalef32_pk_f32_fp4 v[128:129], v18, 1.0 op_sel:[0,1,0]
	v_pk_fma_f32 v[6:7], s[48:49], v[128:129], v[6:7] op_sel_hi:[0,1,1]
	v_cvt_scalef32_pk_f32_fp4 v[128:129], v18, 1.0 op_sel:[1,1,0]
	v_pk_fma_f32 v[8:9], s[48:49], v[128:129], v[8:9] op_sel_hi:[0,1,1]
	v_cvt_scalef32_pk_f32_fp4 v[128:129], v19, 1.0
	v_pk_fma_f32 v[10:11], s[48:49], v[128:129], v[10:11] op_sel_hi:[0,1,1]
	v_cvt_scalef32_pk_f32_fp4 v[128:129], v19, 1.0 op_sel:[1,0,0]
	v_pk_fma_f32 v[12:13], s[48:49], v[128:129], v[12:13] op_sel_hi:[0,1,1]
	v_cvt_scalef32_pk_f32_fp4 v[128:129], v19, 1.0 op_sel:[0,1,0]
	v_cvt_scalef32_pk_f32_fp4 v[18:19], v19, 1.0 op_sel:[1,1,0]
	v_pk_fma_f32 v[14:15], s[48:49], v[128:129], v[14:15] op_sel_hi:[0,1,1]
	v_pk_fma_f32 v[16:17], s[48:49], v[18:19], v[16:17] op_sel_hi:[0,1,1]
	v_readlane_b32 s48, v126, 40
	s_waitcnt vmcnt(30)
	v_cvt_scalef32_pk_f32_fp4 v[18:19], v20, 1.0
	v_pk_fma_f32 v[2:3], v[18:19], s[48:49], v[2:3] op_sel_hi:[1,0,1]
	v_cvt_scalef32_pk_f32_fp4 v[18:19], v20, 1.0 op_sel:[1,0,0]
	v_pk_fma_f32 v[4:5], s[48:49], v[18:19], v[4:5] op_sel_hi:[0,1,1]
	v_cvt_scalef32_pk_f32_fp4 v[18:19], v20, 1.0 op_sel:[0,1,0]
	v_pk_fma_f32 v[6:7], s[48:49], v[18:19], v[6:7] op_sel_hi:[0,1,1]
	v_cvt_scalef32_pk_f32_fp4 v[18:19], v20, 1.0 op_sel:[1,1,0]
	v_pk_fma_f32 v[8:9], s[48:49], v[18:19], v[8:9] op_sel_hi:[0,1,1]
	v_cvt_scalef32_pk_f32_fp4 v[18:19], v21, 1.0
	v_pk_fma_f32 v[10:11], s[48:49], v[18:19], v[10:11] op_sel_hi:[0,1,1]
	v_cvt_scalef32_pk_f32_fp4 v[18:19], v21, 1.0 op_sel:[1,0,0]
	v_pk_fma_f32 v[12:13], s[48:49], v[18:19], v[12:13] op_sel_hi:[0,1,1]
	v_cvt_scalef32_pk_f32_fp4 v[18:19], v21, 1.0 op_sel:[0,1,0]
	v_pk_fma_f32 v[14:15], s[48:49], v[18:19], v[14:15] op_sel_hi:[0,1,1]
	v_cvt_scalef32_pk_f32_fp4 v[18:19], v21, 1.0 op_sel:[1,1,0]
	v_pk_fma_f32 v[16:17], s[48:49], v[18:19], v[16:17] op_sel_hi:[0,1,1]
	v_readlane_b32 s48, v126, 36
	s_waitcnt vmcnt(29)
	v_cvt_scalef32_pk_f32_fp4 v[18:19], v22, 1.0
	v_pk_fma_f32 v[2:3], v[18:19], s[48:49], v[2:3] op_sel_hi:[1,0,1]
	v_cvt_scalef32_pk_f32_fp4 v[18:19], v22, 1.0 op_sel:[1,0,0]
	v_pk_fma_f32 v[4:5], s[48:49], v[18:19], v[4:5] op_sel_hi:[0,1,1]
	v_cvt_scalef32_pk_f32_fp4 v[18:19], v22, 1.0 op_sel:[0,1,0]
	v_pk_fma_f32 v[6:7], s[48:49], v[18:19], v[6:7] op_sel_hi:[0,1,1]
	v_cvt_scalef32_pk_f32_fp4 v[18:19], v22, 1.0 op_sel:[1,1,0]
	v_pk_fma_f32 v[8:9], s[48:49], v[18:19], v[8:9] op_sel_hi:[0,1,1]
	v_cvt_scalef32_pk_f32_fp4 v[18:19], v23, 1.0
	v_pk_fma_f32 v[10:11], s[48:49], v[18:19], v[10:11] op_sel_hi:[0,1,1]
	v_cvt_scalef32_pk_f32_fp4 v[18:19], v23, 1.0 op_sel:[1,0,0]
	v_pk_fma_f32 v[12:13], s[48:49], v[18:19], v[12:13] op_sel_hi:[0,1,1]
	v_cvt_scalef32_pk_f32_fp4 v[18:19], v23, 1.0 op_sel:[0,1,0]
	v_pk_fma_f32 v[14:15], s[48:49], v[18:19], v[14:15] op_sel_hi:[0,1,1]
	v_cvt_scalef32_pk_f32_fp4 v[18:19], v23, 1.0 op_sel:[1,1,0]
	v_pk_fma_f32 v[16:17], s[48:49], v[18:19], v[16:17] op_sel_hi:[0,1,1]
	v_readlane_b32 s48, v126, 44
	s_waitcnt vmcnt(28)
	v_cvt_scalef32_pk_f32_fp4 v[18:19], v24, 1.0
	v_pk_fma_f32 v[2:3], v[18:19], s[48:49], v[2:3] op_sel_hi:[1,0,1]
	v_cvt_scalef32_pk_f32_fp4 v[18:19], v24, 1.0 op_sel:[1,0,0]
	v_pk_fma_f32 v[4:5], s[48:49], v[18:19], v[4:5] op_sel_hi:[0,1,1]
	v_cvt_scalef32_pk_f32_fp4 v[18:19], v24, 1.0 op_sel:[0,1,0]
	v_pk_fma_f32 v[6:7], s[48:49], v[18:19], v[6:7] op_sel_hi:[0,1,1]
	v_cvt_scalef32_pk_f32_fp4 v[18:19], v24, 1.0 op_sel:[1,1,0]
	v_pk_fma_f32 v[8:9], s[48:49], v[18:19], v[8:9] op_sel_hi:[0,1,1]
	v_cvt_scalef32_pk_f32_fp4 v[18:19], v25, 1.0
	v_pk_fma_f32 v[10:11], s[48:49], v[18:19], v[10:11] op_sel_hi:[0,1,1]
	v_cvt_scalef32_pk_f32_fp4 v[18:19], v25, 1.0 op_sel:[1,0,0]
	v_pk_fma_f32 v[12:13], s[48:49], v[18:19], v[12:13] op_sel_hi:[0,1,1]
	v_cvt_scalef32_pk_f32_fp4 v[18:19], v25, 1.0 op_sel:[0,1,0]
	v_pk_fma_f32 v[14:15], s[48:49], v[18:19], v[14:15] op_sel_hi:[0,1,1]
	v_cvt_scalef32_pk_f32_fp4 v[18:19], v25, 1.0 op_sel:[1,1,0]
	v_pk_fma_f32 v[16:17], s[48:49], v[18:19], v[16:17] op_sel_hi:[0,1,1]
	v_readlane_b32 s48, v126, 34
	s_waitcnt vmcnt(27)
	v_cvt_scalef32_pk_f32_fp4 v[18:19], v26, 1.0
	v_pk_fma_f32 v[2:3], v[18:19], s[48:49], v[2:3] op_sel_hi:[1,0,1]
	v_cvt_scalef32_pk_f32_fp4 v[18:19], v26, 1.0 op_sel:[1,0,0]
	v_pk_fma_f32 v[4:5], s[48:49], v[18:19], v[4:5] op_sel_hi:[0,1,1]
	v_cvt_scalef32_pk_f32_fp4 v[18:19], v26, 1.0 op_sel:[0,1,0]
	v_pk_fma_f32 v[6:7], s[48:49], v[18:19], v[6:7] op_sel_hi:[0,1,1]
	v_cvt_scalef32_pk_f32_fp4 v[18:19], v26, 1.0 op_sel:[1,1,0]
	v_pk_fma_f32 v[8:9], s[48:49], v[18:19], v[8:9] op_sel_hi:[0,1,1]
	v_cvt_scalef32_pk_f32_fp4 v[18:19], v27, 1.0
	v_pk_fma_f32 v[10:11], s[48:49], v[18:19], v[10:11] op_sel_hi:[0,1,1]
	v_cvt_scalef32_pk_f32_fp4 v[18:19], v27, 1.0 op_sel:[1,0,0]
	v_pk_fma_f32 v[12:13], s[48:49], v[18:19], v[12:13] op_sel_hi:[0,1,1]
	v_cvt_scalef32_pk_f32_fp4 v[18:19], v27, 1.0 op_sel:[0,1,0]
	v_pk_fma_f32 v[14:15], s[48:49], v[18:19], v[14:15] op_sel_hi:[0,1,1]
	v_cvt_scalef32_pk_f32_fp4 v[18:19], v27, 1.0 op_sel:[1,1,0]
	v_pk_fma_f32 v[16:17], s[48:49], v[18:19], v[16:17] op_sel_hi:[0,1,1]
	v_readlane_b32 s48, v126, 42
	s_waitcnt vmcnt(26)
	v_cvt_scalef32_pk_f32_fp4 v[18:19], v28, 1.0
	v_pk_fma_f32 v[2:3], v[18:19], s[48:49], v[2:3] op_sel_hi:[1,0,1]
	v_cvt_scalef32_pk_f32_fp4 v[18:19], v28, 1.0 op_sel:[1,0,0]
	v_pk_fma_f32 v[4:5], s[48:49], v[18:19], v[4:5] op_sel_hi:[0,1,1]
	v_cvt_scalef32_pk_f32_fp4 v[18:19], v28, 1.0 op_sel:[0,1,0]
	v_pk_fma_f32 v[6:7], s[48:49], v[18:19], v[6:7] op_sel_hi:[0,1,1]
	v_cvt_scalef32_pk_f32_fp4 v[18:19], v28, 1.0 op_sel:[1,1,0]
	v_pk_fma_f32 v[8:9], s[48:49], v[18:19], v[8:9] op_sel_hi:[0,1,1]
	v_cvt_scalef32_pk_f32_fp4 v[18:19], v29, 1.0
	v_pk_fma_f32 v[10:11], s[48:49], v[18:19], v[10:11] op_sel_hi:[0,1,1]
	v_cvt_scalef32_pk_f32_fp4 v[18:19], v29, 1.0 op_sel:[1,0,0]
	v_pk_fma_f32 v[12:13], s[48:49], v[18:19], v[12:13] op_sel_hi:[0,1,1]
	v_cvt_scalef32_pk_f32_fp4 v[18:19], v29, 1.0 op_sel:[0,1,0]
	v_pk_fma_f32 v[14:15], s[48:49], v[18:19], v[14:15] op_sel_hi:[0,1,1]
	v_cvt_scalef32_pk_f32_fp4 v[18:19], v29, 1.0 op_sel:[1,1,0]
	v_pk_fma_f32 v[16:17], s[48:49], v[18:19], v[16:17] op_sel_hi:[0,1,1]
	v_readlane_b32 s48, v126, 38
	s_waitcnt vmcnt(25)
	v_cvt_scalef32_pk_f32_fp4 v[18:19], v30, 1.0
	v_pk_fma_f32 v[2:3], v[18:19], s[48:49], v[2:3] op_sel_hi:[1,0,1]
	v_cvt_scalef32_pk_f32_fp4 v[18:19], v30, 1.0 op_sel:[1,0,0]
	v_pk_fma_f32 v[4:5], s[48:49], v[18:19], v[4:5] op_sel_hi:[0,1,1]
	v_cvt_scalef32_pk_f32_fp4 v[18:19], v30, 1.0 op_sel:[0,1,0]
	v_pk_fma_f32 v[6:7], s[48:49], v[18:19], v[6:7] op_sel_hi:[0,1,1]
	v_cvt_scalef32_pk_f32_fp4 v[18:19], v30, 1.0 op_sel:[1,1,0]
	v_pk_fma_f32 v[8:9], s[48:49], v[18:19], v[8:9] op_sel_hi:[0,1,1]
	v_cvt_scalef32_pk_f32_fp4 v[18:19], v31, 1.0
	v_pk_fma_f32 v[10:11], s[48:49], v[18:19], v[10:11] op_sel_hi:[0,1,1]
	v_cvt_scalef32_pk_f32_fp4 v[18:19], v31, 1.0 op_sel:[1,0,0]
	v_pk_fma_f32 v[12:13], s[48:49], v[18:19], v[12:13] op_sel_hi:[0,1,1]
	v_cvt_scalef32_pk_f32_fp4 v[18:19], v31, 1.0 op_sel:[0,1,0]
	v_pk_fma_f32 v[14:15], s[48:49], v[18:19], v[14:15] op_sel_hi:[0,1,1]
	v_cvt_scalef32_pk_f32_fp4 v[18:19], v31, 1.0 op_sel:[1,1,0]
	v_pk_fma_f32 v[16:17], s[48:49], v[18:19], v[16:17] op_sel_hi:[0,1,1]
	v_readlane_b32 s48, v126, 46
	s_waitcnt vmcnt(24)
	v_cvt_scalef32_pk_f32_fp4 v[18:19], v32, 1.0
	v_pk_fma_f32 v[2:3], v[18:19], s[48:49], v[2:3] op_sel_hi:[1,0,1]
	v_cvt_scalef32_pk_f32_fp4 v[18:19], v32, 1.0 op_sel:[1,0,0]
	v_pk_fma_f32 v[4:5], s[48:49], v[18:19], v[4:5] op_sel_hi:[0,1,1]
	v_cvt_scalef32_pk_f32_fp4 v[18:19], v32, 1.0 op_sel:[0,1,0]
	v_pk_fma_f32 v[6:7], s[48:49], v[18:19], v[6:7] op_sel_hi:[0,1,1]
	v_cvt_scalef32_pk_f32_fp4 v[18:19], v32, 1.0 op_sel:[1,1,0]
	v_pk_fma_f32 v[8:9], s[48:49], v[18:19], v[8:9] op_sel_hi:[0,1,1]
	v_cvt_scalef32_pk_f32_fp4 v[18:19], v33, 1.0
	v_pk_fma_f32 v[10:11], s[48:49], v[18:19], v[10:11] op_sel_hi:[0,1,1]
	v_cvt_scalef32_pk_f32_fp4 v[18:19], v33, 1.0 op_sel:[1,0,0]
	v_pk_fma_f32 v[12:13], s[48:49], v[18:19], v[12:13] op_sel_hi:[0,1,1]
	v_cvt_scalef32_pk_f32_fp4 v[18:19], v33, 1.0 op_sel:[0,1,0]
	v_pk_fma_f32 v[14:15], s[48:49], v[18:19], v[14:15] op_sel_hi:[0,1,1]
	v_cvt_scalef32_pk_f32_fp4 v[18:19], v33, 1.0 op_sel:[1,1,0]
	v_pk_fma_f32 v[16:17], s[48:49], v[18:19], v[16:17] op_sel_hi:[0,1,1]
	v_readlane_b32 s48, v126, 33
	s_waitcnt vmcnt(23)
	v_cvt_scalef32_pk_f32_fp4 v[18:19], v56, 1.0
	v_pk_fma_f32 v[2:3], v[18:19], s[48:49], v[2:3] op_sel_hi:[1,0,1]
	v_cvt_scalef32_pk_f32_fp4 v[18:19], v56, 1.0 op_sel:[1,0,0]
	v_pk_fma_f32 v[4:5], s[48:49], v[18:19], v[4:5] op_sel_hi:[0,1,1]
	v_cvt_scalef32_pk_f32_fp4 v[18:19], v56, 1.0 op_sel:[0,1,0]
	v_pk_fma_f32 v[6:7], s[48:49], v[18:19], v[6:7] op_sel_hi:[0,1,1]
	v_cvt_scalef32_pk_f32_fp4 v[18:19], v56, 1.0 op_sel:[1,1,0]
	v_pk_fma_f32 v[8:9], s[48:49], v[18:19], v[8:9] op_sel_hi:[0,1,1]
	v_cvt_scalef32_pk_f32_fp4 v[18:19], v57, 1.0
	v_pk_fma_f32 v[10:11], s[48:49], v[18:19], v[10:11] op_sel_hi:[0,1,1]
	v_cvt_scalef32_pk_f32_fp4 v[18:19], v57, 1.0 op_sel:[1,0,0]
	v_pk_fma_f32 v[12:13], s[48:49], v[18:19], v[12:13] op_sel_hi:[0,1,1]
	v_cvt_scalef32_pk_f32_fp4 v[18:19], v57, 1.0 op_sel:[0,1,0]
	v_pk_fma_f32 v[14:15], s[48:49], v[18:19], v[14:15] op_sel_hi:[0,1,1]
	v_cvt_scalef32_pk_f32_fp4 v[18:19], v57, 1.0 op_sel:[1,1,0]
	v_pk_fma_f32 v[16:17], s[48:49], v[18:19], v[16:17] op_sel_hi:[0,1,1]
	v_readlane_b32 s48, v126, 41
	s_waitcnt vmcnt(22)
	v_cvt_scalef32_pk_f32_fp4 v[18:19], v58, 1.0
	v_pk_fma_f32 v[2:3], v[18:19], s[48:49], v[2:3] op_sel_hi:[1,0,1]
	v_cvt_scalef32_pk_f32_fp4 v[18:19], v58, 1.0 op_sel:[1,0,0]
	v_pk_fma_f32 v[4:5], s[48:49], v[18:19], v[4:5] op_sel_hi:[0,1,1]
	v_cvt_scalef32_pk_f32_fp4 v[18:19], v58, 1.0 op_sel:[0,1,0]
	v_pk_fma_f32 v[6:7], s[48:49], v[18:19], v[6:7] op_sel_hi:[0,1,1]
	v_cvt_scalef32_pk_f32_fp4 v[18:19], v58, 1.0 op_sel:[1,1,0]
	v_pk_fma_f32 v[8:9], s[48:49], v[18:19], v[8:9] op_sel_hi:[0,1,1]
	v_cvt_scalef32_pk_f32_fp4 v[18:19], v59, 1.0
	v_pk_fma_f32 v[10:11], s[48:49], v[18:19], v[10:11] op_sel_hi:[0,1,1]
	v_cvt_scalef32_pk_f32_fp4 v[18:19], v59, 1.0 op_sel:[1,0,0]
	v_pk_fma_f32 v[12:13], s[48:49], v[18:19], v[12:13] op_sel_hi:[0,1,1]
	v_cvt_scalef32_pk_f32_fp4 v[18:19], v59, 1.0 op_sel:[0,1,0]
	v_pk_fma_f32 v[14:15], s[48:49], v[18:19], v[14:15] op_sel_hi:[0,1,1]
	v_cvt_scalef32_pk_f32_fp4 v[18:19], v59, 1.0 op_sel:[1,1,0]
	v_pk_fma_f32 v[16:17], s[48:49], v[18:19], v[16:17] op_sel_hi:[0,1,1]
	v_readlane_b32 s48, v126, 37
	s_waitcnt vmcnt(21)
	v_cvt_scalef32_pk_f32_fp4 v[18:19], v60, 1.0
	v_pk_fma_f32 v[2:3], v[18:19], s[48:49], v[2:3] op_sel_hi:[1,0,1]
	v_cvt_scalef32_pk_f32_fp4 v[18:19], v60, 1.0 op_sel:[1,0,0]
	v_pk_fma_f32 v[4:5], s[48:49], v[18:19], v[4:5] op_sel_hi:[0,1,1]
	v_cvt_scalef32_pk_f32_fp4 v[18:19], v60, 1.0 op_sel:[0,1,0]
	v_pk_fma_f32 v[6:7], s[48:49], v[18:19], v[6:7] op_sel_hi:[0,1,1]
	v_cvt_scalef32_pk_f32_fp4 v[18:19], v60, 1.0 op_sel:[1,1,0]
	v_pk_fma_f32 v[8:9], s[48:49], v[18:19], v[8:9] op_sel_hi:[0,1,1]
	v_cvt_scalef32_pk_f32_fp4 v[18:19], v61, 1.0
	v_pk_fma_f32 v[10:11], s[48:49], v[18:19], v[10:11] op_sel_hi:[0,1,1]
	v_cvt_scalef32_pk_f32_fp4 v[18:19], v61, 1.0 op_sel:[1,0,0]
	v_pk_fma_f32 v[12:13], s[48:49], v[18:19], v[12:13] op_sel_hi:[0,1,1]
	v_cvt_scalef32_pk_f32_fp4 v[18:19], v61, 1.0 op_sel:[0,1,0]
	v_pk_fma_f32 v[14:15], s[48:49], v[18:19], v[14:15] op_sel_hi:[0,1,1]
	v_cvt_scalef32_pk_f32_fp4 v[18:19], v61, 1.0 op_sel:[1,1,0]
	v_pk_fma_f32 v[16:17], s[48:49], v[18:19], v[16:17] op_sel_hi:[0,1,1]
	v_readlane_b32 s48, v126, 45
	s_waitcnt vmcnt(20)
	v_cvt_scalef32_pk_f32_fp4 v[18:19], v62, 1.0
	v_pk_fma_f32 v[2:3], v[18:19], s[48:49], v[2:3] op_sel_hi:[1,0,1]
	v_cvt_scalef32_pk_f32_fp4 v[18:19], v62, 1.0 op_sel:[1,0,0]
	v_pk_fma_f32 v[4:5], s[48:49], v[18:19], v[4:5] op_sel_hi:[0,1,1]
	v_cvt_scalef32_pk_f32_fp4 v[18:19], v62, 1.0 op_sel:[0,1,0]
	v_pk_fma_f32 v[6:7], s[48:49], v[18:19], v[6:7] op_sel_hi:[0,1,1]
	v_cvt_scalef32_pk_f32_fp4 v[18:19], v62, 1.0 op_sel:[1,1,0]
	v_pk_fma_f32 v[8:9], s[48:49], v[18:19], v[8:9] op_sel_hi:[0,1,1]
	v_cvt_scalef32_pk_f32_fp4 v[18:19], v63, 1.0
	v_pk_fma_f32 v[10:11], s[48:49], v[18:19], v[10:11] op_sel_hi:[0,1,1]
	v_cvt_scalef32_pk_f32_fp4 v[18:19], v63, 1.0 op_sel:[1,0,0]
	v_pk_fma_f32 v[12:13], s[48:49], v[18:19], v[12:13] op_sel_hi:[0,1,1]
	v_cvt_scalef32_pk_f32_fp4 v[18:19], v63, 1.0 op_sel:[0,1,0]
	v_pk_fma_f32 v[14:15], s[48:49], v[18:19], v[14:15] op_sel_hi:[0,1,1]
	v_cvt_scalef32_pk_f32_fp4 v[18:19], v63, 1.0 op_sel:[1,1,0]
	v_pk_fma_f32 v[16:17], s[48:49], v[18:19], v[16:17] op_sel_hi:[0,1,1]
	v_readlane_b32 s24, v126, 35
	s_waitcnt vmcnt(19)
	v_cvt_scalef32_pk_f32_fp4 v[18:19], v64, 1.0
	v_pk_fma_f32 v[2:3], v[18:19], s[24:25], v[2:3] op_sel_hi:[1,0,1]
	v_cvt_scalef32_pk_f32_fp4 v[18:19], v64, 1.0 op_sel:[1,0,0]
	v_pk_fma_f32 v[4:5], s[24:25], v[18:19], v[4:5] op_sel_hi:[0,1,1]
	v_cvt_scalef32_pk_f32_fp4 v[18:19], v64, 1.0 op_sel:[0,1,0]
	v_pk_fma_f32 v[6:7], s[24:25], v[18:19], v[6:7] op_sel_hi:[0,1,1]
	v_cvt_scalef32_pk_f32_fp4 v[18:19], v64, 1.0 op_sel:[1,1,0]
	v_pk_fma_f32 v[8:9], s[24:25], v[18:19], v[8:9] op_sel_hi:[0,1,1]
	v_cvt_scalef32_pk_f32_fp4 v[18:19], v65, 1.0
	v_pk_fma_f32 v[10:11], s[24:25], v[18:19], v[10:11] op_sel_hi:[0,1,1]
	v_cvt_scalef32_pk_f32_fp4 v[18:19], v65, 1.0 op_sel:[1,0,0]
	v_pk_fma_f32 v[12:13], s[24:25], v[18:19], v[12:13] op_sel_hi:[0,1,1]
	v_cvt_scalef32_pk_f32_fp4 v[18:19], v65, 1.0 op_sel:[0,1,0]
	v_pk_fma_f32 v[14:15], s[24:25], v[18:19], v[14:15] op_sel_hi:[0,1,1]
	v_cvt_scalef32_pk_f32_fp4 v[18:19], v65, 1.0 op_sel:[1,1,0]
	v_pk_fma_f32 v[16:17], s[24:25], v[18:19], v[16:17] op_sel_hi:[0,1,1]
	v_readlane_b32 s24, v126, 43
	s_waitcnt vmcnt(18)
	v_cvt_scalef32_pk_f32_fp4 v[18:19], v66, 1.0
	v_pk_fma_f32 v[2:3], v[18:19], s[24:25], v[2:3] op_sel_hi:[1,0,1]
	v_cvt_scalef32_pk_f32_fp4 v[18:19], v66, 1.0 op_sel:[1,0,0]
	v_pk_fma_f32 v[4:5], s[24:25], v[18:19], v[4:5] op_sel_hi:[0,1,1]
	v_cvt_scalef32_pk_f32_fp4 v[18:19], v66, 1.0 op_sel:[0,1,0]
	v_pk_fma_f32 v[6:7], s[24:25], v[18:19], v[6:7] op_sel_hi:[0,1,1]
	v_cvt_scalef32_pk_f32_fp4 v[18:19], v66, 1.0 op_sel:[1,1,0]
	v_pk_fma_f32 v[8:9], s[24:25], v[18:19], v[8:9] op_sel_hi:[0,1,1]
	v_cvt_scalef32_pk_f32_fp4 v[18:19], v67, 1.0
	v_pk_fma_f32 v[10:11], s[24:25], v[18:19], v[10:11] op_sel_hi:[0,1,1]
	v_cvt_scalef32_pk_f32_fp4 v[18:19], v67, 1.0 op_sel:[1,0,0]
	v_pk_fma_f32 v[12:13], s[24:25], v[18:19], v[12:13] op_sel_hi:[0,1,1]
	v_cvt_scalef32_pk_f32_fp4 v[18:19], v67, 1.0 op_sel:[0,1,0]
	v_pk_fma_f32 v[14:15], s[24:25], v[18:19], v[14:15] op_sel_hi:[0,1,1]
	v_cvt_scalef32_pk_f32_fp4 v[18:19], v67, 1.0 op_sel:[1,1,0]
	v_pk_fma_f32 v[16:17], s[24:25], v[18:19], v[16:17] op_sel_hi:[0,1,1]
	v_readlane_b32 s24, v126, 39
	s_waitcnt vmcnt(17)
	v_cvt_scalef32_pk_f32_fp4 v[18:19], v68, 1.0
	v_pk_fma_f32 v[2:3], v[18:19], s[24:25], v[2:3] op_sel_hi:[1,0,1]
	v_cvt_scalef32_pk_f32_fp4 v[18:19], v68, 1.0 op_sel:[1,0,0]
	v_pk_fma_f32 v[4:5], s[24:25], v[18:19], v[4:5] op_sel_hi:[0,1,1]
	v_cvt_scalef32_pk_f32_fp4 v[18:19], v68, 1.0 op_sel:[0,1,0]
	v_pk_fma_f32 v[6:7], s[24:25], v[18:19], v[6:7] op_sel_hi:[0,1,1]
	v_cvt_scalef32_pk_f32_fp4 v[18:19], v68, 1.0 op_sel:[1,1,0]
	v_pk_fma_f32 v[8:9], s[24:25], v[18:19], v[8:9] op_sel_hi:[0,1,1]
	v_cvt_scalef32_pk_f32_fp4 v[18:19], v69, 1.0
	v_pk_fma_f32 v[10:11], s[24:25], v[18:19], v[10:11] op_sel_hi:[0,1,1]
	v_cvt_scalef32_pk_f32_fp4 v[18:19], v69, 1.0 op_sel:[1,0,0]
	v_pk_fma_f32 v[12:13], s[24:25], v[18:19], v[12:13] op_sel_hi:[0,1,1]
	v_cvt_scalef32_pk_f32_fp4 v[18:19], v69, 1.0 op_sel:[0,1,0]
	v_pk_fma_f32 v[14:15], s[24:25], v[18:19], v[14:15] op_sel_hi:[0,1,1]
	v_cvt_scalef32_pk_f32_fp4 v[18:19], v69, 1.0 op_sel:[1,1,0]
	v_pk_fma_f32 v[16:17], s[24:25], v[18:19], v[16:17] op_sel_hi:[0,1,1]
	v_readlane_b32 s24, v126, 47
	s_waitcnt vmcnt(16)
	v_cvt_scalef32_pk_f32_fp4 v[18:19], v70, 1.0
	v_pk_fma_f32 v[2:3], v[18:19], s[24:25], v[2:3] op_sel_hi:[1,0,1]
	v_cvt_scalef32_pk_f32_fp4 v[18:19], v70, 1.0 op_sel:[1,0,0]
	v_pk_fma_f32 v[4:5], s[24:25], v[18:19], v[4:5] op_sel_hi:[0,1,1]
	v_cvt_scalef32_pk_f32_fp4 v[18:19], v70, 1.0 op_sel:[0,1,0]
	v_pk_fma_f32 v[6:7], s[24:25], v[18:19], v[6:7] op_sel_hi:[0,1,1]
	v_cvt_scalef32_pk_f32_fp4 v[18:19], v70, 1.0 op_sel:[1,1,0]
	v_pk_fma_f32 v[8:9], s[24:25], v[18:19], v[8:9] op_sel_hi:[0,1,1]
	v_cvt_scalef32_pk_f32_fp4 v[18:19], v71, 1.0
	v_pk_fma_f32 v[10:11], s[24:25], v[18:19], v[10:11] op_sel_hi:[0,1,1]
	v_cvt_scalef32_pk_f32_fp4 v[18:19], v71, 1.0 op_sel:[1,0,0]
	v_pk_fma_f32 v[12:13], s[24:25], v[18:19], v[12:13] op_sel_hi:[0,1,1]
	v_cvt_scalef32_pk_f32_fp4 v[18:19], v71, 1.0 op_sel:[0,1,0]
	v_pk_fma_f32 v[14:15], s[24:25], v[18:19], v[14:15] op_sel_hi:[0,1,1]
	v_cvt_scalef32_pk_f32_fp4 v[18:19], v71, 1.0 op_sel:[1,1,0]
	v_pk_fma_f32 v[16:17], s[24:25], v[18:19], v[16:17] op_sel_hi:[0,1,1]
	v_readlane_b32 s24, v126, 48
	s_waitcnt vmcnt(15)
	v_cvt_scalef32_pk_f32_fp4 v[18:19], v72, 1.0
	v_pk_fma_f32 v[2:3], v[18:19], s[24:25], v[2:3] op_sel_hi:[1,0,1]
	v_cvt_scalef32_pk_f32_fp4 v[18:19], v72, 1.0 op_sel:[1,0,0]
	v_pk_fma_f32 v[4:5], s[24:25], v[18:19], v[4:5] op_sel_hi:[0,1,1]
	v_cvt_scalef32_pk_f32_fp4 v[18:19], v72, 1.0 op_sel:[0,1,0]
	v_pk_fma_f32 v[6:7], s[24:25], v[18:19], v[6:7] op_sel_hi:[0,1,1]
	v_cvt_scalef32_pk_f32_fp4 v[18:19], v72, 1.0 op_sel:[1,1,0]
	v_pk_fma_f32 v[8:9], s[24:25], v[18:19], v[8:9] op_sel_hi:[0,1,1]
	v_cvt_scalef32_pk_f32_fp4 v[18:19], v73, 1.0
	v_pk_fma_f32 v[10:11], s[24:25], v[18:19], v[10:11] op_sel_hi:[0,1,1]
	v_cvt_scalef32_pk_f32_fp4 v[18:19], v73, 1.0 op_sel:[1,0,0]
	v_pk_fma_f32 v[12:13], s[24:25], v[18:19], v[12:13] op_sel_hi:[0,1,1]
	v_cvt_scalef32_pk_f32_fp4 v[18:19], v73, 1.0 op_sel:[0,1,0]
	v_pk_fma_f32 v[14:15], s[24:25], v[18:19], v[14:15] op_sel_hi:[0,1,1]
	v_cvt_scalef32_pk_f32_fp4 v[18:19], v73, 1.0 op_sel:[1,1,0]
	v_pk_fma_f32 v[16:17], s[24:25], v[18:19], v[16:17] op_sel_hi:[0,1,1]
	v_readlane_b32 s24, v126, 56
	s_waitcnt vmcnt(14)
	v_cvt_scalef32_pk_f32_fp4 v[18:19], v74, 1.0
	v_pk_fma_f32 v[2:3], v[18:19], s[24:25], v[2:3] op_sel_hi:[1,0,1]
	v_cvt_scalef32_pk_f32_fp4 v[18:19], v74, 1.0 op_sel:[1,0,0]
	v_pk_fma_f32 v[4:5], s[24:25], v[18:19], v[4:5] op_sel_hi:[0,1,1]
	v_cvt_scalef32_pk_f32_fp4 v[18:19], v74, 1.0 op_sel:[0,1,0]
	v_pk_fma_f32 v[6:7], s[24:25], v[18:19], v[6:7] op_sel_hi:[0,1,1]
	v_cvt_scalef32_pk_f32_fp4 v[18:19], v74, 1.0 op_sel:[1,1,0]
	v_pk_fma_f32 v[8:9], s[24:25], v[18:19], v[8:9] op_sel_hi:[0,1,1]
	v_cvt_scalef32_pk_f32_fp4 v[18:19], v75, 1.0
	v_pk_fma_f32 v[10:11], s[24:25], v[18:19], v[10:11] op_sel_hi:[0,1,1]
	v_cvt_scalef32_pk_f32_fp4 v[18:19], v75, 1.0 op_sel:[1,0,0]
	v_pk_fma_f32 v[12:13], s[24:25], v[18:19], v[12:13] op_sel_hi:[0,1,1]
	v_cvt_scalef32_pk_f32_fp4 v[18:19], v75, 1.0 op_sel:[0,1,0]
	v_pk_fma_f32 v[14:15], s[24:25], v[18:19], v[14:15] op_sel_hi:[0,1,1]
	v_cvt_scalef32_pk_f32_fp4 v[18:19], v75, 1.0 op_sel:[1,1,0]
	v_pk_fma_f32 v[16:17], s[24:25], v[18:19], v[16:17] op_sel_hi:[0,1,1]
	v_readlane_b32 s24, v126, 52
	s_waitcnt vmcnt(13)
	v_cvt_scalef32_pk_f32_fp4 v[18:19], v76, 1.0
	v_pk_fma_f32 v[2:3], v[18:19], s[24:25], v[2:3] op_sel_hi:[1,0,1]
	v_cvt_scalef32_pk_f32_fp4 v[18:19], v76, 1.0 op_sel:[1,0,0]
	v_pk_fma_f32 v[4:5], s[24:25], v[18:19], v[4:5] op_sel_hi:[0,1,1]
	v_cvt_scalef32_pk_f32_fp4 v[18:19], v76, 1.0 op_sel:[0,1,0]
	v_pk_fma_f32 v[6:7], s[24:25], v[18:19], v[6:7] op_sel_hi:[0,1,1]
	v_cvt_scalef32_pk_f32_fp4 v[18:19], v76, 1.0 op_sel:[1,1,0]
	v_pk_fma_f32 v[8:9], s[24:25], v[18:19], v[8:9] op_sel_hi:[0,1,1]
	v_cvt_scalef32_pk_f32_fp4 v[18:19], v77, 1.0
	v_pk_fma_f32 v[10:11], s[24:25], v[18:19], v[10:11] op_sel_hi:[0,1,1]
	v_cvt_scalef32_pk_f32_fp4 v[18:19], v77, 1.0 op_sel:[1,0,0]
	v_pk_fma_f32 v[12:13], s[24:25], v[18:19], v[12:13] op_sel_hi:[0,1,1]
	v_cvt_scalef32_pk_f32_fp4 v[18:19], v77, 1.0 op_sel:[0,1,0]
	v_pk_fma_f32 v[14:15], s[24:25], v[18:19], v[14:15] op_sel_hi:[0,1,1]
	v_cvt_scalef32_pk_f32_fp4 v[18:19], v77, 1.0 op_sel:[1,1,0]
	v_pk_fma_f32 v[16:17], s[24:25], v[18:19], v[16:17] op_sel_hi:[0,1,1]
	v_readlane_b32 s24, v126, 60
	s_waitcnt vmcnt(12)
	v_cvt_scalef32_pk_f32_fp4 v[18:19], v78, 1.0
	v_pk_fma_f32 v[2:3], v[18:19], s[24:25], v[2:3] op_sel_hi:[1,0,1]
	v_cvt_scalef32_pk_f32_fp4 v[18:19], v78, 1.0 op_sel:[1,0,0]
	v_pk_fma_f32 v[4:5], s[24:25], v[18:19], v[4:5] op_sel_hi:[0,1,1]
	v_cvt_scalef32_pk_f32_fp4 v[18:19], v78, 1.0 op_sel:[0,1,0]
	v_pk_fma_f32 v[6:7], s[24:25], v[18:19], v[6:7] op_sel_hi:[0,1,1]
	v_cvt_scalef32_pk_f32_fp4 v[18:19], v78, 1.0 op_sel:[1,1,0]
	v_pk_fma_f32 v[8:9], s[24:25], v[18:19], v[8:9] op_sel_hi:[0,1,1]
	v_cvt_scalef32_pk_f32_fp4 v[18:19], v79, 1.0
	v_pk_fma_f32 v[10:11], s[24:25], v[18:19], v[10:11] op_sel_hi:[0,1,1]
	v_cvt_scalef32_pk_f32_fp4 v[18:19], v79, 1.0 op_sel:[1,0,0]
	v_pk_fma_f32 v[12:13], s[24:25], v[18:19], v[12:13] op_sel_hi:[0,1,1]
	v_cvt_scalef32_pk_f32_fp4 v[18:19], v79, 1.0 op_sel:[0,1,0]
	v_pk_fma_f32 v[14:15], s[24:25], v[18:19], v[14:15] op_sel_hi:[0,1,1]
	v_cvt_scalef32_pk_f32_fp4 v[18:19], v79, 1.0 op_sel:[1,1,0]
	v_pk_fma_f32 v[16:17], s[24:25], v[18:19], v[16:17] op_sel_hi:[0,1,1]
	v_readlane_b32 s24, v126, 50
	s_waitcnt vmcnt(11)
	v_cvt_scalef32_pk_f32_fp4 v[18:19], v80, 1.0
	v_pk_fma_f32 v[2:3], v[18:19], s[24:25], v[2:3] op_sel_hi:[1,0,1]
	v_cvt_scalef32_pk_f32_fp4 v[18:19], v80, 1.0 op_sel:[1,0,0]
	v_pk_fma_f32 v[4:5], s[24:25], v[18:19], v[4:5] op_sel_hi:[0,1,1]
	v_cvt_scalef32_pk_f32_fp4 v[18:19], v80, 1.0 op_sel:[0,1,0]
	v_pk_fma_f32 v[6:7], s[24:25], v[18:19], v[6:7] op_sel_hi:[0,1,1]
	v_cvt_scalef32_pk_f32_fp4 v[18:19], v80, 1.0 op_sel:[1,1,0]
	v_pk_fma_f32 v[8:9], s[24:25], v[18:19], v[8:9] op_sel_hi:[0,1,1]
	v_cvt_scalef32_pk_f32_fp4 v[18:19], v81, 1.0
	v_pk_fma_f32 v[10:11], s[24:25], v[18:19], v[10:11] op_sel_hi:[0,1,1]
	v_cvt_scalef32_pk_f32_fp4 v[18:19], v81, 1.0 op_sel:[1,0,0]
	v_pk_fma_f32 v[12:13], s[24:25], v[18:19], v[12:13] op_sel_hi:[0,1,1]
	v_cvt_scalef32_pk_f32_fp4 v[18:19], v81, 1.0 op_sel:[0,1,0]
	v_pk_fma_f32 v[14:15], s[24:25], v[18:19], v[14:15] op_sel_hi:[0,1,1]
	v_cvt_scalef32_pk_f32_fp4 v[18:19], v81, 1.0 op_sel:[1,1,0]
	v_pk_fma_f32 v[16:17], s[24:25], v[18:19], v[16:17] op_sel_hi:[0,1,1]
	v_readlane_b32 s24, v126, 58
	s_waitcnt vmcnt(10)
	v_cvt_scalef32_pk_f32_fp4 v[18:19], v82, 1.0
	v_pk_fma_f32 v[2:3], v[18:19], s[24:25], v[2:3] op_sel_hi:[1,0,1]
	v_cvt_scalef32_pk_f32_fp4 v[18:19], v82, 1.0 op_sel:[1,0,0]
	v_pk_fma_f32 v[4:5], s[24:25], v[18:19], v[4:5] op_sel_hi:[0,1,1]
	v_cvt_scalef32_pk_f32_fp4 v[18:19], v82, 1.0 op_sel:[0,1,0]
	v_pk_fma_f32 v[6:7], s[24:25], v[18:19], v[6:7] op_sel_hi:[0,1,1]
	v_cvt_scalef32_pk_f32_fp4 v[18:19], v82, 1.0 op_sel:[1,1,0]
	v_pk_fma_f32 v[8:9], s[24:25], v[18:19], v[8:9] op_sel_hi:[0,1,1]
	v_cvt_scalef32_pk_f32_fp4 v[18:19], v83, 1.0
	v_pk_fma_f32 v[10:11], s[24:25], v[18:19], v[10:11] op_sel_hi:[0,1,1]
	v_cvt_scalef32_pk_f32_fp4 v[18:19], v83, 1.0 op_sel:[1,0,0]
	v_pk_fma_f32 v[12:13], s[24:25], v[18:19], v[12:13] op_sel_hi:[0,1,1]
	v_cvt_scalef32_pk_f32_fp4 v[18:19], v83, 1.0 op_sel:[0,1,0]
	v_pk_fma_f32 v[14:15], s[24:25], v[18:19], v[14:15] op_sel_hi:[0,1,1]
	v_cvt_scalef32_pk_f32_fp4 v[18:19], v83, 1.0 op_sel:[1,1,0]
	v_pk_fma_f32 v[16:17], s[24:25], v[18:19], v[16:17] op_sel_hi:[0,1,1]
	v_readlane_b32 s24, v126, 54
	s_waitcnt vmcnt(9)
	v_cvt_scalef32_pk_f32_fp4 v[18:19], v84, 1.0
	v_add_u32_e32 v116, 32, v116
	v_pk_fma_f32 v[2:3], v[18:19], s[24:25], v[2:3] op_sel_hi:[1,0,1]
	v_cvt_scalef32_pk_f32_fp4 v[18:19], v84, 1.0 op_sel:[1,0,0]
	v_pk_fma_f32 v[4:5], s[24:25], v[18:19], v[4:5] op_sel_hi:[0,1,1]
	v_cvt_scalef32_pk_f32_fp4 v[18:19], v84, 1.0 op_sel:[0,1,0]
	v_pk_fma_f32 v[6:7], s[24:25], v[18:19], v[6:7] op_sel_hi:[0,1,1]
	v_cvt_scalef32_pk_f32_fp4 v[18:19], v84, 1.0 op_sel:[1,1,0]
	v_pk_fma_f32 v[8:9], s[24:25], v[18:19], v[8:9] op_sel_hi:[0,1,1]
	v_cvt_scalef32_pk_f32_fp4 v[18:19], v85, 1.0
	v_pk_fma_f32 v[10:11], s[24:25], v[18:19], v[10:11] op_sel_hi:[0,1,1]
	v_cvt_scalef32_pk_f32_fp4 v[18:19], v85, 1.0 op_sel:[1,0,0]
	v_pk_fma_f32 v[12:13], s[24:25], v[18:19], v[12:13] op_sel_hi:[0,1,1]
	v_cvt_scalef32_pk_f32_fp4 v[18:19], v85, 1.0 op_sel:[0,1,0]
	v_pk_fma_f32 v[14:15], s[24:25], v[18:19], v[14:15] op_sel_hi:[0,1,1]
	v_cvt_scalef32_pk_f32_fp4 v[18:19], v85, 1.0 op_sel:[1,1,0]
	v_pk_fma_f32 v[16:17], s[24:25], v[18:19], v[16:17] op_sel_hi:[0,1,1]
	v_readlane_b32 s24, v126, 62
	s_waitcnt vmcnt(8)
	v_cvt_scalef32_pk_f32_fp4 v[18:19], v86, 1.0
	v_cmp_ge_u32_e32 vcc, v116, v51
	v_pk_fma_f32 v[2:3], v[18:19], s[24:25], v[2:3] op_sel_hi:[1,0,1]
	v_cvt_scalef32_pk_f32_fp4 v[18:19], v86, 1.0 op_sel:[1,0,0]
	v_pk_fma_f32 v[4:5], s[24:25], v[18:19], v[4:5] op_sel_hi:[0,1,1]
	v_cvt_scalef32_pk_f32_fp4 v[18:19], v86, 1.0 op_sel:[0,1,0]
	v_pk_fma_f32 v[6:7], s[24:25], v[18:19], v[6:7] op_sel_hi:[0,1,1]
	v_cvt_scalef32_pk_f32_fp4 v[18:19], v86, 1.0 op_sel:[1,1,0]
	v_pk_fma_f32 v[8:9], s[24:25], v[18:19], v[8:9] op_sel_hi:[0,1,1]
	v_cvt_scalef32_pk_f32_fp4 v[18:19], v87, 1.0
	v_pk_fma_f32 v[10:11], s[24:25], v[18:19], v[10:11] op_sel_hi:[0,1,1]
	v_cvt_scalef32_pk_f32_fp4 v[18:19], v87, 1.0 op_sel:[1,0,0]
	v_pk_fma_f32 v[12:13], s[24:25], v[18:19], v[12:13] op_sel_hi:[0,1,1]
	v_cvt_scalef32_pk_f32_fp4 v[18:19], v87, 1.0 op_sel:[0,1,0]
	v_pk_fma_f32 v[14:15], s[24:25], v[18:19], v[14:15] op_sel_hi:[0,1,1]
	v_cvt_scalef32_pk_f32_fp4 v[18:19], v87, 1.0 op_sel:[1,1,0]
	v_pk_fma_f32 v[16:17], s[24:25], v[18:19], v[16:17] op_sel_hi:[0,1,1]
	s_waitcnt vmcnt(7)
	v_cvt_scalef32_pk_f32_fp4 v[18:19], v88, 1.0
	s_or_b64 s[12:13], vcc, s[12:13]
	s_nop 0
	v_readlane_b32 s24, v126, 49
	s_nop 1
	v_pk_fma_f32 v[2:3], v[18:19], s[24:25], v[2:3] op_sel_hi:[1,0,1]
	v_cvt_scalef32_pk_f32_fp4 v[18:19], v88, 1.0 op_sel:[1,0,0]
	v_pk_fma_f32 v[4:5], s[24:25], v[18:19], v[4:5] op_sel_hi:[0,1,1]
	v_cvt_scalef32_pk_f32_fp4 v[18:19], v88, 1.0 op_sel:[0,1,0]
	v_pk_fma_f32 v[6:7], s[24:25], v[18:19], v[6:7] op_sel_hi:[0,1,1]
	v_cvt_scalef32_pk_f32_fp4 v[18:19], v88, 1.0 op_sel:[1,1,0]
	v_pk_fma_f32 v[8:9], s[24:25], v[18:19], v[8:9] op_sel_hi:[0,1,1]
	v_cvt_scalef32_pk_f32_fp4 v[18:19], v89, 1.0
	v_pk_fma_f32 v[10:11], s[24:25], v[18:19], v[10:11] op_sel_hi:[0,1,1]
	v_cvt_scalef32_pk_f32_fp4 v[18:19], v89, 1.0 op_sel:[1,0,0]
	v_pk_fma_f32 v[12:13], s[24:25], v[18:19], v[12:13] op_sel_hi:[0,1,1]
	v_cvt_scalef32_pk_f32_fp4 v[18:19], v89, 1.0 op_sel:[0,1,0]
	v_pk_fma_f32 v[14:15], s[24:25], v[18:19], v[14:15] op_sel_hi:[0,1,1]
	v_cvt_scalef32_pk_f32_fp4 v[18:19], v89, 1.0 op_sel:[1,1,0]
	v_pk_fma_f32 v[16:17], s[24:25], v[18:19], v[16:17] op_sel_hi:[0,1,1]
	s_waitcnt vmcnt(6)
	v_cvt_scalef32_pk_f32_fp4 v[18:19], v90, 1.0
	s_nop 1
	v_readlane_b32 s24, v126, 57
	s_nop 1
	v_pk_fma_f32 v[2:3], v[18:19], s[24:25], v[2:3] op_sel_hi:[1,0,1]
	v_cvt_scalef32_pk_f32_fp4 v[18:19], v90, 1.0 op_sel:[1,0,0]
	v_pk_fma_f32 v[4:5], s[24:25], v[18:19], v[4:5] op_sel_hi:[0,1,1]
	v_cvt_scalef32_pk_f32_fp4 v[18:19], v90, 1.0 op_sel:[0,1,0]
	v_pk_fma_f32 v[6:7], s[24:25], v[18:19], v[6:7] op_sel_hi:[0,1,1]
	v_cvt_scalef32_pk_f32_fp4 v[18:19], v90, 1.0 op_sel:[1,1,0]
	v_pk_fma_f32 v[8:9], s[24:25], v[18:19], v[8:9] op_sel_hi:[0,1,1]
	v_cvt_scalef32_pk_f32_fp4 v[18:19], v91, 1.0
	v_pk_fma_f32 v[10:11], s[24:25], v[18:19], v[10:11] op_sel_hi:[0,1,1]
	v_cvt_scalef32_pk_f32_fp4 v[18:19], v91, 1.0 op_sel:[1,0,0]
	v_pk_fma_f32 v[12:13], s[24:25], v[18:19], v[12:13] op_sel_hi:[0,1,1]
	v_cvt_scalef32_pk_f32_fp4 v[18:19], v91, 1.0 op_sel:[0,1,0]
	v_pk_fma_f32 v[14:15], s[24:25], v[18:19], v[14:15] op_sel_hi:[0,1,1]
	v_cvt_scalef32_pk_f32_fp4 v[18:19], v91, 1.0 op_sel:[1,1,0]
	v_pk_fma_f32 v[16:17], s[24:25], v[18:19], v[16:17] op_sel_hi:[0,1,1]
	s_waitcnt vmcnt(5)
	v_cvt_scalef32_pk_f32_fp4 v[18:19], v92, 1.0
	s_nop 1
	v_readlane_b32 s24, v126, 53
	s_nop 1
	v_pk_fma_f32 v[2:3], v[18:19], s[24:25], v[2:3] op_sel_hi:[1,0,1]
	v_cvt_scalef32_pk_f32_fp4 v[18:19], v92, 1.0 op_sel:[1,0,0]
	v_pk_fma_f32 v[4:5], s[24:25], v[18:19], v[4:5] op_sel_hi:[0,1,1]
	v_cvt_scalef32_pk_f32_fp4 v[18:19], v92, 1.0 op_sel:[0,1,0]
	v_pk_fma_f32 v[6:7], s[24:25], v[18:19], v[6:7] op_sel_hi:[0,1,1]
	v_cvt_scalef32_pk_f32_fp4 v[18:19], v92, 1.0 op_sel:[1,1,0]
	v_pk_fma_f32 v[8:9], s[24:25], v[18:19], v[8:9] op_sel_hi:[0,1,1]
	v_cvt_scalef32_pk_f32_fp4 v[18:19], v93, 1.0
	v_pk_fma_f32 v[10:11], s[24:25], v[18:19], v[10:11] op_sel_hi:[0,1,1]
	v_cvt_scalef32_pk_f32_fp4 v[18:19], v93, 1.0 op_sel:[1,0,0]
	v_pk_fma_f32 v[12:13], s[24:25], v[18:19], v[12:13] op_sel_hi:[0,1,1]
	v_cvt_scalef32_pk_f32_fp4 v[18:19], v93, 1.0 op_sel:[0,1,0]
	v_pk_fma_f32 v[14:15], s[24:25], v[18:19], v[14:15] op_sel_hi:[0,1,1]
	v_cvt_scalef32_pk_f32_fp4 v[18:19], v93, 1.0 op_sel:[1,1,0]
	v_pk_fma_f32 v[16:17], s[24:25], v[18:19], v[16:17] op_sel_hi:[0,1,1]
	s_waitcnt vmcnt(4)
	v_cvt_scalef32_pk_f32_fp4 v[18:19], v94, 1.0
	s_nop 1
	v_readlane_b32 s24, v126, 61
	s_nop 1
	v_pk_fma_f32 v[2:3], v[18:19], s[24:25], v[2:3] op_sel_hi:[1,0,1]
	v_cvt_scalef32_pk_f32_fp4 v[18:19], v94, 1.0 op_sel:[1,0,0]
	v_pk_fma_f32 v[4:5], s[24:25], v[18:19], v[4:5] op_sel_hi:[0,1,1]
	v_cvt_scalef32_pk_f32_fp4 v[18:19], v94, 1.0 op_sel:[0,1,0]
	v_pk_fma_f32 v[6:7], s[24:25], v[18:19], v[6:7] op_sel_hi:[0,1,1]
	v_cvt_scalef32_pk_f32_fp4 v[18:19], v94, 1.0 op_sel:[1,1,0]
	v_pk_fma_f32 v[8:9], s[24:25], v[18:19], v[8:9] op_sel_hi:[0,1,1]
	v_cvt_scalef32_pk_f32_fp4 v[18:19], v95, 1.0
	v_pk_fma_f32 v[10:11], s[24:25], v[18:19], v[10:11] op_sel_hi:[0,1,1]
	v_cvt_scalef32_pk_f32_fp4 v[18:19], v95, 1.0 op_sel:[1,0,0]
	v_pk_fma_f32 v[12:13], s[24:25], v[18:19], v[12:13] op_sel_hi:[0,1,1]
	v_cvt_scalef32_pk_f32_fp4 v[18:19], v95, 1.0 op_sel:[0,1,0]
	v_pk_fma_f32 v[14:15], s[24:25], v[18:19], v[14:15] op_sel_hi:[0,1,1]
	v_cvt_scalef32_pk_f32_fp4 v[18:19], v95, 1.0 op_sel:[1,1,0]
	v_pk_fma_f32 v[16:17], s[24:25], v[18:19], v[16:17] op_sel_hi:[0,1,1]
	s_waitcnt vmcnt(3)
	v_cvt_scalef32_pk_f32_fp4 v[18:19], v96, 1.0
	s_nop 1
	v_readlane_b32 s24, v126, 51
	s_nop 1
	v_pk_fma_f32 v[2:3], v[18:19], s[24:25], v[2:3] op_sel_hi:[1,0,1]
	v_cvt_scalef32_pk_f32_fp4 v[18:19], v96, 1.0 op_sel:[1,0,0]
	v_pk_fma_f32 v[4:5], s[24:25], v[18:19], v[4:5] op_sel_hi:[0,1,1]
	v_cvt_scalef32_pk_f32_fp4 v[18:19], v96, 1.0 op_sel:[0,1,0]
	v_pk_fma_f32 v[6:7], s[24:25], v[18:19], v[6:7] op_sel_hi:[0,1,1]
	v_cvt_scalef32_pk_f32_fp4 v[18:19], v96, 1.0 op_sel:[1,1,0]
	v_pk_fma_f32 v[8:9], s[24:25], v[18:19], v[8:9] op_sel_hi:[0,1,1]
	v_cvt_scalef32_pk_f32_fp4 v[18:19], v97, 1.0
	v_pk_fma_f32 v[10:11], s[24:25], v[18:19], v[10:11] op_sel_hi:[0,1,1]
	v_cvt_scalef32_pk_f32_fp4 v[18:19], v97, 1.0 op_sel:[1,0,0]
	v_pk_fma_f32 v[12:13], s[24:25], v[18:19], v[12:13] op_sel_hi:[0,1,1]
	v_cvt_scalef32_pk_f32_fp4 v[18:19], v97, 1.0 op_sel:[0,1,0]
	v_pk_fma_f32 v[14:15], s[24:25], v[18:19], v[14:15] op_sel_hi:[0,1,1]
	v_cvt_scalef32_pk_f32_fp4 v[18:19], v97, 1.0 op_sel:[1,1,0]
	v_pk_fma_f32 v[16:17], s[24:25], v[18:19], v[16:17] op_sel_hi:[0,1,1]
	s_waitcnt vmcnt(2)
	v_cvt_scalef32_pk_f32_fp4 v[18:19], v98, 1.0
	s_nop 1
	v_readlane_b32 s24, v126, 59
	s_nop 1
	v_pk_fma_f32 v[2:3], v[18:19], s[24:25], v[2:3] op_sel_hi:[1,0,1]
	v_cvt_scalef32_pk_f32_fp4 v[18:19], v98, 1.0 op_sel:[1,0,0]
	v_pk_fma_f32 v[4:5], s[24:25], v[18:19], v[4:5] op_sel_hi:[0,1,1]
	v_cvt_scalef32_pk_f32_fp4 v[18:19], v98, 1.0 op_sel:[0,1,0]
	v_pk_fma_f32 v[6:7], s[24:25], v[18:19], v[6:7] op_sel_hi:[0,1,1]
	v_cvt_scalef32_pk_f32_fp4 v[18:19], v98, 1.0 op_sel:[1,1,0]
	v_pk_fma_f32 v[8:9], s[24:25], v[18:19], v[8:9] op_sel_hi:[0,1,1]
	v_cvt_scalef32_pk_f32_fp4 v[18:19], v99, 1.0
	v_pk_fma_f32 v[10:11], s[24:25], v[18:19], v[10:11] op_sel_hi:[0,1,1]
	v_cvt_scalef32_pk_f32_fp4 v[18:19], v99, 1.0 op_sel:[1,0,0]
	v_pk_fma_f32 v[12:13], s[24:25], v[18:19], v[12:13] op_sel_hi:[0,1,1]
	v_cvt_scalef32_pk_f32_fp4 v[18:19], v99, 1.0 op_sel:[0,1,0]
	v_pk_fma_f32 v[14:15], s[24:25], v[18:19], v[14:15] op_sel_hi:[0,1,1]
	v_cvt_scalef32_pk_f32_fp4 v[18:19], v99, 1.0 op_sel:[1,1,0]
	v_pk_fma_f32 v[16:17], s[24:25], v[18:19], v[16:17] op_sel_hi:[0,1,1]
	s_waitcnt vmcnt(1)
	v_cvt_scalef32_pk_f32_fp4 v[18:19], v100, 1.0
	s_nop 1
	v_readlane_b32 s24, v126, 55
	s_nop 1
	v_pk_fma_f32 v[2:3], v[18:19], s[24:25], v[2:3] op_sel_hi:[1,0,1]
	v_cvt_scalef32_pk_f32_fp4 v[18:19], v100, 1.0 op_sel:[1,0,0]
	v_pk_fma_f32 v[4:5], s[24:25], v[18:19], v[4:5] op_sel_hi:[0,1,1]
	v_cvt_scalef32_pk_f32_fp4 v[18:19], v100, 1.0 op_sel:[0,1,0]
	v_pk_fma_f32 v[6:7], s[24:25], v[18:19], v[6:7] op_sel_hi:[0,1,1]
	v_cvt_scalef32_pk_f32_fp4 v[18:19], v100, 1.0 op_sel:[1,1,0]
	v_pk_fma_f32 v[8:9], s[24:25], v[18:19], v[8:9] op_sel_hi:[0,1,1]
	v_cvt_scalef32_pk_f32_fp4 v[18:19], v101, 1.0
	v_pk_fma_f32 v[10:11], s[24:25], v[18:19], v[10:11] op_sel_hi:[0,1,1]
	v_cvt_scalef32_pk_f32_fp4 v[18:19], v101, 1.0 op_sel:[1,0,0]
	v_pk_fma_f32 v[12:13], s[24:25], v[18:19], v[12:13] op_sel_hi:[0,1,1]
	v_cvt_scalef32_pk_f32_fp4 v[18:19], v101, 1.0 op_sel:[0,1,0]
	v_pk_fma_f32 v[14:15], s[24:25], v[18:19], v[14:15] op_sel_hi:[0,1,1]
	v_cvt_scalef32_pk_f32_fp4 v[18:19], v101, 1.0 op_sel:[1,1,0]
	v_pk_fma_f32 v[16:17], s[24:25], v[18:19], v[16:17] op_sel_hi:[0,1,1]
	s_waitcnt vmcnt(0)
	v_cvt_scalef32_pk_f32_fp4 v[18:19], v102, 1.0
	s_nop 1
	v_readlane_b32 s24, v126, 63
	s_nop 1
	v_pk_fma_f32 v[2:3], v[18:19], s[24:25], v[2:3] op_sel_hi:[1,0,1]
	v_cvt_scalef32_pk_f32_fp4 v[18:19], v102, 1.0 op_sel:[1,0,0]
	v_pk_fma_f32 v[4:5], s[24:25], v[18:19], v[4:5] op_sel_hi:[0,1,1]
	v_cvt_scalef32_pk_f32_fp4 v[18:19], v102, 1.0 op_sel:[0,1,0]
	v_pk_fma_f32 v[6:7], s[24:25], v[18:19], v[6:7] op_sel_hi:[0,1,1]
	v_cvt_scalef32_pk_f32_fp4 v[18:19], v102, 1.0 op_sel:[1,1,0]
	v_pk_fma_f32 v[8:9], s[24:25], v[18:19], v[8:9] op_sel_hi:[0,1,1]
	v_cvt_scalef32_pk_f32_fp4 v[18:19], v103, 1.0
	v_pk_fma_f32 v[10:11], s[24:25], v[18:19], v[10:11] op_sel_hi:[0,1,1]
	v_cvt_scalef32_pk_f32_fp4 v[18:19], v103, 1.0 op_sel:[1,0,0]
	v_pk_fma_f32 v[12:13], s[24:25], v[18:19], v[12:13] op_sel_hi:[0,1,1]
	v_cvt_scalef32_pk_f32_fp4 v[18:19], v103, 1.0 op_sel:[0,1,0]
	v_pk_fma_f32 v[14:15], s[24:25], v[18:19], v[14:15] op_sel_hi:[0,1,1]
	v_cvt_scalef32_pk_f32_fp4 v[18:19], v103, 1.0 op_sel:[1,1,0]
	v_pk_fma_f32 v[16:17], s[24:25], v[18:19], v[16:17] op_sel_hi:[0,1,1]
